# GEMM K-loops: back-edge rotation - counter / pointer / exit-test SALU block moved ahead of the iteration's last s_barrier (all 13 loops and their peeled first iterations)
# speedup vs baseline: 1.0019x; 1.0019x over previous
; #define PG8_STAGE(bufoff, gbase, voff) do { _Pragma("unroll") for (int _i = 0; _i < 2; ++_i) \
;         __builtin_amdgcn_global_load_lds((const unsigned*)((const char*)(gbase) + (voff)[_i]), (PG8_LAS unsigned*)(lds + (bufoff) + ldsw + _i * 8192), 16, 0, 0); } while (0)
; #define PG8_LDA(dst, b, h) do { _Pragma("unroll") for (int m = 0; m < 4; ++m) _Pragma("unroll") for (int k = 0; k < 2; ++k) dst[m][k] = *(const PG8_LAS bf16x8*)(lds + PG8_SA(b, h) + aoff + m * 2048 + k * 1024); } while (0)
; #define PG8_LDB(dst, b, h) do { _Pragma("unroll") for (int n = 0; n < 2; ++n) _Pragma("unroll") for (int k = 0; k < 2; ++k) dst[n][k] = *(const PG8_LAS bf16x8*)(lds + PG8_SB(b, h) + boff + n * 2048 + k * 1024); } while (0)
;     __host__ __device__ bool next(int i, Unit& u) const {
;         const long L = (long)i * G + c; if (L >= nwg) return false;
;         int wgid = (int)L; { const int q = nwg / NXCD, r = nwg % NXCD, xcd = wgid % NXCD, off = wgid / NXCD; wgid = (xcd < r ? xcd * (q + 1) : r * (q + 1) + (xcd - r) * q) + off; }
;         const int nig = WGM * nN, gid = wgid / nig, fm = gid * WGM, gsz = (nM - fm) < WGM ? (nM - fm) : WGM;
;         u.pm = fm + ((wgid % nig) % gsz); u.pn = (wgid % nig) / gsz; u.ks = 0; return true;
; template <class Epi, class Sched, bool ALIGN_EPI = false, bool SP2 = false>
; __device__ __forceinline__ void gemm_phase(PG8_LAS unsigned char* lds, const Gemm g, const Sched& S, const Epi& E) {
;     ...
;         const bool has_next = S.next(ui + 1, nxt);
;         const char* nA = has_next ? (const char*)g.A + (size_t)nxt.pm * tstep + (size_t)nxt.ks * K * 2 : cA; const char* nB = has_next ? (const char*)g.Bt + (size_t)nxt.pn * tstep + (size_t)nxt.ks * K * 2 : cB;
;         for (int t = 0; t < nt; t += 2) {
;             const bool last = (t == nt - 2);
;             const char* a1 = cA + (size_t)(t + 1) * kstep;
;             const char* a2 = last ? nA : cA + (size_t)(t + 2) * kstep; const char* b2 = last ? nB : cB + (size_t)(t + 2) * kstep;
;             const char* a3 = a2 + kstep; const char* b3 = b2 + kstep;
;             if (last && has_next) S.a_ready(nxt);
;             if constexpr (SP2) {
;             PG8_LDB(B0, 0, 0); PG8_LDB(B1, 0, 1); PG8_SCHED; PG8_LDA(At, 0, 0); PG8_STAGE(PG8_SA(1, 1), a1 + hstep, voffA);
;             PG8_WAIT_V(8); PG8_WAIT_L(0); PG8_BAR; PG8_MMA(0, 0, At, B0); PG8_MMA(0, 1, At, B1); PG8_BAR; PG8_SCHED;
.LBB0_256:
	s_ashr_i32 s13, s12, 31
	s_lshl_b64 s[22:23], s[12:13], 19
	s_add_u32 s22, s28, s22
	s_addc_u32 s23, s29, s23
	s_and_b64 s[24:25], s[2:3], exec
	s_cselect_b32 s13, s23, s45
	s_cselect_b32 s36, s22, s44
	s_ashr_i32 s11, s10, 31
	s_lshl_b64 s[24:25], s[10:11], 19
	s_add_u32 s24, s30, s24
	s_addc_u32 s25, s31, s25
	s_and_b64 s[40:41], s[2:3], exec
	s_cselect_b32 s11, s25, s43
	s_cselect_b32 s37, s24, s42
	s_add_u32 s40, s42, 0x100
	s_addc_u32 s41, s43, 0
	s_add_u32 s42, s44, 0x40080
	s_addc_u32 s43, s45, 0
	s_mov_b32 s48, -2
	ds_read_b128 v[146:149], v152
	ds_read_b128 v[158:161], v152 offset:1024
	ds_read_b128 v[162:165], v152 offset:2048
	ds_read_b128 v[166:169], v152 offset:3072
	ds_read_b128 v[170:173], v153
	ds_read_b128 v[174:177], v153 offset:1024
	ds_read_b128 v[178:181], v153 offset:2048
	ds_read_b128 v[182:185], v153 offset:3072
	s_add_u32 s44, s42, 0xfffc0080
	s_addc_u32 s45, s43, -1
	s_cmp_eq_u32 s48, 12
	s_cselect_b32 s47, s13, s45
	s_cselect_b32 s46, s36, s44
	s_cselect_b32 s45, s11, s41
	s_cselect_b32 s44, s37, s40
	v_lshl_add_u64 v[218:219], s[42:43], 0, v[140:141]
	s_add_i32 m0, s61, 0xc000
	ds_read_b128 v[186:189], v154
	ds_read_b128 v[190:193], v154 offset:1024
	ds_read_b128 v[194:197], v154 offset:2048
	ds_read_b128 v[198:201], v154 offset:3072
	ds_read_b128 v[202:205], v154 offset:4096
	ds_read_b128 v[206:209], v154 offset:5120
	ds_read_b128 v[210:213], v154 offset:6144
	ds_read_b128 v[214:217], v154 offset:7168
	global_load_lds_dwordx4 v[218:219], off
	v_lshl_add_u64 v[218:219], s[42:43], 0, v[138:139]
	s_add_i32 m0, s61, 0xe000
	s_nop 0
	global_load_lds_dwordx4 v[218:219], off
	s_waitcnt vmcnt(8)
	s_waitcnt lgkmcnt(0)
	s_barrier
	s_setprio 1
	s_waitcnt lgkmcnt(0)
	v_mfma_f32_16x16x32_bf16 v[126:129], v[146:149], v[186:189], 0
	v_mfma_f32_16x16x32_bf16 v[118:121], v[162:165], v[186:189], 0
	v_mfma_f32_16x16x32_bf16 v[110:113], v[146:149], v[194:197], 0
	v_mfma_f32_16x16x32_bf16 v[102:105], v[162:165], v[194:197], 0
	v_mfma_f32_16x16x32_bf16 v[94:97], v[146:149], v[202:205], 0
	v_mfma_f32_16x16x32_bf16 v[86:89], v[162:165], v[202:205], 0
	v_mfma_f32_16x16x32_bf16 v[78:81], v[146:149], v[210:213], 0
	v_mfma_f32_16x16x32_bf16 v[70:73], v[162:165], v[210:213], 0
	v_mfma_f32_16x16x32_bf16 v[126:129], v[158:161], v[190:193], v[126:129]
	v_mfma_f32_16x16x32_bf16 v[118:121], v[166:169], v[190:193], v[118:121]
	v_mfma_f32_16x16x32_bf16 v[110:113], v[158:161], v[198:201], v[110:113]
	v_mfma_f32_16x16x32_bf16 v[102:105], v[166:169], v[198:201], v[102:105]
	v_mfma_f32_16x16x32_bf16 v[94:97], v[158:161], v[206:209], v[94:97]
	v_mfma_f32_16x16x32_bf16 v[86:89], v[166:169], v[206:209], v[86:89]
	v_mfma_f32_16x16x32_bf16 v[78:81], v[158:161], v[214:217], v[78:81]
	v_mfma_f32_16x16x32_bf16 v[70:73], v[166:169], v[214:217], v[70:73]
	s_setprio 0
	s_setprio 1
	v_mfma_f32_16x16x32_bf16 v[122:125], v[170:173], v[186:189], 0
	v_mfma_f32_16x16x32_bf16 v[114:117], v[178:181], v[186:189], 0
	v_mfma_f32_16x16x32_bf16 v[106:109], v[170:173], v[194:197], 0
	v_mfma_f32_16x16x32_bf16 v[98:101], v[178:181], v[194:197], 0
	v_mfma_f32_16x16x32_bf16 v[90:93], v[170:173], v[202:205], 0
	v_mfma_f32_16x16x32_bf16 v[82:85], v[178:181], v[202:205], 0
	v_mfma_f32_16x16x32_bf16 v[74:77], v[170:173], v[210:213], 0
	v_mfma_f32_16x16x32_bf16 v[66:69], v[178:181], v[210:213], 0
	v_mfma_f32_16x16x32_bf16 v[122:125], v[174:177], v[190:193], v[122:125]
	v_mfma_f32_16x16x32_bf16 v[114:117], v[182:185], v[190:193], v[114:117]
	v_mfma_f32_16x16x32_bf16 v[106:109], v[174:177], v[198:201], v[106:109]
	v_mfma_f32_16x16x32_bf16 v[98:101], v[182:185], v[198:201], v[98:101]
	v_mfma_f32_16x16x32_bf16 v[90:93], v[174:177], v[206:209], v[90:93]
	v_mfma_f32_16x16x32_bf16 v[82:85], v[182:185], v[206:209], v[82:85]
	v_mfma_f32_16x16x32_bf16 v[74:77], v[174:177], v[214:217], v[74:77]
	v_mfma_f32_16x16x32_bf16 v[66:69], v[182:185], v[214:217], v[66:69]
	s_setprio 0
	s_barrier
	s_mov_b32 m0, s39
	v_lshl_add_u64 v[218:219], s[44:45], 0, v[134:135]
	s_add_u32 s50, s44, 0x40000
	ds_read_b128 v[186:189], v154 offset:16384
	ds_read_b128 v[190:193], v154 offset:17408
	ds_read_b128 v[194:197], v154 offset:18432
	ds_read_b128 v[198:201], v154 offset:19456
	ds_read_b128 v[202:205], v154 offset:20480
	ds_read_b128 v[206:209], v154 offset:21504
	ds_read_b128 v[210:213], v154 offset:22528
	ds_read_b128 v[214:217], v154 offset:23552
	global_load_lds_dwordx4 v[218:219], off
	v_lshl_add_u64 v[220:221], s[44:45], 0, v[130:131]
	s_mov_b32 m0, s56
	s_addc_u32 s51, s45, 0
	global_load_lds_dwordx4 v[220:221], off
	v_lshl_add_u64 v[222:223], s[50:51], 0, v[134:135]
	s_mov_b32 m0, s57
	v_lshl_add_u64 v[224:225], s[46:47], 0, v[132:133]
	global_load_lds_dwordx4 v[222:223], off
	v_lshl_add_u64 v[222:223], s[50:51], 0, v[130:131]
	s_mov_b32 m0, s60
	s_nop 0
	global_load_lds_dwordx4 v[222:223], off
	v_lshl_add_u64 v[222:223], s[46:47], 0, v[136:137]
	s_mov_b32 m0, s61
	s_nop 0
	global_load_lds_dwordx4 v[222:223], off
	s_mov_b32 m0, s62
	s_nop 0
	global_load_lds_dwordx4 v[224:225], off
	s_waitcnt vmcnt(8)
	s_waitcnt lgkmcnt(0)
	s_barrier
; #define PG8_STAGE(bufoff, gbase, voff) do { _Pragma("unroll") for (int _i = 0; _i < 2; ++_i) \
;         __builtin_amdgcn_global_load_lds((const unsigned*)((const char*)(gbase) + (voff)[_i]), (PG8_LAS unsigned*)(lds + (bufoff) + ldsw + _i * 8192), 16, 0, 0); } while (0)
; #define PG8_LDA(dst, b, h) do { _Pragma("unroll") for (int m = 0; m < 4; ++m) _Pragma("unroll") for (int k = 0; k < 2; ++k) dst[m][k] = *(const PG8_LAS bf16x8*)(lds + PG8_SA(b, h) + aoff + m * 2048 + k * 1024); } while (0)
; #define PG8_LDB(dst, b, h) do { _Pragma("unroll") for (int n = 0; n < 2; ++n) _Pragma("unroll") for (int k = 0; k < 2; ++k) dst[n][k] = *(const PG8_LAS bf16x8*)(lds + PG8_SB(b, h) + boff + n * 2048 + k * 1024); } while (0)
; #define PG8_MMA(ai, bj, At, Bt) do { __builtin_amdgcn_s_setprio(1); _Pragma("unroll") for (int m = 0; m < 4; ++m) _Pragma("unroll") for (int n = 0; n < 2; ++n) _Pragma("unroll") for (int k = 0; k < 2; ++k) \
;         acc[ai][bj][m][n] = __builtin_amdgcn_mfma_f32_16x16x32_bf16(Bt[n][k], At[m][k], acc[ai][bj][m][n], 0, 0, 0); __builtin_amdgcn_s_setprio(0); } while (0)
; #define PG8_WAIT_V(n) asm volatile("s_waitcnt vmcnt(" #n ")" ::: "memory")
; #define PG8_WAIT_L(n) asm volatile("s_waitcnt lgkmcnt(" #n ")" ::: "memory")
; #define PG8_BAR __builtin_amdgcn_s_barrier()
; #define PG8_SCHED __builtin_amdgcn_sched_barrier(0)
; template <class Epi, class Sched, bool ALIGN_EPI = false, bool SP2 = false>
; __device__ __forceinline__ void gemm_phase(PG8_LAS unsigned char* lds, const Gemm g, const Sched& S, const Epi& E) {
;     ...
;             PG8_WAIT_V(8); PG8_WAIT_L(0); PG8_BAR; PG8_MMA(0, 0, At, B0); PG8_MMA(0, 1, At, B1); PG8_BAR; PG8_SCHED;
;             PG8_LDA(At, 0, 1); PG8_STAGE(PG8_SB(0, 0), b2, voffB); PG8_STAGE(PG8_SB(0, 1), b2 + hstep, voffB); PG8_STAGE(PG8_SA(0, 0), a2, voffA);
;             PG8_WAIT_V(8); PG8_WAIT_L(0); PG8_BAR; PG8_MMA(1, 0, At, B0); PG8_MMA(1, 1, At, B1); PG8_BAR; PG8_SCHED;
;             PG8_LDB(B0, 1, 0); PG8_LDB(B1, 1, 1); PG8_SCHED; PG8_LDA(At, 1, 0); PG8_STAGE(PG8_SA(0, 1), a2 + hstep, voffA);
;             PG8_WAIT_V(8); PG8_WAIT_L(0); PG8_BAR; PG8_MMA(0, 0, At, B0); PG8_MMA(0, 1, At, B1); PG8_BAR; PG8_SCHED;
	s_setprio 1
	s_waitcnt lgkmcnt(0)
	v_mfma_f32_16x16x32_bf16 v[62:65], v[146:149], v[186:189], 0
	v_mfma_f32_16x16x32_bf16 v[54:57], v[162:165], v[186:189], 0
	v_mfma_f32_16x16x32_bf16 v[46:49], v[146:149], v[194:197], 0
	v_mfma_f32_16x16x32_bf16 v[38:41], v[162:165], v[194:197], 0
	v_mfma_f32_16x16x32_bf16 v[30:33], v[146:149], v[202:205], 0
	v_mfma_f32_16x16x32_bf16 v[22:25], v[162:165], v[202:205], 0
	v_mfma_f32_16x16x32_bf16 v[14:17], v[146:149], v[210:213], 0
	v_mfma_f32_16x16x32_bf16 v[6:9], v[162:165], v[210:213], 0
	v_mfma_f32_16x16x32_bf16 v[62:65], v[158:161], v[190:193], v[62:65]
	v_mfma_f32_16x16x32_bf16 v[54:57], v[166:169], v[190:193], v[54:57]
	v_mfma_f32_16x16x32_bf16 v[46:49], v[158:161], v[198:201], v[46:49]
	v_mfma_f32_16x16x32_bf16 v[38:41], v[166:169], v[198:201], v[38:41]
	v_mfma_f32_16x16x32_bf16 v[30:33], v[158:161], v[206:209], v[30:33]
	v_mfma_f32_16x16x32_bf16 v[22:25], v[166:169], v[206:209], v[22:25]
	v_mfma_f32_16x16x32_bf16 v[14:17], v[158:161], v[214:217], v[14:17]
	v_mfma_f32_16x16x32_bf16 v[6:9], v[166:169], v[214:217], v[6:9]
	s_setprio 0
	s_setprio 1
	v_mfma_f32_16x16x32_bf16 v[58:61], v[170:173], v[186:189], 0
	v_mfma_f32_16x16x32_bf16 v[50:53], v[178:181], v[186:189], 0
	v_mfma_f32_16x16x32_bf16 v[42:45], v[170:173], v[194:197], 0
	v_mfma_f32_16x16x32_bf16 v[34:37], v[178:181], v[194:197], 0
	v_mfma_f32_16x16x32_bf16 v[26:29], v[170:173], v[202:205], 0
	v_mfma_f32_16x16x32_bf16 v[18:21], v[178:181], v[202:205], 0
	v_mfma_f32_16x16x32_bf16 v[10:13], v[170:173], v[210:213], 0
	v_mfma_f32_16x16x32_bf16 v[2:5], v[178:181], v[210:213], 0
	v_mfma_f32_16x16x32_bf16 v[58:61], v[174:177], v[190:193], v[58:61]
	v_mfma_f32_16x16x32_bf16 v[50:53], v[182:185], v[190:193], v[50:53]
	v_mfma_f32_16x16x32_bf16 v[42:45], v[174:177], v[198:201], v[42:45]
	v_mfma_f32_16x16x32_bf16 v[34:37], v[182:185], v[198:201], v[34:37]
	v_mfma_f32_16x16x32_bf16 v[26:29], v[174:177], v[206:209], v[26:29]
	v_mfma_f32_16x16x32_bf16 v[18:21], v[182:185], v[206:209], v[18:21]
	v_mfma_f32_16x16x32_bf16 v[10:13], v[174:177], v[214:217], v[10:13]
	v_mfma_f32_16x16x32_bf16 v[2:5], v[182:185], v[214:217], v[2:5]
	s_setprio 0
	s_barrier
	ds_read_b128 v[146:149], v155
	ds_read_b128 v[158:161], v155 offset:1024
	ds_read_b128 v[162:165], v155 offset:2048
	ds_read_b128 v[166:169], v155 offset:3072
	ds_read_b128 v[170:173], v156
	ds_read_b128 v[174:177], v156 offset:1024
	ds_read_b128 v[178:181], v156 offset:2048
	ds_read_b128 v[182:185], v156 offset:3072
	s_add_u32 s46, s46, 0x40000
	s_addc_u32 s47, s47, 0
	s_mov_b32 m0, s63
	v_lshl_add_u64 v[226:227], s[46:47], 0, v[136:137]
	ds_read_b128 v[186:189], v154 offset:32768
	ds_read_b128 v[190:193], v154 offset:33792
	ds_read_b128 v[194:197], v154 offset:34816
	ds_read_b128 v[198:201], v154 offset:35840
	ds_read_b128 v[202:205], v154 offset:36864
	ds_read_b128 v[206:209], v154 offset:37888
	ds_read_b128 v[210:213], v154 offset:38912
	ds_read_b128 v[214:217], v154 offset:39936
	global_load_lds_dwordx4 v[226:227], off
	v_lshl_add_u64 v[226:227], s[46:47], 0, v[132:133]
	s_mov_b32 m0, s64
	s_nop 0
	global_load_lds_dwordx4 v[226:227], off
	s_waitcnt vmcnt(8)
	s_waitcnt lgkmcnt(0)
	s_barrier
	s_setprio 1
	s_waitcnt lgkmcnt(0)
	v_mfma_f32_16x16x32_bf16 v[126:129], v[146:149], v[186:189], v[126:129]
	v_mfma_f32_16x16x32_bf16 v[118:121], v[162:165], v[186:189], v[118:121]
	v_mfma_f32_16x16x32_bf16 v[110:113], v[146:149], v[194:197], v[110:113]
	v_mfma_f32_16x16x32_bf16 v[102:105], v[162:165], v[194:197], v[102:105]
	v_mfma_f32_16x16x32_bf16 v[94:97], v[146:149], v[202:205], v[94:97]
	v_mfma_f32_16x16x32_bf16 v[86:89], v[162:165], v[202:205], v[86:89]
	v_mfma_f32_16x16x32_bf16 v[78:81], v[146:149], v[210:213], v[78:81]
	v_mfma_f32_16x16x32_bf16 v[70:73], v[162:165], v[210:213], v[70:73]
	v_mfma_f32_16x16x32_bf16 v[126:129], v[158:161], v[190:193], v[126:129]
	v_mfma_f32_16x16x32_bf16 v[118:121], v[166:169], v[190:193], v[118:121]
	v_mfma_f32_16x16x32_bf16 v[110:113], v[158:161], v[198:201], v[110:113]
	v_mfma_f32_16x16x32_bf16 v[102:105], v[166:169], v[198:201], v[102:105]
	v_mfma_f32_16x16x32_bf16 v[94:97], v[158:161], v[206:209], v[94:97]
	v_mfma_f32_16x16x32_bf16 v[86:89], v[166:169], v[206:209], v[86:89]
	v_mfma_f32_16x16x32_bf16 v[78:81], v[158:161], v[214:217], v[78:81]
	v_mfma_f32_16x16x32_bf16 v[70:73], v[166:169], v[214:217], v[70:73]
	s_setprio 0
	s_setprio 1
	v_mfma_f32_16x16x32_bf16 v[122:125], v[170:173], v[186:189], v[122:125]
	v_mfma_f32_16x16x32_bf16 v[114:117], v[178:181], v[186:189], v[114:117]
	v_mfma_f32_16x16x32_bf16 v[106:109], v[170:173], v[194:197], v[106:109]
	v_mfma_f32_16x16x32_bf16 v[98:101], v[178:181], v[194:197], v[98:101]
	v_mfma_f32_16x16x32_bf16 v[90:93], v[170:173], v[202:205], v[90:93]
	v_mfma_f32_16x16x32_bf16 v[82:85], v[178:181], v[202:205], v[82:85]
	v_mfma_f32_16x16x32_bf16 v[74:77], v[170:173], v[210:213], v[74:77]
	v_mfma_f32_16x16x32_bf16 v[66:69], v[178:181], v[210:213], v[66:69]
	v_mfma_f32_16x16x32_bf16 v[122:125], v[174:177], v[190:193], v[122:125]
	v_mfma_f32_16x16x32_bf16 v[114:117], v[182:185], v[190:193], v[114:117]
	v_mfma_f32_16x16x32_bf16 v[106:109], v[174:177], v[198:201], v[106:109]
	v_mfma_f32_16x16x32_bf16 v[98:101], v[182:185], v[198:201], v[98:101]
	v_mfma_f32_16x16x32_bf16 v[90:93], v[174:177], v[206:209], v[90:93]
	v_mfma_f32_16x16x32_bf16 v[82:85], v[182:185], v[206:209], v[82:85]
	v_mfma_f32_16x16x32_bf16 v[74:77], v[174:177], v[214:217], v[74:77]
	v_mfma_f32_16x16x32_bf16 v[66:69], v[182:185], v[214:217], v[66:69]
	s_setprio 0
	s_barrier
; #define PG8_STAGE(bufoff, gbase, voff) do { _Pragma("unroll") for (int _i = 0; _i < 2; ++_i) \
;         __builtin_amdgcn_global_load_lds((const unsigned*)((const char*)(gbase) + (voff)[_i]), (PG8_LAS unsigned*)(lds + (bufoff) + ldsw + _i * 8192), 16, 0, 0); } while (0)
; #define PG8_LDA(dst, b, h) do { _Pragma("unroll") for (int m = 0; m < 4; ++m) _Pragma("unroll") for (int k = 0; k < 2; ++k) dst[m][k] = *(const PG8_LAS bf16x8*)(lds + PG8_SA(b, h) + aoff + m * 2048 + k * 1024); } while (0)
; #define PG8_LDB(dst, b, h) do { _Pragma("unroll") for (int n = 0; n < 2; ++n) _Pragma("unroll") for (int k = 0; k < 2; ++k) dst[n][k] = *(const PG8_LAS bf16x8*)(lds + PG8_SB(b, h) + boff + n * 2048 + k * 1024); } while (0)
; #define PG8_MMA(ai, bj, At, Bt) do { __builtin_amdgcn_s_setprio(1); _Pragma("unroll") for (int m = 0; m < 4; ++m) _Pragma("unroll") for (int n = 0; n < 2; ++n) _Pragma("unroll") for (int k = 0; k < 2; ++k) \
;         acc[ai][bj][m][n] = __builtin_amdgcn_mfma_f32_16x16x32_bf16(Bt[n][k], At[m][k], acc[ai][bj][m][n], 0, 0, 0); __builtin_amdgcn_s_setprio(0); } while (0)
; #define PG8_WAIT_V(n) asm volatile("s_waitcnt vmcnt(" #n ")" ::: "memory")
; template <class Epi, class Sched, bool ALIGN_EPI = false, bool SP2 = false>
; __device__ __forceinline__ void gemm_phase(PG8_LAS unsigned char* lds, const Gemm g, const Sched& S, const Epi& E) {
;     ...
;             PG8_LDB(B0, 0, 0); PG8_LDB(B1, 0, 1); PG8_SCHED; PG8_LDA(At, 0, 0); PG8_STAGE(PG8_SA(1, 1), a1 + hstep, voffA);
;             PG8_WAIT_V(8); PG8_WAIT_L(0); PG8_BAR; PG8_MMA(0, 0, At, B0); PG8_MMA(0, 1, At, B1); PG8_BAR; PG8_SCHED;
;             PG8_LDA(At, 0, 1); PG8_STAGE(PG8_SB(0, 0), b2, voffB); PG8_STAGE(PG8_SB(0, 1), b2 + hstep, voffB); PG8_STAGE(PG8_SA(0, 0), a2, voffA);
;             PG8_WAIT_V(8); PG8_WAIT_L(0); PG8_BAR; PG8_MMA(1, 0, At, B0); PG8_MMA(1, 1, At, B1); PG8_BAR; PG8_SCHED;
;             PG8_LDB(B0, 1, 0); PG8_LDB(B1, 1, 1); PG8_SCHED; PG8_LDA(At, 1, 0); PG8_STAGE(PG8_SA(0, 1), a2 + hstep, voffA);
;             PG8_WAIT_V(8); PG8_WAIT_L(0); PG8_BAR; PG8_MMA(0, 0, At, B0); PG8_MMA(0, 1, At, B1); PG8_BAR; PG8_SCHED;
;             PG8_LDA(At, 1, 1); PG8_STAGE(PG8_SB(1, 0), b3, voffB); PG8_STAGE(PG8_SB(1, 1), b3 + hstep, voffB); PG8_STAGE(PG8_SA(1, 0), a3, voffA);
;             PG8_WAIT_V(8); PG8_WAIT_L(0); PG8_BAR; PG8_MMA(1, 0, At, B0); PG8_MMA(1, 1, At, B1); PG8_BAR; PG8_SCHED;
	s_mov_b32 m0, s65
	v_lshl_add_u64 v[218:219], v[218:219], 0, s[6:7]
	s_add_u32 s44, s44, 0x40080
	ds_read_b128 v[186:189], v154 offset:49152
	ds_read_b128 v[190:193], v154 offset:50176
	ds_read_b128 v[194:197], v154 offset:51200
	ds_read_b128 v[198:201], v154 offset:52224
	ds_read_b128 v[202:205], v154 offset:53248
	ds_read_b128 v[206:209], v154 offset:54272
	ds_read_b128 v[210:213], v154 offset:55296
	ds_read_b128 v[214:217], v154 offset:56320
	global_load_lds_dwordx4 v[218:219], off
	v_lshl_add_u64 v[218:219], v[220:221], 0, s[6:7]
	s_mov_b32 m0, s66
	s_addc_u32 s45, s45, 0
	global_load_lds_dwordx4 v[218:219], off
	v_lshl_add_u64 v[218:219], s[44:45], 0, v[134:135]
	s_mov_b32 m0, s69
	s_nop 0
	global_load_lds_dwordx4 v[218:219], off
	v_lshl_add_u64 v[218:219], s[44:45], 0, v[130:131]
	s_mov_b32 m0, s70
	s_nop 0
	global_load_lds_dwordx4 v[218:219], off
	v_lshl_add_u64 v[218:219], v[222:223], 0, s[6:7]
	s_mov_b32 m0, s67
	s_nop 0
	global_load_lds_dwordx4 v[218:219], off
	v_lshl_add_u64 v[218:219], v[224:225], 0, s[6:7]
	s_mov_b32 m0, s68
	s_nop 0
	global_load_lds_dwordx4 v[218:219], off
	s_waitcnt vmcnt(8)
	s_waitcnt lgkmcnt(0)
	s_barrier
	s_setprio 1
	s_waitcnt lgkmcnt(0)
	v_mfma_f32_16x16x32_bf16 v[62:65], v[146:149], v[186:189], v[62:65]
	v_mfma_f32_16x16x32_bf16 v[54:57], v[162:165], v[186:189], v[54:57]
	v_mfma_f32_16x16x32_bf16 v[46:49], v[146:149], v[194:197], v[46:49]
	v_mfma_f32_16x16x32_bf16 v[38:41], v[162:165], v[194:197], v[38:41]
	v_mfma_f32_16x16x32_bf16 v[30:33], v[146:149], v[202:205], v[30:33]
	v_mfma_f32_16x16x32_bf16 v[22:25], v[162:165], v[202:205], v[22:25]
	v_mfma_f32_16x16x32_bf16 v[14:17], v[146:149], v[210:213], v[14:17]
	v_mfma_f32_16x16x32_bf16 v[6:9], v[162:165], v[210:213], v[6:9]
	v_mfma_f32_16x16x32_bf16 v[62:65], v[158:161], v[190:193], v[62:65]
	v_mfma_f32_16x16x32_bf16 v[54:57], v[166:169], v[190:193], v[54:57]
	v_mfma_f32_16x16x32_bf16 v[46:49], v[158:161], v[198:201], v[46:49]
	v_mfma_f32_16x16x32_bf16 v[38:41], v[166:169], v[198:201], v[38:41]
	v_mfma_f32_16x16x32_bf16 v[30:33], v[158:161], v[206:209], v[30:33]
	v_mfma_f32_16x16x32_bf16 v[22:25], v[166:169], v[206:209], v[22:25]
	v_mfma_f32_16x16x32_bf16 v[14:17], v[158:161], v[214:217], v[14:17]
	v_mfma_f32_16x16x32_bf16 v[6:9], v[166:169], v[214:217], v[6:9]
	s_setprio 0
	s_setprio 1
	v_mfma_f32_16x16x32_bf16 v[58:61], v[170:173], v[186:189], v[58:61]
	v_mfma_f32_16x16x32_bf16 v[50:53], v[178:181], v[186:189], v[50:53]
	v_mfma_f32_16x16x32_bf16 v[42:45], v[170:173], v[194:197], v[42:45]
	v_mfma_f32_16x16x32_bf16 v[34:37], v[178:181], v[194:197], v[34:37]
	v_mfma_f32_16x16x32_bf16 v[26:29], v[170:173], v[202:205], v[26:29]
	v_mfma_f32_16x16x32_bf16 v[18:21], v[178:181], v[202:205], v[18:21]
	v_mfma_f32_16x16x32_bf16 v[10:13], v[170:173], v[210:213], v[10:13]
	v_mfma_f32_16x16x32_bf16 v[2:5], v[178:181], v[210:213], v[2:5]
	v_mfma_f32_16x16x32_bf16 v[58:61], v[174:177], v[190:193], v[58:61]
	v_mfma_f32_16x16x32_bf16 v[50:53], v[182:185], v[190:193], v[50:53]
	v_mfma_f32_16x16x32_bf16 v[42:45], v[174:177], v[198:201], v[42:45]
	v_mfma_f32_16x16x32_bf16 v[34:37], v[182:185], v[198:201], v[34:37]
	v_mfma_f32_16x16x32_bf16 v[26:29], v[174:177], v[206:209], v[26:29]
	v_mfma_f32_16x16x32_bf16 v[18:21], v[182:185], v[206:209], v[18:21]
	v_mfma_f32_16x16x32_bf16 v[10:13], v[174:177], v[214:217], v[10:13]
	v_mfma_f32_16x16x32_bf16 v[2:5], v[182:185], v[214:217], v[2:5]
	s_setprio 0
	s_add_i32 s48, s48, 2
	s_add_u32 s40, s40, 0x100
	s_addc_u32 s41, s41, 0
	s_add_u32 s42, s42, 0x100
	s_addc_u32 s43, s43, 0
	s_cmp_gt_u32 s48, 13
	s_barrier
.LBB0_257:
	ds_read_b128 v[146:149], v152
	ds_read_b128 v[158:161], v152 offset:1024
	ds_read_b128 v[162:165], v152 offset:2048
	ds_read_b128 v[166:169], v152 offset:3072
	ds_read_b128 v[170:173], v153
	ds_read_b128 v[174:177], v153 offset:1024
	ds_read_b128 v[178:181], v153 offset:2048
	ds_read_b128 v[182:185], v153 offset:3072
	s_add_u32 s44, s42, 0xfffc0080
	s_addc_u32 s45, s43, -1
	s_cmp_eq_u32 s48, 12
	s_cselect_b32 s47, s13, s45
	s_cselect_b32 s46, s36, s44
	s_cselect_b32 s45, s11, s41
	s_cselect_b32 s44, s37, s40
	v_lshl_add_u64 v[218:219], s[42:43], 0, v[140:141]
	s_add_i32 m0, s61, 0xc000
	ds_read_b128 v[186:189], v154
	ds_read_b128 v[190:193], v154 offset:1024
	ds_read_b128 v[194:197], v154 offset:2048
	ds_read_b128 v[198:201], v154 offset:3072
	ds_read_b128 v[202:205], v154 offset:4096
	ds_read_b128 v[206:209], v154 offset:5120
	ds_read_b128 v[210:213], v154 offset:6144
	ds_read_b128 v[214:217], v154 offset:7168
	global_load_lds_dwordx4 v[218:219], off
	v_lshl_add_u64 v[218:219], s[42:43], 0, v[138:139]
	s_add_i32 m0, s61, 0xe000
	s_nop 0
	global_load_lds_dwordx4 v[218:219], off
	s_waitcnt vmcnt(8)
	s_waitcnt lgkmcnt(0)
	s_barrier
; #define PG8_STAGE(bufoff, gbase, voff) do { _Pragma("unroll") for (int _i = 0; _i < 2; ++_i) \
;         __builtin_amdgcn_global_load_lds((const unsigned*)((const char*)(gbase) + (voff)[_i]), (PG8_LAS unsigned*)(lds + (bufoff) + ldsw + _i * 8192), 16, 0, 0); } while (0)
; #define PG8_LDA(dst, b, h) do { _Pragma("unroll") for (int m = 0; m < 4; ++m) _Pragma("unroll") for (int k = 0; k < 2; ++k) dst[m][k] = *(const PG8_LAS bf16x8*)(lds + PG8_SA(b, h) + aoff + m * 2048 + k * 1024); } while (0)
; #define PG8_MMA(ai, bj, At, Bt) do { __builtin_amdgcn_s_setprio(1); _Pragma("unroll") for (int m = 0; m < 4; ++m) _Pragma("unroll") for (int n = 0; n < 2; ++n) _Pragma("unroll") for (int k = 0; k < 2; ++k) \
;         acc[ai][bj][m][n] = __builtin_amdgcn_mfma_f32_16x16x32_bf16(Bt[n][k], At[m][k], acc[ai][bj][m][n], 0, 0, 0); __builtin_amdgcn_s_setprio(0); } while (0)
; #define PG8_WAIT_V(n) asm volatile("s_waitcnt vmcnt(" #n ")" ::: "memory")
; #define PG8_WAIT_L(n) asm volatile("s_waitcnt lgkmcnt(" #n ")" ::: "memory")
; #define PG8_BAR __builtin_amdgcn_s_barrier()
; #define PG8_SCHED __builtin_amdgcn_sched_barrier(0)
; template <class Epi, class Sched, bool ALIGN_EPI = false, bool SP2 = false>
; __device__ __forceinline__ void gemm_phase(PG8_LAS unsigned char* lds, const Gemm g, const Sched& S, const Epi& E) {
;     ...
;             PG8_WAIT_V(8); PG8_WAIT_L(0); PG8_BAR; PG8_MMA(0, 0, At, B0); PG8_MMA(0, 1, At, B1); PG8_BAR; PG8_SCHED;
;             PG8_LDA(At, 0, 1); PG8_STAGE(PG8_SB(0, 0), b2, voffB); PG8_STAGE(PG8_SB(0, 1), b2 + hstep, voffB); PG8_STAGE(PG8_SA(0, 0), a2, voffA);
;             PG8_WAIT_V(8); PG8_WAIT_L(0); PG8_BAR; PG8_MMA(1, 0, At, B0); PG8_MMA(1, 1, At, B1); PG8_BAR; PG8_SCHED;
	s_setprio 1
	s_waitcnt lgkmcnt(0)
	v_mfma_f32_16x16x32_bf16 v[126:129], v[146:149], v[186:189], v[126:129]
	v_mfma_f32_16x16x32_bf16 v[118:121], v[162:165], v[186:189], v[118:121]
	v_mfma_f32_16x16x32_bf16 v[110:113], v[146:149], v[194:197], v[110:113]
	v_mfma_f32_16x16x32_bf16 v[102:105], v[162:165], v[194:197], v[102:105]
	v_mfma_f32_16x16x32_bf16 v[94:97], v[146:149], v[202:205], v[94:97]
	v_mfma_f32_16x16x32_bf16 v[86:89], v[162:165], v[202:205], v[86:89]
	v_mfma_f32_16x16x32_bf16 v[78:81], v[146:149], v[210:213], v[78:81]
	v_mfma_f32_16x16x32_bf16 v[70:73], v[162:165], v[210:213], v[70:73]
	v_mfma_f32_16x16x32_bf16 v[126:129], v[158:161], v[190:193], v[126:129]
	v_mfma_f32_16x16x32_bf16 v[118:121], v[166:169], v[190:193], v[118:121]
	v_mfma_f32_16x16x32_bf16 v[110:113], v[158:161], v[198:201], v[110:113]
	v_mfma_f32_16x16x32_bf16 v[102:105], v[166:169], v[198:201], v[102:105]
	v_mfma_f32_16x16x32_bf16 v[94:97], v[158:161], v[206:209], v[94:97]
	v_mfma_f32_16x16x32_bf16 v[86:89], v[166:169], v[206:209], v[86:89]
	v_mfma_f32_16x16x32_bf16 v[78:81], v[158:161], v[214:217], v[78:81]
	v_mfma_f32_16x16x32_bf16 v[70:73], v[166:169], v[214:217], v[70:73]
	s_setprio 0
	s_setprio 1
	v_mfma_f32_16x16x32_bf16 v[122:125], v[170:173], v[186:189], v[122:125]
	v_mfma_f32_16x16x32_bf16 v[114:117], v[178:181], v[186:189], v[114:117]
	v_mfma_f32_16x16x32_bf16 v[106:109], v[170:173], v[194:197], v[106:109]
	v_mfma_f32_16x16x32_bf16 v[98:101], v[178:181], v[194:197], v[98:101]
	v_mfma_f32_16x16x32_bf16 v[90:93], v[170:173], v[202:205], v[90:93]
	v_mfma_f32_16x16x32_bf16 v[82:85], v[178:181], v[202:205], v[82:85]
	v_mfma_f32_16x16x32_bf16 v[74:77], v[170:173], v[210:213], v[74:77]
	v_mfma_f32_16x16x32_bf16 v[66:69], v[178:181], v[210:213], v[66:69]
	v_mfma_f32_16x16x32_bf16 v[122:125], v[174:177], v[190:193], v[122:125]
	v_mfma_f32_16x16x32_bf16 v[114:117], v[182:185], v[190:193], v[114:117]
	v_mfma_f32_16x16x32_bf16 v[106:109], v[174:177], v[198:201], v[106:109]
	v_mfma_f32_16x16x32_bf16 v[98:101], v[182:185], v[198:201], v[98:101]
	v_mfma_f32_16x16x32_bf16 v[90:93], v[174:177], v[206:209], v[90:93]
	v_mfma_f32_16x16x32_bf16 v[82:85], v[182:185], v[206:209], v[82:85]
	v_mfma_f32_16x16x32_bf16 v[74:77], v[174:177], v[214:217], v[74:77]
	v_mfma_f32_16x16x32_bf16 v[66:69], v[182:185], v[214:217], v[66:69]
	s_setprio 0
	s_barrier
	s_mov_b32 m0, s39
	v_lshl_add_u64 v[218:219], s[44:45], 0, v[134:135]
	s_add_u32 s50, s44, 0x40000
	ds_read_b128 v[186:189], v154 offset:16384
	ds_read_b128 v[190:193], v154 offset:17408
	ds_read_b128 v[194:197], v154 offset:18432
	ds_read_b128 v[198:201], v154 offset:19456
	ds_read_b128 v[202:205], v154 offset:20480
	ds_read_b128 v[206:209], v154 offset:21504
	ds_read_b128 v[210:213], v154 offset:22528
	ds_read_b128 v[214:217], v154 offset:23552
	global_load_lds_dwordx4 v[218:219], off
	v_lshl_add_u64 v[220:221], s[44:45], 0, v[130:131]
	s_mov_b32 m0, s56
	s_addc_u32 s51, s45, 0
	global_load_lds_dwordx4 v[220:221], off
	v_lshl_add_u64 v[222:223], s[50:51], 0, v[134:135]
	s_mov_b32 m0, s57
	v_lshl_add_u64 v[224:225], s[46:47], 0, v[132:133]
	global_load_lds_dwordx4 v[222:223], off
	v_lshl_add_u64 v[222:223], s[50:51], 0, v[130:131]
	s_mov_b32 m0, s60
	s_nop 0
	global_load_lds_dwordx4 v[222:223], off
	v_lshl_add_u64 v[222:223], s[46:47], 0, v[136:137]
	s_mov_b32 m0, s61
	s_nop 0
	global_load_lds_dwordx4 v[222:223], off
	s_mov_b32 m0, s62
	s_nop 0
	global_load_lds_dwordx4 v[224:225], off
	s_waitcnt vmcnt(8)
	s_waitcnt lgkmcnt(0)
	s_barrier
	s_setprio 1
	s_waitcnt lgkmcnt(0)
	v_mfma_f32_16x16x32_bf16 v[62:65], v[146:149], v[186:189], v[62:65]
	v_mfma_f32_16x16x32_bf16 v[54:57], v[162:165], v[186:189], v[54:57]
	v_mfma_f32_16x16x32_bf16 v[46:49], v[146:149], v[194:197], v[46:49]
	v_mfma_f32_16x16x32_bf16 v[38:41], v[162:165], v[194:197], v[38:41]
	v_mfma_f32_16x16x32_bf16 v[30:33], v[146:149], v[202:205], v[30:33]
	v_mfma_f32_16x16x32_bf16 v[22:25], v[162:165], v[202:205], v[22:25]
	v_mfma_f32_16x16x32_bf16 v[14:17], v[146:149], v[210:213], v[14:17]
	v_mfma_f32_16x16x32_bf16 v[6:9], v[162:165], v[210:213], v[6:9]
	v_mfma_f32_16x16x32_bf16 v[62:65], v[158:161], v[190:193], v[62:65]
	v_mfma_f32_16x16x32_bf16 v[54:57], v[166:169], v[190:193], v[54:57]
	v_mfma_f32_16x16x32_bf16 v[46:49], v[158:161], v[198:201], v[46:49]
	v_mfma_f32_16x16x32_bf16 v[38:41], v[166:169], v[198:201], v[38:41]
	v_mfma_f32_16x16x32_bf16 v[30:33], v[158:161], v[206:209], v[30:33]
	v_mfma_f32_16x16x32_bf16 v[22:25], v[166:169], v[206:209], v[22:25]
	v_mfma_f32_16x16x32_bf16 v[14:17], v[158:161], v[214:217], v[14:17]
	v_mfma_f32_16x16x32_bf16 v[6:9], v[166:169], v[214:217], v[6:9]
	s_setprio 0
	s_setprio 1
	v_mfma_f32_16x16x32_bf16 v[58:61], v[170:173], v[186:189], v[58:61]
	v_mfma_f32_16x16x32_bf16 v[50:53], v[178:181], v[186:189], v[50:53]
	v_mfma_f32_16x16x32_bf16 v[42:45], v[170:173], v[194:197], v[42:45]
	v_mfma_f32_16x16x32_bf16 v[34:37], v[178:181], v[194:197], v[34:37]
	v_mfma_f32_16x16x32_bf16 v[26:29], v[170:173], v[202:205], v[26:29]
	v_mfma_f32_16x16x32_bf16 v[18:21], v[178:181], v[202:205], v[18:21]
	v_mfma_f32_16x16x32_bf16 v[10:13], v[170:173], v[210:213], v[10:13]
	v_mfma_f32_16x16x32_bf16 v[2:5], v[178:181], v[210:213], v[2:5]
	v_mfma_f32_16x16x32_bf16 v[58:61], v[174:177], v[190:193], v[58:61]
	v_mfma_f32_16x16x32_bf16 v[50:53], v[182:185], v[190:193], v[50:53]
	v_mfma_f32_16x16x32_bf16 v[42:45], v[174:177], v[198:201], v[42:45]
	v_mfma_f32_16x16x32_bf16 v[34:37], v[182:185], v[198:201], v[34:37]
	v_mfma_f32_16x16x32_bf16 v[26:29], v[174:177], v[206:209], v[26:29]
	v_mfma_f32_16x16x32_bf16 v[18:21], v[182:185], v[206:209], v[18:21]
	v_mfma_f32_16x16x32_bf16 v[10:13], v[174:177], v[214:217], v[10:13]
	v_mfma_f32_16x16x32_bf16 v[2:5], v[182:185], v[214:217], v[2:5]
	s_setprio 0
	s_barrier
; #define PG8_STAGE(bufoff, gbase, voff) do { _Pragma("unroll") for (int _i = 0; _i < 2; ++_i) \
;         __builtin_amdgcn_global_load_lds((const unsigned*)((const char*)(gbase) + (voff)[_i]), (PG8_LAS unsigned*)(lds + (bufoff) + ldsw + _i * 8192), 16, 0, 0); } while (0)
; #define PG8_LDA(dst, b, h) do { _Pragma("unroll") for (int m = 0; m < 4; ++m) _Pragma("unroll") for (int k = 0; k < 2; ++k) dst[m][k] = *(const PG8_LAS bf16x8*)(lds + PG8_SA(b, h) + aoff + m * 2048 + k * 1024); } while (0)
; #define PG8_LDB(dst, b, h) do { _Pragma("unroll") for (int n = 0; n < 2; ++n) _Pragma("unroll") for (int k = 0; k < 2; ++k) dst[n][k] = *(const PG8_LAS bf16x8*)(lds + PG8_SB(b, h) + boff + n * 2048 + k * 1024); } while (0)
; #define PG8_MMA(ai, bj, At, Bt) do { __builtin_amdgcn_s_setprio(1); _Pragma("unroll") for (int m = 0; m < 4; ++m) _Pragma("unroll") for (int n = 0; n < 2; ++n) _Pragma("unroll") for (int k = 0; k < 2; ++k) \
;         acc[ai][bj][m][n] = __builtin_amdgcn_mfma_f32_16x16x32_bf16(Bt[n][k], At[m][k], acc[ai][bj][m][n], 0, 0, 0); __builtin_amdgcn_s_setprio(0); } while (0)
; #define PG8_WAIT_V(n) asm volatile("s_waitcnt vmcnt(" #n ")" ::: "memory")
; #define PG8_WAIT_L(n) asm volatile("s_waitcnt lgkmcnt(" #n ")" ::: "memory")
; #define PG8_BAR __builtin_amdgcn_s_barrier()
; #define PG8_SCHED __builtin_amdgcn_sched_barrier(0)
; template <class Epi, class Sched, bool ALIGN_EPI = false, bool SP2 = false>
; __device__ __forceinline__ void gemm_phase(PG8_LAS unsigned char* lds, const Gemm g, const Sched& S, const Epi& E) {
;     ...
;             PG8_LDB(B0, 1, 0); PG8_LDB(B1, 1, 1); PG8_SCHED; PG8_LDA(At, 1, 0); PG8_STAGE(PG8_SA(0, 1), a2 + hstep, voffA);
;             PG8_WAIT_V(8); PG8_WAIT_L(0); PG8_BAR; PG8_MMA(0, 0, At, B0); PG8_MMA(0, 1, At, B1); PG8_BAR; PG8_SCHED;
;             PG8_LDA(At, 1, 1); PG8_STAGE(PG8_SB(1, 0), b3, voffB); PG8_STAGE(PG8_SB(1, 1), b3 + hstep, voffB); PG8_STAGE(PG8_SA(1, 0), a3, voffA);
;             PG8_WAIT_V(8); PG8_WAIT_L(0); PG8_BAR; PG8_MMA(1, 0, At, B0); PG8_MMA(1, 1, At, B1); PG8_BAR; PG8_SCHED;
	ds_read_b128 v[146:149], v155
	ds_read_b128 v[158:161], v155 offset:1024
	ds_read_b128 v[162:165], v155 offset:2048
	ds_read_b128 v[166:169], v155 offset:3072
	ds_read_b128 v[170:173], v156
	ds_read_b128 v[174:177], v156 offset:1024
	ds_read_b128 v[178:181], v156 offset:2048
	ds_read_b128 v[182:185], v156 offset:3072
	s_add_u32 s46, s46, 0x40000
	s_addc_u32 s47, s47, 0
	s_mov_b32 m0, s63
	v_lshl_add_u64 v[226:227], s[46:47], 0, v[136:137]
	ds_read_b128 v[186:189], v154 offset:32768
	ds_read_b128 v[190:193], v154 offset:33792
	ds_read_b128 v[194:197], v154 offset:34816
	ds_read_b128 v[198:201], v154 offset:35840
	ds_read_b128 v[202:205], v154 offset:36864
	ds_read_b128 v[206:209], v154 offset:37888
	ds_read_b128 v[210:213], v154 offset:38912
	ds_read_b128 v[214:217], v154 offset:39936
	global_load_lds_dwordx4 v[226:227], off
	v_lshl_add_u64 v[226:227], s[46:47], 0, v[132:133]
	s_mov_b32 m0, s64
	s_nop 0
	global_load_lds_dwordx4 v[226:227], off
	s_waitcnt vmcnt(8)
	s_waitcnt lgkmcnt(0)
	s_barrier
	s_setprio 1
	s_waitcnt lgkmcnt(0)
	v_mfma_f32_16x16x32_bf16 v[126:129], v[146:149], v[186:189], v[126:129]
	v_mfma_f32_16x16x32_bf16 v[118:121], v[162:165], v[186:189], v[118:121]
	v_mfma_f32_16x16x32_bf16 v[110:113], v[146:149], v[194:197], v[110:113]
	v_mfma_f32_16x16x32_bf16 v[102:105], v[162:165], v[194:197], v[102:105]
	v_mfma_f32_16x16x32_bf16 v[94:97], v[146:149], v[202:205], v[94:97]
	v_mfma_f32_16x16x32_bf16 v[86:89], v[162:165], v[202:205], v[86:89]
	v_mfma_f32_16x16x32_bf16 v[78:81], v[146:149], v[210:213], v[78:81]
	v_mfma_f32_16x16x32_bf16 v[70:73], v[162:165], v[210:213], v[70:73]
	v_mfma_f32_16x16x32_bf16 v[126:129], v[158:161], v[190:193], v[126:129]
	v_mfma_f32_16x16x32_bf16 v[118:121], v[166:169], v[190:193], v[118:121]
	v_mfma_f32_16x16x32_bf16 v[110:113], v[158:161], v[198:201], v[110:113]
	v_mfma_f32_16x16x32_bf16 v[102:105], v[166:169], v[198:201], v[102:105]
	v_mfma_f32_16x16x32_bf16 v[94:97], v[158:161], v[206:209], v[94:97]
	v_mfma_f32_16x16x32_bf16 v[86:89], v[166:169], v[206:209], v[86:89]
	v_mfma_f32_16x16x32_bf16 v[78:81], v[158:161], v[214:217], v[78:81]
	v_mfma_f32_16x16x32_bf16 v[70:73], v[166:169], v[214:217], v[70:73]
	s_setprio 0
	s_setprio 1
	v_mfma_f32_16x16x32_bf16 v[122:125], v[170:173], v[186:189], v[122:125]
	v_mfma_f32_16x16x32_bf16 v[114:117], v[178:181], v[186:189], v[114:117]
	v_mfma_f32_16x16x32_bf16 v[106:109], v[170:173], v[194:197], v[106:109]
	v_mfma_f32_16x16x32_bf16 v[98:101], v[178:181], v[194:197], v[98:101]
	v_mfma_f32_16x16x32_bf16 v[90:93], v[170:173], v[202:205], v[90:93]
	v_mfma_f32_16x16x32_bf16 v[82:85], v[178:181], v[202:205], v[82:85]
	v_mfma_f32_16x16x32_bf16 v[74:77], v[170:173], v[210:213], v[74:77]
	v_mfma_f32_16x16x32_bf16 v[66:69], v[178:181], v[210:213], v[66:69]
	v_mfma_f32_16x16x32_bf16 v[122:125], v[174:177], v[190:193], v[122:125]
	v_mfma_f32_16x16x32_bf16 v[114:117], v[182:185], v[190:193], v[114:117]
	v_mfma_f32_16x16x32_bf16 v[106:109], v[174:177], v[198:201], v[106:109]
	v_mfma_f32_16x16x32_bf16 v[98:101], v[182:185], v[198:201], v[98:101]
	v_mfma_f32_16x16x32_bf16 v[90:93], v[174:177], v[206:209], v[90:93]
	v_mfma_f32_16x16x32_bf16 v[82:85], v[182:185], v[206:209], v[82:85]
	v_mfma_f32_16x16x32_bf16 v[74:77], v[174:177], v[214:217], v[74:77]
	v_mfma_f32_16x16x32_bf16 v[66:69], v[182:185], v[214:217], v[66:69]
	s_setprio 0
	s_barrier
	s_mov_b32 m0, s65
	v_lshl_add_u64 v[218:219], v[218:219], 0, s[6:7]
	s_add_u32 s44, s44, 0x40080
	ds_read_b128 v[186:189], v154 offset:49152
	ds_read_b128 v[190:193], v154 offset:50176
	ds_read_b128 v[194:197], v154 offset:51200
	ds_read_b128 v[198:201], v154 offset:52224
	ds_read_b128 v[202:205], v154 offset:53248
	ds_read_b128 v[206:209], v154 offset:54272
	ds_read_b128 v[210:213], v154 offset:55296
	ds_read_b128 v[214:217], v154 offset:56320
	global_load_lds_dwordx4 v[218:219], off
	v_lshl_add_u64 v[218:219], v[220:221], 0, s[6:7]
	s_mov_b32 m0, s66
	s_addc_u32 s45, s45, 0
	global_load_lds_dwordx4 v[218:219], off
	v_lshl_add_u64 v[218:219], s[44:45], 0, v[134:135]
	s_mov_b32 m0, s69
	s_nop 0
	global_load_lds_dwordx4 v[218:219], off
	v_lshl_add_u64 v[218:219], s[44:45], 0, v[130:131]
	s_mov_b32 m0, s70
	s_nop 0
	global_load_lds_dwordx4 v[218:219], off
	v_lshl_add_u64 v[218:219], v[222:223], 0, s[6:7]
	s_mov_b32 m0, s67
	s_nop 0
	global_load_lds_dwordx4 v[218:219], off
	v_lshl_add_u64 v[218:219], v[224:225], 0, s[6:7]
	s_mov_b32 m0, s68
	s_nop 0
	global_load_lds_dwordx4 v[218:219], off
	s_waitcnt vmcnt(8)
	s_waitcnt lgkmcnt(0)
	s_barrier
	s_setprio 1
	s_waitcnt lgkmcnt(0)
	v_mfma_f32_16x16x32_bf16 v[62:65], v[146:149], v[186:189], v[62:65]
	v_mfma_f32_16x16x32_bf16 v[54:57], v[162:165], v[186:189], v[54:57]
	v_mfma_f32_16x16x32_bf16 v[46:49], v[146:149], v[194:197], v[46:49]
	v_mfma_f32_16x16x32_bf16 v[38:41], v[162:165], v[194:197], v[38:41]
	v_mfma_f32_16x16x32_bf16 v[30:33], v[146:149], v[202:205], v[30:33]
	v_mfma_f32_16x16x32_bf16 v[22:25], v[162:165], v[202:205], v[22:25]
	v_mfma_f32_16x16x32_bf16 v[14:17], v[146:149], v[210:213], v[14:17]
	v_mfma_f32_16x16x32_bf16 v[6:9], v[162:165], v[210:213], v[6:9]
	v_mfma_f32_16x16x32_bf16 v[62:65], v[158:161], v[190:193], v[62:65]
	v_mfma_f32_16x16x32_bf16 v[54:57], v[166:169], v[190:193], v[54:57]
	v_mfma_f32_16x16x32_bf16 v[46:49], v[158:161], v[198:201], v[46:49]
	v_mfma_f32_16x16x32_bf16 v[38:41], v[166:169], v[198:201], v[38:41]
	v_mfma_f32_16x16x32_bf16 v[30:33], v[158:161], v[206:209], v[30:33]
	v_mfma_f32_16x16x32_bf16 v[22:25], v[166:169], v[206:209], v[22:25]
	v_mfma_f32_16x16x32_bf16 v[14:17], v[158:161], v[214:217], v[14:17]
	v_mfma_f32_16x16x32_bf16 v[6:9], v[166:169], v[214:217], v[6:9]
	s_setprio 0
	s_setprio 1
	v_mfma_f32_16x16x32_bf16 v[58:61], v[170:173], v[186:189], v[58:61]
	v_mfma_f32_16x16x32_bf16 v[50:53], v[178:181], v[186:189], v[50:53]
	v_mfma_f32_16x16x32_bf16 v[42:45], v[170:173], v[194:197], v[42:45]
	v_mfma_f32_16x16x32_bf16 v[34:37], v[178:181], v[194:197], v[34:37]
	v_mfma_f32_16x16x32_bf16 v[26:29], v[170:173], v[202:205], v[26:29]
	v_mfma_f32_16x16x32_bf16 v[18:21], v[178:181], v[202:205], v[18:21]
	v_mfma_f32_16x16x32_bf16 v[10:13], v[170:173], v[210:213], v[10:13]
	v_mfma_f32_16x16x32_bf16 v[2:5], v[178:181], v[210:213], v[2:5]
	v_mfma_f32_16x16x32_bf16 v[58:61], v[174:177], v[190:193], v[58:61]
	v_mfma_f32_16x16x32_bf16 v[50:53], v[182:185], v[190:193], v[50:53]
	v_mfma_f32_16x16x32_bf16 v[42:45], v[174:177], v[198:201], v[42:45]
	v_mfma_f32_16x16x32_bf16 v[34:37], v[182:185], v[198:201], v[34:37]
	v_mfma_f32_16x16x32_bf16 v[26:29], v[174:177], v[206:209], v[26:29]
	v_mfma_f32_16x16x32_bf16 v[18:21], v[182:185], v[206:209], v[18:21]
	v_mfma_f32_16x16x32_bf16 v[10:13], v[174:177], v[214:217], v[10:13]
	v_mfma_f32_16x16x32_bf16 v[2:5], v[182:185], v[214:217], v[2:5]
	s_setprio 0
	s_add_i32 s48, s48, 2
	s_add_u32 s40, s40, 0x100
	s_addc_u32 s41, s41, 0
	s_add_u32 s42, s42, 0x100
	s_addc_u32 s43, s43, 0
	s_cmp_gt_u32 s48, 13
	s_barrier
	s_cbranch_scc0 .LBB0_257
	s_and_b64 vcc, exec, s[8:9]
	s_cbranch_vccz .LBB0_260
	s_barrier

; #define PG8_STAGE(bufoff, gbase, voff) do { _Pragma("unroll") for (int _i = 0; _i < 2; ++_i) \
;         __builtin_amdgcn_global_load_lds((const unsigned*)((const char*)(gbase) + (voff)[_i]), (PG8_LAS unsigned*)(lds + (bufoff) + ldsw + _i * 8192), 16, 0, 0); } while (0)
; #define PG8_LDA(dst, b, h) do { _Pragma("unroll") for (int m = 0; m < 4; ++m) _Pragma("unroll") for (int k = 0; k < 2; ++k) dst[m][k] = *(const PG8_LAS bf16x8*)(lds + PG8_SA(b, h) + aoff + m * 2048 + k * 1024); } while (0)
; #define PG8_LDB(dst, b, h) do { _Pragma("unroll") for (int n = 0; n < 2; ++n) _Pragma("unroll") for (int k = 0; k < 2; ++k) dst[n][k] = *(const PG8_LAS bf16x8*)(lds + PG8_SB(b, h) + boff + n * 2048 + k * 1024); } while (0)
; #define PG8_MMA(ai, bj, At, Bt) do { __builtin_amdgcn_s_setprio(1); _Pragma("unroll") for (int m = 0; m < 4; ++m) _Pragma("unroll") for (int n = 0; n < 2; ++n) _Pragma("unroll") for (int k = 0; k < 2; ++k) \
;         acc[ai][bj][m][n] = __builtin_amdgcn_mfma_f32_16x16x32_bf16(Bt[n][k], At[m][k], acc[ai][bj][m][n], 0, 0, 0); __builtin_amdgcn_s_setprio(0); } while (0)
; #define PG8_WAIT_V(n) asm volatile("s_waitcnt vmcnt(" #n ")" ::: "memory")
; #define PG8_WAIT_L(n) asm volatile("s_waitcnt lgkmcnt(" #n ")" ::: "memory")
; #define PG8_BAR __builtin_amdgcn_s_barrier()
; #define PG8_SCHED __builtin_amdgcn_sched_barrier(0)
; template <class Epi, class Sched, bool ALIGN_EPI = false, bool SP2 = false>
; __device__ __forceinline__ void gemm_phase(PG8_LAS unsigned char* lds, const Gemm g, const Sched& S, const Epi& E) {
;     ...
;         for (int t = 0; t < nt; t += 2) {
;             const bool last = (t == nt - 2);
;             const char* a1 = cA + (size_t)(t + 1) * kstep;
;             const char* a2 = last ? nA : cA + (size_t)(t + 2) * kstep; const char* b2 = last ? nB : cB + (size_t)(t + 2) * kstep;
;             const char* a3 = a2 + kstep; const char* b3 = b2 + kstep;
;             if (last && has_next) S.a_ready(nxt);
;             if constexpr (SP2) {
;             PG8_LDB(B0, 0, 0); PG8_LDB(B1, 0, 1); PG8_SCHED; PG8_LDA(At, 0, 0); PG8_STAGE(PG8_SA(1, 1), a1 + hstep, voffA);
;             PG8_WAIT_V(8); PG8_WAIT_L(0); PG8_BAR; PG8_MMA(0, 0, At, B0); PG8_MMA(0, 1, At, B1); PG8_BAR; PG8_SCHED;
;             PG8_LDA(At, 0, 1); PG8_STAGE(PG8_SB(0, 0), b2, voffB); PG8_STAGE(PG8_SB(0, 1), b2 + hstep, voffB); PG8_STAGE(PG8_SA(0, 0), a2, voffA);
.LBB0_345:
	s_add_u32 vcc_lo, s72, 0x100
	s_addc_u32 vcc_hi, s73, 0
	s_mov_b32 s74, 0
	ds_read_b128 v[150:153], v147
	ds_read_b128 v[154:157], v147 offset:1024
	ds_read_b128 v[158:161], v147 offset:2048
	ds_read_b128 v[162:165], v147 offset:3072
	ds_read_b128 v[166:169], v148
	ds_read_b128 v[170:173], v148 offset:1024
	ds_read_b128 v[174:177], v148 offset:2048
	ds_read_b128 v[178:181], v148 offset:3072
	s_add_i32 s38, s74, 2
	s_add_u32 s72, s70, 0x100
	s_addc_u32 s73, s71, 0
	s_cmp_eq_u32 s50, s74
	s_cselect_b32 s74, s68, vcc_lo
	s_cselect_b32 s77, s61, s73
	s_cselect_b32 s76, s60, s72
	s_cselect_b32 s75, s69, vcc_hi
	v_lshl_add_u64 v[214:215], s[70:71], 0, v[140:141]
	s_add_i32 m0, s89, 0xc000
	ds_read_b128 v[182:185], v146
	ds_read_b128 v[186:189], v146 offset:1024
	ds_read_b128 v[190:193], v146 offset:2048
	ds_read_b128 v[194:197], v146 offset:3072
	ds_read_b128 v[198:201], v146 offset:4096
	ds_read_b128 v[202:205], v146 offset:5120
	ds_read_b128 v[206:209], v146 offset:6144
	ds_read_b128 v[210:213], v146 offset:7168
	global_load_lds_dwordx4 v[214:215], off
	v_lshl_add_u64 v[214:215], s[70:71], 0, v[138:139]
	s_add_i32 m0, s89, 0xe000
	s_nop 0
	global_load_lds_dwordx4 v[214:215], off
	s_waitcnt vmcnt(8)
	s_waitcnt lgkmcnt(0)
	s_barrier
	s_setprio 1
	s_waitcnt lgkmcnt(0)
	v_mfma_f32_16x16x32_bf16 v[126:129], v[150:153], v[182:185], 0
	v_mfma_f32_16x16x32_bf16 v[122:125], v[158:161], v[182:185], 0
	v_mfma_f32_16x16x32_bf16 v[118:121], v[150:153], v[190:193], 0
	v_mfma_f32_16x16x32_bf16 v[114:117], v[158:161], v[190:193], 0
	v_mfma_f32_16x16x32_bf16 v[102:105], v[150:153], v[198:201], 0
	v_mfma_f32_16x16x32_bf16 v[98:101], v[158:161], v[198:201], 0
	v_mfma_f32_16x16x32_bf16 v[86:89], v[150:153], v[206:209], 0
	v_mfma_f32_16x16x32_bf16 v[82:85], v[158:161], v[206:209], 0
	v_mfma_f32_16x16x32_bf16 v[126:129], v[154:157], v[186:189], v[126:129]
	v_mfma_f32_16x16x32_bf16 v[122:125], v[162:165], v[186:189], v[122:125]
	v_mfma_f32_16x16x32_bf16 v[118:121], v[154:157], v[194:197], v[118:121]
	v_mfma_f32_16x16x32_bf16 v[114:117], v[162:165], v[194:197], v[114:117]
	v_mfma_f32_16x16x32_bf16 v[102:105], v[154:157], v[202:205], v[102:105]
	v_mfma_f32_16x16x32_bf16 v[98:101], v[162:165], v[202:205], v[98:101]
	v_mfma_f32_16x16x32_bf16 v[86:89], v[154:157], v[210:213], v[86:89]
	v_mfma_f32_16x16x32_bf16 v[82:85], v[162:165], v[210:213], v[82:85]
	s_setprio 0
	s_setprio 1
	v_mfma_f32_16x16x32_bf16 v[110:113], v[166:169], v[182:185], 0
	v_mfma_f32_16x16x32_bf16 v[106:109], v[174:177], v[182:185], 0
	v_mfma_f32_16x16x32_bf16 v[94:97], v[166:169], v[190:193], 0
	v_mfma_f32_16x16x32_bf16 v[90:93], v[174:177], v[190:193], 0
	v_mfma_f32_16x16x32_bf16 v[78:81], v[166:169], v[198:201], 0
	v_mfma_f32_16x16x32_bf16 v[74:77], v[174:177], v[198:201], 0
	v_mfma_f32_16x16x32_bf16 v[70:73], v[166:169], v[206:209], 0
	v_mfma_f32_16x16x32_bf16 v[66:69], v[174:177], v[206:209], 0
	v_mfma_f32_16x16x32_bf16 v[110:113], v[170:173], v[186:189], v[110:113]
	v_mfma_f32_16x16x32_bf16 v[106:109], v[178:181], v[186:189], v[106:109]
	v_mfma_f32_16x16x32_bf16 v[94:97], v[170:173], v[194:197], v[94:97]
	v_mfma_f32_16x16x32_bf16 v[90:93], v[178:181], v[194:197], v[90:93]
	v_mfma_f32_16x16x32_bf16 v[78:81], v[170:173], v[202:205], v[78:81]
	v_mfma_f32_16x16x32_bf16 v[74:77], v[178:181], v[202:205], v[74:77]
	v_mfma_f32_16x16x32_bf16 v[70:73], v[170:173], v[210:213], v[70:73]
	v_mfma_f32_16x16x32_bf16 v[66:69], v[178:181], v[210:213], v[66:69]
	s_setprio 0
	s_barrier
	s_mov_b32 m0, s85
	v_lshl_add_u64 v[214:215], s[74:75], 0, v[130:131]
	s_add_u32 s70, s74, 0xb0000
	ds_read_b128 v[182:185], v146 offset:16384
	ds_read_b128 v[186:189], v146 offset:17408
	ds_read_b128 v[190:193], v146 offset:18432
	ds_read_b128 v[194:197], v146 offset:19456
	ds_read_b128 v[198:201], v146 offset:20480
	ds_read_b128 v[202:205], v146 offset:21504
	ds_read_b128 v[206:209], v146 offset:22528
	ds_read_b128 v[210:213], v146 offset:23552
	global_load_lds_dwordx4 v[214:215], off
	v_lshl_add_u64 v[216:217], s[74:75], 0, v[136:137]
	s_mov_b32 m0, s86
	s_addc_u32 s71, s75, 0
	global_load_lds_dwordx4 v[216:217], off
	v_lshl_add_u64 v[218:219], s[70:71], 0, v[130:131]
	s_mov_b32 m0, s87
	v_lshl_add_u64 v[220:221], s[76:77], 0, v[134:135]
	global_load_lds_dwordx4 v[218:219], off
	v_lshl_add_u64 v[218:219], s[70:71], 0, v[136:137]
	s_mov_b32 m0, s88
	s_nop 0
	global_load_lds_dwordx4 v[218:219], off
	v_lshl_add_u64 v[218:219], s[76:77], 0, v[132:133]
	s_mov_b32 m0, s89
	s_nop 0
	global_load_lds_dwordx4 v[218:219], off
	s_mov_b32 m0, s90
	s_nop 0
	global_load_lds_dwordx4 v[220:221], off
	s_waitcnt vmcnt(8)
	s_waitcnt lgkmcnt(0)
	s_barrier
; #define PG8_STAGE(bufoff, gbase, voff) do { _Pragma("unroll") for (int _i = 0; _i < 2; ++_i) \
;         __builtin_amdgcn_global_load_lds((const unsigned*)((const char*)(gbase) + (voff)[_i]), (PG8_LAS unsigned*)(lds + (bufoff) + ldsw + _i * 8192), 16, 0, 0); } while (0)
; #define PG8_LDA(dst, b, h) do { _Pragma("unroll") for (int m = 0; m < 4; ++m) _Pragma("unroll") for (int k = 0; k < 2; ++k) dst[m][k] = *(const PG8_LAS bf16x8*)(lds + PG8_SA(b, h) + aoff + m * 2048 + k * 1024); } while (0)
; #define PG8_LDB(dst, b, h) do { _Pragma("unroll") for (int n = 0; n < 2; ++n) _Pragma("unroll") for (int k = 0; k < 2; ++k) dst[n][k] = *(const PG8_LAS bf16x8*)(lds + PG8_SB(b, h) + boff + n * 2048 + k * 1024); } while (0)
; #define PG8_MMA(ai, bj, At, Bt) do { __builtin_amdgcn_s_setprio(1); _Pragma("unroll") for (int m = 0; m < 4; ++m) _Pragma("unroll") for (int n = 0; n < 2; ++n) _Pragma("unroll") for (int k = 0; k < 2; ++k) \
;         acc[ai][bj][m][n] = __builtin_amdgcn_mfma_f32_16x16x32_bf16(Bt[n][k], At[m][k], acc[ai][bj][m][n], 0, 0, 0); __builtin_amdgcn_s_setprio(0); } while (0)
; #define PG8_WAIT_V(n) asm volatile("s_waitcnt vmcnt(" #n ")" ::: "memory")
; #define PG8_WAIT_L(n) asm volatile("s_waitcnt lgkmcnt(" #n ")" ::: "memory")
; #define PG8_BAR __builtin_amdgcn_s_barrier()
; #define PG8_SCHED __builtin_amdgcn_sched_barrier(0)
; template <class Epi, class Sched, bool ALIGN_EPI = false, bool SP2 = false>
; __device__ __forceinline__ void gemm_phase(PG8_LAS unsigned char* lds, const Gemm g, const Sched& S, const Epi& E) {
;     ...
;             PG8_WAIT_V(8); PG8_WAIT_L(0); PG8_BAR; PG8_MMA(1, 0, At, B0); PG8_MMA(1, 1, At, B1); PG8_BAR; PG8_SCHED;
;             PG8_LDB(B0, 1, 0); PG8_LDB(B1, 1, 1); PG8_SCHED; PG8_LDA(At, 1, 0); PG8_STAGE(PG8_SA(0, 1), a2 + hstep, voffA);
;             PG8_WAIT_V(8); PG8_WAIT_L(0); PG8_BAR; PG8_MMA(0, 0, At, B0); PG8_MMA(0, 1, At, B1); PG8_BAR; PG8_SCHED;
	s_setprio 1
	s_waitcnt lgkmcnt(0)
	v_mfma_f32_16x16x32_bf16 v[62:65], v[150:153], v[182:185], 0
	v_mfma_f32_16x16x32_bf16 v[58:61], v[158:161], v[182:185], 0
	v_mfma_f32_16x16x32_bf16 v[54:57], v[150:153], v[190:193], 0
	v_mfma_f32_16x16x32_bf16 v[50:53], v[158:161], v[190:193], 0
	v_mfma_f32_16x16x32_bf16 v[38:41], v[150:153], v[198:201], 0
	v_mfma_f32_16x16x32_bf16 v[34:37], v[158:161], v[198:201], 0
	v_mfma_f32_16x16x32_bf16 v[22:25], v[150:153], v[206:209], 0
	v_mfma_f32_16x16x32_bf16 v[18:21], v[158:161], v[206:209], 0
	v_mfma_f32_16x16x32_bf16 v[62:65], v[154:157], v[186:189], v[62:65]
	v_mfma_f32_16x16x32_bf16 v[58:61], v[162:165], v[186:189], v[58:61]
	v_mfma_f32_16x16x32_bf16 v[54:57], v[154:157], v[194:197], v[54:57]
	v_mfma_f32_16x16x32_bf16 v[50:53], v[162:165], v[194:197], v[50:53]
	v_mfma_f32_16x16x32_bf16 v[38:41], v[154:157], v[202:205], v[38:41]
	v_mfma_f32_16x16x32_bf16 v[34:37], v[162:165], v[202:205], v[34:37]
	v_mfma_f32_16x16x32_bf16 v[22:25], v[154:157], v[210:213], v[22:25]
	v_mfma_f32_16x16x32_bf16 v[18:21], v[162:165], v[210:213], v[18:21]
	s_setprio 0
	s_setprio 1
	v_mfma_f32_16x16x32_bf16 v[46:49], v[166:169], v[182:185], 0
	v_mfma_f32_16x16x32_bf16 v[42:45], v[174:177], v[182:185], 0
	v_mfma_f32_16x16x32_bf16 v[30:33], v[166:169], v[190:193], 0
	v_mfma_f32_16x16x32_bf16 v[26:29], v[174:177], v[190:193], 0
	v_mfma_f32_16x16x32_bf16 v[14:17], v[166:169], v[198:201], 0
	v_mfma_f32_16x16x32_bf16 v[10:13], v[174:177], v[198:201], 0
	v_mfma_f32_16x16x32_bf16 v[6:9], v[166:169], v[206:209], 0
	v_mfma_f32_16x16x32_bf16 v[2:5], v[174:177], v[206:209], 0
	v_mfma_f32_16x16x32_bf16 v[46:49], v[170:173], v[186:189], v[46:49]
	v_mfma_f32_16x16x32_bf16 v[42:45], v[178:181], v[186:189], v[42:45]
	v_mfma_f32_16x16x32_bf16 v[30:33], v[170:173], v[194:197], v[30:33]
	v_mfma_f32_16x16x32_bf16 v[26:29], v[178:181], v[194:197], v[26:29]
	v_mfma_f32_16x16x32_bf16 v[14:17], v[170:173], v[202:205], v[14:17]
	v_mfma_f32_16x16x32_bf16 v[10:13], v[178:181], v[202:205], v[10:13]
	v_mfma_f32_16x16x32_bf16 v[6:9], v[170:173], v[210:213], v[6:9]
	v_mfma_f32_16x16x32_bf16 v[2:5], v[178:181], v[210:213], v[2:5]
	s_setprio 0
	s_barrier
	v_add_u32_e32 v178, s78, v144
	ds_read_b128 v[150:153], v149
	ds_read_b128 v[154:157], v149 offset:1024
	ds_read_b128 v[158:161], v149 offset:2048
	ds_read_b128 v[162:165], v149 offset:3072
	ds_read_b128 v[166:169], v178
	ds_read_b128 v[170:173], v178 offset:1024
	ds_read_b128 v[174:177], v178 offset:2048
	ds_read_b128 v[178:181], v178 offset:3072
	s_add_u32 s70, s76, 0xb0000
	s_addc_u32 s71, s77, 0
	s_mov_b32 m0, s91
	v_lshl_add_u64 v[222:223], s[70:71], 0, v[132:133]
	ds_read_b128 v[182:185], v146 offset:32768
	ds_read_b128 v[186:189], v146 offset:33792
	ds_read_b128 v[190:193], v146 offset:34816
	ds_read_b128 v[194:197], v146 offset:35840
	ds_read_b128 v[198:201], v146 offset:36864
	ds_read_b128 v[202:205], v146 offset:37888
	ds_read_b128 v[206:209], v146 offset:38912
	ds_read_b128 v[210:213], v146 offset:39936
	global_load_lds_dwordx4 v[222:223], off
	v_lshl_add_u64 v[222:223], s[70:71], 0, v[134:135]
	s_mov_b32 m0, s92
	s_nop 0
	global_load_lds_dwordx4 v[222:223], off
	s_waitcnt vmcnt(8)
	s_waitcnt lgkmcnt(0)
	s_barrier
	s_setprio 1
	s_waitcnt lgkmcnt(0)
	v_mfma_f32_16x16x32_bf16 v[126:129], v[150:153], v[182:185], v[126:129]
	v_mfma_f32_16x16x32_bf16 v[122:125], v[158:161], v[182:185], v[122:125]
	v_mfma_f32_16x16x32_bf16 v[118:121], v[150:153], v[190:193], v[118:121]
	v_mfma_f32_16x16x32_bf16 v[114:117], v[158:161], v[190:193], v[114:117]
	v_mfma_f32_16x16x32_bf16 v[102:105], v[150:153], v[198:201], v[102:105]
	v_mfma_f32_16x16x32_bf16 v[98:101], v[158:161], v[198:201], v[98:101]
	v_mfma_f32_16x16x32_bf16 v[86:89], v[150:153], v[206:209], v[86:89]
	v_mfma_f32_16x16x32_bf16 v[82:85], v[158:161], v[206:209], v[82:85]
	v_mfma_f32_16x16x32_bf16 v[126:129], v[154:157], v[186:189], v[126:129]
	v_mfma_f32_16x16x32_bf16 v[122:125], v[162:165], v[186:189], v[122:125]
	v_mfma_f32_16x16x32_bf16 v[118:121], v[154:157], v[194:197], v[118:121]
	v_mfma_f32_16x16x32_bf16 v[114:117], v[162:165], v[194:197], v[114:117]
	v_mfma_f32_16x16x32_bf16 v[102:105], v[154:157], v[202:205], v[102:105]
	v_mfma_f32_16x16x32_bf16 v[98:101], v[162:165], v[202:205], v[98:101]
	v_mfma_f32_16x16x32_bf16 v[86:89], v[154:157], v[210:213], v[86:89]
	v_mfma_f32_16x16x32_bf16 v[82:85], v[162:165], v[210:213], v[82:85]
	s_setprio 0
	s_setprio 1
	v_mfma_f32_16x16x32_bf16 v[110:113], v[166:169], v[182:185], v[110:113]
	v_mfma_f32_16x16x32_bf16 v[106:109], v[174:177], v[182:185], v[106:109]
	v_mfma_f32_16x16x32_bf16 v[94:97], v[166:169], v[190:193], v[94:97]
	v_mfma_f32_16x16x32_bf16 v[90:93], v[174:177], v[190:193], v[90:93]
	v_mfma_f32_16x16x32_bf16 v[78:81], v[166:169], v[198:201], v[78:81]
	v_mfma_f32_16x16x32_bf16 v[74:77], v[174:177], v[198:201], v[74:77]
	v_mfma_f32_16x16x32_bf16 v[70:73], v[166:169], v[206:209], v[70:73]
	v_mfma_f32_16x16x32_bf16 v[66:69], v[174:177], v[206:209], v[66:69]
	v_mfma_f32_16x16x32_bf16 v[110:113], v[170:173], v[186:189], v[110:113]
	v_mfma_f32_16x16x32_bf16 v[106:109], v[178:181], v[186:189], v[106:109]
	v_mfma_f32_16x16x32_bf16 v[94:97], v[170:173], v[194:197], v[94:97]
	v_mfma_f32_16x16x32_bf16 v[90:93], v[178:181], v[194:197], v[90:93]
	v_mfma_f32_16x16x32_bf16 v[78:81], v[170:173], v[202:205], v[78:81]
	v_mfma_f32_16x16x32_bf16 v[74:77], v[178:181], v[202:205], v[74:77]
	v_mfma_f32_16x16x32_bf16 v[70:73], v[170:173], v[210:213], v[70:73]
	v_mfma_f32_16x16x32_bf16 v[66:69], v[178:181], v[210:213], v[66:69]
	s_setprio 0
	s_barrier
; #define PG8_STAGE(bufoff, gbase, voff) do { _Pragma("unroll") for (int _i = 0; _i < 2; ++_i) \
;         __builtin_amdgcn_global_load_lds((const unsigned*)((const char*)(gbase) + (voff)[_i]), (PG8_LAS unsigned*)(lds + (bufoff) + ldsw + _i * 8192), 16, 0, 0); } while (0)
; #define PG8_LDA(dst, b, h) do { _Pragma("unroll") for (int m = 0; m < 4; ++m) _Pragma("unroll") for (int k = 0; k < 2; ++k) dst[m][k] = *(const PG8_LAS bf16x8*)(lds + PG8_SA(b, h) + aoff + m * 2048 + k * 1024); } while (0)
; #define PG8_LDB(dst, b, h) do { _Pragma("unroll") for (int n = 0; n < 2; ++n) _Pragma("unroll") for (int k = 0; k < 2; ++k) dst[n][k] = *(const PG8_LAS bf16x8*)(lds + PG8_SB(b, h) + boff + n * 2048 + k * 1024); } while (0)
; #define PG8_MMA(ai, bj, At, Bt) do { __builtin_amdgcn_s_setprio(1); _Pragma("unroll") for (int m = 0; m < 4; ++m) _Pragma("unroll") for (int n = 0; n < 2; ++n) _Pragma("unroll") for (int k = 0; k < 2; ++k) \
;         acc[ai][bj][m][n] = __builtin_amdgcn_mfma_f32_16x16x32_bf16(Bt[n][k], At[m][k], acc[ai][bj][m][n], 0, 0, 0); __builtin_amdgcn_s_setprio(0); } while (0)
; #define PG8_WAIT_V(n) asm volatile("s_waitcnt vmcnt(" #n ")" ::: "memory")
; template <class Epi, class Sched, bool ALIGN_EPI = false, bool SP2 = false>
; __device__ __forceinline__ void gemm_phase(PG8_LAS unsigned char* lds, const Gemm g, const Sched& S, const Epi& E) {
;     ...
;             PG8_LDB(B0, 0, 0); PG8_LDB(B1, 0, 1); PG8_SCHED; PG8_LDA(At, 0, 0); PG8_STAGE(PG8_SA(1, 1), a1 + hstep, voffA);
;             PG8_WAIT_V(8); PG8_WAIT_L(0); PG8_BAR; PG8_MMA(0, 0, At, B0); PG8_MMA(0, 1, At, B1); PG8_BAR; PG8_SCHED;
;             PG8_LDA(At, 0, 1); PG8_STAGE(PG8_SB(0, 0), b2, voffB); PG8_STAGE(PG8_SB(0, 1), b2 + hstep, voffB); PG8_STAGE(PG8_SA(0, 0), a2, voffA);
;             PG8_WAIT_V(8); PG8_WAIT_L(0); PG8_BAR; PG8_MMA(1, 0, At, B0); PG8_MMA(1, 1, At, B1); PG8_BAR; PG8_SCHED;
;             PG8_LDB(B0, 1, 0); PG8_LDB(B1, 1, 1); PG8_SCHED; PG8_LDA(At, 1, 0); PG8_STAGE(PG8_SA(0, 1), a2 + hstep, voffA);
;             PG8_WAIT_V(8); PG8_WAIT_L(0); PG8_BAR; PG8_MMA(0, 0, At, B0); PG8_MMA(0, 1, At, B1); PG8_BAR; PG8_SCHED;
;             PG8_LDA(At, 1, 1); PG8_STAGE(PG8_SB(1, 0), b3, voffB); PG8_STAGE(PG8_SB(1, 1), b3 + hstep, voffB); PG8_STAGE(PG8_SA(1, 0), a3, voffA);
;             PG8_WAIT_V(8); PG8_WAIT_L(0); PG8_BAR; PG8_MMA(1, 0, At, B0); PG8_MMA(1, 1, At, B1); PG8_BAR; PG8_SCHED;
	s_mov_b32 m0, s33
	v_lshl_add_u64 v[214:215], v[214:215], 0, s[24:25]
	s_add_u32 s70, s74, 0xb0080
	ds_read_b128 v[182:185], v146 offset:49152
	ds_read_b128 v[186:189], v146 offset:50176
	ds_read_b128 v[190:193], v146 offset:51200
	ds_read_b128 v[194:197], v146 offset:52224
	ds_read_b128 v[198:201], v146 offset:53248
	ds_read_b128 v[202:205], v146 offset:54272
	ds_read_b128 v[206:209], v146 offset:55296
	ds_read_b128 v[210:213], v146 offset:56320
	global_load_lds_dwordx4 v[214:215], off
	v_lshl_add_u64 v[214:215], v[216:217], 0, s[24:25]
	s_mov_b32 m0, s36
	s_addc_u32 s71, s75, 0
	global_load_lds_dwordx4 v[214:215], off
	v_lshl_add_u64 v[214:215], s[70:71], 0, v[130:131]
	s_mov_b32 m0, s48
	s_nop 0
	global_load_lds_dwordx4 v[214:215], off
	v_lshl_add_u64 v[214:215], s[70:71], 0, v[136:137]
	s_mov_b32 m0, s49
	s_nop 0
	global_load_lds_dwordx4 v[214:215], off
	v_lshl_add_u64 v[214:215], v[218:219], 0, s[24:25]
	s_mov_b32 m0, s37
	s_nop 0
	global_load_lds_dwordx4 v[214:215], off
	v_lshl_add_u64 v[214:215], v[220:221], 0, s[24:25]
	s_mov_b32 m0, s40
	s_nop 0
	global_load_lds_dwordx4 v[214:215], off
	s_waitcnt vmcnt(8)
	s_waitcnt lgkmcnt(0)
	s_barrier
	s_setprio 1
	s_waitcnt lgkmcnt(0)
	v_mfma_f32_16x16x32_bf16 v[62:65], v[150:153], v[182:185], v[62:65]
	v_mfma_f32_16x16x32_bf16 v[58:61], v[158:161], v[182:185], v[58:61]
	v_mfma_f32_16x16x32_bf16 v[54:57], v[150:153], v[190:193], v[54:57]
	v_mfma_f32_16x16x32_bf16 v[50:53], v[158:161], v[190:193], v[50:53]
	v_mfma_f32_16x16x32_bf16 v[38:41], v[150:153], v[198:201], v[38:41]
	v_mfma_f32_16x16x32_bf16 v[34:37], v[158:161], v[198:201], v[34:37]
	v_mfma_f32_16x16x32_bf16 v[22:25], v[150:153], v[206:209], v[22:25]
	v_mfma_f32_16x16x32_bf16 v[18:21], v[158:161], v[206:209], v[18:21]
	v_mfma_f32_16x16x32_bf16 v[62:65], v[154:157], v[186:189], v[62:65]
	v_mfma_f32_16x16x32_bf16 v[58:61], v[162:165], v[186:189], v[58:61]
	v_mfma_f32_16x16x32_bf16 v[54:57], v[154:157], v[194:197], v[54:57]
	v_mfma_f32_16x16x32_bf16 v[50:53], v[162:165], v[194:197], v[50:53]
	v_mfma_f32_16x16x32_bf16 v[38:41], v[154:157], v[202:205], v[38:41]
	v_mfma_f32_16x16x32_bf16 v[34:37], v[162:165], v[202:205], v[34:37]
	v_mfma_f32_16x16x32_bf16 v[22:25], v[154:157], v[210:213], v[22:25]
	v_mfma_f32_16x16x32_bf16 v[18:21], v[162:165], v[210:213], v[18:21]
	s_setprio 0
	s_setprio 1
	v_mfma_f32_16x16x32_bf16 v[46:49], v[166:169], v[182:185], v[46:49]
	v_mfma_f32_16x16x32_bf16 v[42:45], v[174:177], v[182:185], v[42:45]
	v_mfma_f32_16x16x32_bf16 v[30:33], v[166:169], v[190:193], v[30:33]
	v_mfma_f32_16x16x32_bf16 v[26:29], v[174:177], v[190:193], v[26:29]
	v_mfma_f32_16x16x32_bf16 v[14:17], v[166:169], v[198:201], v[14:17]
	v_mfma_f32_16x16x32_bf16 v[10:13], v[174:177], v[198:201], v[10:13]
	v_mfma_f32_16x16x32_bf16 v[6:9], v[166:169], v[206:209], v[6:9]
	v_mfma_f32_16x16x32_bf16 v[2:5], v[174:177], v[206:209], v[2:5]
	v_mfma_f32_16x16x32_bf16 v[46:49], v[170:173], v[186:189], v[46:49]
	v_mfma_f32_16x16x32_bf16 v[42:45], v[178:181], v[186:189], v[42:45]
	v_mfma_f32_16x16x32_bf16 v[30:33], v[170:173], v[194:197], v[30:33]
	v_mfma_f32_16x16x32_bf16 v[26:29], v[178:181], v[194:197], v[26:29]
	v_mfma_f32_16x16x32_bf16 v[14:17], v[170:173], v[202:205], v[14:17]
	v_mfma_f32_16x16x32_bf16 v[10:13], v[178:181], v[202:205], v[10:13]
	v_mfma_f32_16x16x32_bf16 v[6:9], v[170:173], v[210:213], v[6:9]
	v_mfma_f32_16x16x32_bf16 v[2:5], v[178:181], v[210:213], v[2:5]
	s_setprio 0
	s_add_u32 vcc_lo, vcc_lo, 0x100
	s_addc_u32 vcc_hi, vcc_hi, 0
	s_cmp_ge_u32 s38, s93
	s_mov_b64 s[70:71], s[72:73]
	s_mov_b32 s74, s38
	s_barrier
.LBB0_346:
	ds_read_b128 v[150:153], v147
	ds_read_b128 v[154:157], v147 offset:1024
	ds_read_b128 v[158:161], v147 offset:2048
	ds_read_b128 v[162:165], v147 offset:3072
	ds_read_b128 v[166:169], v148
	ds_read_b128 v[170:173], v148 offset:1024
	ds_read_b128 v[174:177], v148 offset:2048
	ds_read_b128 v[178:181], v148 offset:3072
	s_add_i32 s38, s74, 2
	s_add_u32 s72, s70, 0x100
	s_addc_u32 s73, s71, 0
	s_cmp_eq_u32 s50, s74
	s_cselect_b32 s74, s68, vcc_lo
	s_cselect_b32 s77, s61, s73
	s_cselect_b32 s76, s60, s72
	s_cselect_b32 s75, s69, vcc_hi
	v_lshl_add_u64 v[214:215], s[70:71], 0, v[140:141]
	s_add_i32 m0, s89, 0xc000
	ds_read_b128 v[182:185], v146
	ds_read_b128 v[186:189], v146 offset:1024
	ds_read_b128 v[190:193], v146 offset:2048
	ds_read_b128 v[194:197], v146 offset:3072
	ds_read_b128 v[198:201], v146 offset:4096
	ds_read_b128 v[202:205], v146 offset:5120
	ds_read_b128 v[206:209], v146 offset:6144
	ds_read_b128 v[210:213], v146 offset:7168
	global_load_lds_dwordx4 v[214:215], off
	v_lshl_add_u64 v[214:215], s[70:71], 0, v[138:139]
	s_add_i32 m0, s89, 0xe000
	s_nop 0
	global_load_lds_dwordx4 v[214:215], off
	s_waitcnt vmcnt(8)
	s_waitcnt lgkmcnt(0)
	s_barrier
; #define PG8_STAGE(bufoff, gbase, voff) do { _Pragma("unroll") for (int _i = 0; _i < 2; ++_i) \
;         __builtin_amdgcn_global_load_lds((const unsigned*)((const char*)(gbase) + (voff)[_i]), (PG8_LAS unsigned*)(lds + (bufoff) + ldsw + _i * 8192), 16, 0, 0); } while (0)
; #define PG8_LDA(dst, b, h) do { _Pragma("unroll") for (int m = 0; m < 4; ++m) _Pragma("unroll") for (int k = 0; k < 2; ++k) dst[m][k] = *(const PG8_LAS bf16x8*)(lds + PG8_SA(b, h) + aoff + m * 2048 + k * 1024); } while (0)
; #define PG8_MMA(ai, bj, At, Bt) do { __builtin_amdgcn_s_setprio(1); _Pragma("unroll") for (int m = 0; m < 4; ++m) _Pragma("unroll") for (int n = 0; n < 2; ++n) _Pragma("unroll") for (int k = 0; k < 2; ++k) \
;         acc[ai][bj][m][n] = __builtin_amdgcn_mfma_f32_16x16x32_bf16(Bt[n][k], At[m][k], acc[ai][bj][m][n], 0, 0, 0); __builtin_amdgcn_s_setprio(0); } while (0)
; #define PG8_WAIT_V(n) asm volatile("s_waitcnt vmcnt(" #n ")" ::: "memory")
; #define PG8_WAIT_L(n) asm volatile("s_waitcnt lgkmcnt(" #n ")" ::: "memory")
; #define PG8_BAR __builtin_amdgcn_s_barrier()
; #define PG8_SCHED __builtin_amdgcn_sched_barrier(0)
; template <class Epi, class Sched, bool ALIGN_EPI = false, bool SP2 = false>
; __device__ __forceinline__ void gemm_phase(PG8_LAS unsigned char* lds, const Gemm g, const Sched& S, const Epi& E) {
;     ...
;             PG8_WAIT_V(8); PG8_WAIT_L(0); PG8_BAR; PG8_MMA(0, 0, At, B0); PG8_MMA(0, 1, At, B1); PG8_BAR; PG8_SCHED;
;             PG8_LDA(At, 0, 1); PG8_STAGE(PG8_SB(0, 0), b2, voffB); PG8_STAGE(PG8_SB(0, 1), b2 + hstep, voffB); PG8_STAGE(PG8_SA(0, 0), a2, voffA);
;             PG8_WAIT_V(8); PG8_WAIT_L(0); PG8_BAR; PG8_MMA(1, 0, At, B0); PG8_MMA(1, 1, At, B1); PG8_BAR; PG8_SCHED;
	s_setprio 1
	s_waitcnt lgkmcnt(0)
	v_mfma_f32_16x16x32_bf16 v[126:129], v[150:153], v[182:185], v[126:129]
	v_mfma_f32_16x16x32_bf16 v[122:125], v[158:161], v[182:185], v[122:125]
	v_mfma_f32_16x16x32_bf16 v[118:121], v[150:153], v[190:193], v[118:121]
	v_mfma_f32_16x16x32_bf16 v[114:117], v[158:161], v[190:193], v[114:117]
	v_mfma_f32_16x16x32_bf16 v[102:105], v[150:153], v[198:201], v[102:105]
	v_mfma_f32_16x16x32_bf16 v[98:101], v[158:161], v[198:201], v[98:101]
	v_mfma_f32_16x16x32_bf16 v[86:89], v[150:153], v[206:209], v[86:89]
	v_mfma_f32_16x16x32_bf16 v[82:85], v[158:161], v[206:209], v[82:85]
	v_mfma_f32_16x16x32_bf16 v[126:129], v[154:157], v[186:189], v[126:129]
	v_mfma_f32_16x16x32_bf16 v[122:125], v[162:165], v[186:189], v[122:125]
	v_mfma_f32_16x16x32_bf16 v[118:121], v[154:157], v[194:197], v[118:121]
	v_mfma_f32_16x16x32_bf16 v[114:117], v[162:165], v[194:197], v[114:117]
	v_mfma_f32_16x16x32_bf16 v[102:105], v[154:157], v[202:205], v[102:105]
	v_mfma_f32_16x16x32_bf16 v[98:101], v[162:165], v[202:205], v[98:101]
	v_mfma_f32_16x16x32_bf16 v[86:89], v[154:157], v[210:213], v[86:89]
	v_mfma_f32_16x16x32_bf16 v[82:85], v[162:165], v[210:213], v[82:85]
	s_setprio 0
	s_setprio 1
	v_mfma_f32_16x16x32_bf16 v[110:113], v[166:169], v[182:185], v[110:113]
	v_mfma_f32_16x16x32_bf16 v[106:109], v[174:177], v[182:185], v[106:109]
	v_mfma_f32_16x16x32_bf16 v[94:97], v[166:169], v[190:193], v[94:97]
	v_mfma_f32_16x16x32_bf16 v[90:93], v[174:177], v[190:193], v[90:93]
	v_mfma_f32_16x16x32_bf16 v[78:81], v[166:169], v[198:201], v[78:81]
	v_mfma_f32_16x16x32_bf16 v[74:77], v[174:177], v[198:201], v[74:77]
	v_mfma_f32_16x16x32_bf16 v[70:73], v[166:169], v[206:209], v[70:73]
	v_mfma_f32_16x16x32_bf16 v[66:69], v[174:177], v[206:209], v[66:69]
	v_mfma_f32_16x16x32_bf16 v[110:113], v[170:173], v[186:189], v[110:113]
	v_mfma_f32_16x16x32_bf16 v[106:109], v[178:181], v[186:189], v[106:109]
	v_mfma_f32_16x16x32_bf16 v[94:97], v[170:173], v[194:197], v[94:97]
	v_mfma_f32_16x16x32_bf16 v[90:93], v[178:181], v[194:197], v[90:93]
	v_mfma_f32_16x16x32_bf16 v[78:81], v[170:173], v[202:205], v[78:81]
	v_mfma_f32_16x16x32_bf16 v[74:77], v[178:181], v[202:205], v[74:77]
	v_mfma_f32_16x16x32_bf16 v[70:73], v[170:173], v[210:213], v[70:73]
	v_mfma_f32_16x16x32_bf16 v[66:69], v[178:181], v[210:213], v[66:69]
	s_setprio 0
	s_barrier
	s_mov_b32 m0, s85
	v_lshl_add_u64 v[214:215], s[74:75], 0, v[130:131]
	s_add_u32 s70, s74, 0xb0000
	ds_read_b128 v[182:185], v146 offset:16384
	ds_read_b128 v[186:189], v146 offset:17408
	ds_read_b128 v[190:193], v146 offset:18432
	ds_read_b128 v[194:197], v146 offset:19456
	ds_read_b128 v[198:201], v146 offset:20480
	ds_read_b128 v[202:205], v146 offset:21504
	ds_read_b128 v[206:209], v146 offset:22528
	ds_read_b128 v[210:213], v146 offset:23552
	global_load_lds_dwordx4 v[214:215], off
	v_lshl_add_u64 v[216:217], s[74:75], 0, v[136:137]
	s_mov_b32 m0, s86
	s_addc_u32 s71, s75, 0
	global_load_lds_dwordx4 v[216:217], off
	v_lshl_add_u64 v[218:219], s[70:71], 0, v[130:131]
	s_mov_b32 m0, s87
	v_lshl_add_u64 v[220:221], s[76:77], 0, v[134:135]
	global_load_lds_dwordx4 v[218:219], off
	v_lshl_add_u64 v[218:219], s[70:71], 0, v[136:137]
	s_mov_b32 m0, s88
	s_nop 0
	global_load_lds_dwordx4 v[218:219], off
	v_lshl_add_u64 v[218:219], s[76:77], 0, v[132:133]
	s_mov_b32 m0, s89
	s_nop 0
	global_load_lds_dwordx4 v[218:219], off
	s_mov_b32 m0, s90
	s_nop 0
	global_load_lds_dwordx4 v[220:221], off
	s_waitcnt vmcnt(8)
	s_waitcnt lgkmcnt(0)
	s_barrier
	s_setprio 1
	s_waitcnt lgkmcnt(0)
	v_mfma_f32_16x16x32_bf16 v[62:65], v[150:153], v[182:185], v[62:65]
	v_mfma_f32_16x16x32_bf16 v[58:61], v[158:161], v[182:185], v[58:61]
	v_mfma_f32_16x16x32_bf16 v[54:57], v[150:153], v[190:193], v[54:57]
	v_mfma_f32_16x16x32_bf16 v[50:53], v[158:161], v[190:193], v[50:53]
	v_mfma_f32_16x16x32_bf16 v[38:41], v[150:153], v[198:201], v[38:41]
	v_mfma_f32_16x16x32_bf16 v[34:37], v[158:161], v[198:201], v[34:37]
	v_mfma_f32_16x16x32_bf16 v[22:25], v[150:153], v[206:209], v[22:25]
	v_mfma_f32_16x16x32_bf16 v[18:21], v[158:161], v[206:209], v[18:21]
	v_mfma_f32_16x16x32_bf16 v[62:65], v[154:157], v[186:189], v[62:65]
	v_mfma_f32_16x16x32_bf16 v[58:61], v[162:165], v[186:189], v[58:61]
	v_mfma_f32_16x16x32_bf16 v[54:57], v[154:157], v[194:197], v[54:57]
	v_mfma_f32_16x16x32_bf16 v[50:53], v[162:165], v[194:197], v[50:53]
	v_mfma_f32_16x16x32_bf16 v[38:41], v[154:157], v[202:205], v[38:41]
	v_mfma_f32_16x16x32_bf16 v[34:37], v[162:165], v[202:205], v[34:37]
	v_mfma_f32_16x16x32_bf16 v[22:25], v[154:157], v[210:213], v[22:25]
	v_mfma_f32_16x16x32_bf16 v[18:21], v[162:165], v[210:213], v[18:21]
	s_setprio 0
	s_setprio 1
	v_mfma_f32_16x16x32_bf16 v[46:49], v[166:169], v[182:185], v[46:49]
	v_mfma_f32_16x16x32_bf16 v[42:45], v[174:177], v[182:185], v[42:45]
	v_mfma_f32_16x16x32_bf16 v[30:33], v[166:169], v[190:193], v[30:33]
	v_mfma_f32_16x16x32_bf16 v[26:29], v[174:177], v[190:193], v[26:29]
	v_mfma_f32_16x16x32_bf16 v[14:17], v[166:169], v[198:201], v[14:17]
	v_mfma_f32_16x16x32_bf16 v[10:13], v[174:177], v[198:201], v[10:13]
	v_mfma_f32_16x16x32_bf16 v[6:9], v[166:169], v[206:209], v[6:9]
	v_mfma_f32_16x16x32_bf16 v[2:5], v[174:177], v[206:209], v[2:5]
	v_mfma_f32_16x16x32_bf16 v[46:49], v[170:173], v[186:189], v[46:49]
	v_mfma_f32_16x16x32_bf16 v[42:45], v[178:181], v[186:189], v[42:45]
	v_mfma_f32_16x16x32_bf16 v[30:33], v[170:173], v[194:197], v[30:33]
	v_mfma_f32_16x16x32_bf16 v[26:29], v[178:181], v[194:197], v[26:29]
	v_mfma_f32_16x16x32_bf16 v[14:17], v[170:173], v[202:205], v[14:17]
	v_mfma_f32_16x16x32_bf16 v[10:13], v[178:181], v[202:205], v[10:13]
	v_mfma_f32_16x16x32_bf16 v[6:9], v[170:173], v[210:213], v[6:9]
	v_mfma_f32_16x16x32_bf16 v[2:5], v[178:181], v[210:213], v[2:5]
	s_setprio 0
	s_barrier
; #define PG8_STAGE(bufoff, gbase, voff) do { _Pragma("unroll") for (int _i = 0; _i < 2; ++_i) \
;         __builtin_amdgcn_global_load_lds((const unsigned*)((const char*)(gbase) + (voff)[_i]), (PG8_LAS unsigned*)(lds + (bufoff) + ldsw + _i * 8192), 16, 0, 0); } while (0)
; #define PG8_LDA(dst, b, h) do { _Pragma("unroll") for (int m = 0; m < 4; ++m) _Pragma("unroll") for (int k = 0; k < 2; ++k) dst[m][k] = *(const PG8_LAS bf16x8*)(lds + PG8_SA(b, h) + aoff + m * 2048 + k * 1024); } while (0)
; #define PG8_LDB(dst, b, h) do { _Pragma("unroll") for (int n = 0; n < 2; ++n) _Pragma("unroll") for (int k = 0; k < 2; ++k) dst[n][k] = *(const PG8_LAS bf16x8*)(lds + PG8_SB(b, h) + boff + n * 2048 + k * 1024); } while (0)
; #define PG8_MMA(ai, bj, At, Bt) do { __builtin_amdgcn_s_setprio(1); _Pragma("unroll") for (int m = 0; m < 4; ++m) _Pragma("unroll") for (int n = 0; n < 2; ++n) _Pragma("unroll") for (int k = 0; k < 2; ++k) \
;         acc[ai][bj][m][n] = __builtin_amdgcn_mfma_f32_16x16x32_bf16(Bt[n][k], At[m][k], acc[ai][bj][m][n], 0, 0, 0); __builtin_amdgcn_s_setprio(0); } while (0)
; #define PG8_WAIT_V(n) asm volatile("s_waitcnt vmcnt(" #n ")" ::: "memory")
; #define PG8_WAIT_L(n) asm volatile("s_waitcnt lgkmcnt(" #n ")" ::: "memory")
; #define PG8_BAR __builtin_amdgcn_s_barrier()
; #define PG8_SCHED __builtin_amdgcn_sched_barrier(0)
; template <class Epi, class Sched, bool ALIGN_EPI = false, bool SP2 = false>
; __device__ __forceinline__ void gemm_phase(PG8_LAS unsigned char* lds, const Gemm g, const Sched& S, const Epi& E) {
;     ...
;             PG8_LDB(B0, 1, 0); PG8_LDB(B1, 1, 1); PG8_SCHED; PG8_LDA(At, 1, 0); PG8_STAGE(PG8_SA(0, 1), a2 + hstep, voffA);
;             PG8_WAIT_V(8); PG8_WAIT_L(0); PG8_BAR; PG8_MMA(0, 0, At, B0); PG8_MMA(0, 1, At, B1); PG8_BAR; PG8_SCHED;
	v_add_u32_e32 v178, s78, v144
	ds_read_b128 v[150:153], v149
	ds_read_b128 v[154:157], v149 offset:1024
	ds_read_b128 v[158:161], v149 offset:2048
	ds_read_b128 v[162:165], v149 offset:3072
	ds_read_b128 v[166:169], v178
	ds_read_b128 v[170:173], v178 offset:1024
	ds_read_b128 v[174:177], v178 offset:2048
	ds_read_b128 v[178:181], v178 offset:3072
	s_add_u32 s70, s76, 0xb0000
	s_addc_u32 s71, s77, 0
	s_mov_b32 m0, s91
	v_lshl_add_u64 v[222:223], s[70:71], 0, v[132:133]
	ds_read_b128 v[182:185], v146 offset:32768
	ds_read_b128 v[186:189], v146 offset:33792
	ds_read_b128 v[190:193], v146 offset:34816
	ds_read_b128 v[194:197], v146 offset:35840
	ds_read_b128 v[198:201], v146 offset:36864
	ds_read_b128 v[202:205], v146 offset:37888
	ds_read_b128 v[206:209], v146 offset:38912
	ds_read_b128 v[210:213], v146 offset:39936
	global_load_lds_dwordx4 v[222:223], off
	v_lshl_add_u64 v[222:223], s[70:71], 0, v[134:135]
	s_mov_b32 m0, s92
	s_nop 0
	global_load_lds_dwordx4 v[222:223], off
	s_waitcnt vmcnt(8)
	s_waitcnt lgkmcnt(0)
	s_barrier
	s_setprio 1
	s_waitcnt lgkmcnt(0)
	v_mfma_f32_16x16x32_bf16 v[126:129], v[150:153], v[182:185], v[126:129]
	v_mfma_f32_16x16x32_bf16 v[122:125], v[158:161], v[182:185], v[122:125]
	v_mfma_f32_16x16x32_bf16 v[118:121], v[150:153], v[190:193], v[118:121]
	v_mfma_f32_16x16x32_bf16 v[114:117], v[158:161], v[190:193], v[114:117]
	v_mfma_f32_16x16x32_bf16 v[102:105], v[150:153], v[198:201], v[102:105]
	v_mfma_f32_16x16x32_bf16 v[98:101], v[158:161], v[198:201], v[98:101]
	v_mfma_f32_16x16x32_bf16 v[86:89], v[150:153], v[206:209], v[86:89]
	v_mfma_f32_16x16x32_bf16 v[82:85], v[158:161], v[206:209], v[82:85]
	v_mfma_f32_16x16x32_bf16 v[126:129], v[154:157], v[186:189], v[126:129]
	v_mfma_f32_16x16x32_bf16 v[122:125], v[162:165], v[186:189], v[122:125]
	v_mfma_f32_16x16x32_bf16 v[118:121], v[154:157], v[194:197], v[118:121]
	v_mfma_f32_16x16x32_bf16 v[114:117], v[162:165], v[194:197], v[114:117]
	v_mfma_f32_16x16x32_bf16 v[102:105], v[154:157], v[202:205], v[102:105]
	v_mfma_f32_16x16x32_bf16 v[98:101], v[162:165], v[202:205], v[98:101]
	v_mfma_f32_16x16x32_bf16 v[86:89], v[154:157], v[210:213], v[86:89]
	v_mfma_f32_16x16x32_bf16 v[82:85], v[162:165], v[210:213], v[82:85]
	s_setprio 0
	s_setprio 1
	v_mfma_f32_16x16x32_bf16 v[110:113], v[166:169], v[182:185], v[110:113]
	v_mfma_f32_16x16x32_bf16 v[106:109], v[174:177], v[182:185], v[106:109]
	v_mfma_f32_16x16x32_bf16 v[94:97], v[166:169], v[190:193], v[94:97]
	v_mfma_f32_16x16x32_bf16 v[90:93], v[174:177], v[190:193], v[90:93]
	v_mfma_f32_16x16x32_bf16 v[78:81], v[166:169], v[198:201], v[78:81]
	v_mfma_f32_16x16x32_bf16 v[74:77], v[174:177], v[198:201], v[74:77]
	v_mfma_f32_16x16x32_bf16 v[70:73], v[166:169], v[206:209], v[70:73]
	v_mfma_f32_16x16x32_bf16 v[66:69], v[174:177], v[206:209], v[66:69]
	v_mfma_f32_16x16x32_bf16 v[110:113], v[170:173], v[186:189], v[110:113]
	v_mfma_f32_16x16x32_bf16 v[106:109], v[178:181], v[186:189], v[106:109]
	v_mfma_f32_16x16x32_bf16 v[94:97], v[170:173], v[194:197], v[94:97]
	v_mfma_f32_16x16x32_bf16 v[90:93], v[178:181], v[194:197], v[90:93]
	v_mfma_f32_16x16x32_bf16 v[78:81], v[170:173], v[202:205], v[78:81]
	v_mfma_f32_16x16x32_bf16 v[74:77], v[178:181], v[202:205], v[74:77]
	v_mfma_f32_16x16x32_bf16 v[70:73], v[170:173], v[210:213], v[70:73]
	v_mfma_f32_16x16x32_bf16 v[66:69], v[178:181], v[210:213], v[66:69]
	s_setprio 0
	s_barrier
; #define PG8_STAGE(bufoff, gbase, voff) do { _Pragma("unroll") for (int _i = 0; _i < 2; ++_i) \
;         __builtin_amdgcn_global_load_lds((const unsigned*)((const char*)(gbase) + (voff)[_i]), (PG8_LAS unsigned*)(lds + (bufoff) + ldsw + _i * 8192), 16, 0, 0); } while (0)
; #define PG8_LDA(dst, b, h) do { _Pragma("unroll") for (int m = 0; m < 4; ++m) _Pragma("unroll") for (int k = 0; k < 2; ++k) dst[m][k] = *(const PG8_LAS bf16x8*)(lds + PG8_SA(b, h) + aoff + m * 2048 + k * 1024); } while (0)
; #define PG8_MMA(ai, bj, At, Bt) do { __builtin_amdgcn_s_setprio(1); _Pragma("unroll") for (int m = 0; m < 4; ++m) _Pragma("unroll") for (int n = 0; n < 2; ++n) _Pragma("unroll") for (int k = 0; k < 2; ++k) \
;         acc[ai][bj][m][n] = __builtin_amdgcn_mfma_f32_16x16x32_bf16(Bt[n][k], At[m][k], acc[ai][bj][m][n], 0, 0, 0); __builtin_amdgcn_s_setprio(0); } while (0)
; #define PG8_WAIT_V(n) asm volatile("s_waitcnt vmcnt(" #n ")" ::: "memory")
; #define PG8_WAIT_L(n) asm volatile("s_waitcnt lgkmcnt(" #n ")" ::: "memory")
; #define PG8_BAR __builtin_amdgcn_s_barrier()
; #define PG8_SCHED __builtin_amdgcn_sched_barrier(0)
; template <class Epi, class Sched, bool ALIGN_EPI = false, bool SP2 = false>
; __device__ __forceinline__ void gemm_phase(PG8_LAS unsigned char* lds, const Gemm g, const Sched& S, const Epi& E) {
;     ...
;             PG8_LDA(At, 1, 1); PG8_STAGE(PG8_SB(1, 0), b3, voffB); PG8_STAGE(PG8_SB(1, 1), b3 + hstep, voffB); PG8_STAGE(PG8_SA(1, 0), a3, voffA);
;             PG8_WAIT_V(8); PG8_WAIT_L(0); PG8_BAR; PG8_MMA(1, 0, At, B0); PG8_MMA(1, 1, At, B1); PG8_BAR; PG8_SCHED;
	s_mov_b32 m0, s33
	v_lshl_add_u64 v[214:215], v[214:215], 0, s[24:25]
	s_add_u32 s70, s74, 0xb0080
	ds_read_b128 v[182:185], v146 offset:49152
	ds_read_b128 v[186:189], v146 offset:50176
	ds_read_b128 v[190:193], v146 offset:51200
	ds_read_b128 v[194:197], v146 offset:52224
	ds_read_b128 v[198:201], v146 offset:53248
	ds_read_b128 v[202:205], v146 offset:54272
	ds_read_b128 v[206:209], v146 offset:55296
	ds_read_b128 v[210:213], v146 offset:56320
	global_load_lds_dwordx4 v[214:215], off
	v_lshl_add_u64 v[214:215], v[216:217], 0, s[24:25]
	s_mov_b32 m0, s36
	s_addc_u32 s71, s75, 0
	global_load_lds_dwordx4 v[214:215], off
	v_lshl_add_u64 v[214:215], s[70:71], 0, v[130:131]
	s_mov_b32 m0, s48
	s_nop 0
	global_load_lds_dwordx4 v[214:215], off
	v_lshl_add_u64 v[214:215], s[70:71], 0, v[136:137]
	s_mov_b32 m0, s49
	s_nop 0
	global_load_lds_dwordx4 v[214:215], off
	v_lshl_add_u64 v[214:215], v[218:219], 0, s[24:25]
	s_mov_b32 m0, s37
	s_nop 0
	global_load_lds_dwordx4 v[214:215], off
	v_lshl_add_u64 v[214:215], v[220:221], 0, s[24:25]
	s_mov_b32 m0, s40
	s_nop 0
	global_load_lds_dwordx4 v[214:215], off
	s_waitcnt vmcnt(8)
	s_waitcnt lgkmcnt(0)
	s_barrier
	s_setprio 1
	s_waitcnt lgkmcnt(0)
	v_mfma_f32_16x16x32_bf16 v[62:65], v[150:153], v[182:185], v[62:65]
	v_mfma_f32_16x16x32_bf16 v[58:61], v[158:161], v[182:185], v[58:61]
	v_mfma_f32_16x16x32_bf16 v[54:57], v[150:153], v[190:193], v[54:57]
	v_mfma_f32_16x16x32_bf16 v[50:53], v[158:161], v[190:193], v[50:53]
	v_mfma_f32_16x16x32_bf16 v[38:41], v[150:153], v[198:201], v[38:41]
	v_mfma_f32_16x16x32_bf16 v[34:37], v[158:161], v[198:201], v[34:37]
	v_mfma_f32_16x16x32_bf16 v[22:25], v[150:153], v[206:209], v[22:25]
	v_mfma_f32_16x16x32_bf16 v[18:21], v[158:161], v[206:209], v[18:21]
	v_mfma_f32_16x16x32_bf16 v[62:65], v[154:157], v[186:189], v[62:65]
	v_mfma_f32_16x16x32_bf16 v[58:61], v[162:165], v[186:189], v[58:61]
	v_mfma_f32_16x16x32_bf16 v[54:57], v[154:157], v[194:197], v[54:57]
	v_mfma_f32_16x16x32_bf16 v[50:53], v[162:165], v[194:197], v[50:53]
	v_mfma_f32_16x16x32_bf16 v[38:41], v[154:157], v[202:205], v[38:41]
	v_mfma_f32_16x16x32_bf16 v[34:37], v[162:165], v[202:205], v[34:37]
	v_mfma_f32_16x16x32_bf16 v[22:25], v[154:157], v[210:213], v[22:25]
	v_mfma_f32_16x16x32_bf16 v[18:21], v[162:165], v[210:213], v[18:21]
	s_setprio 0
	s_setprio 1
	v_mfma_f32_16x16x32_bf16 v[46:49], v[166:169], v[182:185], v[46:49]
	v_mfma_f32_16x16x32_bf16 v[42:45], v[174:177], v[182:185], v[42:45]
	v_mfma_f32_16x16x32_bf16 v[30:33], v[166:169], v[190:193], v[30:33]
	v_mfma_f32_16x16x32_bf16 v[26:29], v[174:177], v[190:193], v[26:29]
	v_mfma_f32_16x16x32_bf16 v[14:17], v[166:169], v[198:201], v[14:17]
	v_mfma_f32_16x16x32_bf16 v[10:13], v[174:177], v[198:201], v[10:13]
	v_mfma_f32_16x16x32_bf16 v[6:9], v[166:169], v[206:209], v[6:9]
	v_mfma_f32_16x16x32_bf16 v[2:5], v[174:177], v[206:209], v[2:5]
	v_mfma_f32_16x16x32_bf16 v[46:49], v[170:173], v[186:189], v[46:49]
	v_mfma_f32_16x16x32_bf16 v[42:45], v[178:181], v[186:189], v[42:45]
	v_mfma_f32_16x16x32_bf16 v[30:33], v[170:173], v[194:197], v[30:33]
	v_mfma_f32_16x16x32_bf16 v[26:29], v[178:181], v[194:197], v[26:29]
	v_mfma_f32_16x16x32_bf16 v[14:17], v[170:173], v[202:205], v[14:17]
	v_mfma_f32_16x16x32_bf16 v[10:13], v[178:181], v[202:205], v[10:13]
	v_mfma_f32_16x16x32_bf16 v[6:9], v[170:173], v[210:213], v[6:9]
	v_mfma_f32_16x16x32_bf16 v[2:5], v[178:181], v[210:213], v[2:5]
	s_setprio 0
	s_add_u32 vcc_lo, vcc_lo, 0x100
	s_addc_u32 vcc_hi, vcc_hi, 0
	s_cmp_ge_u32 s38, s93
	s_mov_b64 s[70:71], s[72:73]
	s_mov_b32 s74, s38
	s_barrier
	s_cbranch_scc0 .LBB0_346
	s_and_b64 vcc, exec, s[56:57]
	s_cbranch_vccz .LBB0_349
	s_barrier

; #define PG8_STAGE(bufoff, gbase, voff) do { _Pragma("unroll") for (int _i = 0; _i < 2; ++_i) \
;         __builtin_amdgcn_global_load_lds((const unsigned*)((const char*)(gbase) + (voff)[_i]), (PG8_LAS unsigned*)(lds + (bufoff) + ldsw + _i * 8192), 16, 0, 0); } while (0)
; #define PG8_LDA(dst, b, h) do { _Pragma("unroll") for (int m = 0; m < 4; ++m) _Pragma("unroll") for (int k = 0; k < 2; ++k) dst[m][k] = *(const PG8_LAS bf16x8*)(lds + PG8_SA(b, h) + aoff + m * 2048 + k * 1024); } while (0)
; #define PG8_WAIT_V(n) asm volatile("s_waitcnt vmcnt(" #n ")" ::: "memory")
;     __host__ __device__ bool next(int i, Unit& u) const {
;         const long L = (long)i * G + c; if (L >= nwg) return false;
;         int wgid = (int)L; { const int q = nwg / NXCD, r = nwg % NXCD, xcd = wgid % NXCD, off = wgid / NXCD; wgid = (xcd < r ? xcd * (q + 1) : r * (q + 1) + (xcd - r) * q) + off; }
;         const int nig = WGM * nN, gid = wgid / nig, fm = gid * WGM, gsz = (nM - fm) < WGM ? (nM - fm) : WGM;
;         u.pm = fm + ((wgid % nig) % gsz); u.pn = (wgid % nig) / gsz; u.ks = 0; return true;
; template <class Epi, class Sched, bool ALIGN_EPI = false, bool SP2 = false>
; __device__ __forceinline__ void gemm_phase(PG8_LAS unsigned char* lds, const Gemm g, const Sched& S, const Epi& E) {
;     ...
;         const bool has_next = S.next(ui + 1, nxt);
;         const char* nA = has_next ? (const char*)g.A + (size_t)nxt.pm * tstep + (size_t)nxt.ks * K * 2 : cA; const char* nB = has_next ? (const char*)g.Bt + (size_t)nxt.pn * tstep + (size_t)nxt.ks * K * 2 : cB;
;         for (int t = 0; t < nt; t += 2) {
;             const bool last = (t == nt - 2);
;             const char* a1 = cA + (size_t)(t + 1) * kstep;
;             const char* a2 = last ? nA : cA + (size_t)(t + 2) * kstep; const char* b2 = last ? nB : cB + (size_t)(t + 2) * kstep;
;             const char* a3 = a2 + kstep; const char* b3 = b2 + kstep;
;             if (last && has_next) S.a_ready(nxt);
;             if constexpr (SP2) {
;             PG8_LDB(B0, 0, 0); PG8_LDB(B1, 0, 1); PG8_SCHED; PG8_LDA(At, 0, 0); PG8_STAGE(PG8_SA(1, 1), a1 + hstep, voffA);
;             PG8_WAIT_V(8); PG8_WAIT_L(0); PG8_BAR; PG8_MMA(0, 0, At, B0); PG8_MMA(0, 1, At, B1); PG8_BAR; PG8_SCHED;
;             PG8_LDA(At, 0, 1); PG8_STAGE(PG8_SB(0, 0), b2, voffB); PG8_STAGE(PG8_SB(0, 1), b2 + hstep, voffB); PG8_STAGE(PG8_SA(0, 0), a2, voffA);
.LBB0_516:
	s_ashr_i32 s39, s38, 31
	s_lshl_b64 s[40:41], s[38:39], 19
	s_add_u32 s40, s28, s40
	s_addc_u32 s41, s29, s41
	s_and_b64 s[42:43], s[2:3], exec
	s_cselect_b32 s33, s41, s53
	s_cselect_b32 s39, s40, s52
	s_ashr_i32 s37, s36, 31
	s_lshl_b64 s[42:43], s[36:37], 19
	s_add_u32 s42, s30, s42
	s_addc_u32 s43, s31, s43
	s_and_b64 s[48:49], s[2:3], exec
	s_cselect_b32 s37, s43, s47
	s_cselect_b32 s45, s42, s46
	s_add_u32 s48, s46, 0x100
	s_addc_u32 s49, s47, 0
	s_add_u32 s46, s52, 0x40080
	s_addc_u32 s47, s53, 0
	s_mov_b32 s50, -2
	ds_read_b128 v[148:151], v161
	ds_read_b128 v[152:155], v161 offset:1024
	ds_read_b128 v[166:169], v161 offset:2048
	ds_read_b128 v[170:173], v161 offset:3072
	ds_read_b128 v[174:177], v162
	ds_read_b128 v[178:181], v162 offset:1024
	ds_read_b128 v[182:185], v162 offset:2048
	ds_read_b128 v[186:189], v162 offset:3072
	s_add_u32 s51, s46, 0xfffc0080
	s_addc_u32 s52, s47, -1
	s_cmp_eq_u32 s50, 12
	s_cselect_b32 s57, s33, s52
	s_cselect_b32 s56, s39, s51
	s_cselect_b32 s53, s37, s49
	s_cselect_b32 s52, s45, s48
	v_lshl_add_u64 v[156:157], s[46:47], 0, v[142:143]
	s_add_i32 m0, s66, 0xc000
	ds_read_b128 v[190:193], v163
	ds_read_b128 v[194:197], v163 offset:1024
	ds_read_b128 v[198:201], v163 offset:2048
	ds_read_b128 v[202:205], v163 offset:3072
	ds_read_b128 v[206:209], v163 offset:4096
	ds_read_b128 v[210:213], v163 offset:5120
	ds_read_b128 v[214:217], v163 offset:6144
	ds_read_b128 v[218:221], v163 offset:7168
	global_load_lds_dwordx4 v[156:157], off
	v_lshl_add_u64 v[156:157], s[46:47], 0, v[140:141]
	s_add_i32 m0, s66, 0xe000
	s_nop 0
	global_load_lds_dwordx4 v[156:157], off
	s_waitcnt vmcnt(8)
	s_waitcnt lgkmcnt(0)
	s_barrier
	s_setprio 1
	s_waitcnt lgkmcnt(0)
	v_mfma_f32_16x16x32_bf16 v[126:129], v[148:151], v[190:193], 0
	v_mfma_f32_16x16x32_bf16 v[122:125], v[166:169], v[190:193], 0
	v_mfma_f32_16x16x32_bf16 v[118:121], v[148:151], v[198:201], 0
	v_mfma_f32_16x16x32_bf16 v[114:117], v[166:169], v[198:201], 0
	v_mfma_f32_16x16x32_bf16 v[102:105], v[148:151], v[206:209], 0
	v_mfma_f32_16x16x32_bf16 v[98:101], v[166:169], v[206:209], 0
	v_mfma_f32_16x16x32_bf16 v[86:89], v[148:151], v[214:217], 0
	v_mfma_f32_16x16x32_bf16 v[82:85], v[166:169], v[214:217], 0
	v_mfma_f32_16x16x32_bf16 v[126:129], v[152:155], v[194:197], v[126:129]
	v_mfma_f32_16x16x32_bf16 v[122:125], v[170:173], v[194:197], v[122:125]
	v_mfma_f32_16x16x32_bf16 v[118:121], v[152:155], v[202:205], v[118:121]
	v_mfma_f32_16x16x32_bf16 v[114:117], v[170:173], v[202:205], v[114:117]
	v_mfma_f32_16x16x32_bf16 v[102:105], v[152:155], v[210:213], v[102:105]
	v_mfma_f32_16x16x32_bf16 v[98:101], v[170:173], v[210:213], v[98:101]
	v_mfma_f32_16x16x32_bf16 v[86:89], v[152:155], v[218:221], v[86:89]
	v_mfma_f32_16x16x32_bf16 v[82:85], v[170:173], v[218:221], v[82:85]
	s_setprio 0
	s_setprio 1
	v_mfma_f32_16x16x32_bf16 v[110:113], v[174:177], v[190:193], 0
	v_mfma_f32_16x16x32_bf16 v[106:109], v[182:185], v[190:193], 0
	v_mfma_f32_16x16x32_bf16 v[94:97], v[174:177], v[198:201], 0
	v_mfma_f32_16x16x32_bf16 v[90:93], v[182:185], v[198:201], 0
	v_mfma_f32_16x16x32_bf16 v[78:81], v[174:177], v[206:209], 0
	v_mfma_f32_16x16x32_bf16 v[74:77], v[182:185], v[206:209], 0
	v_mfma_f32_16x16x32_bf16 v[70:73], v[174:177], v[214:217], 0
	v_mfma_f32_16x16x32_bf16 v[66:69], v[182:185], v[214:217], 0
	v_mfma_f32_16x16x32_bf16 v[110:113], v[178:181], v[194:197], v[110:113]
	v_mfma_f32_16x16x32_bf16 v[106:109], v[186:189], v[194:197], v[106:109]
	v_mfma_f32_16x16x32_bf16 v[94:97], v[178:181], v[202:205], v[94:97]
	v_mfma_f32_16x16x32_bf16 v[90:93], v[186:189], v[202:205], v[90:93]
	v_mfma_f32_16x16x32_bf16 v[78:81], v[178:181], v[210:213], v[78:81]
	v_mfma_f32_16x16x32_bf16 v[74:77], v[186:189], v[210:213], v[74:77]
	v_mfma_f32_16x16x32_bf16 v[70:73], v[178:181], v[218:221], v[70:73]
	v_mfma_f32_16x16x32_bf16 v[66:69], v[186:189], v[218:221], v[66:69]
	s_setprio 0
	s_barrier
	s_mov_b32 m0, s62
	v_lshl_add_u64 v[156:157], s[52:53], 0, v[134:135]
	s_add_u32 s54, s52, 0x40000
	ds_read_b128 v[190:193], v163 offset:16384
	ds_read_b128 v[194:197], v163 offset:17408
	ds_read_b128 v[198:201], v163 offset:18432
	ds_read_b128 v[202:205], v163 offset:19456
	ds_read_b128 v[206:209], v163 offset:20480
	ds_read_b128 v[210:213], v163 offset:21504
	ds_read_b128 v[214:217], v163 offset:22528
	ds_read_b128 v[218:221], v163 offset:23552
	global_load_lds_dwordx4 v[156:157], off
	v_lshl_add_u64 v[222:223], s[52:53], 0, v[130:131]
	s_mov_b32 m0, s63
	s_addc_u32 s55, s53, 0
	global_load_lds_dwordx4 v[222:223], off
	v_lshl_add_u64 v[224:225], s[54:55], 0, v[134:135]
	s_mov_b32 m0, s64
	v_lshl_add_u64 v[226:227], s[56:57], 0, v[132:133]
	global_load_lds_dwordx4 v[224:225], off
	v_lshl_add_u64 v[224:225], s[54:55], 0, v[130:131]
	s_mov_b32 m0, s65
	s_nop 0
	global_load_lds_dwordx4 v[224:225], off
	v_lshl_add_u64 v[224:225], s[56:57], 0, v[136:137]
	s_mov_b32 m0, s66
	s_nop 0
	global_load_lds_dwordx4 v[224:225], off
	s_mov_b32 m0, s67
	s_nop 0
	global_load_lds_dwordx4 v[226:227], off
	s_waitcnt vmcnt(8)
	s_waitcnt lgkmcnt(0)
	s_barrier
; #define PG8_STAGE(bufoff, gbase, voff) do { _Pragma("unroll") for (int _i = 0; _i < 2; ++_i) \
;         __builtin_amdgcn_global_load_lds((const unsigned*)((const char*)(gbase) + (voff)[_i]), (PG8_LAS unsigned*)(lds + (bufoff) + ldsw + _i * 8192), 16, 0, 0); } while (0)
; #define PG8_LDA(dst, b, h) do { _Pragma("unroll") for (int m = 0; m < 4; ++m) _Pragma("unroll") for (int k = 0; k < 2; ++k) dst[m][k] = *(const PG8_LAS bf16x8*)(lds + PG8_SA(b, h) + aoff + m * 2048 + k * 1024); } while (0)
; #define PG8_LDB(dst, b, h) do { _Pragma("unroll") for (int n = 0; n < 2; ++n) _Pragma("unroll") for (int k = 0; k < 2; ++k) dst[n][k] = *(const PG8_LAS bf16x8*)(lds + PG8_SB(b, h) + boff + n * 2048 + k * 1024); } while (0)
; #define PG8_MMA(ai, bj, At, Bt) do { __builtin_amdgcn_s_setprio(1); _Pragma("unroll") for (int m = 0; m < 4; ++m) _Pragma("unroll") for (int n = 0; n < 2; ++n) _Pragma("unroll") for (int k = 0; k < 2; ++k) \
;         acc[ai][bj][m][n] = __builtin_amdgcn_mfma_f32_16x16x32_bf16(Bt[n][k], At[m][k], acc[ai][bj][m][n], 0, 0, 0); __builtin_amdgcn_s_setprio(0); } while (0)
; #define PG8_WAIT_V(n) asm volatile("s_waitcnt vmcnt(" #n ")" ::: "memory")
; #define PG8_WAIT_L(n) asm volatile("s_waitcnt lgkmcnt(" #n ")" ::: "memory")
; #define PG8_BAR __builtin_amdgcn_s_barrier()
; #define PG8_SCHED __builtin_amdgcn_sched_barrier(0)
; template <class Epi, class Sched, bool ALIGN_EPI = false, bool SP2 = false>
; __device__ __forceinline__ void gemm_phase(PG8_LAS unsigned char* lds, const Gemm g, const Sched& S, const Epi& E) {
;     ...
;             PG8_WAIT_V(8); PG8_WAIT_L(0); PG8_BAR; PG8_MMA(1, 0, At, B0); PG8_MMA(1, 1, At, B1); PG8_BAR; PG8_SCHED;
;             PG8_LDB(B0, 1, 0); PG8_LDB(B1, 1, 1); PG8_SCHED; PG8_LDA(At, 1, 0); PG8_STAGE(PG8_SA(0, 1), a2 + hstep, voffA);
;             PG8_WAIT_V(8); PG8_WAIT_L(0); PG8_BAR; PG8_MMA(0, 0, At, B0); PG8_MMA(0, 1, At, B1); PG8_BAR; PG8_SCHED;
	s_setprio 1
	s_waitcnt lgkmcnt(0)
	v_mfma_f32_16x16x32_bf16 v[62:65], v[148:151], v[190:193], 0
	v_mfma_f32_16x16x32_bf16 v[58:61], v[166:169], v[190:193], 0
	v_mfma_f32_16x16x32_bf16 v[54:57], v[148:151], v[198:201], 0
	v_mfma_f32_16x16x32_bf16 v[50:53], v[166:169], v[198:201], 0
	v_mfma_f32_16x16x32_bf16 v[38:41], v[148:151], v[206:209], 0
	v_mfma_f32_16x16x32_bf16 v[34:37], v[166:169], v[206:209], 0
	v_mfma_f32_16x16x32_bf16 v[22:25], v[148:151], v[214:217], 0
	v_mfma_f32_16x16x32_bf16 v[18:21], v[166:169], v[214:217], 0
	v_mfma_f32_16x16x32_bf16 v[62:65], v[152:155], v[194:197], v[62:65]
	v_mfma_f32_16x16x32_bf16 v[58:61], v[170:173], v[194:197], v[58:61]
	v_mfma_f32_16x16x32_bf16 v[54:57], v[152:155], v[202:205], v[54:57]
	v_mfma_f32_16x16x32_bf16 v[50:53], v[170:173], v[202:205], v[50:53]
	v_mfma_f32_16x16x32_bf16 v[38:41], v[152:155], v[210:213], v[38:41]
	v_mfma_f32_16x16x32_bf16 v[34:37], v[170:173], v[210:213], v[34:37]
	v_mfma_f32_16x16x32_bf16 v[22:25], v[152:155], v[218:221], v[22:25]
	v_mfma_f32_16x16x32_bf16 v[18:21], v[170:173], v[218:221], v[18:21]
	s_setprio 0
	s_setprio 1
	v_mfma_f32_16x16x32_bf16 v[46:49], v[174:177], v[190:193], 0
	v_mfma_f32_16x16x32_bf16 v[42:45], v[182:185], v[190:193], 0
	v_mfma_f32_16x16x32_bf16 v[30:33], v[174:177], v[198:201], 0
	v_mfma_f32_16x16x32_bf16 v[26:29], v[182:185], v[198:201], 0
	v_mfma_f32_16x16x32_bf16 v[14:17], v[174:177], v[206:209], 0
	v_mfma_f32_16x16x32_bf16 v[10:13], v[182:185], v[206:209], 0
	v_mfma_f32_16x16x32_bf16 v[6:9], v[174:177], v[214:217], 0
	v_mfma_f32_16x16x32_bf16 v[2:5], v[182:185], v[214:217], 0
	v_mfma_f32_16x16x32_bf16 v[46:49], v[178:181], v[194:197], v[46:49]
	v_mfma_f32_16x16x32_bf16 v[42:45], v[186:189], v[194:197], v[42:45]
	v_mfma_f32_16x16x32_bf16 v[30:33], v[178:181], v[202:205], v[30:33]
	v_mfma_f32_16x16x32_bf16 v[26:29], v[186:189], v[202:205], v[26:29]
	v_mfma_f32_16x16x32_bf16 v[14:17], v[178:181], v[210:213], v[14:17]
	v_mfma_f32_16x16x32_bf16 v[10:13], v[186:189], v[210:213], v[10:13]
	v_mfma_f32_16x16x32_bf16 v[6:9], v[178:181], v[218:221], v[6:9]
	v_mfma_f32_16x16x32_bf16 v[2:5], v[186:189], v[218:221], v[2:5]
	s_setprio 0
	s_barrier
	ds_read_b128 v[148:151], v164
	ds_read_b128 v[152:155], v164 offset:1024
	ds_read_b128 v[166:169], v164 offset:2048
	ds_read_b128 v[170:173], v164 offset:3072
	ds_read_b128 v[174:177], v165
	ds_read_b128 v[178:181], v165 offset:1024
	ds_read_b128 v[182:185], v165 offset:2048
	ds_read_b128 v[186:189], v165 offset:3072
	s_add_u32 s54, s56, 0x40000
	s_addc_u32 s55, s57, 0
	s_mov_b32 m0, s68
	v_lshl_add_u64 v[228:229], s[54:55], 0, v[136:137]
	ds_read_b128 v[190:193], v163 offset:32768
	ds_read_b128 v[194:197], v163 offset:33792
	ds_read_b128 v[198:201], v163 offset:34816
	ds_read_b128 v[202:205], v163 offset:35840
	ds_read_b128 v[206:209], v163 offset:36864
	ds_read_b128 v[210:213], v163 offset:37888
	ds_read_b128 v[214:217], v163 offset:38912
	ds_read_b128 v[218:221], v163 offset:39936
	global_load_lds_dwordx4 v[228:229], off
	v_lshl_add_u64 v[228:229], s[54:55], 0, v[132:133]
	s_mov_b32 m0, s69
	s_nop 0
	global_load_lds_dwordx4 v[228:229], off
	s_waitcnt vmcnt(8)
	s_waitcnt lgkmcnt(0)
	s_barrier
	s_setprio 1
	s_waitcnt lgkmcnt(0)
	v_mfma_f32_16x16x32_bf16 v[126:129], v[148:151], v[190:193], v[126:129]
	v_mfma_f32_16x16x32_bf16 v[122:125], v[166:169], v[190:193], v[122:125]
	v_mfma_f32_16x16x32_bf16 v[118:121], v[148:151], v[198:201], v[118:121]
	v_mfma_f32_16x16x32_bf16 v[114:117], v[166:169], v[198:201], v[114:117]
	v_mfma_f32_16x16x32_bf16 v[102:105], v[148:151], v[206:209], v[102:105]
	v_mfma_f32_16x16x32_bf16 v[98:101], v[166:169], v[206:209], v[98:101]
	v_mfma_f32_16x16x32_bf16 v[86:89], v[148:151], v[214:217], v[86:89]
	v_mfma_f32_16x16x32_bf16 v[82:85], v[166:169], v[214:217], v[82:85]
	v_mfma_f32_16x16x32_bf16 v[126:129], v[152:155], v[194:197], v[126:129]
	v_mfma_f32_16x16x32_bf16 v[122:125], v[170:173], v[194:197], v[122:125]
	v_mfma_f32_16x16x32_bf16 v[118:121], v[152:155], v[202:205], v[118:121]
	v_mfma_f32_16x16x32_bf16 v[114:117], v[170:173], v[202:205], v[114:117]
	v_mfma_f32_16x16x32_bf16 v[102:105], v[152:155], v[210:213], v[102:105]
	v_mfma_f32_16x16x32_bf16 v[98:101], v[170:173], v[210:213], v[98:101]
	v_mfma_f32_16x16x32_bf16 v[86:89], v[152:155], v[218:221], v[86:89]
	v_mfma_f32_16x16x32_bf16 v[82:85], v[170:173], v[218:221], v[82:85]
	s_setprio 0
	s_setprio 1
	v_mfma_f32_16x16x32_bf16 v[110:113], v[174:177], v[190:193], v[110:113]
	v_mfma_f32_16x16x32_bf16 v[106:109], v[182:185], v[190:193], v[106:109]
	v_mfma_f32_16x16x32_bf16 v[94:97], v[174:177], v[198:201], v[94:97]
	v_mfma_f32_16x16x32_bf16 v[90:93], v[182:185], v[198:201], v[90:93]
	v_mfma_f32_16x16x32_bf16 v[78:81], v[174:177], v[206:209], v[78:81]
	v_mfma_f32_16x16x32_bf16 v[74:77], v[182:185], v[206:209], v[74:77]
	v_mfma_f32_16x16x32_bf16 v[70:73], v[174:177], v[214:217], v[70:73]
	v_mfma_f32_16x16x32_bf16 v[66:69], v[182:185], v[214:217], v[66:69]
	v_mfma_f32_16x16x32_bf16 v[110:113], v[178:181], v[194:197], v[110:113]
	v_mfma_f32_16x16x32_bf16 v[106:109], v[186:189], v[194:197], v[106:109]
	v_mfma_f32_16x16x32_bf16 v[94:97], v[178:181], v[202:205], v[94:97]
	v_mfma_f32_16x16x32_bf16 v[90:93], v[186:189], v[202:205], v[90:93]
	v_mfma_f32_16x16x32_bf16 v[78:81], v[178:181], v[210:213], v[78:81]
	v_mfma_f32_16x16x32_bf16 v[74:77], v[186:189], v[210:213], v[74:77]
	v_mfma_f32_16x16x32_bf16 v[70:73], v[178:181], v[218:221], v[70:73]
	v_mfma_f32_16x16x32_bf16 v[66:69], v[186:189], v[218:221], v[66:69]
	s_setprio 0
	s_barrier
; #define PG8_STAGE(bufoff, gbase, voff) do { _Pragma("unroll") for (int _i = 0; _i < 2; ++_i) \
;         __builtin_amdgcn_global_load_lds((const unsigned*)((const char*)(gbase) + (voff)[_i]), (PG8_LAS unsigned*)(lds + (bufoff) + ldsw + _i * 8192), 16, 0, 0); } while (0)
; #define PG8_LDA(dst, b, h) do { _Pragma("unroll") for (int m = 0; m < 4; ++m) _Pragma("unroll") for (int k = 0; k < 2; ++k) dst[m][k] = *(const PG8_LAS bf16x8*)(lds + PG8_SA(b, h) + aoff + m * 2048 + k * 1024); } while (0)
; #define PG8_LDB(dst, b, h) do { _Pragma("unroll") for (int n = 0; n < 2; ++n) _Pragma("unroll") for (int k = 0; k < 2; ++k) dst[n][k] = *(const PG8_LAS bf16x8*)(lds + PG8_SB(b, h) + boff + n * 2048 + k * 1024); } while (0)
; #define PG8_MMA(ai, bj, At, Bt) do { __builtin_amdgcn_s_setprio(1); _Pragma("unroll") for (int m = 0; m < 4; ++m) _Pragma("unroll") for (int n = 0; n < 2; ++n) _Pragma("unroll") for (int k = 0; k < 2; ++k) \
;         acc[ai][bj][m][n] = __builtin_amdgcn_mfma_f32_16x16x32_bf16(Bt[n][k], At[m][k], acc[ai][bj][m][n], 0, 0, 0); __builtin_amdgcn_s_setprio(0); } while (0)
; #define PG8_WAIT_V(n) asm volatile("s_waitcnt vmcnt(" #n ")" ::: "memory")
; template <class Epi, class Sched, bool ALIGN_EPI = false, bool SP2 = false>
; __device__ __forceinline__ void gemm_phase(PG8_LAS unsigned char* lds, const Gemm g, const Sched& S, const Epi& E) {
;     ...
;             PG8_LDB(B0, 0, 0); PG8_LDB(B1, 0, 1); PG8_SCHED; PG8_LDA(At, 0, 0); PG8_STAGE(PG8_SA(1, 1), a1 + hstep, voffA);
;             PG8_WAIT_V(8); PG8_WAIT_L(0); PG8_BAR; PG8_MMA(0, 0, At, B0); PG8_MMA(0, 1, At, B1); PG8_BAR; PG8_SCHED;
;             PG8_LDA(At, 0, 1); PG8_STAGE(PG8_SB(0, 0), b2, voffB); PG8_STAGE(PG8_SB(0, 1), b2 + hstep, voffB); PG8_STAGE(PG8_SA(0, 0), a2, voffA);
;             PG8_WAIT_V(8); PG8_WAIT_L(0); PG8_BAR; PG8_MMA(1, 0, At, B0); PG8_MMA(1, 1, At, B1); PG8_BAR; PG8_SCHED;
;             PG8_LDB(B0, 1, 0); PG8_LDB(B1, 1, 1); PG8_SCHED; PG8_LDA(At, 1, 0); PG8_STAGE(PG8_SA(0, 1), a2 + hstep, voffA);
;             PG8_WAIT_V(8); PG8_WAIT_L(0); PG8_BAR; PG8_MMA(0, 0, At, B0); PG8_MMA(0, 1, At, B1); PG8_BAR; PG8_SCHED;
;             PG8_LDA(At, 1, 1); PG8_STAGE(PG8_SB(1, 0), b3, voffB); PG8_STAGE(PG8_SB(1, 1), b3 + hstep, voffB); PG8_STAGE(PG8_SA(1, 0), a3, voffA);
;             PG8_WAIT_V(8); PG8_WAIT_L(0); PG8_BAR; PG8_MMA(1, 0, At, B0); PG8_MMA(1, 1, At, B1); PG8_BAR; PG8_SCHED;
	s_mov_b32 m0, s70
	v_lshl_add_u64 v[156:157], v[156:157], 0, s[8:9]
	s_add_u32 s52, s52, 0x40080
	ds_read_b128 v[190:193], v163 offset:49152
	ds_read_b128 v[194:197], v163 offset:50176
	ds_read_b128 v[198:201], v163 offset:51200
	ds_read_b128 v[202:205], v163 offset:52224
	ds_read_b128 v[206:209], v163 offset:53248
	ds_read_b128 v[210:213], v163 offset:54272
	ds_read_b128 v[214:217], v163 offset:55296
	ds_read_b128 v[218:221], v163 offset:56320
	global_load_lds_dwordx4 v[156:157], off
	v_lshl_add_u64 v[156:157], v[222:223], 0, s[8:9]
	s_mov_b32 m0, s71
	s_addc_u32 s53, s53, 0
	global_load_lds_dwordx4 v[156:157], off
	v_lshl_add_u64 v[156:157], s[52:53], 0, v[134:135]
	s_mov_b32 m0, s74
	s_nop 0
	global_load_lds_dwordx4 v[156:157], off
	v_lshl_add_u64 v[156:157], s[52:53], 0, v[130:131]
	s_mov_b32 m0, s75
	s_nop 0
	global_load_lds_dwordx4 v[156:157], off
	v_lshl_add_u64 v[156:157], v[224:225], 0, s[8:9]
	s_mov_b32 m0, s72
	s_nop 0
	global_load_lds_dwordx4 v[156:157], off
	v_lshl_add_u64 v[156:157], v[226:227], 0, s[8:9]
	s_mov_b32 m0, s73
	s_nop 0
	global_load_lds_dwordx4 v[156:157], off
	s_waitcnt vmcnt(8)
	s_waitcnt lgkmcnt(0)
	s_barrier
	s_setprio 1
	s_waitcnt lgkmcnt(0)
	v_mfma_f32_16x16x32_bf16 v[62:65], v[148:151], v[190:193], v[62:65]
	v_mfma_f32_16x16x32_bf16 v[58:61], v[166:169], v[190:193], v[58:61]
	v_mfma_f32_16x16x32_bf16 v[54:57], v[148:151], v[198:201], v[54:57]
	v_mfma_f32_16x16x32_bf16 v[50:53], v[166:169], v[198:201], v[50:53]
	v_mfma_f32_16x16x32_bf16 v[38:41], v[148:151], v[206:209], v[38:41]
	v_mfma_f32_16x16x32_bf16 v[34:37], v[166:169], v[206:209], v[34:37]
	v_mfma_f32_16x16x32_bf16 v[22:25], v[148:151], v[214:217], v[22:25]
	v_mfma_f32_16x16x32_bf16 v[18:21], v[166:169], v[214:217], v[18:21]
	v_mfma_f32_16x16x32_bf16 v[62:65], v[152:155], v[194:197], v[62:65]
	v_mfma_f32_16x16x32_bf16 v[58:61], v[170:173], v[194:197], v[58:61]
	v_mfma_f32_16x16x32_bf16 v[54:57], v[152:155], v[202:205], v[54:57]
	v_mfma_f32_16x16x32_bf16 v[50:53], v[170:173], v[202:205], v[50:53]
	v_mfma_f32_16x16x32_bf16 v[38:41], v[152:155], v[210:213], v[38:41]
	v_mfma_f32_16x16x32_bf16 v[34:37], v[170:173], v[210:213], v[34:37]
	v_mfma_f32_16x16x32_bf16 v[22:25], v[152:155], v[218:221], v[22:25]
	v_mfma_f32_16x16x32_bf16 v[18:21], v[170:173], v[218:221], v[18:21]
	s_setprio 0
	s_setprio 1
	v_mfma_f32_16x16x32_bf16 v[46:49], v[174:177], v[190:193], v[46:49]
	v_mfma_f32_16x16x32_bf16 v[42:45], v[182:185], v[190:193], v[42:45]
	v_mfma_f32_16x16x32_bf16 v[30:33], v[174:177], v[198:201], v[30:33]
	v_mfma_f32_16x16x32_bf16 v[26:29], v[182:185], v[198:201], v[26:29]
	v_mfma_f32_16x16x32_bf16 v[14:17], v[174:177], v[206:209], v[14:17]
	v_mfma_f32_16x16x32_bf16 v[10:13], v[182:185], v[206:209], v[10:13]
	v_mfma_f32_16x16x32_bf16 v[6:9], v[174:177], v[214:217], v[6:9]
	v_mfma_f32_16x16x32_bf16 v[2:5], v[182:185], v[214:217], v[2:5]
	v_mfma_f32_16x16x32_bf16 v[46:49], v[178:181], v[194:197], v[46:49]
	v_mfma_f32_16x16x32_bf16 v[42:45], v[186:189], v[194:197], v[42:45]
	v_mfma_f32_16x16x32_bf16 v[30:33], v[178:181], v[202:205], v[30:33]
	v_mfma_f32_16x16x32_bf16 v[26:29], v[186:189], v[202:205], v[26:29]
	v_mfma_f32_16x16x32_bf16 v[14:17], v[178:181], v[210:213], v[14:17]
	v_mfma_f32_16x16x32_bf16 v[10:13], v[186:189], v[210:213], v[10:13]
	v_mfma_f32_16x16x32_bf16 v[6:9], v[178:181], v[218:221], v[6:9]
	v_mfma_f32_16x16x32_bf16 v[2:5], v[186:189], v[218:221], v[2:5]
	s_setprio 0
	s_add_i32 s50, s50, 2
	s_add_u32 s48, s48, 0x100
	s_addc_u32 s49, s49, 0
	s_add_u32 s46, s46, 0x100
	s_addc_u32 s47, s47, 0
	s_cmp_gt_u32 s50, 13
	s_barrier
.LBB0_517:
	ds_read_b128 v[148:151], v161
	ds_read_b128 v[152:155], v161 offset:1024
	ds_read_b128 v[166:169], v161 offset:2048
	ds_read_b128 v[170:173], v161 offset:3072
	ds_read_b128 v[174:177], v162
	ds_read_b128 v[178:181], v162 offset:1024
	ds_read_b128 v[182:185], v162 offset:2048
	ds_read_b128 v[186:189], v162 offset:3072
	s_add_u32 s51, s46, 0xfffc0080
	s_addc_u32 s52, s47, -1
	s_cmp_eq_u32 s50, 12
	s_cselect_b32 s57, s33, s52
	s_cselect_b32 s56, s39, s51
	s_cselect_b32 s53, s37, s49
	s_cselect_b32 s52, s45, s48
	v_lshl_add_u64 v[156:157], s[46:47], 0, v[142:143]
	s_add_i32 m0, s66, 0xc000
	ds_read_b128 v[190:193], v163
	ds_read_b128 v[194:197], v163 offset:1024
	ds_read_b128 v[198:201], v163 offset:2048
	ds_read_b128 v[202:205], v163 offset:3072
	ds_read_b128 v[206:209], v163 offset:4096
	ds_read_b128 v[210:213], v163 offset:5120
	ds_read_b128 v[214:217], v163 offset:6144
	ds_read_b128 v[218:221], v163 offset:7168
	global_load_lds_dwordx4 v[156:157], off
	v_lshl_add_u64 v[156:157], s[46:47], 0, v[140:141]
	s_add_i32 m0, s66, 0xe000
	s_nop 0
	global_load_lds_dwordx4 v[156:157], off
	s_waitcnt vmcnt(8)
	s_waitcnt lgkmcnt(0)
	s_barrier
; #define PG8_STAGE(bufoff, gbase, voff) do { _Pragma("unroll") for (int _i = 0; _i < 2; ++_i) \
;         __builtin_amdgcn_global_load_lds((const unsigned*)((const char*)(gbase) + (voff)[_i]), (PG8_LAS unsigned*)(lds + (bufoff) + ldsw + _i * 8192), 16, 0, 0); } while (0)
; #define PG8_LDA(dst, b, h) do { _Pragma("unroll") for (int m = 0; m < 4; ++m) _Pragma("unroll") for (int k = 0; k < 2; ++k) dst[m][k] = *(const PG8_LAS bf16x8*)(lds + PG8_SA(b, h) + aoff + m * 2048 + k * 1024); } while (0)
; #define PG8_MMA(ai, bj, At, Bt) do { __builtin_amdgcn_s_setprio(1); _Pragma("unroll") for (int m = 0; m < 4; ++m) _Pragma("unroll") for (int n = 0; n < 2; ++n) _Pragma("unroll") for (int k = 0; k < 2; ++k) \
;         acc[ai][bj][m][n] = __builtin_amdgcn_mfma_f32_16x16x32_bf16(Bt[n][k], At[m][k], acc[ai][bj][m][n], 0, 0, 0); __builtin_amdgcn_s_setprio(0); } while (0)
; #define PG8_WAIT_V(n) asm volatile("s_waitcnt vmcnt(" #n ")" ::: "memory")
; #define PG8_WAIT_L(n) asm volatile("s_waitcnt lgkmcnt(" #n ")" ::: "memory")
; #define PG8_BAR __builtin_amdgcn_s_barrier()
; #define PG8_SCHED __builtin_amdgcn_sched_barrier(0)
; template <class Epi, class Sched, bool ALIGN_EPI = false, bool SP2 = false>
; __device__ __forceinline__ void gemm_phase(PG8_LAS unsigned char* lds, const Gemm g, const Sched& S, const Epi& E) {
;     ...
;             PG8_WAIT_V(8); PG8_WAIT_L(0); PG8_BAR; PG8_MMA(0, 0, At, B0); PG8_MMA(0, 1, At, B1); PG8_BAR; PG8_SCHED;
;             PG8_LDA(At, 0, 1); PG8_STAGE(PG8_SB(0, 0), b2, voffB); PG8_STAGE(PG8_SB(0, 1), b2 + hstep, voffB); PG8_STAGE(PG8_SA(0, 0), a2, voffA);
;             PG8_WAIT_V(8); PG8_WAIT_L(0); PG8_BAR; PG8_MMA(1, 0, At, B0); PG8_MMA(1, 1, At, B1); PG8_BAR; PG8_SCHED;
	s_setprio 1
	s_waitcnt lgkmcnt(0)
	v_mfma_f32_16x16x32_bf16 v[126:129], v[148:151], v[190:193], v[126:129]
	v_mfma_f32_16x16x32_bf16 v[122:125], v[166:169], v[190:193], v[122:125]
	v_mfma_f32_16x16x32_bf16 v[118:121], v[148:151], v[198:201], v[118:121]
	v_mfma_f32_16x16x32_bf16 v[114:117], v[166:169], v[198:201], v[114:117]
	v_mfma_f32_16x16x32_bf16 v[102:105], v[148:151], v[206:209], v[102:105]
	v_mfma_f32_16x16x32_bf16 v[98:101], v[166:169], v[206:209], v[98:101]
	v_mfma_f32_16x16x32_bf16 v[86:89], v[148:151], v[214:217], v[86:89]
	v_mfma_f32_16x16x32_bf16 v[82:85], v[166:169], v[214:217], v[82:85]
	v_mfma_f32_16x16x32_bf16 v[126:129], v[152:155], v[194:197], v[126:129]
	v_mfma_f32_16x16x32_bf16 v[122:125], v[170:173], v[194:197], v[122:125]
	v_mfma_f32_16x16x32_bf16 v[118:121], v[152:155], v[202:205], v[118:121]
	v_mfma_f32_16x16x32_bf16 v[114:117], v[170:173], v[202:205], v[114:117]
	v_mfma_f32_16x16x32_bf16 v[102:105], v[152:155], v[210:213], v[102:105]
	v_mfma_f32_16x16x32_bf16 v[98:101], v[170:173], v[210:213], v[98:101]
	v_mfma_f32_16x16x32_bf16 v[86:89], v[152:155], v[218:221], v[86:89]
	v_mfma_f32_16x16x32_bf16 v[82:85], v[170:173], v[218:221], v[82:85]
	s_setprio 0
	s_setprio 1
	v_mfma_f32_16x16x32_bf16 v[110:113], v[174:177], v[190:193], v[110:113]
	v_mfma_f32_16x16x32_bf16 v[106:109], v[182:185], v[190:193], v[106:109]
	v_mfma_f32_16x16x32_bf16 v[94:97], v[174:177], v[198:201], v[94:97]
	v_mfma_f32_16x16x32_bf16 v[90:93], v[182:185], v[198:201], v[90:93]
	v_mfma_f32_16x16x32_bf16 v[78:81], v[174:177], v[206:209], v[78:81]
	v_mfma_f32_16x16x32_bf16 v[74:77], v[182:185], v[206:209], v[74:77]
	v_mfma_f32_16x16x32_bf16 v[70:73], v[174:177], v[214:217], v[70:73]
	v_mfma_f32_16x16x32_bf16 v[66:69], v[182:185], v[214:217], v[66:69]
	v_mfma_f32_16x16x32_bf16 v[110:113], v[178:181], v[194:197], v[110:113]
	v_mfma_f32_16x16x32_bf16 v[106:109], v[186:189], v[194:197], v[106:109]
	v_mfma_f32_16x16x32_bf16 v[94:97], v[178:181], v[202:205], v[94:97]
	v_mfma_f32_16x16x32_bf16 v[90:93], v[186:189], v[202:205], v[90:93]
	v_mfma_f32_16x16x32_bf16 v[78:81], v[178:181], v[210:213], v[78:81]
	v_mfma_f32_16x16x32_bf16 v[74:77], v[186:189], v[210:213], v[74:77]
	v_mfma_f32_16x16x32_bf16 v[70:73], v[178:181], v[218:221], v[70:73]
	v_mfma_f32_16x16x32_bf16 v[66:69], v[186:189], v[218:221], v[66:69]
	s_setprio 0
	s_barrier
	s_mov_b32 m0, s62
	v_lshl_add_u64 v[156:157], s[52:53], 0, v[134:135]
	s_add_u32 s54, s52, 0x40000
	ds_read_b128 v[190:193], v163 offset:16384
	ds_read_b128 v[194:197], v163 offset:17408
	ds_read_b128 v[198:201], v163 offset:18432
	ds_read_b128 v[202:205], v163 offset:19456
	ds_read_b128 v[206:209], v163 offset:20480
	ds_read_b128 v[210:213], v163 offset:21504
	ds_read_b128 v[214:217], v163 offset:22528
	ds_read_b128 v[218:221], v163 offset:23552
	global_load_lds_dwordx4 v[156:157], off
	v_lshl_add_u64 v[222:223], s[52:53], 0, v[130:131]
	s_mov_b32 m0, s63
	s_addc_u32 s55, s53, 0
	global_load_lds_dwordx4 v[222:223], off
	v_lshl_add_u64 v[224:225], s[54:55], 0, v[134:135]
	s_mov_b32 m0, s64
	v_lshl_add_u64 v[226:227], s[56:57], 0, v[132:133]
	global_load_lds_dwordx4 v[224:225], off
	v_lshl_add_u64 v[224:225], s[54:55], 0, v[130:131]
	s_mov_b32 m0, s65
	s_nop 0
	global_load_lds_dwordx4 v[224:225], off
	v_lshl_add_u64 v[224:225], s[56:57], 0, v[136:137]
	s_mov_b32 m0, s66
	s_nop 0
	global_load_lds_dwordx4 v[224:225], off
	s_mov_b32 m0, s67
	s_nop 0
	global_load_lds_dwordx4 v[226:227], off
	s_waitcnt vmcnt(8)
	s_waitcnt lgkmcnt(0)
	s_barrier
	s_setprio 1
	s_waitcnt lgkmcnt(0)
	v_mfma_f32_16x16x32_bf16 v[62:65], v[148:151], v[190:193], v[62:65]
	v_mfma_f32_16x16x32_bf16 v[58:61], v[166:169], v[190:193], v[58:61]
	v_mfma_f32_16x16x32_bf16 v[54:57], v[148:151], v[198:201], v[54:57]
	v_mfma_f32_16x16x32_bf16 v[50:53], v[166:169], v[198:201], v[50:53]
	v_mfma_f32_16x16x32_bf16 v[38:41], v[148:151], v[206:209], v[38:41]
	v_mfma_f32_16x16x32_bf16 v[34:37], v[166:169], v[206:209], v[34:37]
	v_mfma_f32_16x16x32_bf16 v[22:25], v[148:151], v[214:217], v[22:25]
	v_mfma_f32_16x16x32_bf16 v[18:21], v[166:169], v[214:217], v[18:21]
	v_mfma_f32_16x16x32_bf16 v[62:65], v[152:155], v[194:197], v[62:65]
	v_mfma_f32_16x16x32_bf16 v[58:61], v[170:173], v[194:197], v[58:61]
	v_mfma_f32_16x16x32_bf16 v[54:57], v[152:155], v[202:205], v[54:57]
	v_mfma_f32_16x16x32_bf16 v[50:53], v[170:173], v[202:205], v[50:53]
	v_mfma_f32_16x16x32_bf16 v[38:41], v[152:155], v[210:213], v[38:41]
	v_mfma_f32_16x16x32_bf16 v[34:37], v[170:173], v[210:213], v[34:37]
	v_mfma_f32_16x16x32_bf16 v[22:25], v[152:155], v[218:221], v[22:25]
	v_mfma_f32_16x16x32_bf16 v[18:21], v[170:173], v[218:221], v[18:21]
	s_setprio 0
	s_setprio 1
	v_mfma_f32_16x16x32_bf16 v[46:49], v[174:177], v[190:193], v[46:49]
	v_mfma_f32_16x16x32_bf16 v[42:45], v[182:185], v[190:193], v[42:45]
	v_mfma_f32_16x16x32_bf16 v[30:33], v[174:177], v[198:201], v[30:33]
	v_mfma_f32_16x16x32_bf16 v[26:29], v[182:185], v[198:201], v[26:29]
	v_mfma_f32_16x16x32_bf16 v[14:17], v[174:177], v[206:209], v[14:17]
	v_mfma_f32_16x16x32_bf16 v[10:13], v[182:185], v[206:209], v[10:13]
	v_mfma_f32_16x16x32_bf16 v[6:9], v[174:177], v[214:217], v[6:9]
	v_mfma_f32_16x16x32_bf16 v[2:5], v[182:185], v[214:217], v[2:5]
	v_mfma_f32_16x16x32_bf16 v[46:49], v[178:181], v[194:197], v[46:49]
	v_mfma_f32_16x16x32_bf16 v[42:45], v[186:189], v[194:197], v[42:45]
	v_mfma_f32_16x16x32_bf16 v[30:33], v[178:181], v[202:205], v[30:33]
	v_mfma_f32_16x16x32_bf16 v[26:29], v[186:189], v[202:205], v[26:29]
	v_mfma_f32_16x16x32_bf16 v[14:17], v[178:181], v[210:213], v[14:17]
	v_mfma_f32_16x16x32_bf16 v[10:13], v[186:189], v[210:213], v[10:13]
	v_mfma_f32_16x16x32_bf16 v[6:9], v[178:181], v[218:221], v[6:9]
	v_mfma_f32_16x16x32_bf16 v[2:5], v[186:189], v[218:221], v[2:5]
	s_setprio 0
	s_barrier
; #define PG8_STAGE(bufoff, gbase, voff) do { _Pragma("unroll") for (int _i = 0; _i < 2; ++_i) \
;         __builtin_amdgcn_global_load_lds((const unsigned*)((const char*)(gbase) + (voff)[_i]), (PG8_LAS unsigned*)(lds + (bufoff) + ldsw + _i * 8192), 16, 0, 0); } while (0)
; #define PG8_LDA(dst, b, h) do { _Pragma("unroll") for (int m = 0; m < 4; ++m) _Pragma("unroll") for (int k = 0; k < 2; ++k) dst[m][k] = *(const PG8_LAS bf16x8*)(lds + PG8_SA(b, h) + aoff + m * 2048 + k * 1024); } while (0)
; #define PG8_LDB(dst, b, h) do { _Pragma("unroll") for (int n = 0; n < 2; ++n) _Pragma("unroll") for (int k = 0; k < 2; ++k) dst[n][k] = *(const PG8_LAS bf16x8*)(lds + PG8_SB(b, h) + boff + n * 2048 + k * 1024); } while (0)
; #define PG8_MMA(ai, bj, At, Bt) do { __builtin_amdgcn_s_setprio(1); _Pragma("unroll") for (int m = 0; m < 4; ++m) _Pragma("unroll") for (int n = 0; n < 2; ++n) _Pragma("unroll") for (int k = 0; k < 2; ++k) \
;         acc[ai][bj][m][n] = __builtin_amdgcn_mfma_f32_16x16x32_bf16(Bt[n][k], At[m][k], acc[ai][bj][m][n], 0, 0, 0); __builtin_amdgcn_s_setprio(0); } while (0)
; #define PG8_WAIT_V(n) asm volatile("s_waitcnt vmcnt(" #n ")" ::: "memory")
; #define PG8_WAIT_L(n) asm volatile("s_waitcnt lgkmcnt(" #n ")" ::: "memory")
; #define PG8_BAR __builtin_amdgcn_s_barrier()
; #define PG8_SCHED __builtin_amdgcn_sched_barrier(0)
; template <class Epi, class Sched, bool ALIGN_EPI = false, bool SP2 = false>
; __device__ __forceinline__ void gemm_phase(PG8_LAS unsigned char* lds, const Gemm g, const Sched& S, const Epi& E) {
;     ...
;             PG8_LDB(B0, 1, 0); PG8_LDB(B1, 1, 1); PG8_SCHED; PG8_LDA(At, 1, 0); PG8_STAGE(PG8_SA(0, 1), a2 + hstep, voffA);
;             PG8_WAIT_V(8); PG8_WAIT_L(0); PG8_BAR; PG8_MMA(0, 0, At, B0); PG8_MMA(0, 1, At, B1); PG8_BAR; PG8_SCHED;
;             PG8_LDA(At, 1, 1); PG8_STAGE(PG8_SB(1, 0), b3, voffB); PG8_STAGE(PG8_SB(1, 1), b3 + hstep, voffB); PG8_STAGE(PG8_SA(1, 0), a3, voffA);
;             PG8_WAIT_V(8); PG8_WAIT_L(0); PG8_BAR; PG8_MMA(1, 0, At, B0); PG8_MMA(1, 1, At, B1); PG8_BAR; PG8_SCHED;
	ds_read_b128 v[148:151], v164
	ds_read_b128 v[152:155], v164 offset:1024
	ds_read_b128 v[166:169], v164 offset:2048
	ds_read_b128 v[170:173], v164 offset:3072
	ds_read_b128 v[174:177], v165
	ds_read_b128 v[178:181], v165 offset:1024
	ds_read_b128 v[182:185], v165 offset:2048
	ds_read_b128 v[186:189], v165 offset:3072
	s_add_u32 s54, s56, 0x40000
	s_addc_u32 s55, s57, 0
	s_mov_b32 m0, s68
	v_lshl_add_u64 v[228:229], s[54:55], 0, v[136:137]
	ds_read_b128 v[190:193], v163 offset:32768
	ds_read_b128 v[194:197], v163 offset:33792
	ds_read_b128 v[198:201], v163 offset:34816
	ds_read_b128 v[202:205], v163 offset:35840
	ds_read_b128 v[206:209], v163 offset:36864
	ds_read_b128 v[210:213], v163 offset:37888
	ds_read_b128 v[214:217], v163 offset:38912
	ds_read_b128 v[218:221], v163 offset:39936
	global_load_lds_dwordx4 v[228:229], off
	v_lshl_add_u64 v[228:229], s[54:55], 0, v[132:133]
	s_mov_b32 m0, s69
	s_nop 0
	global_load_lds_dwordx4 v[228:229], off
	s_waitcnt vmcnt(8)
	s_waitcnt lgkmcnt(0)
	s_barrier
	s_setprio 1
	s_waitcnt lgkmcnt(0)
	v_mfma_f32_16x16x32_bf16 v[126:129], v[148:151], v[190:193], v[126:129]
	v_mfma_f32_16x16x32_bf16 v[122:125], v[166:169], v[190:193], v[122:125]
	v_mfma_f32_16x16x32_bf16 v[118:121], v[148:151], v[198:201], v[118:121]
	v_mfma_f32_16x16x32_bf16 v[114:117], v[166:169], v[198:201], v[114:117]
	v_mfma_f32_16x16x32_bf16 v[102:105], v[148:151], v[206:209], v[102:105]
	v_mfma_f32_16x16x32_bf16 v[98:101], v[166:169], v[206:209], v[98:101]
	v_mfma_f32_16x16x32_bf16 v[86:89], v[148:151], v[214:217], v[86:89]
	v_mfma_f32_16x16x32_bf16 v[82:85], v[166:169], v[214:217], v[82:85]
	v_mfma_f32_16x16x32_bf16 v[126:129], v[152:155], v[194:197], v[126:129]
	v_mfma_f32_16x16x32_bf16 v[122:125], v[170:173], v[194:197], v[122:125]
	v_mfma_f32_16x16x32_bf16 v[118:121], v[152:155], v[202:205], v[118:121]
	v_mfma_f32_16x16x32_bf16 v[114:117], v[170:173], v[202:205], v[114:117]
	v_mfma_f32_16x16x32_bf16 v[102:105], v[152:155], v[210:213], v[102:105]
	v_mfma_f32_16x16x32_bf16 v[98:101], v[170:173], v[210:213], v[98:101]
	v_mfma_f32_16x16x32_bf16 v[86:89], v[152:155], v[218:221], v[86:89]
	v_mfma_f32_16x16x32_bf16 v[82:85], v[170:173], v[218:221], v[82:85]
	s_setprio 0
	s_setprio 1
	v_mfma_f32_16x16x32_bf16 v[110:113], v[174:177], v[190:193], v[110:113]
	v_mfma_f32_16x16x32_bf16 v[106:109], v[182:185], v[190:193], v[106:109]
	v_mfma_f32_16x16x32_bf16 v[94:97], v[174:177], v[198:201], v[94:97]
	v_mfma_f32_16x16x32_bf16 v[90:93], v[182:185], v[198:201], v[90:93]
	v_mfma_f32_16x16x32_bf16 v[78:81], v[174:177], v[206:209], v[78:81]
	v_mfma_f32_16x16x32_bf16 v[74:77], v[182:185], v[206:209], v[74:77]
	v_mfma_f32_16x16x32_bf16 v[70:73], v[174:177], v[214:217], v[70:73]
	v_mfma_f32_16x16x32_bf16 v[66:69], v[182:185], v[214:217], v[66:69]
	v_mfma_f32_16x16x32_bf16 v[110:113], v[178:181], v[194:197], v[110:113]
	v_mfma_f32_16x16x32_bf16 v[106:109], v[186:189], v[194:197], v[106:109]
	v_mfma_f32_16x16x32_bf16 v[94:97], v[178:181], v[202:205], v[94:97]
	v_mfma_f32_16x16x32_bf16 v[90:93], v[186:189], v[202:205], v[90:93]
	v_mfma_f32_16x16x32_bf16 v[78:81], v[178:181], v[210:213], v[78:81]
	v_mfma_f32_16x16x32_bf16 v[74:77], v[186:189], v[210:213], v[74:77]
	v_mfma_f32_16x16x32_bf16 v[70:73], v[178:181], v[218:221], v[70:73]
	v_mfma_f32_16x16x32_bf16 v[66:69], v[186:189], v[218:221], v[66:69]
	s_setprio 0
	s_barrier
	s_mov_b32 m0, s70
	v_lshl_add_u64 v[156:157], v[156:157], 0, s[8:9]
	s_add_u32 s52, s52, 0x40080
	ds_read_b128 v[190:193], v163 offset:49152
	ds_read_b128 v[194:197], v163 offset:50176
	ds_read_b128 v[198:201], v163 offset:51200
	ds_read_b128 v[202:205], v163 offset:52224
	ds_read_b128 v[206:209], v163 offset:53248
	ds_read_b128 v[210:213], v163 offset:54272
	ds_read_b128 v[214:217], v163 offset:55296
	ds_read_b128 v[218:221], v163 offset:56320
	global_load_lds_dwordx4 v[156:157], off
	v_lshl_add_u64 v[156:157], v[222:223], 0, s[8:9]
	s_mov_b32 m0, s71
	s_addc_u32 s53, s53, 0
	global_load_lds_dwordx4 v[156:157], off
	v_lshl_add_u64 v[156:157], s[52:53], 0, v[134:135]
	s_mov_b32 m0, s74
	s_nop 0
	global_load_lds_dwordx4 v[156:157], off
	v_lshl_add_u64 v[156:157], s[52:53], 0, v[130:131]
	s_mov_b32 m0, s75
	s_nop 0
	global_load_lds_dwordx4 v[156:157], off
	v_lshl_add_u64 v[156:157], v[224:225], 0, s[8:9]
	s_mov_b32 m0, s72
	s_nop 0
	global_load_lds_dwordx4 v[156:157], off
	v_lshl_add_u64 v[156:157], v[226:227], 0, s[8:9]
	s_mov_b32 m0, s73
	s_nop 0
	global_load_lds_dwordx4 v[156:157], off
	s_waitcnt vmcnt(8)
	s_waitcnt lgkmcnt(0)
	s_barrier
	s_setprio 1
	s_waitcnt lgkmcnt(0)
	v_mfma_f32_16x16x32_bf16 v[62:65], v[148:151], v[190:193], v[62:65]
	v_mfma_f32_16x16x32_bf16 v[58:61], v[166:169], v[190:193], v[58:61]
	v_mfma_f32_16x16x32_bf16 v[54:57], v[148:151], v[198:201], v[54:57]
	v_mfma_f32_16x16x32_bf16 v[50:53], v[166:169], v[198:201], v[50:53]
	v_mfma_f32_16x16x32_bf16 v[38:41], v[148:151], v[206:209], v[38:41]
	v_mfma_f32_16x16x32_bf16 v[34:37], v[166:169], v[206:209], v[34:37]
	v_mfma_f32_16x16x32_bf16 v[22:25], v[148:151], v[214:217], v[22:25]
	v_mfma_f32_16x16x32_bf16 v[18:21], v[166:169], v[214:217], v[18:21]
	v_mfma_f32_16x16x32_bf16 v[62:65], v[152:155], v[194:197], v[62:65]
	v_mfma_f32_16x16x32_bf16 v[58:61], v[170:173], v[194:197], v[58:61]
	v_mfma_f32_16x16x32_bf16 v[54:57], v[152:155], v[202:205], v[54:57]
	v_mfma_f32_16x16x32_bf16 v[50:53], v[170:173], v[202:205], v[50:53]
	v_mfma_f32_16x16x32_bf16 v[38:41], v[152:155], v[210:213], v[38:41]
	v_mfma_f32_16x16x32_bf16 v[34:37], v[170:173], v[210:213], v[34:37]
	v_mfma_f32_16x16x32_bf16 v[22:25], v[152:155], v[218:221], v[22:25]
	v_mfma_f32_16x16x32_bf16 v[18:21], v[170:173], v[218:221], v[18:21]
	s_setprio 0
	s_setprio 1
	v_mfma_f32_16x16x32_bf16 v[46:49], v[174:177], v[190:193], v[46:49]
	v_mfma_f32_16x16x32_bf16 v[42:45], v[182:185], v[190:193], v[42:45]
	v_mfma_f32_16x16x32_bf16 v[30:33], v[174:177], v[198:201], v[30:33]
	v_mfma_f32_16x16x32_bf16 v[26:29], v[182:185], v[198:201], v[26:29]
	v_mfma_f32_16x16x32_bf16 v[14:17], v[174:177], v[206:209], v[14:17]
	v_mfma_f32_16x16x32_bf16 v[10:13], v[182:185], v[206:209], v[10:13]
	v_mfma_f32_16x16x32_bf16 v[6:9], v[174:177], v[214:217], v[6:9]
	v_mfma_f32_16x16x32_bf16 v[2:5], v[182:185], v[214:217], v[2:5]
	v_mfma_f32_16x16x32_bf16 v[46:49], v[178:181], v[194:197], v[46:49]
	v_mfma_f32_16x16x32_bf16 v[42:45], v[186:189], v[194:197], v[42:45]
	v_mfma_f32_16x16x32_bf16 v[30:33], v[178:181], v[202:205], v[30:33]
	v_mfma_f32_16x16x32_bf16 v[26:29], v[186:189], v[202:205], v[26:29]
	v_mfma_f32_16x16x32_bf16 v[14:17], v[178:181], v[210:213], v[14:17]
	v_mfma_f32_16x16x32_bf16 v[10:13], v[186:189], v[210:213], v[10:13]
	v_mfma_f32_16x16x32_bf16 v[6:9], v[178:181], v[218:221], v[6:9]
	v_mfma_f32_16x16x32_bf16 v[2:5], v[186:189], v[218:221], v[2:5]
	s_setprio 0
	s_add_i32 s50, s50, 2
	s_add_u32 s48, s48, 0x100
	s_addc_u32 s49, s49, 0
	s_add_u32 s46, s46, 0x100
	s_addc_u32 s47, s47, 0
	s_cmp_gt_u32 s50, 13
	s_barrier
	s_cbranch_scc0 .LBB0_517
	s_and_b64 vcc, exec, s[10:11]
	s_cbranch_vccz .LBB0_520
	s_barrier

; #define PG8_STAGE(bufoff, gbase, voff) do { _Pragma("unroll") for (int _i = 0; _i < 2; ++_i) \
;         __builtin_amdgcn_global_load_lds((const unsigned*)((const char*)(gbase) + (voff)[_i]), (PG8_LAS unsigned*)(lds + (bufoff) + ldsw + _i * 8192), 16, 0, 0); } while (0)
; #define PG8_LDA(dst, b, h) do { _Pragma("unroll") for (int m = 0; m < 4; ++m) _Pragma("unroll") for (int k = 0; k < 2; ++k) dst[m][k] = *(const PG8_LAS bf16x8*)(lds + PG8_SA(b, h) + aoff + m * 2048 + k * 1024); } while (0)
; #define PG8_LDB(dst, b, h) do { _Pragma("unroll") for (int n = 0; n < 2; ++n) _Pragma("unroll") for (int k = 0; k < 2; ++k) dst[n][k] = *(const PG8_LAS bf16x8*)(lds + PG8_SB(b, h) + boff + n * 2048 + k * 1024); } while (0)
; #define PG8_MMA(ai, bj, At, Bt) do { __builtin_amdgcn_s_setprio(1); _Pragma("unroll") for (int m = 0; m < 4; ++m) _Pragma("unroll") for (int n = 0; n < 2; ++n) _Pragma("unroll") for (int k = 0; k < 2; ++k) \
;         acc[ai][bj][m][n] = __builtin_amdgcn_mfma_f32_16x16x32_bf16(Bt[n][k], At[m][k], acc[ai][bj][m][n], 0, 0, 0); __builtin_amdgcn_s_setprio(0); } while (0)
; template <class Epi, class Sched, bool ALIGN_EPI = false, bool SP2 = false>
; __device__ __forceinline__ void gemm_phase(PG8_LAS unsigned char* lds, const Gemm g, const Sched& S, const Epi& E) {
;     ...
;         const bool has_next = S.next(ui + 1, nxt);
;         const char* nA = has_next ? (const char*)g.A + (size_t)nxt.pm * tstep + (size_t)nxt.ks * K * 2 : cA; const char* nB = has_next ? (const char*)g.Bt + (size_t)nxt.pn * tstep + (size_t)nxt.ks * K * 2 : cB;
;         for (int t = 0; t < nt; t += 2) {
;             const bool last = (t == nt - 2);
;             const char* a1 = cA + (size_t)(t + 1) * kstep;
;             const char* a2 = last ? nA : cA + (size_t)(t + 2) * kstep; const char* b2 = last ? nB : cB + (size_t)(t + 2) * kstep;
;             const char* a3 = a2 + kstep; const char* b3 = b2 + kstep;
;             if (last && has_next) S.a_ready(nxt);
;             if constexpr (SP2) {
;             PG8_LDB(B0, 0, 0); PG8_LDB(B1, 0, 1); PG8_SCHED; PG8_LDA(At, 0, 0); PG8_STAGE(PG8_SA(1, 1), a1 + hstep, voffA);
;             PG8_WAIT_V(8); PG8_WAIT_L(0); PG8_BAR; PG8_MMA(0, 0, At, B0); PG8_MMA(0, 1, At, B1); PG8_BAR; PG8_SCHED;
;             PG8_LDA(At, 0, 1); PG8_STAGE(PG8_SB(0, 0), b2, voffB); PG8_STAGE(PG8_SB(0, 1), b2 + hstep, voffB); PG8_STAGE(PG8_SA(0, 0), a2, voffA);
.LBB0_702:
	s_add_u32 s58, s70, 0x100
	s_addc_u32 s59, s71, 0
	s_add_u32 s70, s72, 0x80
	s_addc_u32 s71, s73, 0
	s_mov_b32 s72, 0
	ds_read_b128 v[152:155], v149
	ds_read_b128 v[156:159], v149 offset:1024
	ds_read_b128 v[160:163], v149 offset:2048
	ds_read_b128 v[164:167], v149 offset:3072
	ds_read_b128 v[168:171], v150
	ds_read_b128 v[172:175], v150 offset:1024
	ds_read_b128 v[176:179], v150 offset:2048
	ds_read_b128 v[180:183], v150 offset:3072
	s_add_i32 vcc_lo, s72, 2
	s_add_u32 s30, s70, 0x80
	s_addc_u32 s31, s71, 0
	s_cmp_eq_u32 s95, s72
	s_cselect_b32 s72, s60, s30
	s_cselect_b32 s73, s61, s31
	s_cselect_b32 s31, s69, s59
	s_cselect_b32 s30, s68, s58
	v_lshl_add_u64 v[142:143], s[70:71], 0, v[140:141]
	s_add_i32 m0, s83, 0xc000
	ds_read_b128 v[184:187], v148
	ds_read_b128 v[188:191], v148 offset:1024
	ds_read_b128 v[192:195], v148 offset:2048
	ds_read_b128 v[196:199], v148 offset:3072
	ds_read_b128 v[200:203], v148 offset:4096
	ds_read_b128 v[204:207], v148 offset:5120
	ds_read_b128 v[208:211], v148 offset:6144
	ds_read_b128 v[212:215], v148 offset:7168
	global_load_lds_dwordx4 v[142:143], off
	v_lshl_add_u64 v[142:143], s[70:71], 0, v[138:139]
	s_add_i32 m0, s83, 0xe000
	s_nop 0
	global_load_lds_dwordx4 v[142:143], off
	s_waitcnt vmcnt(8)
	s_waitcnt lgkmcnt(0)
	s_barrier
	s_setprio 1
	s_waitcnt lgkmcnt(0)
	v_mfma_f32_16x16x32_bf16 v[126:129], v[152:155], v[184:187], 0
	v_mfma_f32_16x16x32_bf16 v[122:125], v[160:163], v[184:187], 0
	v_mfma_f32_16x16x32_bf16 v[118:121], v[152:155], v[192:195], 0
	v_mfma_f32_16x16x32_bf16 v[110:113], v[160:163], v[192:195], 0
	v_mfma_f32_16x16x32_bf16 v[102:105], v[152:155], v[200:203], 0
	v_mfma_f32_16x16x32_bf16 v[94:97], v[160:163], v[200:203], 0
	v_mfma_f32_16x16x32_bf16 v[86:89], v[152:155], v[208:211], 0
	v_mfma_f32_16x16x32_bf16 v[78:81], v[160:163], v[208:211], 0
	v_mfma_f32_16x16x32_bf16 v[126:129], v[156:159], v[188:191], v[126:129]
	v_mfma_f32_16x16x32_bf16 v[122:125], v[164:167], v[188:191], v[122:125]
	v_mfma_f32_16x16x32_bf16 v[118:121], v[156:159], v[196:199], v[118:121]
	v_mfma_f32_16x16x32_bf16 v[110:113], v[164:167], v[196:199], v[110:113]
	v_mfma_f32_16x16x32_bf16 v[102:105], v[156:159], v[204:207], v[102:105]
	v_mfma_f32_16x16x32_bf16 v[94:97], v[164:167], v[204:207], v[94:97]
	v_mfma_f32_16x16x32_bf16 v[86:89], v[156:159], v[212:215], v[86:89]
	v_mfma_f32_16x16x32_bf16 v[78:81], v[164:167], v[212:215], v[78:81]
	s_setprio 0
	s_setprio 1
	v_mfma_f32_16x16x32_bf16 v[114:117], v[168:171], v[184:187], 0
	v_mfma_f32_16x16x32_bf16 v[106:109], v[176:179], v[184:187], 0
	v_mfma_f32_16x16x32_bf16 v[98:101], v[168:171], v[192:195], 0
	v_mfma_f32_16x16x32_bf16 v[90:93], v[176:179], v[192:195], 0
	v_mfma_f32_16x16x32_bf16 v[82:85], v[168:171], v[200:203], 0
	v_mfma_f32_16x16x32_bf16 v[74:77], v[176:179], v[200:203], 0
	v_mfma_f32_16x16x32_bf16 v[70:73], v[168:171], v[208:211], 0
	v_mfma_f32_16x16x32_bf16 v[66:69], v[176:179], v[208:211], 0
	v_mfma_f32_16x16x32_bf16 v[114:117], v[172:175], v[188:191], v[114:117]
	v_mfma_f32_16x16x32_bf16 v[106:109], v[180:183], v[188:191], v[106:109]
	v_mfma_f32_16x16x32_bf16 v[98:101], v[172:175], v[196:199], v[98:101]
	v_mfma_f32_16x16x32_bf16 v[90:93], v[180:183], v[196:199], v[90:93]
	v_mfma_f32_16x16x32_bf16 v[82:85], v[172:175], v[204:207], v[82:85]
	v_mfma_f32_16x16x32_bf16 v[74:77], v[180:183], v[204:207], v[74:77]
	v_mfma_f32_16x16x32_bf16 v[70:73], v[172:175], v[212:215], v[70:73]
	v_mfma_f32_16x16x32_bf16 v[66:69], v[180:183], v[212:215], v[66:69]
	s_setprio 0
	s_barrier
	s_mov_b32 m0, s79
	v_lshl_add_u64 v[142:143], s[30:31], 0, v[130:131]
	v_lshl_add_u64 v[216:217], s[30:31], 0, v[136:137]
	s_add_u32 s30, s30, s0
	ds_read_b128 v[184:187], v148 offset:16384
	ds_read_b128 v[188:191], v148 offset:17408
	ds_read_b128 v[192:195], v148 offset:18432
	ds_read_b128 v[196:199], v148 offset:19456
	ds_read_b128 v[200:203], v148 offset:20480
	ds_read_b128 v[204:207], v148 offset:21504
	ds_read_b128 v[208:211], v148 offset:22528
	ds_read_b128 v[212:215], v148 offset:23552
	global_load_lds_dwordx4 v[142:143], off
	s_mov_b32 m0, s80
	s_addc_u32 s31, s31, 0
	global_load_lds_dwordx4 v[216:217], off
	v_lshl_add_u64 v[218:219], s[30:31], 0, v[130:131]
	s_mov_b32 m0, s81
	v_lshl_add_u64 v[220:221], s[30:31], 0, v[136:137]
	global_load_lds_dwordx4 v[218:219], off
	s_mov_b32 m0, s82
	v_lshl_add_u64 v[222:223], s[72:73], 0, v[132:133]
	global_load_lds_dwordx4 v[220:221], off
	s_mov_b32 m0, s83
	v_lshl_add_u64 v[224:225], s[72:73], 0, v[134:135]
	global_load_lds_dwordx4 v[222:223], off
	s_mov_b32 m0, s84
	s_nop 0
	global_load_lds_dwordx4 v[224:225], off
	s_waitcnt vmcnt(8)
	s_waitcnt lgkmcnt(0)
	s_barrier
; #define PG8_STAGE(bufoff, gbase, voff) do { _Pragma("unroll") for (int _i = 0; _i < 2; ++_i) \
;         __builtin_amdgcn_global_load_lds((const unsigned*)((const char*)(gbase) + (voff)[_i]), (PG8_LAS unsigned*)(lds + (bufoff) + ldsw + _i * 8192), 16, 0, 0); } while (0)
; #define PG8_LDA(dst, b, h) do { _Pragma("unroll") for (int m = 0; m < 4; ++m) _Pragma("unroll") for (int k = 0; k < 2; ++k) dst[m][k] = *(const PG8_LAS bf16x8*)(lds + PG8_SA(b, h) + aoff + m * 2048 + k * 1024); } while (0)
; #define PG8_LDB(dst, b, h) do { _Pragma("unroll") for (int n = 0; n < 2; ++n) _Pragma("unroll") for (int k = 0; k < 2; ++k) dst[n][k] = *(const PG8_LAS bf16x8*)(lds + PG8_SB(b, h) + boff + n * 2048 + k * 1024); } while (0)
; #define PG8_MMA(ai, bj, At, Bt) do { __builtin_amdgcn_s_setprio(1); _Pragma("unroll") for (int m = 0; m < 4; ++m) _Pragma("unroll") for (int n = 0; n < 2; ++n) _Pragma("unroll") for (int k = 0; k < 2; ++k) \
;         acc[ai][bj][m][n] = __builtin_amdgcn_mfma_f32_16x16x32_bf16(Bt[n][k], At[m][k], acc[ai][bj][m][n], 0, 0, 0); __builtin_amdgcn_s_setprio(0); } while (0)
; #define PG8_WAIT_V(n) asm volatile("s_waitcnt vmcnt(" #n ")" ::: "memory")
; #define PG8_WAIT_L(n) asm volatile("s_waitcnt lgkmcnt(" #n ")" ::: "memory")
; #define PG8_BAR __builtin_amdgcn_s_barrier()
; #define PG8_SCHED __builtin_amdgcn_sched_barrier(0)
; template <class Epi, class Sched, bool ALIGN_EPI = false, bool SP2 = false>
; __device__ __forceinline__ void gemm_phase(PG8_LAS unsigned char* lds, const Gemm g, const Sched& S, const Epi& E) {
;     ...
;             PG8_WAIT_V(8); PG8_WAIT_L(0); PG8_BAR; PG8_MMA(1, 0, At, B0); PG8_MMA(1, 1, At, B1); PG8_BAR; PG8_SCHED;
;             PG8_LDB(B0, 1, 0); PG8_LDB(B1, 1, 1); PG8_SCHED; PG8_LDA(At, 1, 0); PG8_STAGE(PG8_SA(0, 1), a2 + hstep, voffA);
;             PG8_WAIT_V(8); PG8_WAIT_L(0); PG8_BAR; PG8_MMA(0, 0, At, B0); PG8_MMA(0, 1, At, B1); PG8_BAR; PG8_SCHED;
	s_setprio 1
	s_waitcnt lgkmcnt(0)
	v_mfma_f32_16x16x32_bf16 v[62:65], v[152:155], v[184:187], 0
	v_mfma_f32_16x16x32_bf16 v[58:61], v[160:163], v[184:187], 0
	v_mfma_f32_16x16x32_bf16 v[54:57], v[152:155], v[192:195], 0
	v_mfma_f32_16x16x32_bf16 v[46:49], v[160:163], v[192:195], 0
	v_mfma_f32_16x16x32_bf16 v[38:41], v[152:155], v[200:203], 0
	v_mfma_f32_16x16x32_bf16 v[30:33], v[160:163], v[200:203], 0
	v_mfma_f32_16x16x32_bf16 v[22:25], v[152:155], v[208:211], 0
	v_mfma_f32_16x16x32_bf16 v[14:17], v[160:163], v[208:211], 0
	v_mfma_f32_16x16x32_bf16 v[62:65], v[156:159], v[188:191], v[62:65]
	v_mfma_f32_16x16x32_bf16 v[58:61], v[164:167], v[188:191], v[58:61]
	v_mfma_f32_16x16x32_bf16 v[54:57], v[156:159], v[196:199], v[54:57]
	v_mfma_f32_16x16x32_bf16 v[46:49], v[164:167], v[196:199], v[46:49]
	v_mfma_f32_16x16x32_bf16 v[38:41], v[156:159], v[204:207], v[38:41]
	v_mfma_f32_16x16x32_bf16 v[30:33], v[164:167], v[204:207], v[30:33]
	v_mfma_f32_16x16x32_bf16 v[22:25], v[156:159], v[212:215], v[22:25]
	v_mfma_f32_16x16x32_bf16 v[14:17], v[164:167], v[212:215], v[14:17]
	s_setprio 0
	s_setprio 1
	v_mfma_f32_16x16x32_bf16 v[50:53], v[168:171], v[184:187], 0
	v_mfma_f32_16x16x32_bf16 v[42:45], v[176:179], v[184:187], 0
	v_mfma_f32_16x16x32_bf16 v[34:37], v[168:171], v[192:195], 0
	v_mfma_f32_16x16x32_bf16 v[26:29], v[176:179], v[192:195], 0
	v_mfma_f32_16x16x32_bf16 v[18:21], v[168:171], v[200:203], 0
	v_mfma_f32_16x16x32_bf16 v[10:13], v[176:179], v[200:203], 0
	v_mfma_f32_16x16x32_bf16 v[6:9], v[168:171], v[208:211], 0
	v_mfma_f32_16x16x32_bf16 v[2:5], v[176:179], v[208:211], 0
	v_mfma_f32_16x16x32_bf16 v[50:53], v[172:175], v[188:191], v[50:53]
	v_mfma_f32_16x16x32_bf16 v[42:45], v[180:183], v[188:191], v[42:45]
	v_mfma_f32_16x16x32_bf16 v[34:37], v[172:175], v[196:199], v[34:37]
	v_mfma_f32_16x16x32_bf16 v[26:29], v[180:183], v[196:199], v[26:29]
	v_mfma_f32_16x16x32_bf16 v[18:21], v[172:175], v[204:207], v[18:21]
	v_mfma_f32_16x16x32_bf16 v[10:13], v[180:183], v[204:207], v[10:13]
	v_mfma_f32_16x16x32_bf16 v[6:9], v[172:175], v[212:215], v[6:9]
	v_mfma_f32_16x16x32_bf16 v[2:5], v[180:183], v[212:215], v[2:5]
	s_setprio 0
	s_barrier
	v_add_u32_e32 v180, s66, v146
	ds_read_b128 v[152:155], v151
	ds_read_b128 v[156:159], v151 offset:1024
	ds_read_b128 v[160:163], v151 offset:2048
	ds_read_b128 v[164:167], v151 offset:3072
	ds_read_b128 v[168:171], v180
	ds_read_b128 v[172:175], v180 offset:1024
	ds_read_b128 v[176:179], v180 offset:2048
	ds_read_b128 v[180:183], v180 offset:3072
	s_add_u32 s30, s72, s0
	s_addc_u32 s31, s73, 0
	s_mov_b32 m0, s85
	v_lshl_add_u64 v[226:227], s[30:31], 0, v[132:133]
	ds_read_b128 v[184:187], v148 offset:32768
	ds_read_b128 v[188:191], v148 offset:33792
	ds_read_b128 v[192:195], v148 offset:34816
	ds_read_b128 v[196:199], v148 offset:35840
	ds_read_b128 v[200:203], v148 offset:36864
	ds_read_b128 v[204:207], v148 offset:37888
	ds_read_b128 v[208:211], v148 offset:38912
	ds_read_b128 v[212:215], v148 offset:39936
	global_load_lds_dwordx4 v[226:227], off
	v_lshl_add_u64 v[226:227], s[30:31], 0, v[134:135]
	s_mov_b32 m0, s86
	s_nop 0
	global_load_lds_dwordx4 v[226:227], off
	s_waitcnt vmcnt(8)
	s_waitcnt lgkmcnt(0)
	s_barrier
	s_setprio 1
	s_waitcnt lgkmcnt(0)
	v_mfma_f32_16x16x32_bf16 v[126:129], v[152:155], v[184:187], v[126:129]
	v_mfma_f32_16x16x32_bf16 v[122:125], v[160:163], v[184:187], v[122:125]
	v_mfma_f32_16x16x32_bf16 v[118:121], v[152:155], v[192:195], v[118:121]
	v_mfma_f32_16x16x32_bf16 v[110:113], v[160:163], v[192:195], v[110:113]
	v_mfma_f32_16x16x32_bf16 v[102:105], v[152:155], v[200:203], v[102:105]
	v_mfma_f32_16x16x32_bf16 v[94:97], v[160:163], v[200:203], v[94:97]
	v_mfma_f32_16x16x32_bf16 v[86:89], v[152:155], v[208:211], v[86:89]
	v_mfma_f32_16x16x32_bf16 v[78:81], v[160:163], v[208:211], v[78:81]
	v_mfma_f32_16x16x32_bf16 v[126:129], v[156:159], v[188:191], v[126:129]
	v_mfma_f32_16x16x32_bf16 v[122:125], v[164:167], v[188:191], v[122:125]
	v_mfma_f32_16x16x32_bf16 v[118:121], v[156:159], v[196:199], v[118:121]
	v_mfma_f32_16x16x32_bf16 v[110:113], v[164:167], v[196:199], v[110:113]
	v_mfma_f32_16x16x32_bf16 v[102:105], v[156:159], v[204:207], v[102:105]
	v_mfma_f32_16x16x32_bf16 v[94:97], v[164:167], v[204:207], v[94:97]
	v_mfma_f32_16x16x32_bf16 v[86:89], v[156:159], v[212:215], v[86:89]
	v_mfma_f32_16x16x32_bf16 v[78:81], v[164:167], v[212:215], v[78:81]
	s_setprio 0
	s_setprio 1
	v_mfma_f32_16x16x32_bf16 v[114:117], v[168:171], v[184:187], v[114:117]
	v_mfma_f32_16x16x32_bf16 v[106:109], v[176:179], v[184:187], v[106:109]
	v_mfma_f32_16x16x32_bf16 v[98:101], v[168:171], v[192:195], v[98:101]
	v_mfma_f32_16x16x32_bf16 v[90:93], v[176:179], v[192:195], v[90:93]
	v_mfma_f32_16x16x32_bf16 v[82:85], v[168:171], v[200:203], v[82:85]
	v_mfma_f32_16x16x32_bf16 v[74:77], v[176:179], v[200:203], v[74:77]
	v_mfma_f32_16x16x32_bf16 v[70:73], v[168:171], v[208:211], v[70:73]
	v_mfma_f32_16x16x32_bf16 v[66:69], v[176:179], v[208:211], v[66:69]
	v_mfma_f32_16x16x32_bf16 v[114:117], v[172:175], v[188:191], v[114:117]
	v_mfma_f32_16x16x32_bf16 v[106:109], v[180:183], v[188:191], v[106:109]
	v_mfma_f32_16x16x32_bf16 v[98:101], v[172:175], v[196:199], v[98:101]
	v_mfma_f32_16x16x32_bf16 v[90:93], v[180:183], v[196:199], v[90:93]
	v_mfma_f32_16x16x32_bf16 v[82:85], v[172:175], v[204:207], v[82:85]
	v_mfma_f32_16x16x32_bf16 v[74:77], v[180:183], v[204:207], v[74:77]
	v_mfma_f32_16x16x32_bf16 v[70:73], v[172:175], v[212:215], v[70:73]
	v_mfma_f32_16x16x32_bf16 v[66:69], v[180:183], v[212:215], v[66:69]
	s_setprio 0
	s_barrier
; #define PG8_STAGE(bufoff, gbase, voff) do { _Pragma("unroll") for (int _i = 0; _i < 2; ++_i) \
;         __builtin_amdgcn_global_load_lds((const unsigned*)((const char*)(gbase) + (voff)[_i]), (PG8_LAS unsigned*)(lds + (bufoff) + ldsw + _i * 8192), 16, 0, 0); } while (0)
; #define PG8_LDA(dst, b, h) do { _Pragma("unroll") for (int m = 0; m < 4; ++m) _Pragma("unroll") for (int k = 0; k < 2; ++k) dst[m][k] = *(const PG8_LAS bf16x8*)(lds + PG8_SA(b, h) + aoff + m * 2048 + k * 1024); } while (0)
; #define PG8_LDB(dst, b, h) do { _Pragma("unroll") for (int n = 0; n < 2; ++n) _Pragma("unroll") for (int k = 0; k < 2; ++k) dst[n][k] = *(const PG8_LAS bf16x8*)(lds + PG8_SB(b, h) + boff + n * 2048 + k * 1024); } while (0)
; #define PG8_MMA(ai, bj, At, Bt) do { __builtin_amdgcn_s_setprio(1); _Pragma("unroll") for (int m = 0; m < 4; ++m) _Pragma("unroll") for (int n = 0; n < 2; ++n) _Pragma("unroll") for (int k = 0; k < 2; ++k) \
;         acc[ai][bj][m][n] = __builtin_amdgcn_mfma_f32_16x16x32_bf16(Bt[n][k], At[m][k], acc[ai][bj][m][n], 0, 0, 0); __builtin_amdgcn_s_setprio(0); } while (0)
; #define PG8_WAIT_V(n) asm volatile("s_waitcnt vmcnt(" #n ")" ::: "memory")
; #define PG8_BAR __builtin_amdgcn_s_barrier()
; template <class Epi, class Sched, bool ALIGN_EPI = false, bool SP2 = false>
; __device__ __forceinline__ void gemm_phase(PG8_LAS unsigned char* lds, const Gemm g, const Sched& S, const Epi& E) {
;     ...
;         for (int t = 0; t < nt; t += 2) {
;             const bool last = (t == nt - 2);
;             const char* a1 = cA + (size_t)(t + 1) * kstep;
;             const char* a2 = last ? nA : cA + (size_t)(t + 2) * kstep; const char* b2 = last ? nB : cB + (size_t)(t + 2) * kstep;
;             const char* a3 = a2 + kstep; const char* b3 = b2 + kstep;
;             if (last && has_next) S.a_ready(nxt);
;             if constexpr (SP2) {
;             PG8_LDB(B0, 0, 0); PG8_LDB(B1, 0, 1); PG8_SCHED; PG8_LDA(At, 0, 0); PG8_STAGE(PG8_SA(1, 1), a1 + hstep, voffA);
;             PG8_WAIT_V(8); PG8_WAIT_L(0); PG8_BAR; PG8_MMA(0, 0, At, B0); PG8_MMA(0, 1, At, B1); PG8_BAR; PG8_SCHED;
;     ...
;             PG8_LDA(At, 1, 1); PG8_STAGE(PG8_SB(1, 0), b3, voffB); PG8_STAGE(PG8_SB(1, 1), b3 + hstep, voffB); PG8_STAGE(PG8_SA(1, 0), a3, voffA);
;             PG8_WAIT_V(8); PG8_WAIT_L(0); PG8_BAR; PG8_MMA(1, 0, At, B0); PG8_MMA(1, 1, At, B1); PG8_BAR; PG8_SCHED;
	s_mov_b32 m0, s88
	v_lshl_add_u64 v[142:143], v[142:143], 0, s[18:19]
	ds_read_b128 v[184:187], v148 offset:49152
	ds_read_b128 v[188:191], v148 offset:50176
	ds_read_b128 v[192:195], v148 offset:51200
	ds_read_b128 v[196:199], v148 offset:52224
	ds_read_b128 v[200:203], v148 offset:53248
	ds_read_b128 v[204:207], v148 offset:54272
	ds_read_b128 v[208:211], v148 offset:55296
	ds_read_b128 v[212:215], v148 offset:56320
	global_load_lds_dwordx4 v[142:143], off
	v_lshl_add_u64 v[142:143], v[216:217], 0, s[18:19]
	s_mov_b32 m0, s89
	s_nop 0
	global_load_lds_dwordx4 v[142:143], off
	v_lshl_add_u64 v[142:143], v[218:219], 0, s[18:19]
	s_mov_b32 m0, s92
	s_nop 0
	global_load_lds_dwordx4 v[142:143], off
	v_lshl_add_u64 v[142:143], v[220:221], 0, s[18:19]
	s_mov_b32 m0, s93
	s_nop 0
	global_load_lds_dwordx4 v[142:143], off
	v_lshl_add_u64 v[142:143], v[222:223], 0, s[18:19]
	s_mov_b32 m0, s90
	s_nop 0
	global_load_lds_dwordx4 v[142:143], off
	v_lshl_add_u64 v[142:143], v[224:225], 0, s[18:19]
	s_mov_b32 m0, s91
	s_nop 0
	global_load_lds_dwordx4 v[142:143], off
	s_waitcnt vmcnt(8)
	s_waitcnt lgkmcnt(0)
	s_barrier
	s_setprio 1
	s_waitcnt lgkmcnt(0)
	v_mfma_f32_16x16x32_bf16 v[62:65], v[152:155], v[184:187], v[62:65]
	v_mfma_f32_16x16x32_bf16 v[58:61], v[160:163], v[184:187], v[58:61]
	v_mfma_f32_16x16x32_bf16 v[54:57], v[152:155], v[192:195], v[54:57]
	v_mfma_f32_16x16x32_bf16 v[46:49], v[160:163], v[192:195], v[46:49]
	v_mfma_f32_16x16x32_bf16 v[38:41], v[152:155], v[200:203], v[38:41]
	v_mfma_f32_16x16x32_bf16 v[30:33], v[160:163], v[200:203], v[30:33]
	v_mfma_f32_16x16x32_bf16 v[22:25], v[152:155], v[208:211], v[22:25]
	v_mfma_f32_16x16x32_bf16 v[14:17], v[160:163], v[208:211], v[14:17]
	v_mfma_f32_16x16x32_bf16 v[62:65], v[156:159], v[188:191], v[62:65]
	v_mfma_f32_16x16x32_bf16 v[58:61], v[164:167], v[188:191], v[58:61]
	v_mfma_f32_16x16x32_bf16 v[54:57], v[156:159], v[196:199], v[54:57]
	v_mfma_f32_16x16x32_bf16 v[46:49], v[164:167], v[196:199], v[46:49]
	v_mfma_f32_16x16x32_bf16 v[38:41], v[156:159], v[204:207], v[38:41]
	v_mfma_f32_16x16x32_bf16 v[30:33], v[164:167], v[204:207], v[30:33]
	v_mfma_f32_16x16x32_bf16 v[22:25], v[156:159], v[212:215], v[22:25]
	v_mfma_f32_16x16x32_bf16 v[14:17], v[164:167], v[212:215], v[14:17]
	s_setprio 0
	s_setprio 1
	v_mfma_f32_16x16x32_bf16 v[50:53], v[168:171], v[184:187], v[50:53]
	v_mfma_f32_16x16x32_bf16 v[42:45], v[176:179], v[184:187], v[42:45]
	v_mfma_f32_16x16x32_bf16 v[34:37], v[168:171], v[192:195], v[34:37]
	v_mfma_f32_16x16x32_bf16 v[26:29], v[176:179], v[192:195], v[26:29]
	v_mfma_f32_16x16x32_bf16 v[18:21], v[168:171], v[200:203], v[18:21]
	v_mfma_f32_16x16x32_bf16 v[10:13], v[176:179], v[200:203], v[10:13]
	v_mfma_f32_16x16x32_bf16 v[6:9], v[168:171], v[208:211], v[6:9]
	v_mfma_f32_16x16x32_bf16 v[2:5], v[176:179], v[208:211], v[2:5]
	v_mfma_f32_16x16x32_bf16 v[50:53], v[172:175], v[188:191], v[50:53]
	v_mfma_f32_16x16x32_bf16 v[42:45], v[180:183], v[188:191], v[42:45]
	v_mfma_f32_16x16x32_bf16 v[34:37], v[172:175], v[196:199], v[34:37]
	v_mfma_f32_16x16x32_bf16 v[26:29], v[180:183], v[196:199], v[26:29]
	v_mfma_f32_16x16x32_bf16 v[18:21], v[172:175], v[204:207], v[18:21]
	v_mfma_f32_16x16x32_bf16 v[10:13], v[180:183], v[204:207], v[10:13]
	v_mfma_f32_16x16x32_bf16 v[6:9], v[172:175], v[212:215], v[6:9]
	v_mfma_f32_16x16x32_bf16 v[2:5], v[180:183], v[212:215], v[2:5]
	s_setprio 0
	s_add_u32 s58, s58, 0x100
	s_addc_u32 s59, s59, 0
	s_add_u32 s70, s70, 0x100
	s_addc_u32 s71, s71, 0
	s_cmp_ge_u32 vcc_lo, s87
	s_mov_b32 s72, vcc_lo
	s_barrier
.LBB0_703:
	ds_read_b128 v[152:155], v149
	ds_read_b128 v[156:159], v149 offset:1024
	ds_read_b128 v[160:163], v149 offset:2048
	ds_read_b128 v[164:167], v149 offset:3072
	ds_read_b128 v[168:171], v150
	ds_read_b128 v[172:175], v150 offset:1024
	ds_read_b128 v[176:179], v150 offset:2048
	ds_read_b128 v[180:183], v150 offset:3072
	s_add_i32 vcc_lo, s72, 2
	s_add_u32 s30, s70, 0x80
	s_addc_u32 s31, s71, 0
	s_cmp_eq_u32 s95, s72
	s_cselect_b32 s72, s60, s30
	s_cselect_b32 s73, s61, s31
	s_cselect_b32 s31, s69, s59
	s_cselect_b32 s30, s68, s58
	v_lshl_add_u64 v[142:143], s[70:71], 0, v[140:141]
	s_add_i32 m0, s83, 0xc000
	ds_read_b128 v[184:187], v148
	ds_read_b128 v[188:191], v148 offset:1024
	ds_read_b128 v[192:195], v148 offset:2048
	ds_read_b128 v[196:199], v148 offset:3072
	ds_read_b128 v[200:203], v148 offset:4096
	ds_read_b128 v[204:207], v148 offset:5120
	ds_read_b128 v[208:211], v148 offset:6144
	ds_read_b128 v[212:215], v148 offset:7168
	global_load_lds_dwordx4 v[142:143], off
	v_lshl_add_u64 v[142:143], s[70:71], 0, v[138:139]
	s_add_i32 m0, s83, 0xe000
	s_nop 0
	global_load_lds_dwordx4 v[142:143], off
	s_waitcnt vmcnt(8)
	s_waitcnt lgkmcnt(0)
	s_barrier
; #define PG8_STAGE(bufoff, gbase, voff) do { _Pragma("unroll") for (int _i = 0; _i < 2; ++_i) \
;         __builtin_amdgcn_global_load_lds((const unsigned*)((const char*)(gbase) + (voff)[_i]), (PG8_LAS unsigned*)(lds + (bufoff) + ldsw + _i * 8192), 16, 0, 0); } while (0)
; #define PG8_LDA(dst, b, h) do { _Pragma("unroll") for (int m = 0; m < 4; ++m) _Pragma("unroll") for (int k = 0; k < 2; ++k) dst[m][k] = *(const PG8_LAS bf16x8*)(lds + PG8_SA(b, h) + aoff + m * 2048 + k * 1024); } while (0)
; #define PG8_LDB(dst, b, h) do { _Pragma("unroll") for (int n = 0; n < 2; ++n) _Pragma("unroll") for (int k = 0; k < 2; ++k) dst[n][k] = *(const PG8_LAS bf16x8*)(lds + PG8_SB(b, h) + boff + n * 2048 + k * 1024); } while (0)
; #define PG8_MMA(ai, bj, At, Bt) do { __builtin_amdgcn_s_setprio(1); _Pragma("unroll") for (int m = 0; m < 4; ++m) _Pragma("unroll") for (int n = 0; n < 2; ++n) _Pragma("unroll") for (int k = 0; k < 2; ++k) \
;         acc[ai][bj][m][n] = __builtin_amdgcn_mfma_f32_16x16x32_bf16(Bt[n][k], At[m][k], acc[ai][bj][m][n], 0, 0, 0); __builtin_amdgcn_s_setprio(0); } while (0)
; #define PG8_WAIT_V(n) asm volatile("s_waitcnt vmcnt(" #n ")" ::: "memory")
; #define PG8_WAIT_L(n) asm volatile("s_waitcnt lgkmcnt(" #n ")" ::: "memory")
; #define PG8_BAR __builtin_amdgcn_s_barrier()
; #define PG8_SCHED __builtin_amdgcn_sched_barrier(0)
; template <class Epi, class Sched, bool ALIGN_EPI = false, bool SP2 = false>
; __device__ __forceinline__ void gemm_phase(PG8_LAS unsigned char* lds, const Gemm g, const Sched& S, const Epi& E) {
;     ...
;             PG8_LDB(B0, 0, 0); PG8_LDB(B1, 0, 1); PG8_SCHED; PG8_LDA(At, 0, 0); PG8_STAGE(PG8_SA(1, 1), a1 + hstep, voffA);
;             PG8_WAIT_V(8); PG8_WAIT_L(0); PG8_BAR; PG8_MMA(0, 0, At, B0); PG8_MMA(0, 1, At, B1); PG8_BAR; PG8_SCHED;
;             PG8_LDA(At, 0, 1); PG8_STAGE(PG8_SB(0, 0), b2, voffB); PG8_STAGE(PG8_SB(0, 1), b2 + hstep, voffB); PG8_STAGE(PG8_SA(0, 0), a2, voffA);
;             PG8_WAIT_V(8); PG8_WAIT_L(0); PG8_BAR; PG8_MMA(1, 0, At, B0); PG8_MMA(1, 1, At, B1); PG8_BAR; PG8_SCHED;
	s_setprio 1
	s_waitcnt lgkmcnt(0)
	v_mfma_f32_16x16x32_bf16 v[126:129], v[152:155], v[184:187], v[126:129]
	v_mfma_f32_16x16x32_bf16 v[122:125], v[160:163], v[184:187], v[122:125]
	v_mfma_f32_16x16x32_bf16 v[118:121], v[152:155], v[192:195], v[118:121]
	v_mfma_f32_16x16x32_bf16 v[110:113], v[160:163], v[192:195], v[110:113]
	v_mfma_f32_16x16x32_bf16 v[102:105], v[152:155], v[200:203], v[102:105]
	v_mfma_f32_16x16x32_bf16 v[94:97], v[160:163], v[200:203], v[94:97]
	v_mfma_f32_16x16x32_bf16 v[86:89], v[152:155], v[208:211], v[86:89]
	v_mfma_f32_16x16x32_bf16 v[78:81], v[160:163], v[208:211], v[78:81]
	v_mfma_f32_16x16x32_bf16 v[126:129], v[156:159], v[188:191], v[126:129]
	v_mfma_f32_16x16x32_bf16 v[122:125], v[164:167], v[188:191], v[122:125]
	v_mfma_f32_16x16x32_bf16 v[118:121], v[156:159], v[196:199], v[118:121]
	v_mfma_f32_16x16x32_bf16 v[110:113], v[164:167], v[196:199], v[110:113]
	v_mfma_f32_16x16x32_bf16 v[102:105], v[156:159], v[204:207], v[102:105]
	v_mfma_f32_16x16x32_bf16 v[94:97], v[164:167], v[204:207], v[94:97]
	v_mfma_f32_16x16x32_bf16 v[86:89], v[156:159], v[212:215], v[86:89]
	v_mfma_f32_16x16x32_bf16 v[78:81], v[164:167], v[212:215], v[78:81]
	s_setprio 0
	s_setprio 1
	v_mfma_f32_16x16x32_bf16 v[114:117], v[168:171], v[184:187], v[114:117]
	v_mfma_f32_16x16x32_bf16 v[106:109], v[176:179], v[184:187], v[106:109]
	v_mfma_f32_16x16x32_bf16 v[98:101], v[168:171], v[192:195], v[98:101]
	v_mfma_f32_16x16x32_bf16 v[90:93], v[176:179], v[192:195], v[90:93]
	v_mfma_f32_16x16x32_bf16 v[82:85], v[168:171], v[200:203], v[82:85]
	v_mfma_f32_16x16x32_bf16 v[74:77], v[176:179], v[200:203], v[74:77]
	v_mfma_f32_16x16x32_bf16 v[70:73], v[168:171], v[208:211], v[70:73]
	v_mfma_f32_16x16x32_bf16 v[66:69], v[176:179], v[208:211], v[66:69]
	v_mfma_f32_16x16x32_bf16 v[114:117], v[172:175], v[188:191], v[114:117]
	v_mfma_f32_16x16x32_bf16 v[106:109], v[180:183], v[188:191], v[106:109]
	v_mfma_f32_16x16x32_bf16 v[98:101], v[172:175], v[196:199], v[98:101]
	v_mfma_f32_16x16x32_bf16 v[90:93], v[180:183], v[196:199], v[90:93]
	v_mfma_f32_16x16x32_bf16 v[82:85], v[172:175], v[204:207], v[82:85]
	v_mfma_f32_16x16x32_bf16 v[74:77], v[180:183], v[204:207], v[74:77]
	v_mfma_f32_16x16x32_bf16 v[70:73], v[172:175], v[212:215], v[70:73]
	v_mfma_f32_16x16x32_bf16 v[66:69], v[180:183], v[212:215], v[66:69]
	s_setprio 0
	s_barrier
	s_mov_b32 m0, s79
	v_lshl_add_u64 v[142:143], s[30:31], 0, v[130:131]
	v_lshl_add_u64 v[216:217], s[30:31], 0, v[136:137]
	s_add_u32 s30, s30, s0
	ds_read_b128 v[184:187], v148 offset:16384
	ds_read_b128 v[188:191], v148 offset:17408
	ds_read_b128 v[192:195], v148 offset:18432
	ds_read_b128 v[196:199], v148 offset:19456
	ds_read_b128 v[200:203], v148 offset:20480
	ds_read_b128 v[204:207], v148 offset:21504
	ds_read_b128 v[208:211], v148 offset:22528
	ds_read_b128 v[212:215], v148 offset:23552
	global_load_lds_dwordx4 v[142:143], off
	s_mov_b32 m0, s80
	s_addc_u32 s31, s31, 0
	global_load_lds_dwordx4 v[216:217], off
	v_lshl_add_u64 v[218:219], s[30:31], 0, v[130:131]
	s_mov_b32 m0, s81
	v_lshl_add_u64 v[220:221], s[30:31], 0, v[136:137]
	global_load_lds_dwordx4 v[218:219], off
	s_mov_b32 m0, s82
	v_lshl_add_u64 v[222:223], s[72:73], 0, v[132:133]
	global_load_lds_dwordx4 v[220:221], off
	s_mov_b32 m0, s83
	v_lshl_add_u64 v[224:225], s[72:73], 0, v[134:135]
	global_load_lds_dwordx4 v[222:223], off
	s_mov_b32 m0, s84
	s_nop 0
	global_load_lds_dwordx4 v[224:225], off
	s_waitcnt vmcnt(8)
	s_waitcnt lgkmcnt(0)
	s_barrier
	s_setprio 1
	s_waitcnt lgkmcnt(0)
	v_mfma_f32_16x16x32_bf16 v[62:65], v[152:155], v[184:187], v[62:65]
	v_mfma_f32_16x16x32_bf16 v[58:61], v[160:163], v[184:187], v[58:61]
	v_mfma_f32_16x16x32_bf16 v[54:57], v[152:155], v[192:195], v[54:57]
	v_mfma_f32_16x16x32_bf16 v[46:49], v[160:163], v[192:195], v[46:49]
	v_mfma_f32_16x16x32_bf16 v[38:41], v[152:155], v[200:203], v[38:41]
	v_mfma_f32_16x16x32_bf16 v[30:33], v[160:163], v[200:203], v[30:33]
	v_mfma_f32_16x16x32_bf16 v[22:25], v[152:155], v[208:211], v[22:25]
	v_mfma_f32_16x16x32_bf16 v[14:17], v[160:163], v[208:211], v[14:17]
	v_mfma_f32_16x16x32_bf16 v[62:65], v[156:159], v[188:191], v[62:65]
	v_mfma_f32_16x16x32_bf16 v[58:61], v[164:167], v[188:191], v[58:61]
	v_mfma_f32_16x16x32_bf16 v[54:57], v[156:159], v[196:199], v[54:57]
	v_mfma_f32_16x16x32_bf16 v[46:49], v[164:167], v[196:199], v[46:49]
	v_mfma_f32_16x16x32_bf16 v[38:41], v[156:159], v[204:207], v[38:41]
	v_mfma_f32_16x16x32_bf16 v[30:33], v[164:167], v[204:207], v[30:33]
	v_mfma_f32_16x16x32_bf16 v[22:25], v[156:159], v[212:215], v[22:25]
	v_mfma_f32_16x16x32_bf16 v[14:17], v[164:167], v[212:215], v[14:17]
	s_setprio 0
	s_setprio 1
	v_mfma_f32_16x16x32_bf16 v[50:53], v[168:171], v[184:187], v[50:53]
	v_mfma_f32_16x16x32_bf16 v[42:45], v[176:179], v[184:187], v[42:45]
	v_mfma_f32_16x16x32_bf16 v[34:37], v[168:171], v[192:195], v[34:37]
	v_mfma_f32_16x16x32_bf16 v[26:29], v[176:179], v[192:195], v[26:29]
	v_mfma_f32_16x16x32_bf16 v[18:21], v[168:171], v[200:203], v[18:21]
	v_mfma_f32_16x16x32_bf16 v[10:13], v[176:179], v[200:203], v[10:13]
	v_mfma_f32_16x16x32_bf16 v[6:9], v[168:171], v[208:211], v[6:9]
	v_mfma_f32_16x16x32_bf16 v[2:5], v[176:179], v[208:211], v[2:5]
	v_mfma_f32_16x16x32_bf16 v[50:53], v[172:175], v[188:191], v[50:53]
	v_mfma_f32_16x16x32_bf16 v[42:45], v[180:183], v[188:191], v[42:45]
	v_mfma_f32_16x16x32_bf16 v[34:37], v[172:175], v[196:199], v[34:37]
	v_mfma_f32_16x16x32_bf16 v[26:29], v[180:183], v[196:199], v[26:29]
	v_mfma_f32_16x16x32_bf16 v[18:21], v[172:175], v[204:207], v[18:21]
	v_mfma_f32_16x16x32_bf16 v[10:13], v[180:183], v[204:207], v[10:13]
	v_mfma_f32_16x16x32_bf16 v[6:9], v[172:175], v[212:215], v[6:9]
	v_mfma_f32_16x16x32_bf16 v[2:5], v[180:183], v[212:215], v[2:5]
	s_setprio 0
	s_barrier
; #define PG8_STAGE(bufoff, gbase, voff) do { _Pragma("unroll") for (int _i = 0; _i < 2; ++_i) \
;         __builtin_amdgcn_global_load_lds((const unsigned*)((const char*)(gbase) + (voff)[_i]), (PG8_LAS unsigned*)(lds + (bufoff) + ldsw + _i * 8192), 16, 0, 0); } while (0)
; #define PG8_LDA(dst, b, h) do { _Pragma("unroll") for (int m = 0; m < 4; ++m) _Pragma("unroll") for (int k = 0; k < 2; ++k) dst[m][k] = *(const PG8_LAS bf16x8*)(lds + PG8_SA(b, h) + aoff + m * 2048 + k * 1024); } while (0)
; #define PG8_LDB(dst, b, h) do { _Pragma("unroll") for (int n = 0; n < 2; ++n) _Pragma("unroll") for (int k = 0; k < 2; ++k) dst[n][k] = *(const PG8_LAS bf16x8*)(lds + PG8_SB(b, h) + boff + n * 2048 + k * 1024); } while (0)
; #define PG8_MMA(ai, bj, At, Bt) do { __builtin_amdgcn_s_setprio(1); _Pragma("unroll") for (int m = 0; m < 4; ++m) _Pragma("unroll") for (int n = 0; n < 2; ++n) _Pragma("unroll") for (int k = 0; k < 2; ++k) \
;         acc[ai][bj][m][n] = __builtin_amdgcn_mfma_f32_16x16x32_bf16(Bt[n][k], At[m][k], acc[ai][bj][m][n], 0, 0, 0); __builtin_amdgcn_s_setprio(0); } while (0)
; #define PG8_WAIT_V(n) asm volatile("s_waitcnt vmcnt(" #n ")" ::: "memory")
; #define PG8_WAIT_L(n) asm volatile("s_waitcnt lgkmcnt(" #n ")" ::: "memory")
; #define PG8_BAR __builtin_amdgcn_s_barrier()
; template <class Epi, class Sched, bool ALIGN_EPI = false, bool SP2 = false>
; __device__ __forceinline__ void gemm_phase(PG8_LAS unsigned char* lds, const Gemm g, const Sched& S, const Epi& E) {
;     ...
;         for (int t = 0; t < nt; t += 2) {
;             const bool last = (t == nt - 2);
;             const char* a1 = cA + (size_t)(t + 1) * kstep;
;             const char* a2 = last ? nA : cA + (size_t)(t + 2) * kstep; const char* b2 = last ? nB : cB + (size_t)(t + 2) * kstep;
;             const char* a3 = a2 + kstep; const char* b3 = b2 + kstep;
;     ...
;             PG8_LDB(B0, 1, 0); PG8_LDB(B1, 1, 1); PG8_SCHED; PG8_LDA(At, 1, 0); PG8_STAGE(PG8_SA(0, 1), a2 + hstep, voffA);
;             PG8_WAIT_V(8); PG8_WAIT_L(0); PG8_BAR; PG8_MMA(0, 0, At, B0); PG8_MMA(0, 1, At, B1); PG8_BAR; PG8_SCHED;
;             PG8_LDA(At, 1, 1); PG8_STAGE(PG8_SB(1, 0), b3, voffB); PG8_STAGE(PG8_SB(1, 1), b3 + hstep, voffB); PG8_STAGE(PG8_SA(1, 0), a3, voffA);
;             PG8_WAIT_V(8); PG8_WAIT_L(0); PG8_BAR; PG8_MMA(1, 0, At, B0); PG8_MMA(1, 1, At, B1); PG8_BAR; PG8_SCHED;
	v_add_u32_e32 v180, s66, v146
	ds_read_b128 v[152:155], v151
	ds_read_b128 v[156:159], v151 offset:1024
	ds_read_b128 v[160:163], v151 offset:2048
	ds_read_b128 v[164:167], v151 offset:3072
	ds_read_b128 v[168:171], v180
	ds_read_b128 v[172:175], v180 offset:1024
	ds_read_b128 v[176:179], v180 offset:2048
	ds_read_b128 v[180:183], v180 offset:3072
	s_add_u32 s30, s72, s0
	s_addc_u32 s31, s73, 0
	s_mov_b32 m0, s85
	v_lshl_add_u64 v[226:227], s[30:31], 0, v[132:133]
	ds_read_b128 v[184:187], v148 offset:32768
	ds_read_b128 v[188:191], v148 offset:33792
	ds_read_b128 v[192:195], v148 offset:34816
	ds_read_b128 v[196:199], v148 offset:35840
	ds_read_b128 v[200:203], v148 offset:36864
	ds_read_b128 v[204:207], v148 offset:37888
	ds_read_b128 v[208:211], v148 offset:38912
	ds_read_b128 v[212:215], v148 offset:39936
	global_load_lds_dwordx4 v[226:227], off
	v_lshl_add_u64 v[226:227], s[30:31], 0, v[134:135]
	s_mov_b32 m0, s86
	s_nop 0
	global_load_lds_dwordx4 v[226:227], off
	s_waitcnt vmcnt(8)
	s_waitcnt lgkmcnt(0)
	s_barrier
	s_setprio 1
	s_waitcnt lgkmcnt(0)
	v_mfma_f32_16x16x32_bf16 v[126:129], v[152:155], v[184:187], v[126:129]
	v_mfma_f32_16x16x32_bf16 v[122:125], v[160:163], v[184:187], v[122:125]
	v_mfma_f32_16x16x32_bf16 v[118:121], v[152:155], v[192:195], v[118:121]
	v_mfma_f32_16x16x32_bf16 v[110:113], v[160:163], v[192:195], v[110:113]
	v_mfma_f32_16x16x32_bf16 v[102:105], v[152:155], v[200:203], v[102:105]
	v_mfma_f32_16x16x32_bf16 v[94:97], v[160:163], v[200:203], v[94:97]
	v_mfma_f32_16x16x32_bf16 v[86:89], v[152:155], v[208:211], v[86:89]
	v_mfma_f32_16x16x32_bf16 v[78:81], v[160:163], v[208:211], v[78:81]
	v_mfma_f32_16x16x32_bf16 v[126:129], v[156:159], v[188:191], v[126:129]
	v_mfma_f32_16x16x32_bf16 v[122:125], v[164:167], v[188:191], v[122:125]
	v_mfma_f32_16x16x32_bf16 v[118:121], v[156:159], v[196:199], v[118:121]
	v_mfma_f32_16x16x32_bf16 v[110:113], v[164:167], v[196:199], v[110:113]
	v_mfma_f32_16x16x32_bf16 v[102:105], v[156:159], v[204:207], v[102:105]
	v_mfma_f32_16x16x32_bf16 v[94:97], v[164:167], v[204:207], v[94:97]
	v_mfma_f32_16x16x32_bf16 v[86:89], v[156:159], v[212:215], v[86:89]
	v_mfma_f32_16x16x32_bf16 v[78:81], v[164:167], v[212:215], v[78:81]
	s_setprio 0
	s_setprio 1
	v_mfma_f32_16x16x32_bf16 v[114:117], v[168:171], v[184:187], v[114:117]
	v_mfma_f32_16x16x32_bf16 v[106:109], v[176:179], v[184:187], v[106:109]
	v_mfma_f32_16x16x32_bf16 v[98:101], v[168:171], v[192:195], v[98:101]
	v_mfma_f32_16x16x32_bf16 v[90:93], v[176:179], v[192:195], v[90:93]
	v_mfma_f32_16x16x32_bf16 v[82:85], v[168:171], v[200:203], v[82:85]
	v_mfma_f32_16x16x32_bf16 v[74:77], v[176:179], v[200:203], v[74:77]
	v_mfma_f32_16x16x32_bf16 v[70:73], v[168:171], v[208:211], v[70:73]
	v_mfma_f32_16x16x32_bf16 v[66:69], v[176:179], v[208:211], v[66:69]
	v_mfma_f32_16x16x32_bf16 v[114:117], v[172:175], v[188:191], v[114:117]
	v_mfma_f32_16x16x32_bf16 v[106:109], v[180:183], v[188:191], v[106:109]
	v_mfma_f32_16x16x32_bf16 v[98:101], v[172:175], v[196:199], v[98:101]
	v_mfma_f32_16x16x32_bf16 v[90:93], v[180:183], v[196:199], v[90:93]
	v_mfma_f32_16x16x32_bf16 v[82:85], v[172:175], v[204:207], v[82:85]
	v_mfma_f32_16x16x32_bf16 v[74:77], v[180:183], v[204:207], v[74:77]
	v_mfma_f32_16x16x32_bf16 v[70:73], v[172:175], v[212:215], v[70:73]
	v_mfma_f32_16x16x32_bf16 v[66:69], v[180:183], v[212:215], v[66:69]
	s_setprio 0
	s_barrier
	s_mov_b32 m0, s88
	v_lshl_add_u64 v[142:143], v[142:143], 0, s[18:19]
	ds_read_b128 v[184:187], v148 offset:49152
	ds_read_b128 v[188:191], v148 offset:50176
	ds_read_b128 v[192:195], v148 offset:51200
	ds_read_b128 v[196:199], v148 offset:52224
	ds_read_b128 v[200:203], v148 offset:53248
	ds_read_b128 v[204:207], v148 offset:54272
	ds_read_b128 v[208:211], v148 offset:55296
	ds_read_b128 v[212:215], v148 offset:56320
	global_load_lds_dwordx4 v[142:143], off
	v_lshl_add_u64 v[142:143], v[216:217], 0, s[18:19]
	s_mov_b32 m0, s89
	s_nop 0
	global_load_lds_dwordx4 v[142:143], off
	v_lshl_add_u64 v[142:143], v[218:219], 0, s[18:19]
	s_mov_b32 m0, s92
	s_nop 0
	global_load_lds_dwordx4 v[142:143], off
	v_lshl_add_u64 v[142:143], v[220:221], 0, s[18:19]
	s_mov_b32 m0, s93
	s_nop 0
	global_load_lds_dwordx4 v[142:143], off
	v_lshl_add_u64 v[142:143], v[222:223], 0, s[18:19]
	s_mov_b32 m0, s90
	s_nop 0
	global_load_lds_dwordx4 v[142:143], off
	v_lshl_add_u64 v[142:143], v[224:225], 0, s[18:19]
	s_mov_b32 m0, s91
	s_nop 0
	global_load_lds_dwordx4 v[142:143], off
	s_waitcnt vmcnt(8)
	s_waitcnt lgkmcnt(0)
	s_barrier
	s_setprio 1
	s_waitcnt lgkmcnt(0)
	v_mfma_f32_16x16x32_bf16 v[62:65], v[152:155], v[184:187], v[62:65]
	v_mfma_f32_16x16x32_bf16 v[58:61], v[160:163], v[184:187], v[58:61]
	v_mfma_f32_16x16x32_bf16 v[54:57], v[152:155], v[192:195], v[54:57]
	v_mfma_f32_16x16x32_bf16 v[46:49], v[160:163], v[192:195], v[46:49]
	v_mfma_f32_16x16x32_bf16 v[38:41], v[152:155], v[200:203], v[38:41]
	v_mfma_f32_16x16x32_bf16 v[30:33], v[160:163], v[200:203], v[30:33]
	v_mfma_f32_16x16x32_bf16 v[22:25], v[152:155], v[208:211], v[22:25]
	v_mfma_f32_16x16x32_bf16 v[14:17], v[160:163], v[208:211], v[14:17]
	v_mfma_f32_16x16x32_bf16 v[62:65], v[156:159], v[188:191], v[62:65]
	v_mfma_f32_16x16x32_bf16 v[58:61], v[164:167], v[188:191], v[58:61]
	v_mfma_f32_16x16x32_bf16 v[54:57], v[156:159], v[196:199], v[54:57]
	v_mfma_f32_16x16x32_bf16 v[46:49], v[164:167], v[196:199], v[46:49]
	v_mfma_f32_16x16x32_bf16 v[38:41], v[156:159], v[204:207], v[38:41]
	v_mfma_f32_16x16x32_bf16 v[30:33], v[164:167], v[204:207], v[30:33]
	v_mfma_f32_16x16x32_bf16 v[22:25], v[156:159], v[212:215], v[22:25]
	v_mfma_f32_16x16x32_bf16 v[14:17], v[164:167], v[212:215], v[14:17]
	s_setprio 0
	s_setprio 1
	v_mfma_f32_16x16x32_bf16 v[50:53], v[168:171], v[184:187], v[50:53]
	v_mfma_f32_16x16x32_bf16 v[42:45], v[176:179], v[184:187], v[42:45]
	v_mfma_f32_16x16x32_bf16 v[34:37], v[168:171], v[192:195], v[34:37]
	v_mfma_f32_16x16x32_bf16 v[26:29], v[176:179], v[192:195], v[26:29]
	v_mfma_f32_16x16x32_bf16 v[18:21], v[168:171], v[200:203], v[18:21]
	v_mfma_f32_16x16x32_bf16 v[10:13], v[176:179], v[200:203], v[10:13]
	v_mfma_f32_16x16x32_bf16 v[6:9], v[168:171], v[208:211], v[6:9]
	v_mfma_f32_16x16x32_bf16 v[2:5], v[176:179], v[208:211], v[2:5]
	v_mfma_f32_16x16x32_bf16 v[50:53], v[172:175], v[188:191], v[50:53]
	v_mfma_f32_16x16x32_bf16 v[42:45], v[180:183], v[188:191], v[42:45]
	v_mfma_f32_16x16x32_bf16 v[34:37], v[172:175], v[196:199], v[34:37]
	v_mfma_f32_16x16x32_bf16 v[26:29], v[180:183], v[196:199], v[26:29]
	v_mfma_f32_16x16x32_bf16 v[18:21], v[172:175], v[204:207], v[18:21]
	v_mfma_f32_16x16x32_bf16 v[10:13], v[180:183], v[204:207], v[10:13]
	v_mfma_f32_16x16x32_bf16 v[6:9], v[172:175], v[212:215], v[6:9]
	v_mfma_f32_16x16x32_bf16 v[2:5], v[180:183], v[212:215], v[2:5]
	s_setprio 0
	s_add_u32 s58, s58, 0x100
	s_addc_u32 s59, s59, 0
	s_add_u32 s70, s70, 0x100
	s_addc_u32 s71, s71, 0
	s_cmp_ge_u32 vcc_lo, s87
	s_mov_b32 s72, vcc_lo
	s_barrier
	s_cbranch_scc0 .LBB0_703
	s_and_b64 vcc, exec, s[52:53]
	s_cbranch_vccz .LBB0_706
	s_barrier

; #define PG8_STAGE(bufoff, gbase, voff) do { _Pragma("unroll") for (int _i = 0; _i < 2; ++_i) \
;         __builtin_amdgcn_global_load_lds((const unsigned*)((const char*)(gbase) + (voff)[_i]), (PG8_LAS unsigned*)(lds + (bufoff) + ldsw + _i * 8192), 16, 0, 0); } while (0)
; #define PG8_LDA(dst, b, h) do { _Pragma("unroll") for (int m = 0; m < 4; ++m) _Pragma("unroll") for (int k = 0; k < 2; ++k) dst[m][k] = *(const PG8_LAS bf16x8*)(lds + PG8_SA(b, h) + aoff + m * 2048 + k * 1024); } while (0)
; #define PG8_LDB(dst, b, h) do { _Pragma("unroll") for (int n = 0; n < 2; ++n) _Pragma("unroll") for (int k = 0; k < 2; ++k) dst[n][k] = *(const PG8_LAS bf16x8*)(lds + PG8_SB(b, h) + boff + n * 2048 + k * 1024); } while (0)
; #define PG8_MMA(ai, bj, At, Bt) do { __builtin_amdgcn_s_setprio(1); _Pragma("unroll") for (int m = 0; m < 4; ++m) _Pragma("unroll") for (int n = 0; n < 2; ++n) _Pragma("unroll") for (int k = 0; k < 2; ++k) \
;         acc[ai][bj][m][n] = __builtin_amdgcn_mfma_f32_16x16x32_bf16(Bt[n][k], At[m][k], acc[ai][bj][m][n], 0, 0, 0); __builtin_amdgcn_s_setprio(0); } while (0)
; template <class Epi, class Sched, bool ALIGN_EPI = false, bool SP2 = false>
; __device__ __forceinline__ void gemm_phase(PG8_LAS unsigned char* lds, const Gemm g, const Sched& S, const Epi& E) {
;     ...
;         const bool has_next = S.next(ui + 1, nxt);
;         const char* nA = has_next ? (const char*)g.A + (size_t)nxt.pm * tstep + (size_t)nxt.ks * K * 2 : cA; const char* nB = has_next ? (const char*)g.Bt + (size_t)nxt.pn * tstep + (size_t)nxt.ks * K * 2 : cB;
;         for (int t = 0; t < nt; t += 2) {
;             const bool last = (t == nt - 2);
;             const char* a1 = cA + (size_t)(t + 1) * kstep;
;             const char* a2 = last ? nA : cA + (size_t)(t + 2) * kstep; const char* b2 = last ? nB : cB + (size_t)(t + 2) * kstep;
;             const char* a3 = a2 + kstep; const char* b3 = b2 + kstep;
;             if (last && has_next) S.a_ready(nxt);
;             if constexpr (SP2) {
;             PG8_LDB(B0, 0, 0); PG8_LDB(B1, 0, 1); PG8_SCHED; PG8_LDA(At, 0, 0); PG8_STAGE(PG8_SA(1, 1), a1 + hstep, voffA);
;             PG8_WAIT_V(8); PG8_WAIT_L(0); PG8_BAR; PG8_MMA(0, 0, At, B0); PG8_MMA(0, 1, At, B1); PG8_BAR; PG8_SCHED;
;             PG8_LDA(At, 0, 1); PG8_STAGE(PG8_SB(0, 0), b2, voffB); PG8_STAGE(PG8_SB(0, 1), b2 + hstep, voffB); PG8_STAGE(PG8_SA(0, 0), a2, voffA);
.LBB0_858:
	s_add_u32 s43, s56, 0x100
	s_addc_u32 s45, s57, 0
	s_add_u32 s56, s60, 0x40080
	s_addc_u32 s57, s61, 0
	s_mov_b32 s59, 0
	ds_read_b128 v[150:153], v146
	ds_read_b128 v[154:157], v146 offset:1024
	ds_read_b128 v[158:161], v146 offset:2048
	ds_read_b128 v[162:165], v146 offset:3072
	ds_read_b128 v[166:169], v147
	ds_read_b128 v[170:173], v147 offset:1024
	ds_read_b128 v[174:177], v147 offset:2048
	ds_read_b128 v[178:181], v147 offset:3072
	s_add_i32 s88, s59, 2
	s_add_u32 s60, s56, 0xfffc0080
	s_addc_u32 s61, s57, -1
	s_cmp_eq_u32 s84, s59
	s_cselect_b32 s69, s47, s61
	s_cselect_b32 s68, s46, s60
	s_cselect_b32 s61, s53, s45
	s_cselect_b32 s60, s52, s43
	v_lshl_add_u64 v[214:215], s[56:57], 0, v[140:141]
	s_add_i32 m0, s77, 0xc000
	ds_read_b128 v[182:185], v145
	ds_read_b128 v[186:189], v145 offset:1024
	ds_read_b128 v[190:193], v145 offset:2048
	ds_read_b128 v[194:197], v145 offset:3072
	ds_read_b128 v[198:201], v145 offset:4096
	ds_read_b128 v[202:205], v145 offset:5120
	ds_read_b128 v[206:209], v145 offset:6144
	ds_read_b128 v[210:213], v145 offset:7168
	global_load_lds_dwordx4 v[214:215], off
	v_lshl_add_u64 v[214:215], s[56:57], 0, v[138:139]
	s_add_i32 m0, s77, 0xe000
	s_nop 0
	global_load_lds_dwordx4 v[214:215], off
	s_waitcnt vmcnt(8)
	s_waitcnt lgkmcnt(0)
	s_barrier
	s_setprio 1
	s_waitcnt lgkmcnt(0)
	v_mfma_f32_16x16x32_bf16 v[126:129], v[150:153], v[182:185], 0
	v_mfma_f32_16x16x32_bf16 v[122:125], v[158:161], v[182:185], 0
	v_mfma_f32_16x16x32_bf16 v[118:121], v[150:153], v[190:193], 0
	v_mfma_f32_16x16x32_bf16 v[114:117], v[158:161], v[190:193], 0
	v_mfma_f32_16x16x32_bf16 v[102:105], v[150:153], v[198:201], 0
	v_mfma_f32_16x16x32_bf16 v[98:101], v[158:161], v[198:201], 0
	v_mfma_f32_16x16x32_bf16 v[86:89], v[150:153], v[206:209], 0
	v_mfma_f32_16x16x32_bf16 v[82:85], v[158:161], v[206:209], 0
	v_mfma_f32_16x16x32_bf16 v[126:129], v[154:157], v[186:189], v[126:129]
	v_mfma_f32_16x16x32_bf16 v[122:125], v[162:165], v[186:189], v[122:125]
	v_mfma_f32_16x16x32_bf16 v[118:121], v[154:157], v[194:197], v[118:121]
	v_mfma_f32_16x16x32_bf16 v[114:117], v[162:165], v[194:197], v[114:117]
	v_mfma_f32_16x16x32_bf16 v[102:105], v[154:157], v[202:205], v[102:105]
	v_mfma_f32_16x16x32_bf16 v[98:101], v[162:165], v[202:205], v[98:101]
	v_mfma_f32_16x16x32_bf16 v[86:89], v[154:157], v[210:213], v[86:89]
	v_mfma_f32_16x16x32_bf16 v[82:85], v[162:165], v[210:213], v[82:85]
	s_setprio 0
	s_setprio 1
	v_mfma_f32_16x16x32_bf16 v[110:113], v[166:169], v[182:185], 0
	v_mfma_f32_16x16x32_bf16 v[106:109], v[174:177], v[182:185], 0
	v_mfma_f32_16x16x32_bf16 v[94:97], v[166:169], v[190:193], 0
	v_mfma_f32_16x16x32_bf16 v[90:93], v[174:177], v[190:193], 0
	v_mfma_f32_16x16x32_bf16 v[78:81], v[166:169], v[198:201], 0
	v_mfma_f32_16x16x32_bf16 v[74:77], v[174:177], v[198:201], 0
	v_mfma_f32_16x16x32_bf16 v[70:73], v[166:169], v[206:209], 0
	v_mfma_f32_16x16x32_bf16 v[66:69], v[174:177], v[206:209], 0
	v_mfma_f32_16x16x32_bf16 v[110:113], v[170:173], v[186:189], v[110:113]
	v_mfma_f32_16x16x32_bf16 v[106:109], v[178:181], v[186:189], v[106:109]
	v_mfma_f32_16x16x32_bf16 v[94:97], v[170:173], v[194:197], v[94:97]
	v_mfma_f32_16x16x32_bf16 v[90:93], v[178:181], v[194:197], v[90:93]
	v_mfma_f32_16x16x32_bf16 v[78:81], v[170:173], v[202:205], v[78:81]
	v_mfma_f32_16x16x32_bf16 v[74:77], v[178:181], v[202:205], v[74:77]
	v_mfma_f32_16x16x32_bf16 v[70:73], v[170:173], v[210:213], v[70:73]
	v_mfma_f32_16x16x32_bf16 v[66:69], v[178:181], v[210:213], v[66:69]
	s_setprio 0
	s_barrier
	s_mov_b32 m0, s37
	v_lshl_add_u64 v[214:215], s[60:61], 0, v[130:131]
	s_add_u32 s90, s60, 0x40000
	ds_read_b128 v[182:185], v145 offset:16384
	ds_read_b128 v[186:189], v145 offset:17408
	ds_read_b128 v[190:193], v145 offset:18432
	ds_read_b128 v[194:197], v145 offset:19456
	ds_read_b128 v[198:201], v145 offset:20480
	ds_read_b128 v[202:205], v145 offset:21504
	ds_read_b128 v[206:209], v145 offset:22528
	ds_read_b128 v[210:213], v145 offset:23552
	global_load_lds_dwordx4 v[214:215], off
	v_lshl_add_u64 v[216:217], s[60:61], 0, v[136:137]
	s_mov_b32 m0, s39
	s_addc_u32 s91, s61, 0
	global_load_lds_dwordx4 v[216:217], off
	v_lshl_add_u64 v[218:219], s[90:91], 0, v[130:131]
	s_mov_b32 m0, s75
	v_lshl_add_u64 v[220:221], s[68:69], 0, v[134:135]
	global_load_lds_dwordx4 v[218:219], off
	v_lshl_add_u64 v[218:219], s[90:91], 0, v[136:137]
	s_mov_b32 m0, s76
	s_nop 0
	global_load_lds_dwordx4 v[218:219], off
	v_lshl_add_u64 v[218:219], s[68:69], 0, v[132:133]
	s_mov_b32 m0, s77
	s_nop 0
	global_load_lds_dwordx4 v[218:219], off
	s_mov_b32 m0, s78
	s_nop 0
	global_load_lds_dwordx4 v[220:221], off
	s_waitcnt vmcnt(8)
	s_waitcnt lgkmcnt(0)
	s_barrier
; #define PG8_STAGE(bufoff, gbase, voff) do { _Pragma("unroll") for (int _i = 0; _i < 2; ++_i) \
;         __builtin_amdgcn_global_load_lds((const unsigned*)((const char*)(gbase) + (voff)[_i]), (PG8_LAS unsigned*)(lds + (bufoff) + ldsw + _i * 8192), 16, 0, 0); } while (0)
; #define PG8_LDA(dst, b, h) do { _Pragma("unroll") for (int m = 0; m < 4; ++m) _Pragma("unroll") for (int k = 0; k < 2; ++k) dst[m][k] = *(const PG8_LAS bf16x8*)(lds + PG8_SA(b, h) + aoff + m * 2048 + k * 1024); } while (0)
; #define PG8_LDB(dst, b, h) do { _Pragma("unroll") for (int n = 0; n < 2; ++n) _Pragma("unroll") for (int k = 0; k < 2; ++k) dst[n][k] = *(const PG8_LAS bf16x8*)(lds + PG8_SB(b, h) + boff + n * 2048 + k * 1024); } while (0)
; #define PG8_MMA(ai, bj, At, Bt) do { __builtin_amdgcn_s_setprio(1); _Pragma("unroll") for (int m = 0; m < 4; ++m) _Pragma("unroll") for (int n = 0; n < 2; ++n) _Pragma("unroll") for (int k = 0; k < 2; ++k) \
;         acc[ai][bj][m][n] = __builtin_amdgcn_mfma_f32_16x16x32_bf16(Bt[n][k], At[m][k], acc[ai][bj][m][n], 0, 0, 0); __builtin_amdgcn_s_setprio(0); } while (0)
; #define PG8_WAIT_V(n) asm volatile("s_waitcnt vmcnt(" #n ")" ::: "memory")
; #define PG8_WAIT_L(n) asm volatile("s_waitcnt lgkmcnt(" #n ")" ::: "memory")
; #define PG8_BAR __builtin_amdgcn_s_barrier()
; #define PG8_SCHED __builtin_amdgcn_sched_barrier(0)
; template <class Epi, class Sched, bool ALIGN_EPI = false, bool SP2 = false>
; __device__ __forceinline__ void gemm_phase(PG8_LAS unsigned char* lds, const Gemm g, const Sched& S, const Epi& E) {
;     ...
;             PG8_WAIT_V(8); PG8_WAIT_L(0); PG8_BAR; PG8_MMA(1, 0, At, B0); PG8_MMA(1, 1, At, B1); PG8_BAR; PG8_SCHED;
;             PG8_LDB(B0, 1, 0); PG8_LDB(B1, 1, 1); PG8_SCHED; PG8_LDA(At, 1, 0); PG8_STAGE(PG8_SA(0, 1), a2 + hstep, voffA);
;             PG8_WAIT_V(8); PG8_WAIT_L(0); PG8_BAR; PG8_MMA(0, 0, At, B0); PG8_MMA(0, 1, At, B1); PG8_BAR; PG8_SCHED;
	s_setprio 1
	s_waitcnt lgkmcnt(0)
	v_mfma_f32_16x16x32_bf16 v[62:65], v[150:153], v[182:185], 0
	v_mfma_f32_16x16x32_bf16 v[58:61], v[158:161], v[182:185], 0
	v_mfma_f32_16x16x32_bf16 v[54:57], v[150:153], v[190:193], 0
	v_mfma_f32_16x16x32_bf16 v[50:53], v[158:161], v[190:193], 0
	v_mfma_f32_16x16x32_bf16 v[38:41], v[150:153], v[198:201], 0
	v_mfma_f32_16x16x32_bf16 v[34:37], v[158:161], v[198:201], 0
	v_mfma_f32_16x16x32_bf16 v[22:25], v[150:153], v[206:209], 0
	v_mfma_f32_16x16x32_bf16 v[18:21], v[158:161], v[206:209], 0
	v_mfma_f32_16x16x32_bf16 v[62:65], v[154:157], v[186:189], v[62:65]
	v_mfma_f32_16x16x32_bf16 v[58:61], v[162:165], v[186:189], v[58:61]
	v_mfma_f32_16x16x32_bf16 v[54:57], v[154:157], v[194:197], v[54:57]
	v_mfma_f32_16x16x32_bf16 v[50:53], v[162:165], v[194:197], v[50:53]
	v_mfma_f32_16x16x32_bf16 v[38:41], v[154:157], v[202:205], v[38:41]
	v_mfma_f32_16x16x32_bf16 v[34:37], v[162:165], v[202:205], v[34:37]
	v_mfma_f32_16x16x32_bf16 v[22:25], v[154:157], v[210:213], v[22:25]
	v_mfma_f32_16x16x32_bf16 v[18:21], v[162:165], v[210:213], v[18:21]
	s_setprio 0
	s_setprio 1
	v_mfma_f32_16x16x32_bf16 v[46:49], v[166:169], v[182:185], 0
	v_mfma_f32_16x16x32_bf16 v[42:45], v[174:177], v[182:185], 0
	v_mfma_f32_16x16x32_bf16 v[30:33], v[166:169], v[190:193], 0
	v_mfma_f32_16x16x32_bf16 v[26:29], v[174:177], v[190:193], 0
	v_mfma_f32_16x16x32_bf16 v[14:17], v[166:169], v[198:201], 0
	v_mfma_f32_16x16x32_bf16 v[10:13], v[174:177], v[198:201], 0
	v_mfma_f32_16x16x32_bf16 v[6:9], v[166:169], v[206:209], 0
	v_mfma_f32_16x16x32_bf16 v[2:5], v[174:177], v[206:209], 0
	v_mfma_f32_16x16x32_bf16 v[46:49], v[170:173], v[186:189], v[46:49]
	v_mfma_f32_16x16x32_bf16 v[42:45], v[178:181], v[186:189], v[42:45]
	v_mfma_f32_16x16x32_bf16 v[30:33], v[170:173], v[194:197], v[30:33]
	v_mfma_f32_16x16x32_bf16 v[26:29], v[178:181], v[194:197], v[26:29]
	v_mfma_f32_16x16x32_bf16 v[14:17], v[170:173], v[202:205], v[14:17]
	v_mfma_f32_16x16x32_bf16 v[10:13], v[178:181], v[202:205], v[10:13]
	v_mfma_f32_16x16x32_bf16 v[6:9], v[170:173], v[210:213], v[6:9]
	v_mfma_f32_16x16x32_bf16 v[2:5], v[178:181], v[210:213], v[2:5]
	s_setprio 0
	s_barrier
	ds_read_b128 v[150:153], v148
	ds_read_b128 v[154:157], v148 offset:1024
	ds_read_b128 v[158:161], v148 offset:2048
	ds_read_b128 v[162:165], v148 offset:3072
	ds_read_b128 v[166:169], v149
	ds_read_b128 v[170:173], v149 offset:1024
	ds_read_b128 v[174:177], v149 offset:2048
	ds_read_b128 v[178:181], v149 offset:3072
	s_add_u32 s68, s68, 0x40000
	s_addc_u32 s69, s69, 0
	s_mov_b32 m0, s79
	v_lshl_add_u64 v[222:223], s[68:69], 0, v[132:133]
	ds_read_b128 v[182:185], v145 offset:32768
	ds_read_b128 v[186:189], v145 offset:33792
	ds_read_b128 v[190:193], v145 offset:34816
	ds_read_b128 v[194:197], v145 offset:35840
	ds_read_b128 v[198:201], v145 offset:36864
	ds_read_b128 v[202:205], v145 offset:37888
	ds_read_b128 v[206:209], v145 offset:38912
	ds_read_b128 v[210:213], v145 offset:39936
	global_load_lds_dwordx4 v[222:223], off
	v_lshl_add_u64 v[222:223], s[68:69], 0, v[134:135]
	s_mov_b32 m0, s80
	s_nop 0
	global_load_lds_dwordx4 v[222:223], off
	s_waitcnt vmcnt(8)
	s_waitcnt lgkmcnt(0)
	s_barrier
	s_setprio 1
	s_waitcnt lgkmcnt(0)
	v_mfma_f32_16x16x32_bf16 v[126:129], v[150:153], v[182:185], v[126:129]
	v_mfma_f32_16x16x32_bf16 v[122:125], v[158:161], v[182:185], v[122:125]
	v_mfma_f32_16x16x32_bf16 v[118:121], v[150:153], v[190:193], v[118:121]
	v_mfma_f32_16x16x32_bf16 v[114:117], v[158:161], v[190:193], v[114:117]
	v_mfma_f32_16x16x32_bf16 v[102:105], v[150:153], v[198:201], v[102:105]
	v_mfma_f32_16x16x32_bf16 v[98:101], v[158:161], v[198:201], v[98:101]
	v_mfma_f32_16x16x32_bf16 v[86:89], v[150:153], v[206:209], v[86:89]
	v_mfma_f32_16x16x32_bf16 v[82:85], v[158:161], v[206:209], v[82:85]
	v_mfma_f32_16x16x32_bf16 v[126:129], v[154:157], v[186:189], v[126:129]
	v_mfma_f32_16x16x32_bf16 v[122:125], v[162:165], v[186:189], v[122:125]
	v_mfma_f32_16x16x32_bf16 v[118:121], v[154:157], v[194:197], v[118:121]
	v_mfma_f32_16x16x32_bf16 v[114:117], v[162:165], v[194:197], v[114:117]
	v_mfma_f32_16x16x32_bf16 v[102:105], v[154:157], v[202:205], v[102:105]
	v_mfma_f32_16x16x32_bf16 v[98:101], v[162:165], v[202:205], v[98:101]
	v_mfma_f32_16x16x32_bf16 v[86:89], v[154:157], v[210:213], v[86:89]
	v_mfma_f32_16x16x32_bf16 v[82:85], v[162:165], v[210:213], v[82:85]
	s_setprio 0
	s_setprio 1
	v_mfma_f32_16x16x32_bf16 v[110:113], v[166:169], v[182:185], v[110:113]
	v_mfma_f32_16x16x32_bf16 v[106:109], v[174:177], v[182:185], v[106:109]
	v_mfma_f32_16x16x32_bf16 v[94:97], v[166:169], v[190:193], v[94:97]
	v_mfma_f32_16x16x32_bf16 v[90:93], v[174:177], v[190:193], v[90:93]
	v_mfma_f32_16x16x32_bf16 v[78:81], v[166:169], v[198:201], v[78:81]
	v_mfma_f32_16x16x32_bf16 v[74:77], v[174:177], v[198:201], v[74:77]
	v_mfma_f32_16x16x32_bf16 v[70:73], v[166:169], v[206:209], v[70:73]
	v_mfma_f32_16x16x32_bf16 v[66:69], v[174:177], v[206:209], v[66:69]
	v_mfma_f32_16x16x32_bf16 v[110:113], v[170:173], v[186:189], v[110:113]
	v_mfma_f32_16x16x32_bf16 v[106:109], v[178:181], v[186:189], v[106:109]
	v_mfma_f32_16x16x32_bf16 v[94:97], v[170:173], v[194:197], v[94:97]
	v_mfma_f32_16x16x32_bf16 v[90:93], v[178:181], v[194:197], v[90:93]
	v_mfma_f32_16x16x32_bf16 v[78:81], v[170:173], v[202:205], v[78:81]
	v_mfma_f32_16x16x32_bf16 v[74:77], v[178:181], v[202:205], v[74:77]
	v_mfma_f32_16x16x32_bf16 v[70:73], v[170:173], v[210:213], v[70:73]
	v_mfma_f32_16x16x32_bf16 v[66:69], v[178:181], v[210:213], v[66:69]
	s_setprio 0
	s_barrier
; #define PG8_STAGE(bufoff, gbase, voff) do { _Pragma("unroll") for (int _i = 0; _i < 2; ++_i) \
;         __builtin_amdgcn_global_load_lds((const unsigned*)((const char*)(gbase) + (voff)[_i]), (PG8_LAS unsigned*)(lds + (bufoff) + ldsw + _i * 8192), 16, 0, 0); } while (0)
; #define PG8_LDA(dst, b, h) do { _Pragma("unroll") for (int m = 0; m < 4; ++m) _Pragma("unroll") for (int k = 0; k < 2; ++k) dst[m][k] = *(const PG8_LAS bf16x8*)(lds + PG8_SA(b, h) + aoff + m * 2048 + k * 1024); } while (0)
; #define PG8_LDB(dst, b, h) do { _Pragma("unroll") for (int n = 0; n < 2; ++n) _Pragma("unroll") for (int k = 0; k < 2; ++k) dst[n][k] = *(const PG8_LAS bf16x8*)(lds + PG8_SB(b, h) + boff + n * 2048 + k * 1024); } while (0)
; #define PG8_MMA(ai, bj, At, Bt) do { __builtin_amdgcn_s_setprio(1); _Pragma("unroll") for (int m = 0; m < 4; ++m) _Pragma("unroll") for (int n = 0; n < 2; ++n) _Pragma("unroll") for (int k = 0; k < 2; ++k) \
;         acc[ai][bj][m][n] = __builtin_amdgcn_mfma_f32_16x16x32_bf16(Bt[n][k], At[m][k], acc[ai][bj][m][n], 0, 0, 0); __builtin_amdgcn_s_setprio(0); } while (0)
; #define PG8_WAIT_V(n) asm volatile("s_waitcnt vmcnt(" #n ")" ::: "memory")
; #define PG8_BAR __builtin_amdgcn_s_barrier()
; template <class Epi, class Sched, bool ALIGN_EPI = false, bool SP2 = false>
; __device__ __forceinline__ void gemm_phase(PG8_LAS unsigned char* lds, const Gemm g, const Sched& S, const Epi& E) {
;     ...
;         for (int t = 0; t < nt; t += 2) {
;             const bool last = (t == nt - 2);
;             const char* a1 = cA + (size_t)(t + 1) * kstep;
;             const char* a2 = last ? nA : cA + (size_t)(t + 2) * kstep; const char* b2 = last ? nB : cB + (size_t)(t + 2) * kstep;
;             const char* a3 = a2 + kstep; const char* b3 = b2 + kstep;
;             if (last && has_next) S.a_ready(nxt);
;             if constexpr (SP2) {
;             PG8_LDB(B0, 0, 0); PG8_LDB(B1, 0, 1); PG8_SCHED; PG8_LDA(At, 0, 0); PG8_STAGE(PG8_SA(1, 1), a1 + hstep, voffA);
;             PG8_WAIT_V(8); PG8_WAIT_L(0); PG8_BAR; PG8_MMA(0, 0, At, B0); PG8_MMA(0, 1, At, B1); PG8_BAR; PG8_SCHED;
;     ...
;             PG8_LDA(At, 1, 1); PG8_STAGE(PG8_SB(1, 0), b3, voffB); PG8_STAGE(PG8_SB(1, 1), b3 + hstep, voffB); PG8_STAGE(PG8_SA(1, 0), a3, voffA);
;             PG8_WAIT_V(8); PG8_WAIT_L(0); PG8_BAR; PG8_MMA(1, 0, At, B0); PG8_MMA(1, 1, At, B1); PG8_BAR; PG8_SCHED;
	s_mov_b32 m0, s48
	v_lshl_add_u64 v[214:215], v[214:215], 0, s[16:17]
	s_add_u32 s60, s60, 0x40080
	ds_read_b128 v[182:185], v145 offset:49152
	ds_read_b128 v[186:189], v145 offset:50176
	ds_read_b128 v[190:193], v145 offset:51200
	ds_read_b128 v[194:197], v145 offset:52224
	ds_read_b128 v[198:201], v145 offset:53248
	ds_read_b128 v[202:205], v145 offset:54272
	ds_read_b128 v[206:209], v145 offset:55296
	ds_read_b128 v[210:213], v145 offset:56320
	global_load_lds_dwordx4 v[214:215], off
	v_lshl_add_u64 v[214:215], v[216:217], 0, s[16:17]
	s_mov_b32 m0, s49
	s_addc_u32 s61, s61, 0
	global_load_lds_dwordx4 v[214:215], off
	v_lshl_add_u64 v[214:215], s[60:61], 0, v[130:131]
	s_mov_b32 m0, s82
	s_nop 0
	global_load_lds_dwordx4 v[214:215], off
	v_lshl_add_u64 v[214:215], s[60:61], 0, v[136:137]
	s_mov_b32 m0, s83
	s_nop 0
	global_load_lds_dwordx4 v[214:215], off
	v_lshl_add_u64 v[214:215], v[218:219], 0, s[16:17]
	s_mov_b32 m0, s50
	s_nop 0
	global_load_lds_dwordx4 v[214:215], off
	v_lshl_add_u64 v[214:215], v[220:221], 0, s[16:17]
	s_mov_b32 m0, s51
	s_nop 0
	global_load_lds_dwordx4 v[214:215], off
	s_waitcnt vmcnt(8)
	s_waitcnt lgkmcnt(0)
	s_barrier
	s_setprio 1
	s_waitcnt lgkmcnt(0)
	v_mfma_f32_16x16x32_bf16 v[62:65], v[150:153], v[182:185], v[62:65]
	v_mfma_f32_16x16x32_bf16 v[58:61], v[158:161], v[182:185], v[58:61]
	v_mfma_f32_16x16x32_bf16 v[54:57], v[150:153], v[190:193], v[54:57]
	v_mfma_f32_16x16x32_bf16 v[50:53], v[158:161], v[190:193], v[50:53]
	v_mfma_f32_16x16x32_bf16 v[38:41], v[150:153], v[198:201], v[38:41]
	v_mfma_f32_16x16x32_bf16 v[34:37], v[158:161], v[198:201], v[34:37]
	v_mfma_f32_16x16x32_bf16 v[22:25], v[150:153], v[206:209], v[22:25]
	v_mfma_f32_16x16x32_bf16 v[18:21], v[158:161], v[206:209], v[18:21]
	v_mfma_f32_16x16x32_bf16 v[62:65], v[154:157], v[186:189], v[62:65]
	v_mfma_f32_16x16x32_bf16 v[58:61], v[162:165], v[186:189], v[58:61]
	v_mfma_f32_16x16x32_bf16 v[54:57], v[154:157], v[194:197], v[54:57]
	v_mfma_f32_16x16x32_bf16 v[50:53], v[162:165], v[194:197], v[50:53]
	v_mfma_f32_16x16x32_bf16 v[38:41], v[154:157], v[202:205], v[38:41]
	v_mfma_f32_16x16x32_bf16 v[34:37], v[162:165], v[202:205], v[34:37]
	v_mfma_f32_16x16x32_bf16 v[22:25], v[154:157], v[210:213], v[22:25]
	v_mfma_f32_16x16x32_bf16 v[18:21], v[162:165], v[210:213], v[18:21]
	s_setprio 0
	s_setprio 1
	v_mfma_f32_16x16x32_bf16 v[46:49], v[166:169], v[182:185], v[46:49]
	v_mfma_f32_16x16x32_bf16 v[42:45], v[174:177], v[182:185], v[42:45]
	v_mfma_f32_16x16x32_bf16 v[30:33], v[166:169], v[190:193], v[30:33]
	v_mfma_f32_16x16x32_bf16 v[26:29], v[174:177], v[190:193], v[26:29]
	v_mfma_f32_16x16x32_bf16 v[14:17], v[166:169], v[198:201], v[14:17]
	v_mfma_f32_16x16x32_bf16 v[10:13], v[174:177], v[198:201], v[10:13]
	v_mfma_f32_16x16x32_bf16 v[6:9], v[166:169], v[206:209], v[6:9]
	v_mfma_f32_16x16x32_bf16 v[2:5], v[174:177], v[206:209], v[2:5]
	v_mfma_f32_16x16x32_bf16 v[46:49], v[170:173], v[186:189], v[46:49]
	v_mfma_f32_16x16x32_bf16 v[42:45], v[178:181], v[186:189], v[42:45]
	v_mfma_f32_16x16x32_bf16 v[30:33], v[170:173], v[194:197], v[30:33]
	v_mfma_f32_16x16x32_bf16 v[26:29], v[178:181], v[194:197], v[26:29]
	v_mfma_f32_16x16x32_bf16 v[14:17], v[170:173], v[202:205], v[14:17]
	v_mfma_f32_16x16x32_bf16 v[10:13], v[178:181], v[202:205], v[10:13]
	v_mfma_f32_16x16x32_bf16 v[6:9], v[170:173], v[210:213], v[6:9]
	v_mfma_f32_16x16x32_bf16 v[2:5], v[178:181], v[210:213], v[2:5]
	s_setprio 0
	s_add_u32 s43, s43, 0x100
	s_addc_u32 s45, s45, 0
	s_add_u32 s56, s56, 0x100
	s_addc_u32 s57, s57, 0
	s_cmp_ge_u32 s88, s81
	s_mov_b32 s59, s88
	s_barrier
.LBB0_859:
	ds_read_b128 v[150:153], v146
	ds_read_b128 v[154:157], v146 offset:1024
	ds_read_b128 v[158:161], v146 offset:2048
	ds_read_b128 v[162:165], v146 offset:3072
	ds_read_b128 v[166:169], v147
	ds_read_b128 v[170:173], v147 offset:1024
	ds_read_b128 v[174:177], v147 offset:2048
	ds_read_b128 v[178:181], v147 offset:3072
	s_add_i32 s88, s59, 2
	s_add_u32 s60, s56, 0xfffc0080
	s_addc_u32 s61, s57, -1
	s_cmp_eq_u32 s84, s59
	s_cselect_b32 s69, s47, s61
	s_cselect_b32 s68, s46, s60
	s_cselect_b32 s61, s53, s45
	s_cselect_b32 s60, s52, s43
	v_lshl_add_u64 v[214:215], s[56:57], 0, v[140:141]
	s_add_i32 m0, s77, 0xc000
	ds_read_b128 v[182:185], v145
	ds_read_b128 v[186:189], v145 offset:1024
	ds_read_b128 v[190:193], v145 offset:2048
	ds_read_b128 v[194:197], v145 offset:3072
	ds_read_b128 v[198:201], v145 offset:4096
	ds_read_b128 v[202:205], v145 offset:5120
	ds_read_b128 v[206:209], v145 offset:6144
	ds_read_b128 v[210:213], v145 offset:7168
	global_load_lds_dwordx4 v[214:215], off
	v_lshl_add_u64 v[214:215], s[56:57], 0, v[138:139]
	s_add_i32 m0, s77, 0xe000
	s_nop 0
	global_load_lds_dwordx4 v[214:215], off
	s_waitcnt vmcnt(8)
	s_waitcnt lgkmcnt(0)
	s_barrier
; #define PG8_STAGE(bufoff, gbase, voff) do { _Pragma("unroll") for (int _i = 0; _i < 2; ++_i) \
;         __builtin_amdgcn_global_load_lds((const unsigned*)((const char*)(gbase) + (voff)[_i]), (PG8_LAS unsigned*)(lds + (bufoff) + ldsw + _i * 8192), 16, 0, 0); } while (0)
; #define PG8_LDA(dst, b, h) do { _Pragma("unroll") for (int m = 0; m < 4; ++m) _Pragma("unroll") for (int k = 0; k < 2; ++k) dst[m][k] = *(const PG8_LAS bf16x8*)(lds + PG8_SA(b, h) + aoff + m * 2048 + k * 1024); } while (0)
; #define PG8_LDB(dst, b, h) do { _Pragma("unroll") for (int n = 0; n < 2; ++n) _Pragma("unroll") for (int k = 0; k < 2; ++k) dst[n][k] = *(const PG8_LAS bf16x8*)(lds + PG8_SB(b, h) + boff + n * 2048 + k * 1024); } while (0)
; #define PG8_MMA(ai, bj, At, Bt) do { __builtin_amdgcn_s_setprio(1); _Pragma("unroll") for (int m = 0; m < 4; ++m) _Pragma("unroll") for (int n = 0; n < 2; ++n) _Pragma("unroll") for (int k = 0; k < 2; ++k) \
;         acc[ai][bj][m][n] = __builtin_amdgcn_mfma_f32_16x16x32_bf16(Bt[n][k], At[m][k], acc[ai][bj][m][n], 0, 0, 0); __builtin_amdgcn_s_setprio(0); } while (0)
; #define PG8_WAIT_V(n) asm volatile("s_waitcnt vmcnt(" #n ")" ::: "memory")
; #define PG8_WAIT_L(n) asm volatile("s_waitcnt lgkmcnt(" #n ")" ::: "memory")
; #define PG8_BAR __builtin_amdgcn_s_barrier()
; #define PG8_SCHED __builtin_amdgcn_sched_barrier(0)
; template <class Epi, class Sched, bool ALIGN_EPI = false, bool SP2 = false>
; __device__ __forceinline__ void gemm_phase(PG8_LAS unsigned char* lds, const Gemm g, const Sched& S, const Epi& E) {
;     ...
;             PG8_LDB(B0, 0, 0); PG8_LDB(B1, 0, 1); PG8_SCHED; PG8_LDA(At, 0, 0); PG8_STAGE(PG8_SA(1, 1), a1 + hstep, voffA);
;             PG8_WAIT_V(8); PG8_WAIT_L(0); PG8_BAR; PG8_MMA(0, 0, At, B0); PG8_MMA(0, 1, At, B1); PG8_BAR; PG8_SCHED;
;             PG8_LDA(At, 0, 1); PG8_STAGE(PG8_SB(0, 0), b2, voffB); PG8_STAGE(PG8_SB(0, 1), b2 + hstep, voffB); PG8_STAGE(PG8_SA(0, 0), a2, voffA);
;             PG8_WAIT_V(8); PG8_WAIT_L(0); PG8_BAR; PG8_MMA(1, 0, At, B0); PG8_MMA(1, 1, At, B1); PG8_BAR; PG8_SCHED;
	s_setprio 1
	s_waitcnt lgkmcnt(0)
	v_mfma_f32_16x16x32_bf16 v[126:129], v[150:153], v[182:185], v[126:129]
	v_mfma_f32_16x16x32_bf16 v[122:125], v[158:161], v[182:185], v[122:125]
	v_mfma_f32_16x16x32_bf16 v[118:121], v[150:153], v[190:193], v[118:121]
	v_mfma_f32_16x16x32_bf16 v[114:117], v[158:161], v[190:193], v[114:117]
	v_mfma_f32_16x16x32_bf16 v[102:105], v[150:153], v[198:201], v[102:105]
	v_mfma_f32_16x16x32_bf16 v[98:101], v[158:161], v[198:201], v[98:101]
	v_mfma_f32_16x16x32_bf16 v[86:89], v[150:153], v[206:209], v[86:89]
	v_mfma_f32_16x16x32_bf16 v[82:85], v[158:161], v[206:209], v[82:85]
	v_mfma_f32_16x16x32_bf16 v[126:129], v[154:157], v[186:189], v[126:129]
	v_mfma_f32_16x16x32_bf16 v[122:125], v[162:165], v[186:189], v[122:125]
	v_mfma_f32_16x16x32_bf16 v[118:121], v[154:157], v[194:197], v[118:121]
	v_mfma_f32_16x16x32_bf16 v[114:117], v[162:165], v[194:197], v[114:117]
	v_mfma_f32_16x16x32_bf16 v[102:105], v[154:157], v[202:205], v[102:105]
	v_mfma_f32_16x16x32_bf16 v[98:101], v[162:165], v[202:205], v[98:101]
	v_mfma_f32_16x16x32_bf16 v[86:89], v[154:157], v[210:213], v[86:89]
	v_mfma_f32_16x16x32_bf16 v[82:85], v[162:165], v[210:213], v[82:85]
	s_setprio 0
	s_setprio 1
	v_mfma_f32_16x16x32_bf16 v[110:113], v[166:169], v[182:185], v[110:113]
	v_mfma_f32_16x16x32_bf16 v[106:109], v[174:177], v[182:185], v[106:109]
	v_mfma_f32_16x16x32_bf16 v[94:97], v[166:169], v[190:193], v[94:97]
	v_mfma_f32_16x16x32_bf16 v[90:93], v[174:177], v[190:193], v[90:93]
	v_mfma_f32_16x16x32_bf16 v[78:81], v[166:169], v[198:201], v[78:81]
	v_mfma_f32_16x16x32_bf16 v[74:77], v[174:177], v[198:201], v[74:77]
	v_mfma_f32_16x16x32_bf16 v[70:73], v[166:169], v[206:209], v[70:73]
	v_mfma_f32_16x16x32_bf16 v[66:69], v[174:177], v[206:209], v[66:69]
	v_mfma_f32_16x16x32_bf16 v[110:113], v[170:173], v[186:189], v[110:113]
	v_mfma_f32_16x16x32_bf16 v[106:109], v[178:181], v[186:189], v[106:109]
	v_mfma_f32_16x16x32_bf16 v[94:97], v[170:173], v[194:197], v[94:97]
	v_mfma_f32_16x16x32_bf16 v[90:93], v[178:181], v[194:197], v[90:93]
	v_mfma_f32_16x16x32_bf16 v[78:81], v[170:173], v[202:205], v[78:81]
	v_mfma_f32_16x16x32_bf16 v[74:77], v[178:181], v[202:205], v[74:77]
	v_mfma_f32_16x16x32_bf16 v[70:73], v[170:173], v[210:213], v[70:73]
	v_mfma_f32_16x16x32_bf16 v[66:69], v[178:181], v[210:213], v[66:69]
	s_setprio 0
	s_barrier
	s_mov_b32 m0, s37
	v_lshl_add_u64 v[214:215], s[60:61], 0, v[130:131]
	s_add_u32 s90, s60, 0x40000
	ds_read_b128 v[182:185], v145 offset:16384
	ds_read_b128 v[186:189], v145 offset:17408
	ds_read_b128 v[190:193], v145 offset:18432
	ds_read_b128 v[194:197], v145 offset:19456
	ds_read_b128 v[198:201], v145 offset:20480
	ds_read_b128 v[202:205], v145 offset:21504
	ds_read_b128 v[206:209], v145 offset:22528
	ds_read_b128 v[210:213], v145 offset:23552
	global_load_lds_dwordx4 v[214:215], off
	v_lshl_add_u64 v[216:217], s[60:61], 0, v[136:137]
	s_mov_b32 m0, s39
	s_addc_u32 s91, s61, 0
	global_load_lds_dwordx4 v[216:217], off
	v_lshl_add_u64 v[218:219], s[90:91], 0, v[130:131]
	s_mov_b32 m0, s75
	v_lshl_add_u64 v[220:221], s[68:69], 0, v[134:135]
	global_load_lds_dwordx4 v[218:219], off
	v_lshl_add_u64 v[218:219], s[90:91], 0, v[136:137]
	s_mov_b32 m0, s76
	s_nop 0
	global_load_lds_dwordx4 v[218:219], off
	v_lshl_add_u64 v[218:219], s[68:69], 0, v[132:133]
	s_mov_b32 m0, s77
	s_nop 0
	global_load_lds_dwordx4 v[218:219], off
	s_mov_b32 m0, s78
	s_nop 0
	global_load_lds_dwordx4 v[220:221], off
	s_waitcnt vmcnt(8)
	s_waitcnt lgkmcnt(0)
	s_barrier
	s_setprio 1
	s_waitcnt lgkmcnt(0)
	v_mfma_f32_16x16x32_bf16 v[62:65], v[150:153], v[182:185], v[62:65]
	v_mfma_f32_16x16x32_bf16 v[58:61], v[158:161], v[182:185], v[58:61]
	v_mfma_f32_16x16x32_bf16 v[54:57], v[150:153], v[190:193], v[54:57]
	v_mfma_f32_16x16x32_bf16 v[50:53], v[158:161], v[190:193], v[50:53]
	v_mfma_f32_16x16x32_bf16 v[38:41], v[150:153], v[198:201], v[38:41]
	v_mfma_f32_16x16x32_bf16 v[34:37], v[158:161], v[198:201], v[34:37]
	v_mfma_f32_16x16x32_bf16 v[22:25], v[150:153], v[206:209], v[22:25]
	v_mfma_f32_16x16x32_bf16 v[18:21], v[158:161], v[206:209], v[18:21]
	v_mfma_f32_16x16x32_bf16 v[62:65], v[154:157], v[186:189], v[62:65]
	v_mfma_f32_16x16x32_bf16 v[58:61], v[162:165], v[186:189], v[58:61]
	v_mfma_f32_16x16x32_bf16 v[54:57], v[154:157], v[194:197], v[54:57]
	v_mfma_f32_16x16x32_bf16 v[50:53], v[162:165], v[194:197], v[50:53]
	v_mfma_f32_16x16x32_bf16 v[38:41], v[154:157], v[202:205], v[38:41]
	v_mfma_f32_16x16x32_bf16 v[34:37], v[162:165], v[202:205], v[34:37]
	v_mfma_f32_16x16x32_bf16 v[22:25], v[154:157], v[210:213], v[22:25]
	v_mfma_f32_16x16x32_bf16 v[18:21], v[162:165], v[210:213], v[18:21]
	s_setprio 0
	s_setprio 1
	v_mfma_f32_16x16x32_bf16 v[46:49], v[166:169], v[182:185], v[46:49]
	v_mfma_f32_16x16x32_bf16 v[42:45], v[174:177], v[182:185], v[42:45]
	v_mfma_f32_16x16x32_bf16 v[30:33], v[166:169], v[190:193], v[30:33]
	v_mfma_f32_16x16x32_bf16 v[26:29], v[174:177], v[190:193], v[26:29]
	v_mfma_f32_16x16x32_bf16 v[14:17], v[166:169], v[198:201], v[14:17]
	v_mfma_f32_16x16x32_bf16 v[10:13], v[174:177], v[198:201], v[10:13]
	v_mfma_f32_16x16x32_bf16 v[6:9], v[166:169], v[206:209], v[6:9]
	v_mfma_f32_16x16x32_bf16 v[2:5], v[174:177], v[206:209], v[2:5]
	v_mfma_f32_16x16x32_bf16 v[46:49], v[170:173], v[186:189], v[46:49]
	v_mfma_f32_16x16x32_bf16 v[42:45], v[178:181], v[186:189], v[42:45]
	v_mfma_f32_16x16x32_bf16 v[30:33], v[170:173], v[194:197], v[30:33]
	v_mfma_f32_16x16x32_bf16 v[26:29], v[178:181], v[194:197], v[26:29]
	v_mfma_f32_16x16x32_bf16 v[14:17], v[170:173], v[202:205], v[14:17]
	v_mfma_f32_16x16x32_bf16 v[10:13], v[178:181], v[202:205], v[10:13]
	v_mfma_f32_16x16x32_bf16 v[6:9], v[170:173], v[210:213], v[6:9]
	v_mfma_f32_16x16x32_bf16 v[2:5], v[178:181], v[210:213], v[2:5]
	s_setprio 0
	s_barrier
; #define PG8_STAGE(bufoff, gbase, voff) do { _Pragma("unroll") for (int _i = 0; _i < 2; ++_i) \
;         __builtin_amdgcn_global_load_lds((const unsigned*)((const char*)(gbase) + (voff)[_i]), (PG8_LAS unsigned*)(lds + (bufoff) + ldsw + _i * 8192), 16, 0, 0); } while (0)
; #define PG8_LDA(dst, b, h) do { _Pragma("unroll") for (int m = 0; m < 4; ++m) _Pragma("unroll") for (int k = 0; k < 2; ++k) dst[m][k] = *(const PG8_LAS bf16x8*)(lds + PG8_SA(b, h) + aoff + m * 2048 + k * 1024); } while (0)
; #define PG8_LDB(dst, b, h) do { _Pragma("unroll") for (int n = 0; n < 2; ++n) _Pragma("unroll") for (int k = 0; k < 2; ++k) dst[n][k] = *(const PG8_LAS bf16x8*)(lds + PG8_SB(b, h) + boff + n * 2048 + k * 1024); } while (0)
; #define PG8_MMA(ai, bj, At, Bt) do { __builtin_amdgcn_s_setprio(1); _Pragma("unroll") for (int m = 0; m < 4; ++m) _Pragma("unroll") for (int n = 0; n < 2; ++n) _Pragma("unroll") for (int k = 0; k < 2; ++k) \
;         acc[ai][bj][m][n] = __builtin_amdgcn_mfma_f32_16x16x32_bf16(Bt[n][k], At[m][k], acc[ai][bj][m][n], 0, 0, 0); __builtin_amdgcn_s_setprio(0); } while (0)
; #define PG8_WAIT_V(n) asm volatile("s_waitcnt vmcnt(" #n ")" ::: "memory")
; #define PG8_WAIT_L(n) asm volatile("s_waitcnt lgkmcnt(" #n ")" ::: "memory")
; #define PG8_BAR __builtin_amdgcn_s_barrier()
; template <class Epi, class Sched, bool ALIGN_EPI = false, bool SP2 = false>
; __device__ __forceinline__ void gemm_phase(PG8_LAS unsigned char* lds, const Gemm g, const Sched& S, const Epi& E) {
;     ...
;         for (int t = 0; t < nt; t += 2) {
;             const bool last = (t == nt - 2);
;             const char* a1 = cA + (size_t)(t + 1) * kstep;
;             const char* a2 = last ? nA : cA + (size_t)(t + 2) * kstep; const char* b2 = last ? nB : cB + (size_t)(t + 2) * kstep;
;             const char* a3 = a2 + kstep; const char* b3 = b2 + kstep;
;     ...
;             PG8_LDB(B0, 1, 0); PG8_LDB(B1, 1, 1); PG8_SCHED; PG8_LDA(At, 1, 0); PG8_STAGE(PG8_SA(0, 1), a2 + hstep, voffA);
;             PG8_WAIT_V(8); PG8_WAIT_L(0); PG8_BAR; PG8_MMA(0, 0, At, B0); PG8_MMA(0, 1, At, B1); PG8_BAR; PG8_SCHED;
;             PG8_LDA(At, 1, 1); PG8_STAGE(PG8_SB(1, 0), b3, voffB); PG8_STAGE(PG8_SB(1, 1), b3 + hstep, voffB); PG8_STAGE(PG8_SA(1, 0), a3, voffA);
;             PG8_WAIT_V(8); PG8_WAIT_L(0); PG8_BAR; PG8_MMA(1, 0, At, B0); PG8_MMA(1, 1, At, B1); PG8_BAR; PG8_SCHED;
	ds_read_b128 v[150:153], v148
	ds_read_b128 v[154:157], v148 offset:1024
	ds_read_b128 v[158:161], v148 offset:2048
	ds_read_b128 v[162:165], v148 offset:3072
	ds_read_b128 v[166:169], v149
	ds_read_b128 v[170:173], v149 offset:1024
	ds_read_b128 v[174:177], v149 offset:2048
	ds_read_b128 v[178:181], v149 offset:3072
	s_add_u32 s68, s68, 0x40000
	s_addc_u32 s69, s69, 0
	s_mov_b32 m0, s79
	v_lshl_add_u64 v[222:223], s[68:69], 0, v[132:133]
	ds_read_b128 v[182:185], v145 offset:32768
	ds_read_b128 v[186:189], v145 offset:33792
	ds_read_b128 v[190:193], v145 offset:34816
	ds_read_b128 v[194:197], v145 offset:35840
	ds_read_b128 v[198:201], v145 offset:36864
	ds_read_b128 v[202:205], v145 offset:37888
	ds_read_b128 v[206:209], v145 offset:38912
	ds_read_b128 v[210:213], v145 offset:39936
	global_load_lds_dwordx4 v[222:223], off
	v_lshl_add_u64 v[222:223], s[68:69], 0, v[134:135]
	s_mov_b32 m0, s80
	s_nop 0
	global_load_lds_dwordx4 v[222:223], off
	s_waitcnt vmcnt(8)
	s_waitcnt lgkmcnt(0)
	s_barrier
	s_setprio 1
	s_waitcnt lgkmcnt(0)
	v_mfma_f32_16x16x32_bf16 v[126:129], v[150:153], v[182:185], v[126:129]
	v_mfma_f32_16x16x32_bf16 v[122:125], v[158:161], v[182:185], v[122:125]
	v_mfma_f32_16x16x32_bf16 v[118:121], v[150:153], v[190:193], v[118:121]
	v_mfma_f32_16x16x32_bf16 v[114:117], v[158:161], v[190:193], v[114:117]
	v_mfma_f32_16x16x32_bf16 v[102:105], v[150:153], v[198:201], v[102:105]
	v_mfma_f32_16x16x32_bf16 v[98:101], v[158:161], v[198:201], v[98:101]
	v_mfma_f32_16x16x32_bf16 v[86:89], v[150:153], v[206:209], v[86:89]
	v_mfma_f32_16x16x32_bf16 v[82:85], v[158:161], v[206:209], v[82:85]
	v_mfma_f32_16x16x32_bf16 v[126:129], v[154:157], v[186:189], v[126:129]
	v_mfma_f32_16x16x32_bf16 v[122:125], v[162:165], v[186:189], v[122:125]
	v_mfma_f32_16x16x32_bf16 v[118:121], v[154:157], v[194:197], v[118:121]
	v_mfma_f32_16x16x32_bf16 v[114:117], v[162:165], v[194:197], v[114:117]
	v_mfma_f32_16x16x32_bf16 v[102:105], v[154:157], v[202:205], v[102:105]
	v_mfma_f32_16x16x32_bf16 v[98:101], v[162:165], v[202:205], v[98:101]
	v_mfma_f32_16x16x32_bf16 v[86:89], v[154:157], v[210:213], v[86:89]
	v_mfma_f32_16x16x32_bf16 v[82:85], v[162:165], v[210:213], v[82:85]
	s_setprio 0
	s_setprio 1
	v_mfma_f32_16x16x32_bf16 v[110:113], v[166:169], v[182:185], v[110:113]
	v_mfma_f32_16x16x32_bf16 v[106:109], v[174:177], v[182:185], v[106:109]
	v_mfma_f32_16x16x32_bf16 v[94:97], v[166:169], v[190:193], v[94:97]
	v_mfma_f32_16x16x32_bf16 v[90:93], v[174:177], v[190:193], v[90:93]
	v_mfma_f32_16x16x32_bf16 v[78:81], v[166:169], v[198:201], v[78:81]
	v_mfma_f32_16x16x32_bf16 v[74:77], v[174:177], v[198:201], v[74:77]
	v_mfma_f32_16x16x32_bf16 v[70:73], v[166:169], v[206:209], v[70:73]
	v_mfma_f32_16x16x32_bf16 v[66:69], v[174:177], v[206:209], v[66:69]
	v_mfma_f32_16x16x32_bf16 v[110:113], v[170:173], v[186:189], v[110:113]
	v_mfma_f32_16x16x32_bf16 v[106:109], v[178:181], v[186:189], v[106:109]
	v_mfma_f32_16x16x32_bf16 v[94:97], v[170:173], v[194:197], v[94:97]
	v_mfma_f32_16x16x32_bf16 v[90:93], v[178:181], v[194:197], v[90:93]
	v_mfma_f32_16x16x32_bf16 v[78:81], v[170:173], v[202:205], v[78:81]
	v_mfma_f32_16x16x32_bf16 v[74:77], v[178:181], v[202:205], v[74:77]
	v_mfma_f32_16x16x32_bf16 v[70:73], v[170:173], v[210:213], v[70:73]
	v_mfma_f32_16x16x32_bf16 v[66:69], v[178:181], v[210:213], v[66:69]
	s_setprio 0
	s_barrier
	s_mov_b32 m0, s48
	v_lshl_add_u64 v[214:215], v[214:215], 0, s[16:17]
	s_add_u32 s60, s60, 0x40080
	ds_read_b128 v[182:185], v145 offset:49152
	ds_read_b128 v[186:189], v145 offset:50176
	ds_read_b128 v[190:193], v145 offset:51200
	ds_read_b128 v[194:197], v145 offset:52224
	ds_read_b128 v[198:201], v145 offset:53248
	ds_read_b128 v[202:205], v145 offset:54272
	ds_read_b128 v[206:209], v145 offset:55296
	ds_read_b128 v[210:213], v145 offset:56320
	global_load_lds_dwordx4 v[214:215], off
	v_lshl_add_u64 v[214:215], v[216:217], 0, s[16:17]
	s_mov_b32 m0, s49
	s_addc_u32 s61, s61, 0
	global_load_lds_dwordx4 v[214:215], off
	v_lshl_add_u64 v[214:215], s[60:61], 0, v[130:131]
	s_mov_b32 m0, s82
	s_nop 0
	global_load_lds_dwordx4 v[214:215], off
	v_lshl_add_u64 v[214:215], s[60:61], 0, v[136:137]
	s_mov_b32 m0, s83
	s_nop 0
	global_load_lds_dwordx4 v[214:215], off
	v_lshl_add_u64 v[214:215], v[218:219], 0, s[16:17]
	s_mov_b32 m0, s50
	s_nop 0
	global_load_lds_dwordx4 v[214:215], off
	v_lshl_add_u64 v[214:215], v[220:221], 0, s[16:17]
	s_mov_b32 m0, s51
	s_nop 0
	global_load_lds_dwordx4 v[214:215], off
	s_waitcnt vmcnt(8)
	s_waitcnt lgkmcnt(0)
	s_barrier
	s_setprio 1
	s_waitcnt lgkmcnt(0)
	v_mfma_f32_16x16x32_bf16 v[62:65], v[150:153], v[182:185], v[62:65]
	v_mfma_f32_16x16x32_bf16 v[58:61], v[158:161], v[182:185], v[58:61]
	v_mfma_f32_16x16x32_bf16 v[54:57], v[150:153], v[190:193], v[54:57]
	v_mfma_f32_16x16x32_bf16 v[50:53], v[158:161], v[190:193], v[50:53]
	v_mfma_f32_16x16x32_bf16 v[38:41], v[150:153], v[198:201], v[38:41]
	v_mfma_f32_16x16x32_bf16 v[34:37], v[158:161], v[198:201], v[34:37]
	v_mfma_f32_16x16x32_bf16 v[22:25], v[150:153], v[206:209], v[22:25]
	v_mfma_f32_16x16x32_bf16 v[18:21], v[158:161], v[206:209], v[18:21]
	v_mfma_f32_16x16x32_bf16 v[62:65], v[154:157], v[186:189], v[62:65]
	v_mfma_f32_16x16x32_bf16 v[58:61], v[162:165], v[186:189], v[58:61]
	v_mfma_f32_16x16x32_bf16 v[54:57], v[154:157], v[194:197], v[54:57]
	v_mfma_f32_16x16x32_bf16 v[50:53], v[162:165], v[194:197], v[50:53]
	v_mfma_f32_16x16x32_bf16 v[38:41], v[154:157], v[202:205], v[38:41]
	v_mfma_f32_16x16x32_bf16 v[34:37], v[162:165], v[202:205], v[34:37]
	v_mfma_f32_16x16x32_bf16 v[22:25], v[154:157], v[210:213], v[22:25]
	v_mfma_f32_16x16x32_bf16 v[18:21], v[162:165], v[210:213], v[18:21]
	s_setprio 0
	s_setprio 1
	v_mfma_f32_16x16x32_bf16 v[46:49], v[166:169], v[182:185], v[46:49]
	v_mfma_f32_16x16x32_bf16 v[42:45], v[174:177], v[182:185], v[42:45]
	v_mfma_f32_16x16x32_bf16 v[30:33], v[166:169], v[190:193], v[30:33]
	v_mfma_f32_16x16x32_bf16 v[26:29], v[174:177], v[190:193], v[26:29]
	v_mfma_f32_16x16x32_bf16 v[14:17], v[166:169], v[198:201], v[14:17]
	v_mfma_f32_16x16x32_bf16 v[10:13], v[174:177], v[198:201], v[10:13]
	v_mfma_f32_16x16x32_bf16 v[6:9], v[166:169], v[206:209], v[6:9]
	v_mfma_f32_16x16x32_bf16 v[2:5], v[174:177], v[206:209], v[2:5]
	v_mfma_f32_16x16x32_bf16 v[46:49], v[170:173], v[186:189], v[46:49]
	v_mfma_f32_16x16x32_bf16 v[42:45], v[178:181], v[186:189], v[42:45]
	v_mfma_f32_16x16x32_bf16 v[30:33], v[170:173], v[194:197], v[30:33]
	v_mfma_f32_16x16x32_bf16 v[26:29], v[178:181], v[194:197], v[26:29]
	v_mfma_f32_16x16x32_bf16 v[14:17], v[170:173], v[202:205], v[14:17]
	v_mfma_f32_16x16x32_bf16 v[10:13], v[178:181], v[202:205], v[10:13]
	v_mfma_f32_16x16x32_bf16 v[6:9], v[170:173], v[210:213], v[6:9]
	v_mfma_f32_16x16x32_bf16 v[2:5], v[178:181], v[210:213], v[2:5]
	s_setprio 0
	s_add_u32 s43, s43, 0x100
	s_addc_u32 s45, s45, 0
	s_add_u32 s56, s56, 0x100
	s_addc_u32 s57, s57, 0
	s_cmp_ge_u32 s88, s81
	s_mov_b32 s59, s88
	s_barrier
	s_cbranch_scc0 .LBB0_859
	s_and_b64 vcc, exec, s[40:41]
	s_cbranch_vccz .LBB0_862
	s_barrier

; #define PG8_STAGE(bufoff, gbase, voff) do { _Pragma("unroll") for (int _i = 0; _i < 2; ++_i) \
;         __builtin_amdgcn_global_load_lds((const unsigned*)((const char*)(gbase) + (voff)[_i]), (PG8_LAS unsigned*)(lds + (bufoff) + ldsw + _i * 8192), 16, 0, 0); } while (0)
; #define PG8_LDA(dst, b, h) do { _Pragma("unroll") for (int m = 0; m < 4; ++m) _Pragma("unroll") for (int k = 0; k < 2; ++k) dst[m][k] = *(const PG8_LAS bf16x8*)(lds + PG8_SA(b, h) + aoff + m * 2048 + k * 1024); } while (0)
; #define PG8_LDB(dst, b, h) do { _Pragma("unroll") for (int n = 0; n < 2; ++n) _Pragma("unroll") for (int k = 0; k < 2; ++k) dst[n][k] = *(const PG8_LAS bf16x8*)(lds + PG8_SB(b, h) + boff + n * 2048 + k * 1024); } while (0)
; #define PG8_MMA(ai, bj, At, Bt) do { __builtin_amdgcn_s_setprio(1); _Pragma("unroll") for (int m = 0; m < 4; ++m) _Pragma("unroll") for (int n = 0; n < 2; ++n) _Pragma("unroll") for (int k = 0; k < 2; ++k) \
;         acc[ai][bj][m][n] = __builtin_amdgcn_mfma_f32_16x16x32_bf16(Bt[n][k], At[m][k], acc[ai][bj][m][n], 0, 0, 0); __builtin_amdgcn_s_setprio(0); } while (0)
; template <class Epi, class Sched, bool ALIGN_EPI = false, bool SP2 = false>
; __device__ __forceinline__ void gemm_phase(PG8_LAS unsigned char* lds, const Gemm g, const Sched& S, const Epi& E) {
;     ...
;         const bool has_next = S.next(ui + 1, nxt);
;         const char* nA = has_next ? (const char*)g.A + (size_t)nxt.pm * tstep + (size_t)nxt.ks * K * 2 : cA; const char* nB = has_next ? (const char*)g.Bt + (size_t)nxt.pn * tstep + (size_t)nxt.ks * K * 2 : cB;
;         for (int t = 0; t < nt; t += 2) {
;             const bool last = (t == nt - 2);
;             const char* a1 = cA + (size_t)(t + 1) * kstep;
;             const char* a2 = last ? nA : cA + (size_t)(t + 2) * kstep; const char* b2 = last ? nB : cB + (size_t)(t + 2) * kstep;
;             const char* a3 = a2 + kstep; const char* b3 = b2 + kstep;
;             if (last && has_next) S.a_ready(nxt);
;             if constexpr (SP2) {
;             PG8_LDB(B0, 0, 0); PG8_LDB(B1, 0, 1); PG8_SCHED; PG8_LDA(At, 0, 0); PG8_STAGE(PG8_SA(1, 1), a1 + hstep, voffA);
;             PG8_WAIT_V(8); PG8_WAIT_L(0); PG8_BAR; PG8_MMA(0, 0, At, B0); PG8_MMA(0, 1, At, B1); PG8_BAR; PG8_SCHED;
;             PG8_LDA(At, 0, 1); PG8_STAGE(PG8_SB(0, 0), b2, voffB); PG8_STAGE(PG8_SB(0, 1), b2 + hstep, voffB); PG8_STAGE(PG8_SA(0, 0), a2, voffA);
.LBB0_1037:
	s_ashr_i32 s13, s12, 31
	s_lshl_b64 s[14:15], s[12:13], 19
	s_add_u32 s14, s28, s14
	s_addc_u32 s15, s29, s15
	s_and_b64 s[16:17], s[2:3], exec
	s_cselect_b32 s13, s15, s23
	s_cselect_b32 s48, s14, s22
	s_ashr_i32 s11, s10, 31
	s_lshl_b64 s[16:17], s[10:11], 19
	s_add_u32 s16, s30, s16
	s_addc_u32 s17, s31, s17
	s_and_b64 s[24:25], s[2:3], exec
	s_cselect_b32 s11, s17, s21
	s_cselect_b32 s49, s16, s20
	s_add_u32 s50, s20, 0x100
	s_addc_u32 s51, s21, 0
	s_add_u32 s20, s22, 0x40080
	s_addc_u32 s21, s23, 0
	s_mov_b32 s54, -2
	ds_read_b128 v[146:149], v152
	ds_read_b128 v[158:161], v152 offset:1024
	ds_read_b128 v[162:165], v152 offset:2048
	ds_read_b128 v[166:169], v152 offset:3072
	ds_read_b128 v[170:173], v153
	ds_read_b128 v[174:177], v153 offset:1024
	ds_read_b128 v[178:181], v153 offset:2048
	ds_read_b128 v[182:185], v153 offset:3072
	s_add_u32 s22, s20, 0xfffc0080
	s_addc_u32 s23, s21, -1
	s_cmp_eq_u32 s54, 12
	s_cselect_b32 s25, s13, s23
	s_cselect_b32 s24, s48, s22
	s_cselect_b32 s23, s11, s51
	s_cselect_b32 s22, s49, s50
	v_lshl_add_u64 v[218:219], s[20:21], 0, v[140:141]
	s_add_i32 m0, s41, 0xc000
	ds_read_b128 v[186:189], v154
	ds_read_b128 v[190:193], v154 offset:1024
	ds_read_b128 v[194:197], v154 offset:2048
	ds_read_b128 v[198:201], v154 offset:3072
	ds_read_b128 v[202:205], v154 offset:4096
	ds_read_b128 v[206:209], v154 offset:5120
	ds_read_b128 v[210:213], v154 offset:6144
	ds_read_b128 v[214:217], v154 offset:7168
	global_load_lds_dwordx4 v[218:219], off
	v_lshl_add_u64 v[218:219], s[20:21], 0, v[138:139]
	s_add_i32 m0, s41, 0xe000
	s_nop 0
	global_load_lds_dwordx4 v[218:219], off
	s_waitcnt vmcnt(8)
	s_waitcnt lgkmcnt(0)
	s_barrier
	s_setprio 1
	s_waitcnt lgkmcnt(0)
	v_mfma_f32_16x16x32_bf16 v[126:129], v[146:149], v[186:189], 0
	v_mfma_f32_16x16x32_bf16 v[118:121], v[162:165], v[186:189], 0
	v_mfma_f32_16x16x32_bf16 v[110:113], v[146:149], v[194:197], 0
	v_mfma_f32_16x16x32_bf16 v[102:105], v[162:165], v[194:197], 0
	v_mfma_f32_16x16x32_bf16 v[94:97], v[146:149], v[202:205], 0
	v_mfma_f32_16x16x32_bf16 v[86:89], v[162:165], v[202:205], 0
	v_mfma_f32_16x16x32_bf16 v[78:81], v[146:149], v[210:213], 0
	v_mfma_f32_16x16x32_bf16 v[70:73], v[162:165], v[210:213], 0
	v_mfma_f32_16x16x32_bf16 v[126:129], v[158:161], v[190:193], v[126:129]
	v_mfma_f32_16x16x32_bf16 v[118:121], v[166:169], v[190:193], v[118:121]
	v_mfma_f32_16x16x32_bf16 v[110:113], v[158:161], v[198:201], v[110:113]
	v_mfma_f32_16x16x32_bf16 v[102:105], v[166:169], v[198:201], v[102:105]
	v_mfma_f32_16x16x32_bf16 v[94:97], v[158:161], v[206:209], v[94:97]
	v_mfma_f32_16x16x32_bf16 v[86:89], v[166:169], v[206:209], v[86:89]
	v_mfma_f32_16x16x32_bf16 v[78:81], v[158:161], v[214:217], v[78:81]
	v_mfma_f32_16x16x32_bf16 v[70:73], v[166:169], v[214:217], v[70:73]
	s_setprio 0
	s_setprio 1
	v_mfma_f32_16x16x32_bf16 v[122:125], v[170:173], v[186:189], 0
	v_mfma_f32_16x16x32_bf16 v[114:117], v[178:181], v[186:189], 0
	v_mfma_f32_16x16x32_bf16 v[106:109], v[170:173], v[194:197], 0
	v_mfma_f32_16x16x32_bf16 v[98:101], v[178:181], v[194:197], 0
	v_mfma_f32_16x16x32_bf16 v[90:93], v[170:173], v[202:205], 0
	v_mfma_f32_16x16x32_bf16 v[82:85], v[178:181], v[202:205], 0
	v_mfma_f32_16x16x32_bf16 v[74:77], v[170:173], v[210:213], 0
	v_mfma_f32_16x16x32_bf16 v[66:69], v[178:181], v[210:213], 0
	v_mfma_f32_16x16x32_bf16 v[122:125], v[174:177], v[190:193], v[122:125]
	v_mfma_f32_16x16x32_bf16 v[114:117], v[182:185], v[190:193], v[114:117]
	v_mfma_f32_16x16x32_bf16 v[106:109], v[174:177], v[198:201], v[106:109]
	v_mfma_f32_16x16x32_bf16 v[98:101], v[182:185], v[198:201], v[98:101]
	v_mfma_f32_16x16x32_bf16 v[90:93], v[174:177], v[206:209], v[90:93]
	v_mfma_f32_16x16x32_bf16 v[82:85], v[182:185], v[206:209], v[82:85]
	v_mfma_f32_16x16x32_bf16 v[74:77], v[174:177], v[214:217], v[74:77]
	v_mfma_f32_16x16x32_bf16 v[66:69], v[182:185], v[214:217], v[66:69]
	s_setprio 0
	s_barrier
	s_mov_b32 m0, s19
	v_lshl_add_u64 v[218:219], s[22:23], 0, v[134:135]
	s_add_u32 s58, s22, 0x40000
	ds_read_b128 v[186:189], v154 offset:16384
	ds_read_b128 v[190:193], v154 offset:17408
	ds_read_b128 v[194:197], v154 offset:18432
	ds_read_b128 v[198:201], v154 offset:19456
	ds_read_b128 v[202:205], v154 offset:20480
	ds_read_b128 v[206:209], v154 offset:21504
	ds_read_b128 v[210:213], v154 offset:22528
	ds_read_b128 v[214:217], v154 offset:23552
	global_load_lds_dwordx4 v[218:219], off
	v_lshl_add_u64 v[220:221], s[22:23], 0, v[130:131]
	s_mov_b32 m0, s38
	s_addc_u32 s59, s23, 0
	global_load_lds_dwordx4 v[220:221], off
	v_lshl_add_u64 v[222:223], s[58:59], 0, v[134:135]
	s_mov_b32 m0, s39
	v_lshl_add_u64 v[224:225], s[24:25], 0, v[132:133]
	global_load_lds_dwordx4 v[222:223], off
	v_lshl_add_u64 v[222:223], s[58:59], 0, v[130:131]
	s_mov_b32 m0, s40
	s_nop 0
	global_load_lds_dwordx4 v[222:223], off
	v_lshl_add_u64 v[222:223], s[24:25], 0, v[136:137]
	s_mov_b32 m0, s41
	s_nop 0
	global_load_lds_dwordx4 v[222:223], off
	s_mov_b32 m0, s42
	s_nop 0
	global_load_lds_dwordx4 v[224:225], off
	s_waitcnt vmcnt(8)
	s_waitcnt lgkmcnt(0)
	s_barrier
; #define PG8_STAGE(bufoff, gbase, voff) do { _Pragma("unroll") for (int _i = 0; _i < 2; ++_i) \
;         __builtin_amdgcn_global_load_lds((const unsigned*)((const char*)(gbase) + (voff)[_i]), (PG8_LAS unsigned*)(lds + (bufoff) + ldsw + _i * 8192), 16, 0, 0); } while (0)
; #define PG8_LDA(dst, b, h) do { _Pragma("unroll") for (int m = 0; m < 4; ++m) _Pragma("unroll") for (int k = 0; k < 2; ++k) dst[m][k] = *(const PG8_LAS bf16x8*)(lds + PG8_SA(b, h) + aoff + m * 2048 + k * 1024); } while (0)
; #define PG8_LDB(dst, b, h) do { _Pragma("unroll") for (int n = 0; n < 2; ++n) _Pragma("unroll") for (int k = 0; k < 2; ++k) dst[n][k] = *(const PG8_LAS bf16x8*)(lds + PG8_SB(b, h) + boff + n * 2048 + k * 1024); } while (0)
; #define PG8_MMA(ai, bj, At, Bt) do { __builtin_amdgcn_s_setprio(1); _Pragma("unroll") for (int m = 0; m < 4; ++m) _Pragma("unroll") for (int n = 0; n < 2; ++n) _Pragma("unroll") for (int k = 0; k < 2; ++k) \
;         acc[ai][bj][m][n] = __builtin_amdgcn_mfma_f32_16x16x32_bf16(Bt[n][k], At[m][k], acc[ai][bj][m][n], 0, 0, 0); __builtin_amdgcn_s_setprio(0); } while (0)
; #define PG8_WAIT_V(n) asm volatile("s_waitcnt vmcnt(" #n ")" ::: "memory")
; #define PG8_WAIT_L(n) asm volatile("s_waitcnt lgkmcnt(" #n ")" ::: "memory")
; #define PG8_BAR __builtin_amdgcn_s_barrier()
; #define PG8_SCHED __builtin_amdgcn_sched_barrier(0)
; template <class Epi, class Sched, bool ALIGN_EPI = false, bool SP2 = false>
; __device__ __forceinline__ void gemm_phase(PG8_LAS unsigned char* lds, const Gemm g, const Sched& S, const Epi& E) {
;     ...
;             PG8_WAIT_V(8); PG8_WAIT_L(0); PG8_BAR; PG8_MMA(1, 0, At, B0); PG8_MMA(1, 1, At, B1); PG8_BAR; PG8_SCHED;
;             PG8_LDB(B0, 1, 0); PG8_LDB(B1, 1, 1); PG8_SCHED; PG8_LDA(At, 1, 0); PG8_STAGE(PG8_SA(0, 1), a2 + hstep, voffA);
;             PG8_WAIT_V(8); PG8_WAIT_L(0); PG8_BAR; PG8_MMA(0, 0, At, B0); PG8_MMA(0, 1, At, B1); PG8_BAR; PG8_SCHED;
	s_setprio 1
	s_waitcnt lgkmcnt(0)
	v_mfma_f32_16x16x32_bf16 v[62:65], v[146:149], v[186:189], 0
	v_mfma_f32_16x16x32_bf16 v[54:57], v[162:165], v[186:189], 0
	v_mfma_f32_16x16x32_bf16 v[46:49], v[146:149], v[194:197], 0
	v_mfma_f32_16x16x32_bf16 v[38:41], v[162:165], v[194:197], 0
	v_mfma_f32_16x16x32_bf16 v[30:33], v[146:149], v[202:205], 0
	v_mfma_f32_16x16x32_bf16 v[22:25], v[162:165], v[202:205], 0
	v_mfma_f32_16x16x32_bf16 v[14:17], v[146:149], v[210:213], 0
	v_mfma_f32_16x16x32_bf16 v[6:9], v[162:165], v[210:213], 0
	v_mfma_f32_16x16x32_bf16 v[62:65], v[158:161], v[190:193], v[62:65]
	v_mfma_f32_16x16x32_bf16 v[54:57], v[166:169], v[190:193], v[54:57]
	v_mfma_f32_16x16x32_bf16 v[46:49], v[158:161], v[198:201], v[46:49]
	v_mfma_f32_16x16x32_bf16 v[38:41], v[166:169], v[198:201], v[38:41]
	v_mfma_f32_16x16x32_bf16 v[30:33], v[158:161], v[206:209], v[30:33]
	v_mfma_f32_16x16x32_bf16 v[22:25], v[166:169], v[206:209], v[22:25]
	v_mfma_f32_16x16x32_bf16 v[14:17], v[158:161], v[214:217], v[14:17]
	v_mfma_f32_16x16x32_bf16 v[6:9], v[166:169], v[214:217], v[6:9]
	s_setprio 0
	s_setprio 1
	v_mfma_f32_16x16x32_bf16 v[58:61], v[170:173], v[186:189], 0
	v_mfma_f32_16x16x32_bf16 v[50:53], v[178:181], v[186:189], 0
	v_mfma_f32_16x16x32_bf16 v[42:45], v[170:173], v[194:197], 0
	v_mfma_f32_16x16x32_bf16 v[34:37], v[178:181], v[194:197], 0
	v_mfma_f32_16x16x32_bf16 v[26:29], v[170:173], v[202:205], 0
	v_mfma_f32_16x16x32_bf16 v[18:21], v[178:181], v[202:205], 0
	v_mfma_f32_16x16x32_bf16 v[10:13], v[170:173], v[210:213], 0
	v_mfma_f32_16x16x32_bf16 v[2:5], v[178:181], v[210:213], 0
	v_mfma_f32_16x16x32_bf16 v[58:61], v[174:177], v[190:193], v[58:61]
	v_mfma_f32_16x16x32_bf16 v[50:53], v[182:185], v[190:193], v[50:53]
	v_mfma_f32_16x16x32_bf16 v[42:45], v[174:177], v[198:201], v[42:45]
	v_mfma_f32_16x16x32_bf16 v[34:37], v[182:185], v[198:201], v[34:37]
	v_mfma_f32_16x16x32_bf16 v[26:29], v[174:177], v[206:209], v[26:29]
	v_mfma_f32_16x16x32_bf16 v[18:21], v[182:185], v[206:209], v[18:21]
	v_mfma_f32_16x16x32_bf16 v[10:13], v[174:177], v[214:217], v[10:13]
	v_mfma_f32_16x16x32_bf16 v[2:5], v[182:185], v[214:217], v[2:5]
	s_setprio 0
	s_barrier
	ds_read_b128 v[146:149], v155
	ds_read_b128 v[158:161], v155 offset:1024
	ds_read_b128 v[162:165], v155 offset:2048
	ds_read_b128 v[166:169], v155 offset:3072
	ds_read_b128 v[170:173], v156
	ds_read_b128 v[174:177], v156 offset:1024
	ds_read_b128 v[178:181], v156 offset:2048
	ds_read_b128 v[182:185], v156 offset:3072
	s_add_u32 s24, s24, 0x40000
	s_addc_u32 s25, s25, 0
	s_mov_b32 m0, s43
	v_lshl_add_u64 v[226:227], s[24:25], 0, v[136:137]
	ds_read_b128 v[186:189], v154 offset:32768
	ds_read_b128 v[190:193], v154 offset:33792
	ds_read_b128 v[194:197], v154 offset:34816
	ds_read_b128 v[198:201], v154 offset:35840
	ds_read_b128 v[202:205], v154 offset:36864
	ds_read_b128 v[206:209], v154 offset:37888
	ds_read_b128 v[210:213], v154 offset:38912
	ds_read_b128 v[214:217], v154 offset:39936
	global_load_lds_dwordx4 v[226:227], off
	v_lshl_add_u64 v[226:227], s[24:25], 0, v[132:133]
	s_mov_b32 m0, s44
	s_nop 0
	global_load_lds_dwordx4 v[226:227], off
	s_waitcnt vmcnt(8)
	s_waitcnt lgkmcnt(0)
	s_barrier
	s_setprio 1
	s_waitcnt lgkmcnt(0)
	v_mfma_f32_16x16x32_bf16 v[126:129], v[146:149], v[186:189], v[126:129]
	v_mfma_f32_16x16x32_bf16 v[118:121], v[162:165], v[186:189], v[118:121]
	v_mfma_f32_16x16x32_bf16 v[110:113], v[146:149], v[194:197], v[110:113]
	v_mfma_f32_16x16x32_bf16 v[102:105], v[162:165], v[194:197], v[102:105]
	v_mfma_f32_16x16x32_bf16 v[94:97], v[146:149], v[202:205], v[94:97]
	v_mfma_f32_16x16x32_bf16 v[86:89], v[162:165], v[202:205], v[86:89]
	v_mfma_f32_16x16x32_bf16 v[78:81], v[146:149], v[210:213], v[78:81]
	v_mfma_f32_16x16x32_bf16 v[70:73], v[162:165], v[210:213], v[70:73]
	v_mfma_f32_16x16x32_bf16 v[126:129], v[158:161], v[190:193], v[126:129]
	v_mfma_f32_16x16x32_bf16 v[118:121], v[166:169], v[190:193], v[118:121]
	v_mfma_f32_16x16x32_bf16 v[110:113], v[158:161], v[198:201], v[110:113]
	v_mfma_f32_16x16x32_bf16 v[102:105], v[166:169], v[198:201], v[102:105]
	v_mfma_f32_16x16x32_bf16 v[94:97], v[158:161], v[206:209], v[94:97]
	v_mfma_f32_16x16x32_bf16 v[86:89], v[166:169], v[206:209], v[86:89]
	v_mfma_f32_16x16x32_bf16 v[78:81], v[158:161], v[214:217], v[78:81]
	v_mfma_f32_16x16x32_bf16 v[70:73], v[166:169], v[214:217], v[70:73]
	s_setprio 0
	s_setprio 1
	v_mfma_f32_16x16x32_bf16 v[122:125], v[170:173], v[186:189], v[122:125]
	v_mfma_f32_16x16x32_bf16 v[114:117], v[178:181], v[186:189], v[114:117]
	v_mfma_f32_16x16x32_bf16 v[106:109], v[170:173], v[194:197], v[106:109]
	v_mfma_f32_16x16x32_bf16 v[98:101], v[178:181], v[194:197], v[98:101]
	v_mfma_f32_16x16x32_bf16 v[90:93], v[170:173], v[202:205], v[90:93]
	v_mfma_f32_16x16x32_bf16 v[82:85], v[178:181], v[202:205], v[82:85]
	v_mfma_f32_16x16x32_bf16 v[74:77], v[170:173], v[210:213], v[74:77]
	v_mfma_f32_16x16x32_bf16 v[66:69], v[178:181], v[210:213], v[66:69]
	v_mfma_f32_16x16x32_bf16 v[122:125], v[174:177], v[190:193], v[122:125]
	v_mfma_f32_16x16x32_bf16 v[114:117], v[182:185], v[190:193], v[114:117]
	v_mfma_f32_16x16x32_bf16 v[106:109], v[174:177], v[198:201], v[106:109]
	v_mfma_f32_16x16x32_bf16 v[98:101], v[182:185], v[198:201], v[98:101]
	v_mfma_f32_16x16x32_bf16 v[90:93], v[174:177], v[206:209], v[90:93]
	v_mfma_f32_16x16x32_bf16 v[82:85], v[182:185], v[206:209], v[82:85]
	v_mfma_f32_16x16x32_bf16 v[74:77], v[174:177], v[214:217], v[74:77]
	v_mfma_f32_16x16x32_bf16 v[66:69], v[182:185], v[214:217], v[66:69]
	s_setprio 0
	s_barrier
; #define PG8_STAGE(bufoff, gbase, voff) do { _Pragma("unroll") for (int _i = 0; _i < 2; ++_i) \
;         __builtin_amdgcn_global_load_lds((const unsigned*)((const char*)(gbase) + (voff)[_i]), (PG8_LAS unsigned*)(lds + (bufoff) + ldsw + _i * 8192), 16, 0, 0); } while (0)
; #define PG8_LDA(dst, b, h) do { _Pragma("unroll") for (int m = 0; m < 4; ++m) _Pragma("unroll") for (int k = 0; k < 2; ++k) dst[m][k] = *(const PG8_LAS bf16x8*)(lds + PG8_SA(b, h) + aoff + m * 2048 + k * 1024); } while (0)
; #define PG8_LDB(dst, b, h) do { _Pragma("unroll") for (int n = 0; n < 2; ++n) _Pragma("unroll") for (int k = 0; k < 2; ++k) dst[n][k] = *(const PG8_LAS bf16x8*)(lds + PG8_SB(b, h) + boff + n * 2048 + k * 1024); } while (0)
; #define PG8_MMA(ai, bj, At, Bt) do { __builtin_amdgcn_s_setprio(1); _Pragma("unroll") for (int m = 0; m < 4; ++m) _Pragma("unroll") for (int n = 0; n < 2; ++n) _Pragma("unroll") for (int k = 0; k < 2; ++k) \
;         acc[ai][bj][m][n] = __builtin_amdgcn_mfma_f32_16x16x32_bf16(Bt[n][k], At[m][k], acc[ai][bj][m][n], 0, 0, 0); __builtin_amdgcn_s_setprio(0); } while (0)
; #define PG8_WAIT_V(n) asm volatile("s_waitcnt vmcnt(" #n ")" ::: "memory")
; #define PG8_BAR __builtin_amdgcn_s_barrier()
; template <class Epi, class Sched, bool ALIGN_EPI = false, bool SP2 = false>
; __device__ __forceinline__ void gemm_phase(PG8_LAS unsigned char* lds, const Gemm g, const Sched& S, const Epi& E) {
;     ...
;         for (int t = 0; t < nt; t += 2) {
;             const bool last = (t == nt - 2);
;             const char* a1 = cA + (size_t)(t + 1) * kstep;
;             const char* a2 = last ? nA : cA + (size_t)(t + 2) * kstep; const char* b2 = last ? nB : cB + (size_t)(t + 2) * kstep;
;             const char* a3 = a2 + kstep; const char* b3 = b2 + kstep;
;             if (last && has_next) S.a_ready(nxt);
;             if constexpr (SP2) {
;             PG8_LDB(B0, 0, 0); PG8_LDB(B1, 0, 1); PG8_SCHED; PG8_LDA(At, 0, 0); PG8_STAGE(PG8_SA(1, 1), a1 + hstep, voffA);
;             PG8_WAIT_V(8); PG8_WAIT_L(0); PG8_BAR; PG8_MMA(0, 0, At, B0); PG8_MMA(0, 1, At, B1); PG8_BAR; PG8_SCHED;
;     ...
;             PG8_LDA(At, 1, 1); PG8_STAGE(PG8_SB(1, 0), b3, voffB); PG8_STAGE(PG8_SB(1, 1), b3 + hstep, voffB); PG8_STAGE(PG8_SA(1, 0), a3, voffA);
;             PG8_WAIT_V(8); PG8_WAIT_L(0); PG8_BAR; PG8_MMA(1, 0, At, B0); PG8_MMA(1, 1, At, B1); PG8_BAR; PG8_SCHED;
	s_mov_b32 m0, s45
	v_lshl_add_u64 v[218:219], v[218:219], 0, s[6:7]
	s_add_u32 s22, s22, 0x40080
	ds_read_b128 v[186:189], v154 offset:49152
	ds_read_b128 v[190:193], v154 offset:50176
	ds_read_b128 v[194:197], v154 offset:51200
	ds_read_b128 v[198:201], v154 offset:52224
	ds_read_b128 v[202:205], v154 offset:53248
	ds_read_b128 v[206:209], v154 offset:54272
	ds_read_b128 v[210:213], v154 offset:55296
	ds_read_b128 v[214:217], v154 offset:56320
	global_load_lds_dwordx4 v[218:219], off
	v_lshl_add_u64 v[218:219], v[220:221], 0, s[6:7]
	s_mov_b32 m0, s46
	s_addc_u32 s23, s23, 0
	global_load_lds_dwordx4 v[218:219], off
	v_lshl_add_u64 v[218:219], s[22:23], 0, v[134:135]
	s_mov_b32 m0, s53
	s_nop 0
	global_load_lds_dwordx4 v[218:219], off
	v_lshl_add_u64 v[218:219], s[22:23], 0, v[130:131]
	s_mov_b32 m0, s56
	s_nop 0
	global_load_lds_dwordx4 v[218:219], off
	v_lshl_add_u64 v[218:219], v[222:223], 0, s[6:7]
	s_mov_b32 m0, s47
	s_nop 0
	global_load_lds_dwordx4 v[218:219], off
	v_lshl_add_u64 v[218:219], v[224:225], 0, s[6:7]
	s_mov_b32 m0, s52
	s_nop 0
	global_load_lds_dwordx4 v[218:219], off
	s_waitcnt vmcnt(8)
	s_waitcnt lgkmcnt(0)
	s_barrier
	s_setprio 1
	s_waitcnt lgkmcnt(0)
	v_mfma_f32_16x16x32_bf16 v[62:65], v[146:149], v[186:189], v[62:65]
	v_mfma_f32_16x16x32_bf16 v[54:57], v[162:165], v[186:189], v[54:57]
	v_mfma_f32_16x16x32_bf16 v[46:49], v[146:149], v[194:197], v[46:49]
	v_mfma_f32_16x16x32_bf16 v[38:41], v[162:165], v[194:197], v[38:41]
	v_mfma_f32_16x16x32_bf16 v[30:33], v[146:149], v[202:205], v[30:33]
	v_mfma_f32_16x16x32_bf16 v[22:25], v[162:165], v[202:205], v[22:25]
	v_mfma_f32_16x16x32_bf16 v[14:17], v[146:149], v[210:213], v[14:17]
	v_mfma_f32_16x16x32_bf16 v[6:9], v[162:165], v[210:213], v[6:9]
	v_mfma_f32_16x16x32_bf16 v[62:65], v[158:161], v[190:193], v[62:65]
	v_mfma_f32_16x16x32_bf16 v[54:57], v[166:169], v[190:193], v[54:57]
	v_mfma_f32_16x16x32_bf16 v[46:49], v[158:161], v[198:201], v[46:49]
	v_mfma_f32_16x16x32_bf16 v[38:41], v[166:169], v[198:201], v[38:41]
	v_mfma_f32_16x16x32_bf16 v[30:33], v[158:161], v[206:209], v[30:33]
	v_mfma_f32_16x16x32_bf16 v[22:25], v[166:169], v[206:209], v[22:25]
	v_mfma_f32_16x16x32_bf16 v[14:17], v[158:161], v[214:217], v[14:17]
	v_mfma_f32_16x16x32_bf16 v[6:9], v[166:169], v[214:217], v[6:9]
	s_setprio 0
	s_setprio 1
	v_mfma_f32_16x16x32_bf16 v[58:61], v[170:173], v[186:189], v[58:61]
	v_mfma_f32_16x16x32_bf16 v[50:53], v[178:181], v[186:189], v[50:53]
	v_mfma_f32_16x16x32_bf16 v[42:45], v[170:173], v[194:197], v[42:45]
	v_mfma_f32_16x16x32_bf16 v[34:37], v[178:181], v[194:197], v[34:37]
	v_mfma_f32_16x16x32_bf16 v[26:29], v[170:173], v[202:205], v[26:29]
	v_mfma_f32_16x16x32_bf16 v[18:21], v[178:181], v[202:205], v[18:21]
	v_mfma_f32_16x16x32_bf16 v[10:13], v[170:173], v[210:213], v[10:13]
	v_mfma_f32_16x16x32_bf16 v[2:5], v[178:181], v[210:213], v[2:5]
	v_mfma_f32_16x16x32_bf16 v[58:61], v[174:177], v[190:193], v[58:61]
	v_mfma_f32_16x16x32_bf16 v[50:53], v[182:185], v[190:193], v[50:53]
	v_mfma_f32_16x16x32_bf16 v[42:45], v[174:177], v[198:201], v[42:45]
	v_mfma_f32_16x16x32_bf16 v[34:37], v[182:185], v[198:201], v[34:37]
	v_mfma_f32_16x16x32_bf16 v[26:29], v[174:177], v[206:209], v[26:29]
	v_mfma_f32_16x16x32_bf16 v[18:21], v[182:185], v[206:209], v[18:21]
	v_mfma_f32_16x16x32_bf16 v[10:13], v[174:177], v[214:217], v[10:13]
	v_mfma_f32_16x16x32_bf16 v[2:5], v[182:185], v[214:217], v[2:5]
	s_setprio 0
	s_add_i32 s54, s54, 2
	s_add_u32 s50, s50, 0x100
	s_addc_u32 s51, s51, 0
	s_add_u32 s20, s20, 0x100
	s_addc_u32 s21, s21, 0
	s_cmp_gt_u32 s54, 13
	s_barrier
.LBB0_1038:
	ds_read_b128 v[146:149], v152
	ds_read_b128 v[158:161], v152 offset:1024
	ds_read_b128 v[162:165], v152 offset:2048
	ds_read_b128 v[166:169], v152 offset:3072
	ds_read_b128 v[170:173], v153
	ds_read_b128 v[174:177], v153 offset:1024
	ds_read_b128 v[178:181], v153 offset:2048
	ds_read_b128 v[182:185], v153 offset:3072
	s_add_u32 s22, s20, 0xfffc0080
	s_addc_u32 s23, s21, -1
	s_cmp_eq_u32 s54, 12
	s_cselect_b32 s25, s13, s23
	s_cselect_b32 s24, s48, s22
	s_cselect_b32 s23, s11, s51
	s_cselect_b32 s22, s49, s50
	v_lshl_add_u64 v[218:219], s[20:21], 0, v[140:141]
	s_add_i32 m0, s41, 0xc000
	ds_read_b128 v[186:189], v154
	ds_read_b128 v[190:193], v154 offset:1024
	ds_read_b128 v[194:197], v154 offset:2048
	ds_read_b128 v[198:201], v154 offset:3072
	ds_read_b128 v[202:205], v154 offset:4096
	ds_read_b128 v[206:209], v154 offset:5120
	ds_read_b128 v[210:213], v154 offset:6144
	ds_read_b128 v[214:217], v154 offset:7168
	global_load_lds_dwordx4 v[218:219], off
	v_lshl_add_u64 v[218:219], s[20:21], 0, v[138:139]
	s_add_i32 m0, s41, 0xe000
	s_nop 0
	global_load_lds_dwordx4 v[218:219], off
	s_waitcnt vmcnt(8)
	s_waitcnt lgkmcnt(0)
	s_barrier
; #define PG8_STAGE(bufoff, gbase, voff) do { _Pragma("unroll") for (int _i = 0; _i < 2; ++_i) \
;         __builtin_amdgcn_global_load_lds((const unsigned*)((const char*)(gbase) + (voff)[_i]), (PG8_LAS unsigned*)(lds + (bufoff) + ldsw + _i * 8192), 16, 0, 0); } while (0)
; #define PG8_LDA(dst, b, h) do { _Pragma("unroll") for (int m = 0; m < 4; ++m) _Pragma("unroll") for (int k = 0; k < 2; ++k) dst[m][k] = *(const PG8_LAS bf16x8*)(lds + PG8_SA(b, h) + aoff + m * 2048 + k * 1024); } while (0)
; #define PG8_LDB(dst, b, h) do { _Pragma("unroll") for (int n = 0; n < 2; ++n) _Pragma("unroll") for (int k = 0; k < 2; ++k) dst[n][k] = *(const PG8_LAS bf16x8*)(lds + PG8_SB(b, h) + boff + n * 2048 + k * 1024); } while (0)
; #define PG8_MMA(ai, bj, At, Bt) do { __builtin_amdgcn_s_setprio(1); _Pragma("unroll") for (int m = 0; m < 4; ++m) _Pragma("unroll") for (int n = 0; n < 2; ++n) _Pragma("unroll") for (int k = 0; k < 2; ++k) \
;         acc[ai][bj][m][n] = __builtin_amdgcn_mfma_f32_16x16x32_bf16(Bt[n][k], At[m][k], acc[ai][bj][m][n], 0, 0, 0); __builtin_amdgcn_s_setprio(0); } while (0)
; #define PG8_WAIT_V(n) asm volatile("s_waitcnt vmcnt(" #n ")" ::: "memory")
; #define PG8_WAIT_L(n) asm volatile("s_waitcnt lgkmcnt(" #n ")" ::: "memory")
; #define PG8_BAR __builtin_amdgcn_s_barrier()
; #define PG8_SCHED __builtin_amdgcn_sched_barrier(0)
; template <class Epi, class Sched, bool ALIGN_EPI = false, bool SP2 = false>
; __device__ __forceinline__ void gemm_phase(PG8_LAS unsigned char* lds, const Gemm g, const Sched& S, const Epi& E) {
;     ...
;             PG8_LDB(B0, 0, 0); PG8_LDB(B1, 0, 1); PG8_SCHED; PG8_LDA(At, 0, 0); PG8_STAGE(PG8_SA(1, 1), a1 + hstep, voffA);
;             PG8_WAIT_V(8); PG8_WAIT_L(0); PG8_BAR; PG8_MMA(0, 0, At, B0); PG8_MMA(0, 1, At, B1); PG8_BAR; PG8_SCHED;
;             PG8_LDA(At, 0, 1); PG8_STAGE(PG8_SB(0, 0), b2, voffB); PG8_STAGE(PG8_SB(0, 1), b2 + hstep, voffB); PG8_STAGE(PG8_SA(0, 0), a2, voffA);
;             PG8_WAIT_V(8); PG8_WAIT_L(0); PG8_BAR; PG8_MMA(1, 0, At, B0); PG8_MMA(1, 1, At, B1); PG8_BAR; PG8_SCHED;
	s_setprio 1
	s_waitcnt lgkmcnt(0)
	v_mfma_f32_16x16x32_bf16 v[126:129], v[146:149], v[186:189], v[126:129]
	v_mfma_f32_16x16x32_bf16 v[118:121], v[162:165], v[186:189], v[118:121]
	v_mfma_f32_16x16x32_bf16 v[110:113], v[146:149], v[194:197], v[110:113]
	v_mfma_f32_16x16x32_bf16 v[102:105], v[162:165], v[194:197], v[102:105]
	v_mfma_f32_16x16x32_bf16 v[94:97], v[146:149], v[202:205], v[94:97]
	v_mfma_f32_16x16x32_bf16 v[86:89], v[162:165], v[202:205], v[86:89]
	v_mfma_f32_16x16x32_bf16 v[78:81], v[146:149], v[210:213], v[78:81]
	v_mfma_f32_16x16x32_bf16 v[70:73], v[162:165], v[210:213], v[70:73]
	v_mfma_f32_16x16x32_bf16 v[126:129], v[158:161], v[190:193], v[126:129]
	v_mfma_f32_16x16x32_bf16 v[118:121], v[166:169], v[190:193], v[118:121]
	v_mfma_f32_16x16x32_bf16 v[110:113], v[158:161], v[198:201], v[110:113]
	v_mfma_f32_16x16x32_bf16 v[102:105], v[166:169], v[198:201], v[102:105]
	v_mfma_f32_16x16x32_bf16 v[94:97], v[158:161], v[206:209], v[94:97]
	v_mfma_f32_16x16x32_bf16 v[86:89], v[166:169], v[206:209], v[86:89]
	v_mfma_f32_16x16x32_bf16 v[78:81], v[158:161], v[214:217], v[78:81]
	v_mfma_f32_16x16x32_bf16 v[70:73], v[166:169], v[214:217], v[70:73]
	s_setprio 0
	s_setprio 1
	v_mfma_f32_16x16x32_bf16 v[122:125], v[170:173], v[186:189], v[122:125]
	v_mfma_f32_16x16x32_bf16 v[114:117], v[178:181], v[186:189], v[114:117]
	v_mfma_f32_16x16x32_bf16 v[106:109], v[170:173], v[194:197], v[106:109]
	v_mfma_f32_16x16x32_bf16 v[98:101], v[178:181], v[194:197], v[98:101]
	v_mfma_f32_16x16x32_bf16 v[90:93], v[170:173], v[202:205], v[90:93]
	v_mfma_f32_16x16x32_bf16 v[82:85], v[178:181], v[202:205], v[82:85]
	v_mfma_f32_16x16x32_bf16 v[74:77], v[170:173], v[210:213], v[74:77]
	v_mfma_f32_16x16x32_bf16 v[66:69], v[178:181], v[210:213], v[66:69]
	v_mfma_f32_16x16x32_bf16 v[122:125], v[174:177], v[190:193], v[122:125]
	v_mfma_f32_16x16x32_bf16 v[114:117], v[182:185], v[190:193], v[114:117]
	v_mfma_f32_16x16x32_bf16 v[106:109], v[174:177], v[198:201], v[106:109]
	v_mfma_f32_16x16x32_bf16 v[98:101], v[182:185], v[198:201], v[98:101]
	v_mfma_f32_16x16x32_bf16 v[90:93], v[174:177], v[206:209], v[90:93]
	v_mfma_f32_16x16x32_bf16 v[82:85], v[182:185], v[206:209], v[82:85]
	v_mfma_f32_16x16x32_bf16 v[74:77], v[174:177], v[214:217], v[74:77]
	v_mfma_f32_16x16x32_bf16 v[66:69], v[182:185], v[214:217], v[66:69]
	s_setprio 0
	s_barrier
	s_mov_b32 m0, s19
	v_lshl_add_u64 v[218:219], s[22:23], 0, v[134:135]
	s_add_u32 s58, s22, 0x40000
	ds_read_b128 v[186:189], v154 offset:16384
	ds_read_b128 v[190:193], v154 offset:17408
	ds_read_b128 v[194:197], v154 offset:18432
	ds_read_b128 v[198:201], v154 offset:19456
	ds_read_b128 v[202:205], v154 offset:20480
	ds_read_b128 v[206:209], v154 offset:21504
	ds_read_b128 v[210:213], v154 offset:22528
	ds_read_b128 v[214:217], v154 offset:23552
	global_load_lds_dwordx4 v[218:219], off
	v_lshl_add_u64 v[220:221], s[22:23], 0, v[130:131]
	s_mov_b32 m0, s38
	s_addc_u32 s59, s23, 0
	global_load_lds_dwordx4 v[220:221], off
	v_lshl_add_u64 v[222:223], s[58:59], 0, v[134:135]
	s_mov_b32 m0, s39
	v_lshl_add_u64 v[224:225], s[24:25], 0, v[132:133]
	global_load_lds_dwordx4 v[222:223], off
	v_lshl_add_u64 v[222:223], s[58:59], 0, v[130:131]
	s_mov_b32 m0, s40
	s_nop 0
	global_load_lds_dwordx4 v[222:223], off
	v_lshl_add_u64 v[222:223], s[24:25], 0, v[136:137]
	s_mov_b32 m0, s41
	s_nop 0
	global_load_lds_dwordx4 v[222:223], off
	s_mov_b32 m0, s42
	s_nop 0
	global_load_lds_dwordx4 v[224:225], off
	s_waitcnt vmcnt(8)
	s_waitcnt lgkmcnt(0)
	s_barrier
	s_setprio 1
	s_waitcnt lgkmcnt(0)
	v_mfma_f32_16x16x32_bf16 v[62:65], v[146:149], v[186:189], v[62:65]
	v_mfma_f32_16x16x32_bf16 v[54:57], v[162:165], v[186:189], v[54:57]
	v_mfma_f32_16x16x32_bf16 v[46:49], v[146:149], v[194:197], v[46:49]
	v_mfma_f32_16x16x32_bf16 v[38:41], v[162:165], v[194:197], v[38:41]
	v_mfma_f32_16x16x32_bf16 v[30:33], v[146:149], v[202:205], v[30:33]
	v_mfma_f32_16x16x32_bf16 v[22:25], v[162:165], v[202:205], v[22:25]
	v_mfma_f32_16x16x32_bf16 v[14:17], v[146:149], v[210:213], v[14:17]
	v_mfma_f32_16x16x32_bf16 v[6:9], v[162:165], v[210:213], v[6:9]
	v_mfma_f32_16x16x32_bf16 v[62:65], v[158:161], v[190:193], v[62:65]
	v_mfma_f32_16x16x32_bf16 v[54:57], v[166:169], v[190:193], v[54:57]
	v_mfma_f32_16x16x32_bf16 v[46:49], v[158:161], v[198:201], v[46:49]
	v_mfma_f32_16x16x32_bf16 v[38:41], v[166:169], v[198:201], v[38:41]
	v_mfma_f32_16x16x32_bf16 v[30:33], v[158:161], v[206:209], v[30:33]
	v_mfma_f32_16x16x32_bf16 v[22:25], v[166:169], v[206:209], v[22:25]
	v_mfma_f32_16x16x32_bf16 v[14:17], v[158:161], v[214:217], v[14:17]
	v_mfma_f32_16x16x32_bf16 v[6:9], v[166:169], v[214:217], v[6:9]
	s_setprio 0
	s_setprio 1
	v_mfma_f32_16x16x32_bf16 v[58:61], v[170:173], v[186:189], v[58:61]
	v_mfma_f32_16x16x32_bf16 v[50:53], v[178:181], v[186:189], v[50:53]
	v_mfma_f32_16x16x32_bf16 v[42:45], v[170:173], v[194:197], v[42:45]
	v_mfma_f32_16x16x32_bf16 v[34:37], v[178:181], v[194:197], v[34:37]
	v_mfma_f32_16x16x32_bf16 v[26:29], v[170:173], v[202:205], v[26:29]
	v_mfma_f32_16x16x32_bf16 v[18:21], v[178:181], v[202:205], v[18:21]
	v_mfma_f32_16x16x32_bf16 v[10:13], v[170:173], v[210:213], v[10:13]
	v_mfma_f32_16x16x32_bf16 v[2:5], v[178:181], v[210:213], v[2:5]
	v_mfma_f32_16x16x32_bf16 v[58:61], v[174:177], v[190:193], v[58:61]
	v_mfma_f32_16x16x32_bf16 v[50:53], v[182:185], v[190:193], v[50:53]
	v_mfma_f32_16x16x32_bf16 v[42:45], v[174:177], v[198:201], v[42:45]
	v_mfma_f32_16x16x32_bf16 v[34:37], v[182:185], v[198:201], v[34:37]
	v_mfma_f32_16x16x32_bf16 v[26:29], v[174:177], v[206:209], v[26:29]
	v_mfma_f32_16x16x32_bf16 v[18:21], v[182:185], v[206:209], v[18:21]
	v_mfma_f32_16x16x32_bf16 v[10:13], v[174:177], v[214:217], v[10:13]
	v_mfma_f32_16x16x32_bf16 v[2:5], v[182:185], v[214:217], v[2:5]
	s_setprio 0
	s_barrier
; #define PG8_STAGE(bufoff, gbase, voff) do { _Pragma("unroll") for (int _i = 0; _i < 2; ++_i) \
;         __builtin_amdgcn_global_load_lds((const unsigned*)((const char*)(gbase) + (voff)[_i]), (PG8_LAS unsigned*)(lds + (bufoff) + ldsw + _i * 8192), 16, 0, 0); } while (0)
; #define PG8_LDA(dst, b, h) do { _Pragma("unroll") for (int m = 0; m < 4; ++m) _Pragma("unroll") for (int k = 0; k < 2; ++k) dst[m][k] = *(const PG8_LAS bf16x8*)(lds + PG8_SA(b, h) + aoff + m * 2048 + k * 1024); } while (0)
; #define PG8_LDB(dst, b, h) do { _Pragma("unroll") for (int n = 0; n < 2; ++n) _Pragma("unroll") for (int k = 0; k < 2; ++k) dst[n][k] = *(const PG8_LAS bf16x8*)(lds + PG8_SB(b, h) + boff + n * 2048 + k * 1024); } while (0)
; #define PG8_MMA(ai, bj, At, Bt) do { __builtin_amdgcn_s_setprio(1); _Pragma("unroll") for (int m = 0; m < 4; ++m) _Pragma("unroll") for (int n = 0; n < 2; ++n) _Pragma("unroll") for (int k = 0; k < 2; ++k) \
;         acc[ai][bj][m][n] = __builtin_amdgcn_mfma_f32_16x16x32_bf16(Bt[n][k], At[m][k], acc[ai][bj][m][n], 0, 0, 0); __builtin_amdgcn_s_setprio(0); } while (0)
; #define PG8_WAIT_V(n) asm volatile("s_waitcnt vmcnt(" #n ")" ::: "memory")
; #define PG8_WAIT_L(n) asm volatile("s_waitcnt lgkmcnt(" #n ")" ::: "memory")
; #define PG8_BAR __builtin_amdgcn_s_barrier()
; template <class Epi, class Sched, bool ALIGN_EPI = false, bool SP2 = false>
; __device__ __forceinline__ void gemm_phase(PG8_LAS unsigned char* lds, const Gemm g, const Sched& S, const Epi& E) {
;     ...
;         for (int t = 0; t < nt; t += 2) {
;             const bool last = (t == nt - 2);
;             const char* a1 = cA + (size_t)(t + 1) * kstep;
;             const char* a2 = last ? nA : cA + (size_t)(t + 2) * kstep; const char* b2 = last ? nB : cB + (size_t)(t + 2) * kstep;
;             const char* a3 = a2 + kstep; const char* b3 = b2 + kstep;
;     ...
;             PG8_LDB(B0, 1, 0); PG8_LDB(B1, 1, 1); PG8_SCHED; PG8_LDA(At, 1, 0); PG8_STAGE(PG8_SA(0, 1), a2 + hstep, voffA);
;             PG8_WAIT_V(8); PG8_WAIT_L(0); PG8_BAR; PG8_MMA(0, 0, At, B0); PG8_MMA(0, 1, At, B1); PG8_BAR; PG8_SCHED;
;             PG8_LDA(At, 1, 1); PG8_STAGE(PG8_SB(1, 0), b3, voffB); PG8_STAGE(PG8_SB(1, 1), b3 + hstep, voffB); PG8_STAGE(PG8_SA(1, 0), a3, voffA);
;             PG8_WAIT_V(8); PG8_WAIT_L(0); PG8_BAR; PG8_MMA(1, 0, At, B0); PG8_MMA(1, 1, At, B1); PG8_BAR; PG8_SCHED;
	ds_read_b128 v[146:149], v155
	ds_read_b128 v[158:161], v155 offset:1024
	ds_read_b128 v[162:165], v155 offset:2048
	ds_read_b128 v[166:169], v155 offset:3072
	ds_read_b128 v[170:173], v156
	ds_read_b128 v[174:177], v156 offset:1024
	ds_read_b128 v[178:181], v156 offset:2048
	ds_read_b128 v[182:185], v156 offset:3072
	s_add_u32 s24, s24, 0x40000
	s_addc_u32 s25, s25, 0
	s_mov_b32 m0, s43
	v_lshl_add_u64 v[226:227], s[24:25], 0, v[136:137]
	ds_read_b128 v[186:189], v154 offset:32768
	ds_read_b128 v[190:193], v154 offset:33792
	ds_read_b128 v[194:197], v154 offset:34816
	ds_read_b128 v[198:201], v154 offset:35840
	ds_read_b128 v[202:205], v154 offset:36864
	ds_read_b128 v[206:209], v154 offset:37888
	ds_read_b128 v[210:213], v154 offset:38912
	ds_read_b128 v[214:217], v154 offset:39936
	global_load_lds_dwordx4 v[226:227], off
	v_lshl_add_u64 v[226:227], s[24:25], 0, v[132:133]
	s_mov_b32 m0, s44
	s_nop 0
	global_load_lds_dwordx4 v[226:227], off
	s_waitcnt vmcnt(8)
	s_waitcnt lgkmcnt(0)
	s_barrier
	s_setprio 1
	s_waitcnt lgkmcnt(0)
	v_mfma_f32_16x16x32_bf16 v[126:129], v[146:149], v[186:189], v[126:129]
	v_mfma_f32_16x16x32_bf16 v[118:121], v[162:165], v[186:189], v[118:121]
	v_mfma_f32_16x16x32_bf16 v[110:113], v[146:149], v[194:197], v[110:113]
	v_mfma_f32_16x16x32_bf16 v[102:105], v[162:165], v[194:197], v[102:105]
	v_mfma_f32_16x16x32_bf16 v[94:97], v[146:149], v[202:205], v[94:97]
	v_mfma_f32_16x16x32_bf16 v[86:89], v[162:165], v[202:205], v[86:89]
	v_mfma_f32_16x16x32_bf16 v[78:81], v[146:149], v[210:213], v[78:81]
	v_mfma_f32_16x16x32_bf16 v[70:73], v[162:165], v[210:213], v[70:73]
	v_mfma_f32_16x16x32_bf16 v[126:129], v[158:161], v[190:193], v[126:129]
	v_mfma_f32_16x16x32_bf16 v[118:121], v[166:169], v[190:193], v[118:121]
	v_mfma_f32_16x16x32_bf16 v[110:113], v[158:161], v[198:201], v[110:113]
	v_mfma_f32_16x16x32_bf16 v[102:105], v[166:169], v[198:201], v[102:105]
	v_mfma_f32_16x16x32_bf16 v[94:97], v[158:161], v[206:209], v[94:97]
	v_mfma_f32_16x16x32_bf16 v[86:89], v[166:169], v[206:209], v[86:89]
	v_mfma_f32_16x16x32_bf16 v[78:81], v[158:161], v[214:217], v[78:81]
	v_mfma_f32_16x16x32_bf16 v[70:73], v[166:169], v[214:217], v[70:73]
	s_setprio 0
	s_setprio 1
	v_mfma_f32_16x16x32_bf16 v[122:125], v[170:173], v[186:189], v[122:125]
	v_mfma_f32_16x16x32_bf16 v[114:117], v[178:181], v[186:189], v[114:117]
	v_mfma_f32_16x16x32_bf16 v[106:109], v[170:173], v[194:197], v[106:109]
	v_mfma_f32_16x16x32_bf16 v[98:101], v[178:181], v[194:197], v[98:101]
	v_mfma_f32_16x16x32_bf16 v[90:93], v[170:173], v[202:205], v[90:93]
	v_mfma_f32_16x16x32_bf16 v[82:85], v[178:181], v[202:205], v[82:85]
	v_mfma_f32_16x16x32_bf16 v[74:77], v[170:173], v[210:213], v[74:77]
	v_mfma_f32_16x16x32_bf16 v[66:69], v[178:181], v[210:213], v[66:69]
	v_mfma_f32_16x16x32_bf16 v[122:125], v[174:177], v[190:193], v[122:125]
	v_mfma_f32_16x16x32_bf16 v[114:117], v[182:185], v[190:193], v[114:117]
	v_mfma_f32_16x16x32_bf16 v[106:109], v[174:177], v[198:201], v[106:109]
	v_mfma_f32_16x16x32_bf16 v[98:101], v[182:185], v[198:201], v[98:101]
	v_mfma_f32_16x16x32_bf16 v[90:93], v[174:177], v[206:209], v[90:93]
	v_mfma_f32_16x16x32_bf16 v[82:85], v[182:185], v[206:209], v[82:85]
	v_mfma_f32_16x16x32_bf16 v[74:77], v[174:177], v[214:217], v[74:77]
	v_mfma_f32_16x16x32_bf16 v[66:69], v[182:185], v[214:217], v[66:69]
	s_setprio 0
	s_barrier
	s_mov_b32 m0, s45
	v_lshl_add_u64 v[218:219], v[218:219], 0, s[6:7]
	s_add_u32 s22, s22, 0x40080
	ds_read_b128 v[186:189], v154 offset:49152
	ds_read_b128 v[190:193], v154 offset:50176
	ds_read_b128 v[194:197], v154 offset:51200
	ds_read_b128 v[198:201], v154 offset:52224
	ds_read_b128 v[202:205], v154 offset:53248
	ds_read_b128 v[206:209], v154 offset:54272
	ds_read_b128 v[210:213], v154 offset:55296
	ds_read_b128 v[214:217], v154 offset:56320
	global_load_lds_dwordx4 v[218:219], off
	v_lshl_add_u64 v[218:219], v[220:221], 0, s[6:7]
	s_mov_b32 m0, s46
	s_addc_u32 s23, s23, 0
	global_load_lds_dwordx4 v[218:219], off
	v_lshl_add_u64 v[218:219], s[22:23], 0, v[134:135]
	s_mov_b32 m0, s53
	s_nop 0
	global_load_lds_dwordx4 v[218:219], off
	v_lshl_add_u64 v[218:219], s[22:23], 0, v[130:131]
	s_mov_b32 m0, s56
	s_nop 0
	global_load_lds_dwordx4 v[218:219], off
	v_lshl_add_u64 v[218:219], v[222:223], 0, s[6:7]
	s_mov_b32 m0, s47
	s_nop 0
	global_load_lds_dwordx4 v[218:219], off
	v_lshl_add_u64 v[218:219], v[224:225], 0, s[6:7]
	s_mov_b32 m0, s52
	s_nop 0
	global_load_lds_dwordx4 v[218:219], off
	s_waitcnt vmcnt(8)
	s_waitcnt lgkmcnt(0)
	s_barrier
	s_setprio 1
	s_waitcnt lgkmcnt(0)
	v_mfma_f32_16x16x32_bf16 v[62:65], v[146:149], v[186:189], v[62:65]
	v_mfma_f32_16x16x32_bf16 v[54:57], v[162:165], v[186:189], v[54:57]
	v_mfma_f32_16x16x32_bf16 v[46:49], v[146:149], v[194:197], v[46:49]
	v_mfma_f32_16x16x32_bf16 v[38:41], v[162:165], v[194:197], v[38:41]
	v_mfma_f32_16x16x32_bf16 v[30:33], v[146:149], v[202:205], v[30:33]
	v_mfma_f32_16x16x32_bf16 v[22:25], v[162:165], v[202:205], v[22:25]
	v_mfma_f32_16x16x32_bf16 v[14:17], v[146:149], v[210:213], v[14:17]
	v_mfma_f32_16x16x32_bf16 v[6:9], v[162:165], v[210:213], v[6:9]
	v_mfma_f32_16x16x32_bf16 v[62:65], v[158:161], v[190:193], v[62:65]
	v_mfma_f32_16x16x32_bf16 v[54:57], v[166:169], v[190:193], v[54:57]
	v_mfma_f32_16x16x32_bf16 v[46:49], v[158:161], v[198:201], v[46:49]
	v_mfma_f32_16x16x32_bf16 v[38:41], v[166:169], v[198:201], v[38:41]
	v_mfma_f32_16x16x32_bf16 v[30:33], v[158:161], v[206:209], v[30:33]
	v_mfma_f32_16x16x32_bf16 v[22:25], v[166:169], v[206:209], v[22:25]
	v_mfma_f32_16x16x32_bf16 v[14:17], v[158:161], v[214:217], v[14:17]
	v_mfma_f32_16x16x32_bf16 v[6:9], v[166:169], v[214:217], v[6:9]
	s_setprio 0
	s_setprio 1
	v_mfma_f32_16x16x32_bf16 v[58:61], v[170:173], v[186:189], v[58:61]
	v_mfma_f32_16x16x32_bf16 v[50:53], v[178:181], v[186:189], v[50:53]
	v_mfma_f32_16x16x32_bf16 v[42:45], v[170:173], v[194:197], v[42:45]
	v_mfma_f32_16x16x32_bf16 v[34:37], v[178:181], v[194:197], v[34:37]
	v_mfma_f32_16x16x32_bf16 v[26:29], v[170:173], v[202:205], v[26:29]
	v_mfma_f32_16x16x32_bf16 v[18:21], v[178:181], v[202:205], v[18:21]
	v_mfma_f32_16x16x32_bf16 v[10:13], v[170:173], v[210:213], v[10:13]
	v_mfma_f32_16x16x32_bf16 v[2:5], v[178:181], v[210:213], v[2:5]
	v_mfma_f32_16x16x32_bf16 v[58:61], v[174:177], v[190:193], v[58:61]
	v_mfma_f32_16x16x32_bf16 v[50:53], v[182:185], v[190:193], v[50:53]
	v_mfma_f32_16x16x32_bf16 v[42:45], v[174:177], v[198:201], v[42:45]
	v_mfma_f32_16x16x32_bf16 v[34:37], v[182:185], v[198:201], v[34:37]
	v_mfma_f32_16x16x32_bf16 v[26:29], v[174:177], v[206:209], v[26:29]
	v_mfma_f32_16x16x32_bf16 v[18:21], v[182:185], v[206:209], v[18:21]
	v_mfma_f32_16x16x32_bf16 v[10:13], v[174:177], v[214:217], v[10:13]
	v_mfma_f32_16x16x32_bf16 v[2:5], v[182:185], v[214:217], v[2:5]
	s_setprio 0
	s_add_i32 s54, s54, 2
	s_add_u32 s50, s50, 0x100
	s_addc_u32 s51, s51, 0
	s_add_u32 s20, s20, 0x100
	s_addc_u32 s21, s21, 0
	s_cmp_gt_u32 s54, 13
	s_barrier
	s_cbranch_scc0 .LBB0_1038
	s_and_b64 vcc, exec, s[8:9]
	s_cbranch_vccz .LBB0_1041
	s_barrier

; #define PG8_STAGE(bufoff, gbase, voff) do { _Pragma("unroll") for (int _i = 0; _i < 2; ++_i) \
;         __builtin_amdgcn_global_load_lds((const unsigned*)((const char*)(gbase) + (voff)[_i]), (PG8_LAS unsigned*)(lds + (bufoff) + ldsw + _i * 8192), 16, 0, 0); } while (0)
; #define PG8_LDA(dst, b, h) do { _Pragma("unroll") for (int m = 0; m < 4; ++m) _Pragma("unroll") for (int k = 0; k < 2; ++k) dst[m][k] = *(const PG8_LAS bf16x8*)(lds + PG8_SA(b, h) + aoff + m * 2048 + k * 1024); } while (0)
; #define PG8_LDB(dst, b, h) do { _Pragma("unroll") for (int n = 0; n < 2; ++n) _Pragma("unroll") for (int k = 0; k < 2; ++k) dst[n][k] = *(const PG8_LAS bf16x8*)(lds + PG8_SB(b, h) + boff + n * 2048 + k * 1024); } while (0)
; #define PG8_MMA(ai, bj, At, Bt) do { __builtin_amdgcn_s_setprio(1); _Pragma("unroll") for (int m = 0; m < 4; ++m) _Pragma("unroll") for (int n = 0; n < 2; ++n) _Pragma("unroll") for (int k = 0; k < 2; ++k) \
;         acc[ai][bj][m][n] = __builtin_amdgcn_mfma_f32_16x16x32_bf16(Bt[n][k], At[m][k], acc[ai][bj][m][n], 0, 0, 0); __builtin_amdgcn_s_setprio(0); } while (0)
; template <class Epi, class Sched, bool ALIGN_EPI = false, bool SP2 = false>
; __device__ __forceinline__ void gemm_phase(PG8_LAS unsigned char* lds, const Gemm g, const Sched& S, const Epi& E) {
;     ...
;         const bool has_next = S.next(ui + 1, nxt);
;         const char* nA = has_next ? (const char*)g.A + (size_t)nxt.pm * tstep + (size_t)nxt.ks * K * 2 : cA; const char* nB = has_next ? (const char*)g.Bt + (size_t)nxt.pn * tstep + (size_t)nxt.ks * K * 2 : cB;
;         for (int t = 0; t < nt; t += 2) {
;             const bool last = (t == nt - 2);
;             const char* a1 = cA + (size_t)(t + 1) * kstep;
;             const char* a2 = last ? nA : cA + (size_t)(t + 2) * kstep; const char* b2 = last ? nB : cB + (size_t)(t + 2) * kstep;
;             const char* a3 = a2 + kstep; const char* b3 = b2 + kstep;
;             if (last && has_next) S.a_ready(nxt);
;             if constexpr (SP2) {
;             PG8_LDB(B0, 0, 0); PG8_LDB(B1, 0, 1); PG8_SCHED; PG8_LDA(At, 0, 0); PG8_STAGE(PG8_SA(1, 1), a1 + hstep, voffA);
;             PG8_WAIT_V(8); PG8_WAIT_L(0); PG8_BAR; PG8_MMA(0, 0, At, B0); PG8_MMA(0, 1, At, B1); PG8_BAR; PG8_SCHED;
;             PG8_LDA(At, 0, 1); PG8_STAGE(PG8_SB(0, 0), b2, voffB); PG8_STAGE(PG8_SB(0, 1), b2 + hstep, voffB); PG8_STAGE(PG8_SA(0, 0), a2, voffA);
.LBB0_1125:
	s_add_u32 s91, s46, 0x100
	s_addc_u32 s92, s47, 0
	s_mov_b32 s52, 0
	ds_read_b128 v[150:153], v147
	ds_read_b128 v[154:157], v147 offset:1024
	ds_read_b128 v[158:161], v147 offset:2048
	ds_read_b128 v[162:165], v147 offset:3072
	ds_read_b128 v[166:169], v148
	ds_read_b128 v[170:173], v148 offset:1024
	ds_read_b128 v[174:177], v148 offset:2048
	ds_read_b128 v[178:181], v148 offset:3072
	s_add_i32 s93, s52, 2
	s_add_u32 s46, s44, 0x100
	s_addc_u32 s47, s45, 0
	s_cmp_eq_u32 s86, s52
	s_cselect_b32 s52, s42, s91
	s_cselect_b32 s57, s41, s47
	s_cselect_b32 s56, s40, s46
	s_cselect_b32 s53, s43, s92
	v_lshl_add_u64 v[214:215], s[44:45], 0, v[140:141]
	s_add_i32 m0, s77, 0xc000
	ds_read_b128 v[182:185], v146
	ds_read_b128 v[186:189], v146 offset:1024
	ds_read_b128 v[190:193], v146 offset:2048
	ds_read_b128 v[194:197], v146 offset:3072
	ds_read_b128 v[198:201], v146 offset:4096
	ds_read_b128 v[202:205], v146 offset:5120
	ds_read_b128 v[206:209], v146 offset:6144
	ds_read_b128 v[210:213], v146 offset:7168
	global_load_lds_dwordx4 v[214:215], off
	v_lshl_add_u64 v[214:215], s[44:45], 0, v[138:139]
	s_add_i32 m0, s77, 0xe000
	s_nop 0
	global_load_lds_dwordx4 v[214:215], off
	s_waitcnt vmcnt(8)
	s_waitcnt lgkmcnt(0)
	s_barrier
	s_setprio 1
	s_waitcnt lgkmcnt(0)
	v_mfma_f32_16x16x32_bf16 v[126:129], v[150:153], v[182:185], 0
	v_mfma_f32_16x16x32_bf16 v[122:125], v[158:161], v[182:185], 0
	v_mfma_f32_16x16x32_bf16 v[118:121], v[150:153], v[190:193], 0
	v_mfma_f32_16x16x32_bf16 v[114:117], v[158:161], v[190:193], 0
	v_mfma_f32_16x16x32_bf16 v[102:105], v[150:153], v[198:201], 0
	v_mfma_f32_16x16x32_bf16 v[98:101], v[158:161], v[198:201], 0
	v_mfma_f32_16x16x32_bf16 v[86:89], v[150:153], v[206:209], 0
	v_mfma_f32_16x16x32_bf16 v[82:85], v[158:161], v[206:209], 0
	v_mfma_f32_16x16x32_bf16 v[126:129], v[154:157], v[186:189], v[126:129]
	v_mfma_f32_16x16x32_bf16 v[122:125], v[162:165], v[186:189], v[122:125]
	v_mfma_f32_16x16x32_bf16 v[118:121], v[154:157], v[194:197], v[118:121]
	v_mfma_f32_16x16x32_bf16 v[114:117], v[162:165], v[194:197], v[114:117]
	v_mfma_f32_16x16x32_bf16 v[102:105], v[154:157], v[202:205], v[102:105]
	v_mfma_f32_16x16x32_bf16 v[98:101], v[162:165], v[202:205], v[98:101]
	v_mfma_f32_16x16x32_bf16 v[86:89], v[154:157], v[210:213], v[86:89]
	v_mfma_f32_16x16x32_bf16 v[82:85], v[162:165], v[210:213], v[82:85]
	s_setprio 0
	s_setprio 1
	v_mfma_f32_16x16x32_bf16 v[110:113], v[166:169], v[182:185], 0
	v_mfma_f32_16x16x32_bf16 v[106:109], v[174:177], v[182:185], 0
	v_mfma_f32_16x16x32_bf16 v[94:97], v[166:169], v[190:193], 0
	v_mfma_f32_16x16x32_bf16 v[90:93], v[174:177], v[190:193], 0
	v_mfma_f32_16x16x32_bf16 v[78:81], v[166:169], v[198:201], 0
	v_mfma_f32_16x16x32_bf16 v[74:77], v[174:177], v[198:201], 0
	v_mfma_f32_16x16x32_bf16 v[70:73], v[166:169], v[206:209], 0
	v_mfma_f32_16x16x32_bf16 v[66:69], v[174:177], v[206:209], 0
	v_mfma_f32_16x16x32_bf16 v[110:113], v[170:173], v[186:189], v[110:113]
	v_mfma_f32_16x16x32_bf16 v[106:109], v[178:181], v[186:189], v[106:109]
	v_mfma_f32_16x16x32_bf16 v[94:97], v[170:173], v[194:197], v[94:97]
	v_mfma_f32_16x16x32_bf16 v[90:93], v[178:181], v[194:197], v[90:93]
	v_mfma_f32_16x16x32_bf16 v[78:81], v[170:173], v[202:205], v[78:81]
	v_mfma_f32_16x16x32_bf16 v[74:77], v[178:181], v[202:205], v[74:77]
	v_mfma_f32_16x16x32_bf16 v[70:73], v[170:173], v[210:213], v[70:73]
	v_mfma_f32_16x16x32_bf16 v[66:69], v[178:181], v[210:213], v[66:69]
	s_setprio 0
	s_barrier
	s_mov_b32 m0, s73
	v_lshl_add_u64 v[214:215], s[52:53], 0, v[130:131]
	s_add_u32 s44, s52, 0xb0000
	ds_read_b128 v[182:185], v146 offset:16384
	ds_read_b128 v[186:189], v146 offset:17408
	ds_read_b128 v[190:193], v146 offset:18432
	ds_read_b128 v[194:197], v146 offset:19456
	ds_read_b128 v[198:201], v146 offset:20480
	ds_read_b128 v[202:205], v146 offset:21504
	ds_read_b128 v[206:209], v146 offset:22528
	ds_read_b128 v[210:213], v146 offset:23552
	global_load_lds_dwordx4 v[214:215], off
	v_lshl_add_u64 v[216:217], s[52:53], 0, v[136:137]
	s_mov_b32 m0, s74
	s_addc_u32 s45, s53, 0
	global_load_lds_dwordx4 v[216:217], off
	v_lshl_add_u64 v[218:219], s[44:45], 0, v[130:131]
	s_mov_b32 m0, s75
	v_lshl_add_u64 v[220:221], s[56:57], 0, v[134:135]
	global_load_lds_dwordx4 v[218:219], off
	v_lshl_add_u64 v[218:219], s[44:45], 0, v[136:137]
	s_mov_b32 m0, s76
	s_nop 0
	global_load_lds_dwordx4 v[218:219], off
	v_lshl_add_u64 v[218:219], s[56:57], 0, v[132:133]
	s_mov_b32 m0, s77
	s_nop 0
	global_load_lds_dwordx4 v[218:219], off
	s_mov_b32 m0, s78
	s_nop 0
	global_load_lds_dwordx4 v[220:221], off
	s_waitcnt vmcnt(8)
	s_waitcnt lgkmcnt(0)
	s_barrier
; #define PG8_STAGE(bufoff, gbase, voff) do { _Pragma("unroll") for (int _i = 0; _i < 2; ++_i) \
;         __builtin_amdgcn_global_load_lds((const unsigned*)((const char*)(gbase) + (voff)[_i]), (PG8_LAS unsigned*)(lds + (bufoff) + ldsw + _i * 8192), 16, 0, 0); } while (0)
; #define PG8_LDA(dst, b, h) do { _Pragma("unroll") for (int m = 0; m < 4; ++m) _Pragma("unroll") for (int k = 0; k < 2; ++k) dst[m][k] = *(const PG8_LAS bf16x8*)(lds + PG8_SA(b, h) + aoff + m * 2048 + k * 1024); } while (0)
; #define PG8_LDB(dst, b, h) do { _Pragma("unroll") for (int n = 0; n < 2; ++n) _Pragma("unroll") for (int k = 0; k < 2; ++k) dst[n][k] = *(const PG8_LAS bf16x8*)(lds + PG8_SB(b, h) + boff + n * 2048 + k * 1024); } while (0)
; #define PG8_MMA(ai, bj, At, Bt) do { __builtin_amdgcn_s_setprio(1); _Pragma("unroll") for (int m = 0; m < 4; ++m) _Pragma("unroll") for (int n = 0; n < 2; ++n) _Pragma("unroll") for (int k = 0; k < 2; ++k) \
;         acc[ai][bj][m][n] = __builtin_amdgcn_mfma_f32_16x16x32_bf16(Bt[n][k], At[m][k], acc[ai][bj][m][n], 0, 0, 0); __builtin_amdgcn_s_setprio(0); } while (0)
; #define PG8_WAIT_V(n) asm volatile("s_waitcnt vmcnt(" #n ")" ::: "memory")
; #define PG8_WAIT_L(n) asm volatile("s_waitcnt lgkmcnt(" #n ")" ::: "memory")
; #define PG8_BAR __builtin_amdgcn_s_barrier()
; #define PG8_SCHED __builtin_amdgcn_sched_barrier(0)
; template <class Epi, class Sched, bool ALIGN_EPI = false, bool SP2 = false>
; __device__ __forceinline__ void gemm_phase(PG8_LAS unsigned char* lds, const Gemm g, const Sched& S, const Epi& E) {
;     ...
;             PG8_WAIT_V(8); PG8_WAIT_L(0); PG8_BAR; PG8_MMA(1, 0, At, B0); PG8_MMA(1, 1, At, B1); PG8_BAR; PG8_SCHED;
;             PG8_LDB(B0, 1, 0); PG8_LDB(B1, 1, 1); PG8_SCHED; PG8_LDA(At, 1, 0); PG8_STAGE(PG8_SA(0, 1), a2 + hstep, voffA);
;             PG8_WAIT_V(8); PG8_WAIT_L(0); PG8_BAR; PG8_MMA(0, 0, At, B0); PG8_MMA(0, 1, At, B1); PG8_BAR; PG8_SCHED;
	s_setprio 1
	s_waitcnt lgkmcnt(0)
	v_mfma_f32_16x16x32_bf16 v[62:65], v[150:153], v[182:185], 0
	v_mfma_f32_16x16x32_bf16 v[58:61], v[158:161], v[182:185], 0
	v_mfma_f32_16x16x32_bf16 v[54:57], v[150:153], v[190:193], 0
	v_mfma_f32_16x16x32_bf16 v[50:53], v[158:161], v[190:193], 0
	v_mfma_f32_16x16x32_bf16 v[38:41], v[150:153], v[198:201], 0
	v_mfma_f32_16x16x32_bf16 v[34:37], v[158:161], v[198:201], 0
	v_mfma_f32_16x16x32_bf16 v[22:25], v[150:153], v[206:209], 0
	v_mfma_f32_16x16x32_bf16 v[18:21], v[158:161], v[206:209], 0
	v_mfma_f32_16x16x32_bf16 v[62:65], v[154:157], v[186:189], v[62:65]
	v_mfma_f32_16x16x32_bf16 v[58:61], v[162:165], v[186:189], v[58:61]
	v_mfma_f32_16x16x32_bf16 v[54:57], v[154:157], v[194:197], v[54:57]
	v_mfma_f32_16x16x32_bf16 v[50:53], v[162:165], v[194:197], v[50:53]
	v_mfma_f32_16x16x32_bf16 v[38:41], v[154:157], v[202:205], v[38:41]
	v_mfma_f32_16x16x32_bf16 v[34:37], v[162:165], v[202:205], v[34:37]
	v_mfma_f32_16x16x32_bf16 v[22:25], v[154:157], v[210:213], v[22:25]
	v_mfma_f32_16x16x32_bf16 v[18:21], v[162:165], v[210:213], v[18:21]
	s_setprio 0
	s_setprio 1
	v_mfma_f32_16x16x32_bf16 v[46:49], v[166:169], v[182:185], 0
	v_mfma_f32_16x16x32_bf16 v[42:45], v[174:177], v[182:185], 0
	v_mfma_f32_16x16x32_bf16 v[30:33], v[166:169], v[190:193], 0
	v_mfma_f32_16x16x32_bf16 v[26:29], v[174:177], v[190:193], 0
	v_mfma_f32_16x16x32_bf16 v[14:17], v[166:169], v[198:201], 0
	v_mfma_f32_16x16x32_bf16 v[10:13], v[174:177], v[198:201], 0
	v_mfma_f32_16x16x32_bf16 v[6:9], v[166:169], v[206:209], 0
	v_mfma_f32_16x16x32_bf16 v[2:5], v[174:177], v[206:209], 0
	v_mfma_f32_16x16x32_bf16 v[46:49], v[170:173], v[186:189], v[46:49]
	v_mfma_f32_16x16x32_bf16 v[42:45], v[178:181], v[186:189], v[42:45]
	v_mfma_f32_16x16x32_bf16 v[30:33], v[170:173], v[194:197], v[30:33]
	v_mfma_f32_16x16x32_bf16 v[26:29], v[178:181], v[194:197], v[26:29]
	v_mfma_f32_16x16x32_bf16 v[14:17], v[170:173], v[202:205], v[14:17]
	v_mfma_f32_16x16x32_bf16 v[10:13], v[178:181], v[202:205], v[10:13]
	v_mfma_f32_16x16x32_bf16 v[6:9], v[170:173], v[210:213], v[6:9]
	v_mfma_f32_16x16x32_bf16 v[2:5], v[178:181], v[210:213], v[2:5]
	s_setprio 0
	s_barrier
	v_add_u32_e32 v178, s66, v144
	ds_read_b128 v[150:153], v149
	ds_read_b128 v[154:157], v149 offset:1024
	ds_read_b128 v[158:161], v149 offset:2048
	ds_read_b128 v[162:165], v149 offset:3072
	ds_read_b128 v[166:169], v178
	ds_read_b128 v[170:173], v178 offset:1024
	ds_read_b128 v[174:177], v178 offset:2048
	ds_read_b128 v[178:181], v178 offset:3072
	s_add_u32 s44, s56, 0xb0000
	s_addc_u32 s45, s57, 0
	s_mov_b32 m0, s79
	v_lshl_add_u64 v[222:223], s[44:45], 0, v[132:133]
	ds_read_b128 v[182:185], v146 offset:32768
	ds_read_b128 v[186:189], v146 offset:33792
	ds_read_b128 v[190:193], v146 offset:34816
	ds_read_b128 v[194:197], v146 offset:35840
	ds_read_b128 v[198:201], v146 offset:36864
	ds_read_b128 v[202:205], v146 offset:37888
	ds_read_b128 v[206:209], v146 offset:38912
	ds_read_b128 v[210:213], v146 offset:39936
	global_load_lds_dwordx4 v[222:223], off
	v_lshl_add_u64 v[222:223], s[44:45], 0, v[134:135]
	s_mov_b32 m0, s80
	s_nop 0
	global_load_lds_dwordx4 v[222:223], off
	s_waitcnt vmcnt(8)
	s_waitcnt lgkmcnt(0)
	s_barrier
	s_setprio 1
	s_waitcnt lgkmcnt(0)
	v_mfma_f32_16x16x32_bf16 v[126:129], v[150:153], v[182:185], v[126:129]
	v_mfma_f32_16x16x32_bf16 v[122:125], v[158:161], v[182:185], v[122:125]
	v_mfma_f32_16x16x32_bf16 v[118:121], v[150:153], v[190:193], v[118:121]
	v_mfma_f32_16x16x32_bf16 v[114:117], v[158:161], v[190:193], v[114:117]
	v_mfma_f32_16x16x32_bf16 v[102:105], v[150:153], v[198:201], v[102:105]
	v_mfma_f32_16x16x32_bf16 v[98:101], v[158:161], v[198:201], v[98:101]
	v_mfma_f32_16x16x32_bf16 v[86:89], v[150:153], v[206:209], v[86:89]
	v_mfma_f32_16x16x32_bf16 v[82:85], v[158:161], v[206:209], v[82:85]
	v_mfma_f32_16x16x32_bf16 v[126:129], v[154:157], v[186:189], v[126:129]
	v_mfma_f32_16x16x32_bf16 v[122:125], v[162:165], v[186:189], v[122:125]
	v_mfma_f32_16x16x32_bf16 v[118:121], v[154:157], v[194:197], v[118:121]
	v_mfma_f32_16x16x32_bf16 v[114:117], v[162:165], v[194:197], v[114:117]
	v_mfma_f32_16x16x32_bf16 v[102:105], v[154:157], v[202:205], v[102:105]
	v_mfma_f32_16x16x32_bf16 v[98:101], v[162:165], v[202:205], v[98:101]
	v_mfma_f32_16x16x32_bf16 v[86:89], v[154:157], v[210:213], v[86:89]
	v_mfma_f32_16x16x32_bf16 v[82:85], v[162:165], v[210:213], v[82:85]
	s_setprio 0
	s_setprio 1
	v_mfma_f32_16x16x32_bf16 v[110:113], v[166:169], v[182:185], v[110:113]
	v_mfma_f32_16x16x32_bf16 v[106:109], v[174:177], v[182:185], v[106:109]
	v_mfma_f32_16x16x32_bf16 v[94:97], v[166:169], v[190:193], v[94:97]
	v_mfma_f32_16x16x32_bf16 v[90:93], v[174:177], v[190:193], v[90:93]
	v_mfma_f32_16x16x32_bf16 v[78:81], v[166:169], v[198:201], v[78:81]
	v_mfma_f32_16x16x32_bf16 v[74:77], v[174:177], v[198:201], v[74:77]
	v_mfma_f32_16x16x32_bf16 v[70:73], v[166:169], v[206:209], v[70:73]
	v_mfma_f32_16x16x32_bf16 v[66:69], v[174:177], v[206:209], v[66:69]
	v_mfma_f32_16x16x32_bf16 v[110:113], v[170:173], v[186:189], v[110:113]
	v_mfma_f32_16x16x32_bf16 v[106:109], v[178:181], v[186:189], v[106:109]
	v_mfma_f32_16x16x32_bf16 v[94:97], v[170:173], v[194:197], v[94:97]
	v_mfma_f32_16x16x32_bf16 v[90:93], v[178:181], v[194:197], v[90:93]
	v_mfma_f32_16x16x32_bf16 v[78:81], v[170:173], v[202:205], v[78:81]
	v_mfma_f32_16x16x32_bf16 v[74:77], v[178:181], v[202:205], v[74:77]
	v_mfma_f32_16x16x32_bf16 v[70:73], v[170:173], v[210:213], v[70:73]
	v_mfma_f32_16x16x32_bf16 v[66:69], v[178:181], v[210:213], v[66:69]
	s_setprio 0
	s_barrier
; #define PG8_STAGE(bufoff, gbase, voff) do { _Pragma("unroll") for (int _i = 0; _i < 2; ++_i) \
;         __builtin_amdgcn_global_load_lds((const unsigned*)((const char*)(gbase) + (voff)[_i]), (PG8_LAS unsigned*)(lds + (bufoff) + ldsw + _i * 8192), 16, 0, 0); } while (0)
; #define PG8_LDA(dst, b, h) do { _Pragma("unroll") for (int m = 0; m < 4; ++m) _Pragma("unroll") for (int k = 0; k < 2; ++k) dst[m][k] = *(const PG8_LAS bf16x8*)(lds + PG8_SA(b, h) + aoff + m * 2048 + k * 1024); } while (0)
; #define PG8_LDB(dst, b, h) do { _Pragma("unroll") for (int n = 0; n < 2; ++n) _Pragma("unroll") for (int k = 0; k < 2; ++k) dst[n][k] = *(const PG8_LAS bf16x8*)(lds + PG8_SB(b, h) + boff + n * 2048 + k * 1024); } while (0)
; #define PG8_MMA(ai, bj, At, Bt) do { __builtin_amdgcn_s_setprio(1); _Pragma("unroll") for (int m = 0; m < 4; ++m) _Pragma("unroll") for (int n = 0; n < 2; ++n) _Pragma("unroll") for (int k = 0; k < 2; ++k) \
;         acc[ai][bj][m][n] = __builtin_amdgcn_mfma_f32_16x16x32_bf16(Bt[n][k], At[m][k], acc[ai][bj][m][n], 0, 0, 0); __builtin_amdgcn_s_setprio(0); } while (0)
; #define PG8_WAIT_V(n) asm volatile("s_waitcnt vmcnt(" #n ")" ::: "memory")
; #define PG8_BAR __builtin_amdgcn_s_barrier()
; template <class Epi, class Sched, bool ALIGN_EPI = false, bool SP2 = false>
; __device__ __forceinline__ void gemm_phase(PG8_LAS unsigned char* lds, const Gemm g, const Sched& S, const Epi& E) {
;     ...
;         for (int t = 0; t < nt; t += 2) {
;             const bool last = (t == nt - 2);
;             const char* a1 = cA + (size_t)(t + 1) * kstep;
;             const char* a2 = last ? nA : cA + (size_t)(t + 2) * kstep; const char* b2 = last ? nB : cB + (size_t)(t + 2) * kstep;
;             const char* a3 = a2 + kstep; const char* b3 = b2 + kstep;
;             if (last && has_next) S.a_ready(nxt);
;             if constexpr (SP2) {
;             PG8_LDB(B0, 0, 0); PG8_LDB(B1, 0, 1); PG8_SCHED; PG8_LDA(At, 0, 0); PG8_STAGE(PG8_SA(1, 1), a1 + hstep, voffA);
;             PG8_WAIT_V(8); PG8_WAIT_L(0); PG8_BAR; PG8_MMA(0, 0, At, B0); PG8_MMA(0, 1, At, B1); PG8_BAR; PG8_SCHED;
;     ...
;             PG8_LDA(At, 1, 1); PG8_STAGE(PG8_SB(1, 0), b3, voffB); PG8_STAGE(PG8_SB(1, 1), b3 + hstep, voffB); PG8_STAGE(PG8_SA(1, 0), a3, voffA);
;             PG8_WAIT_V(8); PG8_WAIT_L(0); PG8_BAR; PG8_MMA(1, 0, At, B0); PG8_MMA(1, 1, At, B1); PG8_BAR; PG8_SCHED;
	s_mov_b32 m0, s48
	v_lshl_add_u64 v[214:215], v[214:215], 0, s[16:17]
	s_add_u32 s44, s52, 0xb0080
	ds_read_b128 v[182:185], v146 offset:49152
	ds_read_b128 v[186:189], v146 offset:50176
	ds_read_b128 v[190:193], v146 offset:51200
	ds_read_b128 v[194:197], v146 offset:52224
	ds_read_b128 v[198:201], v146 offset:53248
	ds_read_b128 v[202:205], v146 offset:54272
	ds_read_b128 v[206:209], v146 offset:55296
	ds_read_b128 v[210:213], v146 offset:56320
	global_load_lds_dwordx4 v[214:215], off
	v_lshl_add_u64 v[214:215], v[216:217], 0, s[16:17]
	s_mov_b32 m0, s49
	s_addc_u32 s45, s53, 0
	global_load_lds_dwordx4 v[214:215], off
	v_lshl_add_u64 v[214:215], s[44:45], 0, v[130:131]
	s_mov_b32 m0, s83
	s_nop 0
	global_load_lds_dwordx4 v[214:215], off
	v_lshl_add_u64 v[214:215], s[44:45], 0, v[136:137]
	s_mov_b32 m0, s84
	s_nop 0
	global_load_lds_dwordx4 v[214:215], off
	v_lshl_add_u64 v[214:215], v[218:219], 0, s[16:17]
	s_mov_b32 m0, s50
	s_nop 0
	global_load_lds_dwordx4 v[214:215], off
	v_lshl_add_u64 v[214:215], v[220:221], 0, s[16:17]
	s_mov_b32 m0, s51
	s_nop 0
	global_load_lds_dwordx4 v[214:215], off
	s_waitcnt vmcnt(8)
	s_waitcnt lgkmcnt(0)
	s_barrier
	s_setprio 1
	s_waitcnt lgkmcnt(0)
	v_mfma_f32_16x16x32_bf16 v[62:65], v[150:153], v[182:185], v[62:65]
	v_mfma_f32_16x16x32_bf16 v[58:61], v[158:161], v[182:185], v[58:61]
	v_mfma_f32_16x16x32_bf16 v[54:57], v[150:153], v[190:193], v[54:57]
	v_mfma_f32_16x16x32_bf16 v[50:53], v[158:161], v[190:193], v[50:53]
	v_mfma_f32_16x16x32_bf16 v[38:41], v[150:153], v[198:201], v[38:41]
	v_mfma_f32_16x16x32_bf16 v[34:37], v[158:161], v[198:201], v[34:37]
	v_mfma_f32_16x16x32_bf16 v[22:25], v[150:153], v[206:209], v[22:25]
	v_mfma_f32_16x16x32_bf16 v[18:21], v[158:161], v[206:209], v[18:21]
	v_mfma_f32_16x16x32_bf16 v[62:65], v[154:157], v[186:189], v[62:65]
	v_mfma_f32_16x16x32_bf16 v[58:61], v[162:165], v[186:189], v[58:61]
	v_mfma_f32_16x16x32_bf16 v[54:57], v[154:157], v[194:197], v[54:57]
	v_mfma_f32_16x16x32_bf16 v[50:53], v[162:165], v[194:197], v[50:53]
	v_mfma_f32_16x16x32_bf16 v[38:41], v[154:157], v[202:205], v[38:41]
	v_mfma_f32_16x16x32_bf16 v[34:37], v[162:165], v[202:205], v[34:37]
	v_mfma_f32_16x16x32_bf16 v[22:25], v[154:157], v[210:213], v[22:25]
	v_mfma_f32_16x16x32_bf16 v[18:21], v[162:165], v[210:213], v[18:21]
	s_setprio 0
	s_setprio 1
	v_mfma_f32_16x16x32_bf16 v[46:49], v[166:169], v[182:185], v[46:49]
	v_mfma_f32_16x16x32_bf16 v[42:45], v[174:177], v[182:185], v[42:45]
	v_mfma_f32_16x16x32_bf16 v[30:33], v[166:169], v[190:193], v[30:33]
	v_mfma_f32_16x16x32_bf16 v[26:29], v[174:177], v[190:193], v[26:29]
	v_mfma_f32_16x16x32_bf16 v[14:17], v[166:169], v[198:201], v[14:17]
	v_mfma_f32_16x16x32_bf16 v[10:13], v[174:177], v[198:201], v[10:13]
	v_mfma_f32_16x16x32_bf16 v[6:9], v[166:169], v[206:209], v[6:9]
	v_mfma_f32_16x16x32_bf16 v[2:5], v[174:177], v[206:209], v[2:5]
	v_mfma_f32_16x16x32_bf16 v[46:49], v[170:173], v[186:189], v[46:49]
	v_mfma_f32_16x16x32_bf16 v[42:45], v[178:181], v[186:189], v[42:45]
	v_mfma_f32_16x16x32_bf16 v[30:33], v[170:173], v[194:197], v[30:33]
	v_mfma_f32_16x16x32_bf16 v[26:29], v[178:181], v[194:197], v[26:29]
	v_mfma_f32_16x16x32_bf16 v[14:17], v[170:173], v[202:205], v[14:17]
	v_mfma_f32_16x16x32_bf16 v[10:13], v[178:181], v[202:205], v[10:13]
	v_mfma_f32_16x16x32_bf16 v[6:9], v[170:173], v[210:213], v[6:9]
	v_mfma_f32_16x16x32_bf16 v[2:5], v[178:181], v[210:213], v[2:5]
	s_setprio 0
	s_add_u32 s91, s91, 0x100
	s_addc_u32 s92, s92, 0
	s_cmp_ge_u32 s93, s81
	s_mov_b64 s[44:45], s[46:47]
	s_mov_b32 s52, s93
	s_barrier
.LBB0_1126:
	ds_read_b128 v[150:153], v147
	ds_read_b128 v[154:157], v147 offset:1024
	ds_read_b128 v[158:161], v147 offset:2048
	ds_read_b128 v[162:165], v147 offset:3072
	ds_read_b128 v[166:169], v148
	ds_read_b128 v[170:173], v148 offset:1024
	ds_read_b128 v[174:177], v148 offset:2048
	ds_read_b128 v[178:181], v148 offset:3072
	s_add_i32 s93, s52, 2
	s_add_u32 s46, s44, 0x100
	s_addc_u32 s47, s45, 0
	s_cmp_eq_u32 s86, s52
	s_cselect_b32 s52, s42, s91
	s_cselect_b32 s57, s41, s47
	s_cselect_b32 s56, s40, s46
	s_cselect_b32 s53, s43, s92
	v_lshl_add_u64 v[214:215], s[44:45], 0, v[140:141]
	s_add_i32 m0, s77, 0xc000
	ds_read_b128 v[182:185], v146
	ds_read_b128 v[186:189], v146 offset:1024
	ds_read_b128 v[190:193], v146 offset:2048
	ds_read_b128 v[194:197], v146 offset:3072
	ds_read_b128 v[198:201], v146 offset:4096
	ds_read_b128 v[202:205], v146 offset:5120
	ds_read_b128 v[206:209], v146 offset:6144
	ds_read_b128 v[210:213], v146 offset:7168
	global_load_lds_dwordx4 v[214:215], off
	v_lshl_add_u64 v[214:215], s[44:45], 0, v[138:139]
	s_add_i32 m0, s77, 0xe000
	s_nop 0
	global_load_lds_dwordx4 v[214:215], off
	s_waitcnt vmcnt(8)
	s_waitcnt lgkmcnt(0)
	s_barrier
; #define PG8_STAGE(bufoff, gbase, voff) do { _Pragma("unroll") for (int _i = 0; _i < 2; ++_i) \
;         __builtin_amdgcn_global_load_lds((const unsigned*)((const char*)(gbase) + (voff)[_i]), (PG8_LAS unsigned*)(lds + (bufoff) + ldsw + _i * 8192), 16, 0, 0); } while (0)
; #define PG8_LDA(dst, b, h) do { _Pragma("unroll") for (int m = 0; m < 4; ++m) _Pragma("unroll") for (int k = 0; k < 2; ++k) dst[m][k] = *(const PG8_LAS bf16x8*)(lds + PG8_SA(b, h) + aoff + m * 2048 + k * 1024); } while (0)
; #define PG8_LDB(dst, b, h) do { _Pragma("unroll") for (int n = 0; n < 2; ++n) _Pragma("unroll") for (int k = 0; k < 2; ++k) dst[n][k] = *(const PG8_LAS bf16x8*)(lds + PG8_SB(b, h) + boff + n * 2048 + k * 1024); } while (0)
; #define PG8_MMA(ai, bj, At, Bt) do { __builtin_amdgcn_s_setprio(1); _Pragma("unroll") for (int m = 0; m < 4; ++m) _Pragma("unroll") for (int n = 0; n < 2; ++n) _Pragma("unroll") for (int k = 0; k < 2; ++k) \
;         acc[ai][bj][m][n] = __builtin_amdgcn_mfma_f32_16x16x32_bf16(Bt[n][k], At[m][k], acc[ai][bj][m][n], 0, 0, 0); __builtin_amdgcn_s_setprio(0); } while (0)
; #define PG8_WAIT_V(n) asm volatile("s_waitcnt vmcnt(" #n ")" ::: "memory")
; #define PG8_WAIT_L(n) asm volatile("s_waitcnt lgkmcnt(" #n ")" ::: "memory")
; #define PG8_BAR __builtin_amdgcn_s_barrier()
; #define PG8_SCHED __builtin_amdgcn_sched_barrier(0)
; template <class Epi, class Sched, bool ALIGN_EPI = false, bool SP2 = false>
; __device__ __forceinline__ void gemm_phase(PG8_LAS unsigned char* lds, const Gemm g, const Sched& S, const Epi& E) {
;     ...
;             PG8_LDB(B0, 0, 0); PG8_LDB(B1, 0, 1); PG8_SCHED; PG8_LDA(At, 0, 0); PG8_STAGE(PG8_SA(1, 1), a1 + hstep, voffA);
;             PG8_WAIT_V(8); PG8_WAIT_L(0); PG8_BAR; PG8_MMA(0, 0, At, B0); PG8_MMA(0, 1, At, B1); PG8_BAR; PG8_SCHED;
;             PG8_LDA(At, 0, 1); PG8_STAGE(PG8_SB(0, 0), b2, voffB); PG8_STAGE(PG8_SB(0, 1), b2 + hstep, voffB); PG8_STAGE(PG8_SA(0, 0), a2, voffA);
;             PG8_WAIT_V(8); PG8_WAIT_L(0); PG8_BAR; PG8_MMA(1, 0, At, B0); PG8_MMA(1, 1, At, B1); PG8_BAR; PG8_SCHED;
	s_setprio 1
	s_waitcnt lgkmcnt(0)
	v_mfma_f32_16x16x32_bf16 v[126:129], v[150:153], v[182:185], v[126:129]
	v_mfma_f32_16x16x32_bf16 v[122:125], v[158:161], v[182:185], v[122:125]
	v_mfma_f32_16x16x32_bf16 v[118:121], v[150:153], v[190:193], v[118:121]
	v_mfma_f32_16x16x32_bf16 v[114:117], v[158:161], v[190:193], v[114:117]
	v_mfma_f32_16x16x32_bf16 v[102:105], v[150:153], v[198:201], v[102:105]
	v_mfma_f32_16x16x32_bf16 v[98:101], v[158:161], v[198:201], v[98:101]
	v_mfma_f32_16x16x32_bf16 v[86:89], v[150:153], v[206:209], v[86:89]
	v_mfma_f32_16x16x32_bf16 v[82:85], v[158:161], v[206:209], v[82:85]
	v_mfma_f32_16x16x32_bf16 v[126:129], v[154:157], v[186:189], v[126:129]
	v_mfma_f32_16x16x32_bf16 v[122:125], v[162:165], v[186:189], v[122:125]
	v_mfma_f32_16x16x32_bf16 v[118:121], v[154:157], v[194:197], v[118:121]
	v_mfma_f32_16x16x32_bf16 v[114:117], v[162:165], v[194:197], v[114:117]
	v_mfma_f32_16x16x32_bf16 v[102:105], v[154:157], v[202:205], v[102:105]
	v_mfma_f32_16x16x32_bf16 v[98:101], v[162:165], v[202:205], v[98:101]
	v_mfma_f32_16x16x32_bf16 v[86:89], v[154:157], v[210:213], v[86:89]
	v_mfma_f32_16x16x32_bf16 v[82:85], v[162:165], v[210:213], v[82:85]
	s_setprio 0
	s_setprio 1
	v_mfma_f32_16x16x32_bf16 v[110:113], v[166:169], v[182:185], v[110:113]
	v_mfma_f32_16x16x32_bf16 v[106:109], v[174:177], v[182:185], v[106:109]
	v_mfma_f32_16x16x32_bf16 v[94:97], v[166:169], v[190:193], v[94:97]
	v_mfma_f32_16x16x32_bf16 v[90:93], v[174:177], v[190:193], v[90:93]
	v_mfma_f32_16x16x32_bf16 v[78:81], v[166:169], v[198:201], v[78:81]
	v_mfma_f32_16x16x32_bf16 v[74:77], v[174:177], v[198:201], v[74:77]
	v_mfma_f32_16x16x32_bf16 v[70:73], v[166:169], v[206:209], v[70:73]
	v_mfma_f32_16x16x32_bf16 v[66:69], v[174:177], v[206:209], v[66:69]
	v_mfma_f32_16x16x32_bf16 v[110:113], v[170:173], v[186:189], v[110:113]
	v_mfma_f32_16x16x32_bf16 v[106:109], v[178:181], v[186:189], v[106:109]
	v_mfma_f32_16x16x32_bf16 v[94:97], v[170:173], v[194:197], v[94:97]
	v_mfma_f32_16x16x32_bf16 v[90:93], v[178:181], v[194:197], v[90:93]
	v_mfma_f32_16x16x32_bf16 v[78:81], v[170:173], v[202:205], v[78:81]
	v_mfma_f32_16x16x32_bf16 v[74:77], v[178:181], v[202:205], v[74:77]
	v_mfma_f32_16x16x32_bf16 v[70:73], v[170:173], v[210:213], v[70:73]
	v_mfma_f32_16x16x32_bf16 v[66:69], v[178:181], v[210:213], v[66:69]
	s_setprio 0
	s_barrier
	s_mov_b32 m0, s73
	v_lshl_add_u64 v[214:215], s[52:53], 0, v[130:131]
	s_add_u32 s44, s52, 0xb0000
	ds_read_b128 v[182:185], v146 offset:16384
	ds_read_b128 v[186:189], v146 offset:17408
	ds_read_b128 v[190:193], v146 offset:18432
	ds_read_b128 v[194:197], v146 offset:19456
	ds_read_b128 v[198:201], v146 offset:20480
	ds_read_b128 v[202:205], v146 offset:21504
	ds_read_b128 v[206:209], v146 offset:22528
	ds_read_b128 v[210:213], v146 offset:23552
	global_load_lds_dwordx4 v[214:215], off
	v_lshl_add_u64 v[216:217], s[52:53], 0, v[136:137]
	s_mov_b32 m0, s74
	s_addc_u32 s45, s53, 0
	global_load_lds_dwordx4 v[216:217], off
	v_lshl_add_u64 v[218:219], s[44:45], 0, v[130:131]
	s_mov_b32 m0, s75
	v_lshl_add_u64 v[220:221], s[56:57], 0, v[134:135]
	global_load_lds_dwordx4 v[218:219], off
	v_lshl_add_u64 v[218:219], s[44:45], 0, v[136:137]
	s_mov_b32 m0, s76
	s_nop 0
	global_load_lds_dwordx4 v[218:219], off
	v_lshl_add_u64 v[218:219], s[56:57], 0, v[132:133]
	s_mov_b32 m0, s77
	s_nop 0
	global_load_lds_dwordx4 v[218:219], off
	s_mov_b32 m0, s78
	s_nop 0
	global_load_lds_dwordx4 v[220:221], off
	s_waitcnt vmcnt(8)
	s_waitcnt lgkmcnt(0)
	s_barrier
	s_setprio 1
	s_waitcnt lgkmcnt(0)
	v_mfma_f32_16x16x32_bf16 v[62:65], v[150:153], v[182:185], v[62:65]
	v_mfma_f32_16x16x32_bf16 v[58:61], v[158:161], v[182:185], v[58:61]
	v_mfma_f32_16x16x32_bf16 v[54:57], v[150:153], v[190:193], v[54:57]
	v_mfma_f32_16x16x32_bf16 v[50:53], v[158:161], v[190:193], v[50:53]
	v_mfma_f32_16x16x32_bf16 v[38:41], v[150:153], v[198:201], v[38:41]
	v_mfma_f32_16x16x32_bf16 v[34:37], v[158:161], v[198:201], v[34:37]
	v_mfma_f32_16x16x32_bf16 v[22:25], v[150:153], v[206:209], v[22:25]
	v_mfma_f32_16x16x32_bf16 v[18:21], v[158:161], v[206:209], v[18:21]
	v_mfma_f32_16x16x32_bf16 v[62:65], v[154:157], v[186:189], v[62:65]
	v_mfma_f32_16x16x32_bf16 v[58:61], v[162:165], v[186:189], v[58:61]
	v_mfma_f32_16x16x32_bf16 v[54:57], v[154:157], v[194:197], v[54:57]
	v_mfma_f32_16x16x32_bf16 v[50:53], v[162:165], v[194:197], v[50:53]
	v_mfma_f32_16x16x32_bf16 v[38:41], v[154:157], v[202:205], v[38:41]
	v_mfma_f32_16x16x32_bf16 v[34:37], v[162:165], v[202:205], v[34:37]
	v_mfma_f32_16x16x32_bf16 v[22:25], v[154:157], v[210:213], v[22:25]
	v_mfma_f32_16x16x32_bf16 v[18:21], v[162:165], v[210:213], v[18:21]
	s_setprio 0
	s_setprio 1
	v_mfma_f32_16x16x32_bf16 v[46:49], v[166:169], v[182:185], v[46:49]
	v_mfma_f32_16x16x32_bf16 v[42:45], v[174:177], v[182:185], v[42:45]
	v_mfma_f32_16x16x32_bf16 v[30:33], v[166:169], v[190:193], v[30:33]
	v_mfma_f32_16x16x32_bf16 v[26:29], v[174:177], v[190:193], v[26:29]
	v_mfma_f32_16x16x32_bf16 v[14:17], v[166:169], v[198:201], v[14:17]
	v_mfma_f32_16x16x32_bf16 v[10:13], v[174:177], v[198:201], v[10:13]
	v_mfma_f32_16x16x32_bf16 v[6:9], v[166:169], v[206:209], v[6:9]
	v_mfma_f32_16x16x32_bf16 v[2:5], v[174:177], v[206:209], v[2:5]
	v_mfma_f32_16x16x32_bf16 v[46:49], v[170:173], v[186:189], v[46:49]
	v_mfma_f32_16x16x32_bf16 v[42:45], v[178:181], v[186:189], v[42:45]
	v_mfma_f32_16x16x32_bf16 v[30:33], v[170:173], v[194:197], v[30:33]
	v_mfma_f32_16x16x32_bf16 v[26:29], v[178:181], v[194:197], v[26:29]
	v_mfma_f32_16x16x32_bf16 v[14:17], v[170:173], v[202:205], v[14:17]
	v_mfma_f32_16x16x32_bf16 v[10:13], v[178:181], v[202:205], v[10:13]
	v_mfma_f32_16x16x32_bf16 v[6:9], v[170:173], v[210:213], v[6:9]
	v_mfma_f32_16x16x32_bf16 v[2:5], v[178:181], v[210:213], v[2:5]
	s_setprio 0
	s_barrier
; #define PG8_STAGE(bufoff, gbase, voff) do { _Pragma("unroll") for (int _i = 0; _i < 2; ++_i) \
;         __builtin_amdgcn_global_load_lds((const unsigned*)((const char*)(gbase) + (voff)[_i]), (PG8_LAS unsigned*)(lds + (bufoff) + ldsw + _i * 8192), 16, 0, 0); } while (0)
; #define PG8_LDA(dst, b, h) do { _Pragma("unroll") for (int m = 0; m < 4; ++m) _Pragma("unroll") for (int k = 0; k < 2; ++k) dst[m][k] = *(const PG8_LAS bf16x8*)(lds + PG8_SA(b, h) + aoff + m * 2048 + k * 1024); } while (0)
; #define PG8_LDB(dst, b, h) do { _Pragma("unroll") for (int n = 0; n < 2; ++n) _Pragma("unroll") for (int k = 0; k < 2; ++k) dst[n][k] = *(const PG8_LAS bf16x8*)(lds + PG8_SB(b, h) + boff + n * 2048 + k * 1024); } while (0)
; #define PG8_MMA(ai, bj, At, Bt) do { __builtin_amdgcn_s_setprio(1); _Pragma("unroll") for (int m = 0; m < 4; ++m) _Pragma("unroll") for (int n = 0; n < 2; ++n) _Pragma("unroll") for (int k = 0; k < 2; ++k) \
;         acc[ai][bj][m][n] = __builtin_amdgcn_mfma_f32_16x16x32_bf16(Bt[n][k], At[m][k], acc[ai][bj][m][n], 0, 0, 0); __builtin_amdgcn_s_setprio(0); } while (0)
; #define PG8_WAIT_V(n) asm volatile("s_waitcnt vmcnt(" #n ")" ::: "memory")
; #define PG8_WAIT_L(n) asm volatile("s_waitcnt lgkmcnt(" #n ")" ::: "memory")
; #define PG8_BAR __builtin_amdgcn_s_barrier()
; #define PG8_SCHED __builtin_amdgcn_sched_barrier(0)
; template <class Epi, class Sched, bool ALIGN_EPI = false, bool SP2 = false>
; __device__ __forceinline__ void gemm_phase(PG8_LAS unsigned char* lds, const Gemm g, const Sched& S, const Epi& E) {
;     ...
;             PG8_LDB(B0, 1, 0); PG8_LDB(B1, 1, 1); PG8_SCHED; PG8_LDA(At, 1, 0); PG8_STAGE(PG8_SA(0, 1), a2 + hstep, voffA);
;             PG8_WAIT_V(8); PG8_WAIT_L(0); PG8_BAR; PG8_MMA(0, 0, At, B0); PG8_MMA(0, 1, At, B1); PG8_BAR; PG8_SCHED;
	v_add_u32_e32 v178, s66, v144
	ds_read_b128 v[150:153], v149
	ds_read_b128 v[154:157], v149 offset:1024
	ds_read_b128 v[158:161], v149 offset:2048
	ds_read_b128 v[162:165], v149 offset:3072
	ds_read_b128 v[166:169], v178
	ds_read_b128 v[170:173], v178 offset:1024
	ds_read_b128 v[174:177], v178 offset:2048
	ds_read_b128 v[178:181], v178 offset:3072
	s_add_u32 s44, s56, 0xb0000
	s_addc_u32 s45, s57, 0
	s_mov_b32 m0, s79
	v_lshl_add_u64 v[222:223], s[44:45], 0, v[132:133]
	ds_read_b128 v[182:185], v146 offset:32768
	ds_read_b128 v[186:189], v146 offset:33792
	ds_read_b128 v[190:193], v146 offset:34816
	ds_read_b128 v[194:197], v146 offset:35840
	ds_read_b128 v[198:201], v146 offset:36864
	ds_read_b128 v[202:205], v146 offset:37888
	ds_read_b128 v[206:209], v146 offset:38912
	ds_read_b128 v[210:213], v146 offset:39936
	global_load_lds_dwordx4 v[222:223], off
	v_lshl_add_u64 v[222:223], s[44:45], 0, v[134:135]
	s_mov_b32 m0, s80
	s_nop 0
	global_load_lds_dwordx4 v[222:223], off
	s_waitcnt vmcnt(8)
	s_waitcnt lgkmcnt(0)
	s_barrier
	s_setprio 1
	s_waitcnt lgkmcnt(0)
	v_mfma_f32_16x16x32_bf16 v[126:129], v[150:153], v[182:185], v[126:129]
	v_mfma_f32_16x16x32_bf16 v[122:125], v[158:161], v[182:185], v[122:125]
	v_mfma_f32_16x16x32_bf16 v[118:121], v[150:153], v[190:193], v[118:121]
	v_mfma_f32_16x16x32_bf16 v[114:117], v[158:161], v[190:193], v[114:117]
	v_mfma_f32_16x16x32_bf16 v[102:105], v[150:153], v[198:201], v[102:105]
	v_mfma_f32_16x16x32_bf16 v[98:101], v[158:161], v[198:201], v[98:101]
	v_mfma_f32_16x16x32_bf16 v[86:89], v[150:153], v[206:209], v[86:89]
	v_mfma_f32_16x16x32_bf16 v[82:85], v[158:161], v[206:209], v[82:85]
	v_mfma_f32_16x16x32_bf16 v[126:129], v[154:157], v[186:189], v[126:129]
	v_mfma_f32_16x16x32_bf16 v[122:125], v[162:165], v[186:189], v[122:125]
	v_mfma_f32_16x16x32_bf16 v[118:121], v[154:157], v[194:197], v[118:121]
	v_mfma_f32_16x16x32_bf16 v[114:117], v[162:165], v[194:197], v[114:117]
	v_mfma_f32_16x16x32_bf16 v[102:105], v[154:157], v[202:205], v[102:105]
	v_mfma_f32_16x16x32_bf16 v[98:101], v[162:165], v[202:205], v[98:101]
	v_mfma_f32_16x16x32_bf16 v[86:89], v[154:157], v[210:213], v[86:89]
	v_mfma_f32_16x16x32_bf16 v[82:85], v[162:165], v[210:213], v[82:85]
	s_setprio 0
	s_setprio 1
	v_mfma_f32_16x16x32_bf16 v[110:113], v[166:169], v[182:185], v[110:113]
	v_mfma_f32_16x16x32_bf16 v[106:109], v[174:177], v[182:185], v[106:109]
	v_mfma_f32_16x16x32_bf16 v[94:97], v[166:169], v[190:193], v[94:97]
	v_mfma_f32_16x16x32_bf16 v[90:93], v[174:177], v[190:193], v[90:93]
	v_mfma_f32_16x16x32_bf16 v[78:81], v[166:169], v[198:201], v[78:81]
	v_mfma_f32_16x16x32_bf16 v[74:77], v[174:177], v[198:201], v[74:77]
	v_mfma_f32_16x16x32_bf16 v[70:73], v[166:169], v[206:209], v[70:73]
	v_mfma_f32_16x16x32_bf16 v[66:69], v[174:177], v[206:209], v[66:69]
	v_mfma_f32_16x16x32_bf16 v[110:113], v[170:173], v[186:189], v[110:113]
	v_mfma_f32_16x16x32_bf16 v[106:109], v[178:181], v[186:189], v[106:109]
	v_mfma_f32_16x16x32_bf16 v[94:97], v[170:173], v[194:197], v[94:97]
	v_mfma_f32_16x16x32_bf16 v[90:93], v[178:181], v[194:197], v[90:93]
	v_mfma_f32_16x16x32_bf16 v[78:81], v[170:173], v[202:205], v[78:81]
	v_mfma_f32_16x16x32_bf16 v[74:77], v[178:181], v[202:205], v[74:77]
	v_mfma_f32_16x16x32_bf16 v[70:73], v[170:173], v[210:213], v[70:73]
	v_mfma_f32_16x16x32_bf16 v[66:69], v[178:181], v[210:213], v[66:69]
	s_setprio 0
	s_barrier
; #define PG8_STAGE(bufoff, gbase, voff) do { _Pragma("unroll") for (int _i = 0; _i < 2; ++_i) \
;         __builtin_amdgcn_global_load_lds((const unsigned*)((const char*)(gbase) + (voff)[_i]), (PG8_LAS unsigned*)(lds + (bufoff) + ldsw + _i * 8192), 16, 0, 0); } while (0)
; #define PG8_LDA(dst, b, h) do { _Pragma("unroll") for (int m = 0; m < 4; ++m) _Pragma("unroll") for (int k = 0; k < 2; ++k) dst[m][k] = *(const PG8_LAS bf16x8*)(lds + PG8_SA(b, h) + aoff + m * 2048 + k * 1024); } while (0)
; #define PG8_MMA(ai, bj, At, Bt) do { __builtin_amdgcn_s_setprio(1); _Pragma("unroll") for (int m = 0; m < 4; ++m) _Pragma("unroll") for (int n = 0; n < 2; ++n) _Pragma("unroll") for (int k = 0; k < 2; ++k) \
;         acc[ai][bj][m][n] = __builtin_amdgcn_mfma_f32_16x16x32_bf16(Bt[n][k], At[m][k], acc[ai][bj][m][n], 0, 0, 0); __builtin_amdgcn_s_setprio(0); } while (0)
; #define PG8_WAIT_V(n) asm volatile("s_waitcnt vmcnt(" #n ")" ::: "memory")
; #define PG8_WAIT_L(n) asm volatile("s_waitcnt lgkmcnt(" #n ")" ::: "memory")
; #define PG8_BAR __builtin_amdgcn_s_barrier()
; #define PG8_SCHED __builtin_amdgcn_sched_barrier(0)
; template <class Epi, class Sched, bool ALIGN_EPI = false, bool SP2 = false>
; __device__ __forceinline__ void gemm_phase(PG8_LAS unsigned char* lds, const Gemm g, const Sched& S, const Epi& E) {
;     ...
;         for (int t = 0; t < nt; t += 2) {
;             const bool last = (t == nt - 2);
;             const char* a1 = cA + (size_t)(t + 1) * kstep;
;             const char* a2 = last ? nA : cA + (size_t)(t + 2) * kstep; const char* b2 = last ? nB : cB + (size_t)(t + 2) * kstep;
;             const char* a3 = a2 + kstep; const char* b3 = b2 + kstep;
;     ...
;             PG8_LDA(At, 1, 1); PG8_STAGE(PG8_SB(1, 0), b3, voffB); PG8_STAGE(PG8_SB(1, 1), b3 + hstep, voffB); PG8_STAGE(PG8_SA(1, 0), a3, voffA);
;             PG8_WAIT_V(8); PG8_WAIT_L(0); PG8_BAR; PG8_MMA(1, 0, At, B0); PG8_MMA(1, 1, At, B1); PG8_BAR; PG8_SCHED;
	s_mov_b32 m0, s48
	v_lshl_add_u64 v[214:215], v[214:215], 0, s[16:17]
	s_add_u32 s44, s52, 0xb0080
	ds_read_b128 v[182:185], v146 offset:49152
	ds_read_b128 v[186:189], v146 offset:50176
	ds_read_b128 v[190:193], v146 offset:51200
	ds_read_b128 v[194:197], v146 offset:52224
	ds_read_b128 v[198:201], v146 offset:53248
	ds_read_b128 v[202:205], v146 offset:54272
	ds_read_b128 v[206:209], v146 offset:55296
	ds_read_b128 v[210:213], v146 offset:56320
	global_load_lds_dwordx4 v[214:215], off
	v_lshl_add_u64 v[214:215], v[216:217], 0, s[16:17]
	s_mov_b32 m0, s49
	s_addc_u32 s45, s53, 0
	global_load_lds_dwordx4 v[214:215], off
	v_lshl_add_u64 v[214:215], s[44:45], 0, v[130:131]
	s_mov_b32 m0, s83
	s_nop 0
	global_load_lds_dwordx4 v[214:215], off
	v_lshl_add_u64 v[214:215], s[44:45], 0, v[136:137]
	s_mov_b32 m0, s84
	s_nop 0
	global_load_lds_dwordx4 v[214:215], off
	v_lshl_add_u64 v[214:215], v[218:219], 0, s[16:17]
	s_mov_b32 m0, s50
	s_nop 0
	global_load_lds_dwordx4 v[214:215], off
	v_lshl_add_u64 v[214:215], v[220:221], 0, s[16:17]
	s_mov_b32 m0, s51
	s_nop 0
	global_load_lds_dwordx4 v[214:215], off
	s_waitcnt vmcnt(8)
	s_waitcnt lgkmcnt(0)
	s_barrier
	s_setprio 1
	s_waitcnt lgkmcnt(0)
	v_mfma_f32_16x16x32_bf16 v[62:65], v[150:153], v[182:185], v[62:65]
	v_mfma_f32_16x16x32_bf16 v[58:61], v[158:161], v[182:185], v[58:61]
	v_mfma_f32_16x16x32_bf16 v[54:57], v[150:153], v[190:193], v[54:57]
	v_mfma_f32_16x16x32_bf16 v[50:53], v[158:161], v[190:193], v[50:53]
	v_mfma_f32_16x16x32_bf16 v[38:41], v[150:153], v[198:201], v[38:41]
	v_mfma_f32_16x16x32_bf16 v[34:37], v[158:161], v[198:201], v[34:37]
	v_mfma_f32_16x16x32_bf16 v[22:25], v[150:153], v[206:209], v[22:25]
	v_mfma_f32_16x16x32_bf16 v[18:21], v[158:161], v[206:209], v[18:21]
	v_mfma_f32_16x16x32_bf16 v[62:65], v[154:157], v[186:189], v[62:65]
	v_mfma_f32_16x16x32_bf16 v[58:61], v[162:165], v[186:189], v[58:61]
	v_mfma_f32_16x16x32_bf16 v[54:57], v[154:157], v[194:197], v[54:57]
	v_mfma_f32_16x16x32_bf16 v[50:53], v[162:165], v[194:197], v[50:53]
	v_mfma_f32_16x16x32_bf16 v[38:41], v[154:157], v[202:205], v[38:41]
	v_mfma_f32_16x16x32_bf16 v[34:37], v[162:165], v[202:205], v[34:37]
	v_mfma_f32_16x16x32_bf16 v[22:25], v[154:157], v[210:213], v[22:25]
	v_mfma_f32_16x16x32_bf16 v[18:21], v[162:165], v[210:213], v[18:21]
	s_setprio 0
	s_setprio 1
	v_mfma_f32_16x16x32_bf16 v[46:49], v[166:169], v[182:185], v[46:49]
	v_mfma_f32_16x16x32_bf16 v[42:45], v[174:177], v[182:185], v[42:45]
	v_mfma_f32_16x16x32_bf16 v[30:33], v[166:169], v[190:193], v[30:33]
	v_mfma_f32_16x16x32_bf16 v[26:29], v[174:177], v[190:193], v[26:29]
	v_mfma_f32_16x16x32_bf16 v[14:17], v[166:169], v[198:201], v[14:17]
	v_mfma_f32_16x16x32_bf16 v[10:13], v[174:177], v[198:201], v[10:13]
	v_mfma_f32_16x16x32_bf16 v[6:9], v[166:169], v[206:209], v[6:9]
	v_mfma_f32_16x16x32_bf16 v[2:5], v[174:177], v[206:209], v[2:5]
	v_mfma_f32_16x16x32_bf16 v[46:49], v[170:173], v[186:189], v[46:49]
	v_mfma_f32_16x16x32_bf16 v[42:45], v[178:181], v[186:189], v[42:45]
	v_mfma_f32_16x16x32_bf16 v[30:33], v[170:173], v[194:197], v[30:33]
	v_mfma_f32_16x16x32_bf16 v[26:29], v[178:181], v[194:197], v[26:29]
	v_mfma_f32_16x16x32_bf16 v[14:17], v[170:173], v[202:205], v[14:17]
	v_mfma_f32_16x16x32_bf16 v[10:13], v[178:181], v[202:205], v[10:13]
	v_mfma_f32_16x16x32_bf16 v[6:9], v[170:173], v[210:213], v[6:9]
	v_mfma_f32_16x16x32_bf16 v[2:5], v[178:181], v[210:213], v[2:5]
	s_setprio 0
	s_add_u32 s91, s91, 0x100
	s_addc_u32 s92, s92, 0
	s_cmp_ge_u32 s93, s81
	s_mov_b64 s[44:45], s[46:47]
	s_mov_b32 s52, s93
	s_barrier
	s_cbranch_scc0 .LBB0_1126
	s_and_b64 vcc, exec, s[38:39]
	s_cbranch_vccz .LBB0_1129
	s_barrier

; #define PG8_STAGE(bufoff, gbase, voff) do { _Pragma("unroll") for (int _i = 0; _i < 2; ++_i) \
;         __builtin_amdgcn_global_load_lds((const unsigned*)((const char*)(gbase) + (voff)[_i]), (PG8_LAS unsigned*)(lds + (bufoff) + ldsw + _i * 8192), 16, 0, 0); } while (0)
; #define PG8_LDA(dst, b, h) do { _Pragma("unroll") for (int m = 0; m < 4; ++m) _Pragma("unroll") for (int k = 0; k < 2; ++k) dst[m][k] = *(const PG8_LAS bf16x8*)(lds + PG8_SA(b, h) + aoff + m * 2048 + k * 1024); } while (0)
; #define PG8_LDB(dst, b, h) do { _Pragma("unroll") for (int n = 0; n < 2; ++n) _Pragma("unroll") for (int k = 0; k < 2; ++k) dst[n][k] = *(const PG8_LAS bf16x8*)(lds + PG8_SB(b, h) + boff + n * 2048 + k * 1024); } while (0)
; #define PG8_MMA(ai, bj, At, Bt) do { __builtin_amdgcn_s_setprio(1); _Pragma("unroll") for (int m = 0; m < 4; ++m) _Pragma("unroll") for (int n = 0; n < 2; ++n) _Pragma("unroll") for (int k = 0; k < 2; ++k) \
;         acc[ai][bj][m][n] = __builtin_amdgcn_mfma_f32_16x16x32_bf16(Bt[n][k], At[m][k], acc[ai][bj][m][n], 0, 0, 0); __builtin_amdgcn_s_setprio(0); } while (0)
; template <class Epi, class Sched, bool ALIGN_EPI = false, bool SP2 = false>
; __device__ __forceinline__ void gemm_phase(PG8_LAS unsigned char* lds, const Gemm g, const Sched& S, const Epi& E) {
;     ...
;         const bool has_next = S.next(ui + 1, nxt);
;         const char* nA = has_next ? (const char*)g.A + (size_t)nxt.pm * tstep + (size_t)nxt.ks * K * 2 : cA; const char* nB = has_next ? (const char*)g.Bt + (size_t)nxt.pn * tstep + (size_t)nxt.ks * K * 2 : cB;
;         for (int t = 0; t < nt; t += 2) {
;             const bool last = (t == nt - 2);
;             const char* a1 = cA + (size_t)(t + 1) * kstep;
;             const char* a2 = last ? nA : cA + (size_t)(t + 2) * kstep; const char* b2 = last ? nB : cB + (size_t)(t + 2) * kstep;
;             const char* a3 = a2 + kstep; const char* b3 = b2 + kstep;
;             if (last && has_next) S.a_ready(nxt);
;             if constexpr (SP2) {
;             PG8_LDB(B0, 0, 0); PG8_LDB(B1, 0, 1); PG8_SCHED; PG8_LDA(At, 0, 0); PG8_STAGE(PG8_SA(1, 1), a1 + hstep, voffA);
;             PG8_WAIT_V(8); PG8_WAIT_L(0); PG8_BAR; PG8_MMA(0, 0, At, B0); PG8_MMA(0, 1, At, B1); PG8_BAR; PG8_SCHED;
;             PG8_LDA(At, 0, 1); PG8_STAGE(PG8_SB(0, 0), b2, voffB); PG8_STAGE(PG8_SB(0, 1), b2 + hstep, voffB); PG8_STAGE(PG8_SA(0, 0), a2, voffA);
.LBB0_1582:
	s_ashr_i32 s73, s72, 31
	s_lshl_b64 s[12:13], s[72:73], 19
	s_add_u32 s74, s87, s12
	s_addc_u32 s75, s88, s13
	s_and_b64 s[12:13], s[4:5], exec
	s_cselect_b32 s7, s75, s11
	s_cselect_b32 s14, s74, s10
	s_ashr_i32 s71, s70, 31
	s_lshl_b64 s[12:13], s[70:71], 19
	s_add_u32 s76, s89, s12
	s_addc_u32 s77, s90, s13
	s_and_b64 s[12:13], s[4:5], exec
	s_cselect_b32 s15, s77, s9
	s_cselect_b32 s16, s76, s8
	s_add_u32 s17, s8, 0x100
	s_addc_u32 s18, s9, 0
	s_add_u32 s8, s10, 0x40080
	s_addc_u32 s9, s11, 0
	s_mov_b32 s19, -2
	ds_read_b128 v[130:133], v171
	ds_read_b128 v[134:137], v171 offset:1024
	ds_read_b128 v[156:159], v171 offset:2048
	ds_read_b128 v[160:163], v171 offset:3072
	ds_read_b128 v[164:167], v172
	ds_read_b128 v[178:181], v172 offset:1024
	ds_read_b128 v[182:185], v172 offset:2048
	ds_read_b128 v[186:189], v172 offset:3072
	s_add_u32 s10, s8, 0xfffc0080
	s_addc_u32 s11, s9, -1
	s_cmp_eq_u32 s19, 12
	s_cselect_b32 s13, s7, s11
	s_cselect_b32 s12, s14, s10
	s_cselect_b32 s11, s15, s18
	s_cselect_b32 s10, s16, s17
	v_lshl_add_u64 v[222:223], s[8:9], 0, v[150:151]
	s_add_i32 m0, s95, 0xc000
	ds_read_b128 v[190:193], v173
	ds_read_b128 v[194:197], v173 offset:1024
	ds_read_b128 v[198:201], v173 offset:2048
	ds_read_b128 v[202:205], v173 offset:3072
	ds_read_b128 v[206:209], v173 offset:4096
	ds_read_b128 v[210:213], v173 offset:5120
	ds_read_b128 v[214:217], v173 offset:6144
	ds_read_b128 v[218:221], v173 offset:7168
	global_load_lds_dwordx4 v[222:223], off
	v_lshl_add_u64 v[222:223], s[8:9], 0, v[148:149]
	s_add_i32 m0, s95, 0xe000
	s_nop 0
	global_load_lds_dwordx4 v[222:223], off
	s_waitcnt vmcnt(8)
	s_waitcnt lgkmcnt(0)
	s_barrier
	s_setprio 1
	s_waitcnt lgkmcnt(0)
	v_mfma_f32_16x16x32_bf16 v[126:129], v[130:133], v[190:193], 0
	v_mfma_f32_16x16x32_bf16 v[122:125], v[156:159], v[190:193], 0
	v_mfma_f32_16x16x32_bf16 v[110:113], v[130:133], v[198:201], 0
	v_mfma_f32_16x16x32_bf16 v[106:109], v[156:159], v[198:201], 0
	v_mfma_f32_16x16x32_bf16 v[94:97], v[130:133], v[206:209], 0
	v_mfma_f32_16x16x32_bf16 v[90:93], v[156:159], v[206:209], 0
	v_mfma_f32_16x16x32_bf16 v[78:81], v[130:133], v[214:217], 0
	v_mfma_f32_16x16x32_bf16 v[74:77], v[156:159], v[214:217], 0
	v_mfma_f32_16x16x32_bf16 v[126:129], v[134:137], v[194:197], v[126:129]
	v_mfma_f32_16x16x32_bf16 v[122:125], v[160:163], v[194:197], v[122:125]
	v_mfma_f32_16x16x32_bf16 v[110:113], v[134:137], v[202:205], v[110:113]
	v_mfma_f32_16x16x32_bf16 v[106:109], v[160:163], v[202:205], v[106:109]
	v_mfma_f32_16x16x32_bf16 v[94:97], v[134:137], v[210:213], v[94:97]
	v_mfma_f32_16x16x32_bf16 v[90:93], v[160:163], v[210:213], v[90:93]
	v_mfma_f32_16x16x32_bf16 v[78:81], v[134:137], v[218:221], v[78:81]
	v_mfma_f32_16x16x32_bf16 v[74:77], v[160:163], v[218:221], v[74:77]
	s_setprio 0
	s_setprio 1
	v_mfma_f32_16x16x32_bf16 v[118:121], v[164:167], v[190:193], 0
	v_mfma_f32_16x16x32_bf16 v[114:117], v[182:185], v[190:193], 0
	v_mfma_f32_16x16x32_bf16 v[102:105], v[164:167], v[198:201], 0
	v_mfma_f32_16x16x32_bf16 v[98:101], v[182:185], v[198:201], 0
	v_mfma_f32_16x16x32_bf16 v[86:89], v[164:167], v[206:209], 0
	v_mfma_f32_16x16x32_bf16 v[82:85], v[182:185], v[206:209], 0
	v_mfma_f32_16x16x32_bf16 v[70:73], v[164:167], v[214:217], 0
	v_mfma_f32_16x16x32_bf16 v[66:69], v[182:185], v[214:217], 0
	v_mfma_f32_16x16x32_bf16 v[118:121], v[178:181], v[194:197], v[118:121]
	v_mfma_f32_16x16x32_bf16 v[114:117], v[186:189], v[194:197], v[114:117]
	v_mfma_f32_16x16x32_bf16 v[102:105], v[178:181], v[202:205], v[102:105]
	v_mfma_f32_16x16x32_bf16 v[98:101], v[186:189], v[202:205], v[98:101]
	v_mfma_f32_16x16x32_bf16 v[86:89], v[178:181], v[210:213], v[86:89]
	v_mfma_f32_16x16x32_bf16 v[82:85], v[186:189], v[210:213], v[82:85]
	v_mfma_f32_16x16x32_bf16 v[70:73], v[178:181], v[218:221], v[70:73]
	v_mfma_f32_16x16x32_bf16 v[66:69], v[186:189], v[218:221], v[66:69]
	s_setprio 0
	s_barrier
	s_mov_b32 m0, s91
	v_lshl_add_u64 v[222:223], s[10:11], 0, v[138:139]
	s_add_u32 s20, s10, 0x40000
	ds_read_b128 v[190:193], v173 offset:16384
	ds_read_b128 v[194:197], v173 offset:17408
	ds_read_b128 v[198:201], v173 offset:18432
	ds_read_b128 v[202:205], v173 offset:19456
	ds_read_b128 v[206:209], v173 offset:20480
	ds_read_b128 v[210:213], v173 offset:21504
	ds_read_b128 v[214:217], v173 offset:22528
	ds_read_b128 v[218:221], v173 offset:23552
	global_load_lds_dwordx4 v[222:223], off
	v_lshl_add_u64 v[224:225], s[10:11], 0, v[140:141]
	s_mov_b32 m0, s92
	s_addc_u32 s21, s11, 0
	global_load_lds_dwordx4 v[224:225], off
	v_lshl_add_u64 v[226:227], s[20:21], 0, v[138:139]
	s_mov_b32 m0, s93
	v_lshl_add_u64 v[228:229], s[12:13], 0, v[140:141]
	global_load_lds_dwordx4 v[226:227], off
	v_lshl_add_u64 v[226:227], s[20:21], 0, v[140:141]
	s_mov_b32 m0, s94
	s_nop 0
	global_load_lds_dwordx4 v[226:227], off
	v_lshl_add_u64 v[226:227], s[12:13], 0, v[138:139]
	s_mov_b32 m0, s95
	s_nop 0
	global_load_lds_dwordx4 v[226:227], off
	s_mov_b32 m0, s96
	s_nop 0
	global_load_lds_dwordx4 v[228:229], off
	s_waitcnt vmcnt(8)
	s_waitcnt lgkmcnt(0)
	s_barrier
; #define PG8_STAGE(bufoff, gbase, voff) do { _Pragma("unroll") for (int _i = 0; _i < 2; ++_i) \
;         __builtin_amdgcn_global_load_lds((const unsigned*)((const char*)(gbase) + (voff)[_i]), (PG8_LAS unsigned*)(lds + (bufoff) + ldsw + _i * 8192), 16, 0, 0); } while (0)
; #define PG8_LDA(dst, b, h) do { _Pragma("unroll") for (int m = 0; m < 4; ++m) _Pragma("unroll") for (int k = 0; k < 2; ++k) dst[m][k] = *(const PG8_LAS bf16x8*)(lds + PG8_SA(b, h) + aoff + m * 2048 + k * 1024); } while (0)
; #define PG8_LDB(dst, b, h) do { _Pragma("unroll") for (int n = 0; n < 2; ++n) _Pragma("unroll") for (int k = 0; k < 2; ++k) dst[n][k] = *(const PG8_LAS bf16x8*)(lds + PG8_SB(b, h) + boff + n * 2048 + k * 1024); } while (0)
; #define PG8_MMA(ai, bj, At, Bt) do { __builtin_amdgcn_s_setprio(1); _Pragma("unroll") for (int m = 0; m < 4; ++m) _Pragma("unroll") for (int n = 0; n < 2; ++n) _Pragma("unroll") for (int k = 0; k < 2; ++k) \
;         acc[ai][bj][m][n] = __builtin_amdgcn_mfma_f32_16x16x32_bf16(Bt[n][k], At[m][k], acc[ai][bj][m][n], 0, 0, 0); __builtin_amdgcn_s_setprio(0); } while (0)
; #define PG8_WAIT_V(n) asm volatile("s_waitcnt vmcnt(" #n ")" ::: "memory")
; #define PG8_WAIT_L(n) asm volatile("s_waitcnt lgkmcnt(" #n ")" ::: "memory")
; #define PG8_BAR __builtin_amdgcn_s_barrier()
; #define PG8_SCHED __builtin_amdgcn_sched_barrier(0)
; template <class Epi, class Sched, bool ALIGN_EPI = false, bool SP2 = false>
; __device__ __forceinline__ void gemm_phase(PG8_LAS unsigned char* lds, const Gemm g, const Sched& S, const Epi& E) {
;     ...
;             PG8_WAIT_V(8); PG8_WAIT_L(0); PG8_BAR; PG8_MMA(1, 0, At, B0); PG8_MMA(1, 1, At, B1); PG8_BAR; PG8_SCHED;
;             PG8_LDB(B0, 1, 0); PG8_LDB(B1, 1, 1); PG8_SCHED; PG8_LDA(At, 1, 0); PG8_STAGE(PG8_SA(0, 1), a2 + hstep, voffA);
;             PG8_WAIT_V(8); PG8_WAIT_L(0); PG8_BAR; PG8_MMA(0, 0, At, B0); PG8_MMA(0, 1, At, B1); PG8_BAR; PG8_SCHED;
	s_setprio 1
	s_waitcnt lgkmcnt(0)
	v_mfma_f32_16x16x32_bf16 v[62:65], v[130:133], v[190:193], 0
	v_mfma_f32_16x16x32_bf16 v[58:61], v[156:159], v[190:193], 0
	v_mfma_f32_16x16x32_bf16 v[46:49], v[130:133], v[198:201], 0
	v_mfma_f32_16x16x32_bf16 v[42:45], v[156:159], v[198:201], 0
	v_mfma_f32_16x16x32_bf16 v[30:33], v[130:133], v[206:209], 0
	v_mfma_f32_16x16x32_bf16 v[26:29], v[156:159], v[206:209], 0
	v_mfma_f32_16x16x32_bf16 v[14:17], v[130:133], v[214:217], 0
	v_mfma_f32_16x16x32_bf16 v[10:13], v[156:159], v[214:217], 0
	v_mfma_f32_16x16x32_bf16 v[62:65], v[134:137], v[194:197], v[62:65]
	v_mfma_f32_16x16x32_bf16 v[58:61], v[160:163], v[194:197], v[58:61]
	v_mfma_f32_16x16x32_bf16 v[46:49], v[134:137], v[202:205], v[46:49]
	v_mfma_f32_16x16x32_bf16 v[42:45], v[160:163], v[202:205], v[42:45]
	v_mfma_f32_16x16x32_bf16 v[30:33], v[134:137], v[210:213], v[30:33]
	v_mfma_f32_16x16x32_bf16 v[26:29], v[160:163], v[210:213], v[26:29]
	v_mfma_f32_16x16x32_bf16 v[14:17], v[134:137], v[218:221], v[14:17]
	v_mfma_f32_16x16x32_bf16 v[10:13], v[160:163], v[218:221], v[10:13]
	s_setprio 0
	s_setprio 1
	v_mfma_f32_16x16x32_bf16 v[54:57], v[164:167], v[190:193], 0
	v_mfma_f32_16x16x32_bf16 v[50:53], v[182:185], v[190:193], 0
	v_mfma_f32_16x16x32_bf16 v[38:41], v[164:167], v[198:201], 0
	v_mfma_f32_16x16x32_bf16 v[34:37], v[182:185], v[198:201], 0
	v_mfma_f32_16x16x32_bf16 v[22:25], v[164:167], v[206:209], 0
	v_mfma_f32_16x16x32_bf16 v[18:21], v[182:185], v[206:209], 0
	v_mfma_f32_16x16x32_bf16 v[6:9], v[164:167], v[214:217], 0
	v_mfma_f32_16x16x32_bf16 v[2:5], v[182:185], v[214:217], 0
	v_mfma_f32_16x16x32_bf16 v[54:57], v[178:181], v[194:197], v[54:57]
	v_mfma_f32_16x16x32_bf16 v[50:53], v[186:189], v[194:197], v[50:53]
	v_mfma_f32_16x16x32_bf16 v[38:41], v[178:181], v[202:205], v[38:41]
	v_mfma_f32_16x16x32_bf16 v[34:37], v[186:189], v[202:205], v[34:37]
	v_mfma_f32_16x16x32_bf16 v[22:25], v[178:181], v[210:213], v[22:25]
	v_mfma_f32_16x16x32_bf16 v[18:21], v[186:189], v[210:213], v[18:21]
	v_mfma_f32_16x16x32_bf16 v[6:9], v[178:181], v[218:221], v[6:9]
	v_mfma_f32_16x16x32_bf16 v[2:5], v[186:189], v[218:221], v[2:5]
	s_setprio 0
	s_barrier
	ds_read_b128 v[130:133], v174
	ds_read_b128 v[134:137], v174 offset:1024
	ds_read_b128 v[156:159], v174 offset:2048
	ds_read_b128 v[160:163], v174 offset:3072
	ds_read_b128 v[164:167], v175
	ds_read_b128 v[178:181], v175 offset:1024
	ds_read_b128 v[182:185], v175 offset:2048
	ds_read_b128 v[186:189], v175 offset:3072
	s_add_u32 s12, s12, 0x40000
	s_addc_u32 s13, s13, 0
	s_mov_b32 m0, s97
	v_lshl_add_u64 v[230:231], s[12:13], 0, v[138:139]
	ds_read_b128 v[190:193], v173 offset:32768
	ds_read_b128 v[194:197], v173 offset:33792
	ds_read_b128 v[198:201], v173 offset:34816
	ds_read_b128 v[202:205], v173 offset:35840
	ds_read_b128 v[206:209], v173 offset:36864
	ds_read_b128 v[210:213], v173 offset:37888
	ds_read_b128 v[214:217], v173 offset:38912
	ds_read_b128 v[218:221], v173 offset:39936
	global_load_lds_dwordx4 v[230:231], off
	v_lshl_add_u64 v[230:231], s[12:13], 0, v[140:141]
	s_mov_b32 m0, s30
	s_nop 0
	global_load_lds_dwordx4 v[230:231], off
	s_waitcnt vmcnt(8)
	s_waitcnt lgkmcnt(0)
	s_barrier
	s_setprio 1
	s_waitcnt lgkmcnt(0)
	v_mfma_f32_16x16x32_bf16 v[126:129], v[130:133], v[190:193], v[126:129]
	v_mfma_f32_16x16x32_bf16 v[122:125], v[156:159], v[190:193], v[122:125]
	v_mfma_f32_16x16x32_bf16 v[110:113], v[130:133], v[198:201], v[110:113]
	v_mfma_f32_16x16x32_bf16 v[106:109], v[156:159], v[198:201], v[106:109]
	v_mfma_f32_16x16x32_bf16 v[94:97], v[130:133], v[206:209], v[94:97]
	v_mfma_f32_16x16x32_bf16 v[90:93], v[156:159], v[206:209], v[90:93]
	v_mfma_f32_16x16x32_bf16 v[78:81], v[130:133], v[214:217], v[78:81]
	v_mfma_f32_16x16x32_bf16 v[74:77], v[156:159], v[214:217], v[74:77]
	v_mfma_f32_16x16x32_bf16 v[126:129], v[134:137], v[194:197], v[126:129]
	v_mfma_f32_16x16x32_bf16 v[122:125], v[160:163], v[194:197], v[122:125]
	v_mfma_f32_16x16x32_bf16 v[110:113], v[134:137], v[202:205], v[110:113]
	v_mfma_f32_16x16x32_bf16 v[106:109], v[160:163], v[202:205], v[106:109]
	v_mfma_f32_16x16x32_bf16 v[94:97], v[134:137], v[210:213], v[94:97]
	v_mfma_f32_16x16x32_bf16 v[90:93], v[160:163], v[210:213], v[90:93]
	v_mfma_f32_16x16x32_bf16 v[78:81], v[134:137], v[218:221], v[78:81]
	v_mfma_f32_16x16x32_bf16 v[74:77], v[160:163], v[218:221], v[74:77]
	s_setprio 0
	s_setprio 1
	v_mfma_f32_16x16x32_bf16 v[118:121], v[164:167], v[190:193], v[118:121]
	v_mfma_f32_16x16x32_bf16 v[114:117], v[182:185], v[190:193], v[114:117]
	v_mfma_f32_16x16x32_bf16 v[102:105], v[164:167], v[198:201], v[102:105]
	v_mfma_f32_16x16x32_bf16 v[98:101], v[182:185], v[198:201], v[98:101]
	v_mfma_f32_16x16x32_bf16 v[86:89], v[164:167], v[206:209], v[86:89]
	v_mfma_f32_16x16x32_bf16 v[82:85], v[182:185], v[206:209], v[82:85]
	v_mfma_f32_16x16x32_bf16 v[70:73], v[164:167], v[214:217], v[70:73]
	v_mfma_f32_16x16x32_bf16 v[66:69], v[182:185], v[214:217], v[66:69]
	v_mfma_f32_16x16x32_bf16 v[118:121], v[178:181], v[194:197], v[118:121]
	v_mfma_f32_16x16x32_bf16 v[114:117], v[186:189], v[194:197], v[114:117]
	v_mfma_f32_16x16x32_bf16 v[102:105], v[178:181], v[202:205], v[102:105]
	v_mfma_f32_16x16x32_bf16 v[98:101], v[186:189], v[202:205], v[98:101]
	v_mfma_f32_16x16x32_bf16 v[86:89], v[178:181], v[210:213], v[86:89]
	v_mfma_f32_16x16x32_bf16 v[82:85], v[186:189], v[210:213], v[82:85]
	v_mfma_f32_16x16x32_bf16 v[70:73], v[178:181], v[218:221], v[70:73]
	v_mfma_f32_16x16x32_bf16 v[66:69], v[186:189], v[218:221], v[66:69]
	s_setprio 0
	s_barrier
; #define PG8_STAGE(bufoff, gbase, voff) do { _Pragma("unroll") for (int _i = 0; _i < 2; ++_i) \
;         __builtin_amdgcn_global_load_lds((const unsigned*)((const char*)(gbase) + (voff)[_i]), (PG8_LAS unsigned*)(lds + (bufoff) + ldsw + _i * 8192), 16, 0, 0); } while (0)
; #define PG8_LDA(dst, b, h) do { _Pragma("unroll") for (int m = 0; m < 4; ++m) _Pragma("unroll") for (int k = 0; k < 2; ++k) dst[m][k] = *(const PG8_LAS bf16x8*)(lds + PG8_SA(b, h) + aoff + m * 2048 + k * 1024); } while (0)
; #define PG8_LDB(dst, b, h) do { _Pragma("unroll") for (int n = 0; n < 2; ++n) _Pragma("unroll") for (int k = 0; k < 2; ++k) dst[n][k] = *(const PG8_LAS bf16x8*)(lds + PG8_SB(b, h) + boff + n * 2048 + k * 1024); } while (0)
; #define PG8_MMA(ai, bj, At, Bt) do { __builtin_amdgcn_s_setprio(1); _Pragma("unroll") for (int m = 0; m < 4; ++m) _Pragma("unroll") for (int n = 0; n < 2; ++n) _Pragma("unroll") for (int k = 0; k < 2; ++k) \
;         acc[ai][bj][m][n] = __builtin_amdgcn_mfma_f32_16x16x32_bf16(Bt[n][k], At[m][k], acc[ai][bj][m][n], 0, 0, 0); __builtin_amdgcn_s_setprio(0); } while (0)
; #define PG8_WAIT_V(n) asm volatile("s_waitcnt vmcnt(" #n ")" ::: "memory")
; #define PG8_BAR __builtin_amdgcn_s_barrier()
; template <class Epi, class Sched, bool ALIGN_EPI = false, bool SP2 = false>
; __device__ __forceinline__ void gemm_phase(PG8_LAS unsigned char* lds, const Gemm g, const Sched& S, const Epi& E) {
;     ...
;         for (int t = 0; t < nt; t += 2) {
;             const bool last = (t == nt - 2);
;             const char* a1 = cA + (size_t)(t + 1) * kstep;
;             const char* a2 = last ? nA : cA + (size_t)(t + 2) * kstep; const char* b2 = last ? nB : cB + (size_t)(t + 2) * kstep;
;             const char* a3 = a2 + kstep; const char* b3 = b2 + kstep;
;             if (last && has_next) S.a_ready(nxt);
;             if constexpr (SP2) {
;             PG8_LDB(B0, 0, 0); PG8_LDB(B1, 0, 1); PG8_SCHED; PG8_LDA(At, 0, 0); PG8_STAGE(PG8_SA(1, 1), a1 + hstep, voffA);
;             PG8_WAIT_V(8); PG8_WAIT_L(0); PG8_BAR; PG8_MMA(0, 0, At, B0); PG8_MMA(0, 1, At, B1); PG8_BAR; PG8_SCHED;
;     ...
;             PG8_LDA(At, 1, 1); PG8_STAGE(PG8_SB(1, 0), b3, voffB); PG8_STAGE(PG8_SB(1, 1), b3 + hstep, voffB); PG8_STAGE(PG8_SA(1, 0), a3, voffA);
;             PG8_WAIT_V(8); PG8_WAIT_L(0); PG8_BAR; PG8_MMA(1, 0, At, B0); PG8_MMA(1, 1, At, B1); PG8_BAR; PG8_SCHED;
	s_mov_b32 m0, s63
	v_lshl_add_u64 v[222:223], v[222:223], 0, s[56:57]
	s_add_u32 s10, s10, 0x40080
	ds_read_b128 v[190:193], v173 offset:49152
	ds_read_b128 v[194:197], v173 offset:50176
	ds_read_b128 v[198:201], v173 offset:51200
	ds_read_b128 v[202:205], v173 offset:52224
	ds_read_b128 v[206:209], v173 offset:53248
	ds_read_b128 v[210:213], v173 offset:54272
	ds_read_b128 v[214:217], v173 offset:55296
	ds_read_b128 v[218:221], v173 offset:56320
	global_load_lds_dwordx4 v[222:223], off
	v_lshl_add_u64 v[222:223], v[224:225], 0, s[56:57]
	s_mov_b32 m0, s64
	s_addc_u32 s11, s11, 0
	global_load_lds_dwordx4 v[222:223], off
	v_lshl_add_u64 v[222:223], s[10:11], 0, v[138:139]
	s_mov_b32 m0, s67
	s_nop 0
	global_load_lds_dwordx4 v[222:223], off
	v_lshl_add_u64 v[222:223], s[10:11], 0, v[140:141]
	s_mov_b32 m0, s26
	s_nop 0
	global_load_lds_dwordx4 v[222:223], off
	v_lshl_add_u64 v[222:223], v[226:227], 0, s[56:57]
	s_mov_b32 m0, s65
	s_nop 0
	global_load_lds_dwordx4 v[222:223], off
	v_lshl_add_u64 v[222:223], v[228:229], 0, s[56:57]
	s_mov_b32 m0, s66
	s_nop 0
	global_load_lds_dwordx4 v[222:223], off
	s_waitcnt vmcnt(8)
	s_waitcnt lgkmcnt(0)
	s_barrier
	s_setprio 1
	s_waitcnt lgkmcnt(0)
	v_mfma_f32_16x16x32_bf16 v[62:65], v[130:133], v[190:193], v[62:65]
	v_mfma_f32_16x16x32_bf16 v[58:61], v[156:159], v[190:193], v[58:61]
	v_mfma_f32_16x16x32_bf16 v[46:49], v[130:133], v[198:201], v[46:49]
	v_mfma_f32_16x16x32_bf16 v[42:45], v[156:159], v[198:201], v[42:45]
	v_mfma_f32_16x16x32_bf16 v[30:33], v[130:133], v[206:209], v[30:33]
	v_mfma_f32_16x16x32_bf16 v[26:29], v[156:159], v[206:209], v[26:29]
	v_mfma_f32_16x16x32_bf16 v[14:17], v[130:133], v[214:217], v[14:17]
	v_mfma_f32_16x16x32_bf16 v[10:13], v[156:159], v[214:217], v[10:13]
	v_mfma_f32_16x16x32_bf16 v[62:65], v[134:137], v[194:197], v[62:65]
	v_mfma_f32_16x16x32_bf16 v[58:61], v[160:163], v[194:197], v[58:61]
	v_mfma_f32_16x16x32_bf16 v[46:49], v[134:137], v[202:205], v[46:49]
	v_mfma_f32_16x16x32_bf16 v[42:45], v[160:163], v[202:205], v[42:45]
	v_mfma_f32_16x16x32_bf16 v[30:33], v[134:137], v[210:213], v[30:33]
	v_mfma_f32_16x16x32_bf16 v[26:29], v[160:163], v[210:213], v[26:29]
	v_mfma_f32_16x16x32_bf16 v[14:17], v[134:137], v[218:221], v[14:17]
	v_mfma_f32_16x16x32_bf16 v[10:13], v[160:163], v[218:221], v[10:13]
	s_setprio 0
	s_setprio 1
	v_mfma_f32_16x16x32_bf16 v[54:57], v[164:167], v[190:193], v[54:57]
	v_mfma_f32_16x16x32_bf16 v[50:53], v[182:185], v[190:193], v[50:53]
	v_mfma_f32_16x16x32_bf16 v[38:41], v[164:167], v[198:201], v[38:41]
	v_mfma_f32_16x16x32_bf16 v[34:37], v[182:185], v[198:201], v[34:37]
	v_mfma_f32_16x16x32_bf16 v[22:25], v[164:167], v[206:209], v[22:25]
	v_mfma_f32_16x16x32_bf16 v[18:21], v[182:185], v[206:209], v[18:21]
	v_mfma_f32_16x16x32_bf16 v[6:9], v[164:167], v[214:217], v[6:9]
	v_mfma_f32_16x16x32_bf16 v[2:5], v[182:185], v[214:217], v[2:5]
	v_mfma_f32_16x16x32_bf16 v[54:57], v[178:181], v[194:197], v[54:57]
	v_mfma_f32_16x16x32_bf16 v[50:53], v[186:189], v[194:197], v[50:53]
	v_mfma_f32_16x16x32_bf16 v[38:41], v[178:181], v[202:205], v[38:41]
	v_mfma_f32_16x16x32_bf16 v[34:37], v[186:189], v[202:205], v[34:37]
	v_mfma_f32_16x16x32_bf16 v[22:25], v[178:181], v[210:213], v[22:25]
	v_mfma_f32_16x16x32_bf16 v[18:21], v[186:189], v[210:213], v[18:21]
	v_mfma_f32_16x16x32_bf16 v[6:9], v[178:181], v[218:221], v[6:9]
	v_mfma_f32_16x16x32_bf16 v[2:5], v[186:189], v[218:221], v[2:5]
	s_setprio 0
	s_add_i32 s19, s19, 2
	s_add_u32 s17, s17, 0x100
	s_addc_u32 s18, s18, 0
	s_add_u32 s8, s8, 0x100
	s_addc_u32 s9, s9, 0
	s_cmp_gt_u32 s19, 13
	s_barrier
.LBB0_1583:
	ds_read_b128 v[130:133], v171
	ds_read_b128 v[134:137], v171 offset:1024
	ds_read_b128 v[156:159], v171 offset:2048
	ds_read_b128 v[160:163], v171 offset:3072
	ds_read_b128 v[164:167], v172
	ds_read_b128 v[178:181], v172 offset:1024
	ds_read_b128 v[182:185], v172 offset:2048
	ds_read_b128 v[186:189], v172 offset:3072
	s_add_u32 s10, s8, 0xfffc0080
	s_addc_u32 s11, s9, -1
	s_cmp_eq_u32 s19, 12
	s_cselect_b32 s13, s7, s11
	s_cselect_b32 s12, s14, s10
	s_cselect_b32 s11, s15, s18
	s_cselect_b32 s10, s16, s17
	v_lshl_add_u64 v[222:223], s[8:9], 0, v[150:151]
	s_add_i32 m0, s95, 0xc000
	ds_read_b128 v[190:193], v173
	ds_read_b128 v[194:197], v173 offset:1024
	ds_read_b128 v[198:201], v173 offset:2048
	ds_read_b128 v[202:205], v173 offset:3072
	ds_read_b128 v[206:209], v173 offset:4096
	ds_read_b128 v[210:213], v173 offset:5120
	ds_read_b128 v[214:217], v173 offset:6144
	ds_read_b128 v[218:221], v173 offset:7168
	global_load_lds_dwordx4 v[222:223], off
	v_lshl_add_u64 v[222:223], s[8:9], 0, v[148:149]
	s_add_i32 m0, s95, 0xe000
	s_nop 0
	global_load_lds_dwordx4 v[222:223], off
	s_waitcnt vmcnt(8)
	s_waitcnt lgkmcnt(0)
	s_barrier
; #define PG8_STAGE(bufoff, gbase, voff) do { _Pragma("unroll") for (int _i = 0; _i < 2; ++_i) \
;         __builtin_amdgcn_global_load_lds((const unsigned*)((const char*)(gbase) + (voff)[_i]), (PG8_LAS unsigned*)(lds + (bufoff) + ldsw + _i * 8192), 16, 0, 0); } while (0)
; #define PG8_LDA(dst, b, h) do { _Pragma("unroll") for (int m = 0; m < 4; ++m) _Pragma("unroll") for (int k = 0; k < 2; ++k) dst[m][k] = *(const PG8_LAS bf16x8*)(lds + PG8_SA(b, h) + aoff + m * 2048 + k * 1024); } while (0)
; #define PG8_MMA(ai, bj, At, Bt) do { __builtin_amdgcn_s_setprio(1); _Pragma("unroll") for (int m = 0; m < 4; ++m) _Pragma("unroll") for (int n = 0; n < 2; ++n) _Pragma("unroll") for (int k = 0; k < 2; ++k) \
;         acc[ai][bj][m][n] = __builtin_amdgcn_mfma_f32_16x16x32_bf16(Bt[n][k], At[m][k], acc[ai][bj][m][n], 0, 0, 0); __builtin_amdgcn_s_setprio(0); } while (0)
; #define PG8_WAIT_V(n) asm volatile("s_waitcnt vmcnt(" #n ")" ::: "memory")
; #define PG8_WAIT_L(n) asm volatile("s_waitcnt lgkmcnt(" #n ")" ::: "memory")
; #define PG8_BAR __builtin_amdgcn_s_barrier()
; #define PG8_SCHED __builtin_amdgcn_sched_barrier(0)
; template <class Epi, class Sched, bool ALIGN_EPI = false, bool SP2 = false>
; __device__ __forceinline__ void gemm_phase(PG8_LAS unsigned char* lds, const Gemm g, const Sched& S, const Epi& E) {
;     ...
;             PG8_WAIT_V(8); PG8_WAIT_L(0); PG8_BAR; PG8_MMA(0, 0, At, B0); PG8_MMA(0, 1, At, B1); PG8_BAR; PG8_SCHED;
;             PG8_LDA(At, 0, 1); PG8_STAGE(PG8_SB(0, 0), b2, voffB); PG8_STAGE(PG8_SB(0, 1), b2 + hstep, voffB); PG8_STAGE(PG8_SA(0, 0), a2, voffA);
;             PG8_WAIT_V(8); PG8_WAIT_L(0); PG8_BAR; PG8_MMA(1, 0, At, B0); PG8_MMA(1, 1, At, B1); PG8_BAR; PG8_SCHED;
	s_setprio 1
	s_waitcnt lgkmcnt(0)
	v_mfma_f32_16x16x32_bf16 v[126:129], v[130:133], v[190:193], v[126:129]
	v_mfma_f32_16x16x32_bf16 v[122:125], v[156:159], v[190:193], v[122:125]
	v_mfma_f32_16x16x32_bf16 v[110:113], v[130:133], v[198:201], v[110:113]
	v_mfma_f32_16x16x32_bf16 v[106:109], v[156:159], v[198:201], v[106:109]
	v_mfma_f32_16x16x32_bf16 v[94:97], v[130:133], v[206:209], v[94:97]
	v_mfma_f32_16x16x32_bf16 v[90:93], v[156:159], v[206:209], v[90:93]
	v_mfma_f32_16x16x32_bf16 v[78:81], v[130:133], v[214:217], v[78:81]
	v_mfma_f32_16x16x32_bf16 v[74:77], v[156:159], v[214:217], v[74:77]
	v_mfma_f32_16x16x32_bf16 v[126:129], v[134:137], v[194:197], v[126:129]
	v_mfma_f32_16x16x32_bf16 v[122:125], v[160:163], v[194:197], v[122:125]
	v_mfma_f32_16x16x32_bf16 v[110:113], v[134:137], v[202:205], v[110:113]
	v_mfma_f32_16x16x32_bf16 v[106:109], v[160:163], v[202:205], v[106:109]
	v_mfma_f32_16x16x32_bf16 v[94:97], v[134:137], v[210:213], v[94:97]
	v_mfma_f32_16x16x32_bf16 v[90:93], v[160:163], v[210:213], v[90:93]
	v_mfma_f32_16x16x32_bf16 v[78:81], v[134:137], v[218:221], v[78:81]
	v_mfma_f32_16x16x32_bf16 v[74:77], v[160:163], v[218:221], v[74:77]
	s_setprio 0
	s_setprio 1
	v_mfma_f32_16x16x32_bf16 v[118:121], v[164:167], v[190:193], v[118:121]
	v_mfma_f32_16x16x32_bf16 v[114:117], v[182:185], v[190:193], v[114:117]
	v_mfma_f32_16x16x32_bf16 v[102:105], v[164:167], v[198:201], v[102:105]
	v_mfma_f32_16x16x32_bf16 v[98:101], v[182:185], v[198:201], v[98:101]
	v_mfma_f32_16x16x32_bf16 v[86:89], v[164:167], v[206:209], v[86:89]
	v_mfma_f32_16x16x32_bf16 v[82:85], v[182:185], v[206:209], v[82:85]
	v_mfma_f32_16x16x32_bf16 v[70:73], v[164:167], v[214:217], v[70:73]
	v_mfma_f32_16x16x32_bf16 v[66:69], v[182:185], v[214:217], v[66:69]
	v_mfma_f32_16x16x32_bf16 v[118:121], v[178:181], v[194:197], v[118:121]
	v_mfma_f32_16x16x32_bf16 v[114:117], v[186:189], v[194:197], v[114:117]
	v_mfma_f32_16x16x32_bf16 v[102:105], v[178:181], v[202:205], v[102:105]
	v_mfma_f32_16x16x32_bf16 v[98:101], v[186:189], v[202:205], v[98:101]
	v_mfma_f32_16x16x32_bf16 v[86:89], v[178:181], v[210:213], v[86:89]
	v_mfma_f32_16x16x32_bf16 v[82:85], v[186:189], v[210:213], v[82:85]
	v_mfma_f32_16x16x32_bf16 v[70:73], v[178:181], v[218:221], v[70:73]
	v_mfma_f32_16x16x32_bf16 v[66:69], v[186:189], v[218:221], v[66:69]
	s_setprio 0
	s_barrier
	s_mov_b32 m0, s91
	v_lshl_add_u64 v[222:223], s[10:11], 0, v[138:139]
	s_add_u32 s20, s10, 0x40000
	ds_read_b128 v[190:193], v173 offset:16384
	ds_read_b128 v[194:197], v173 offset:17408
	ds_read_b128 v[198:201], v173 offset:18432
	ds_read_b128 v[202:205], v173 offset:19456
	ds_read_b128 v[206:209], v173 offset:20480
	ds_read_b128 v[210:213], v173 offset:21504
	ds_read_b128 v[214:217], v173 offset:22528
	ds_read_b128 v[218:221], v173 offset:23552
	global_load_lds_dwordx4 v[222:223], off
	v_lshl_add_u64 v[224:225], s[10:11], 0, v[140:141]
	s_mov_b32 m0, s92
	s_addc_u32 s21, s11, 0
	global_load_lds_dwordx4 v[224:225], off
	v_lshl_add_u64 v[226:227], s[20:21], 0, v[138:139]
	s_mov_b32 m0, s93
	v_lshl_add_u64 v[228:229], s[12:13], 0, v[140:141]
	global_load_lds_dwordx4 v[226:227], off
	v_lshl_add_u64 v[226:227], s[20:21], 0, v[140:141]
	s_mov_b32 m0, s94
	s_nop 0
	global_load_lds_dwordx4 v[226:227], off
	v_lshl_add_u64 v[226:227], s[12:13], 0, v[138:139]
	s_mov_b32 m0, s95
	s_nop 0
	global_load_lds_dwordx4 v[226:227], off
	s_mov_b32 m0, s96
	s_nop 0
	global_load_lds_dwordx4 v[228:229], off
	s_waitcnt vmcnt(8)
	s_waitcnt lgkmcnt(0)
	s_barrier
	s_setprio 1
	s_waitcnt lgkmcnt(0)
	v_mfma_f32_16x16x32_bf16 v[62:65], v[130:133], v[190:193], v[62:65]
	v_mfma_f32_16x16x32_bf16 v[58:61], v[156:159], v[190:193], v[58:61]
	v_mfma_f32_16x16x32_bf16 v[46:49], v[130:133], v[198:201], v[46:49]
	v_mfma_f32_16x16x32_bf16 v[42:45], v[156:159], v[198:201], v[42:45]
	v_mfma_f32_16x16x32_bf16 v[30:33], v[130:133], v[206:209], v[30:33]
	v_mfma_f32_16x16x32_bf16 v[26:29], v[156:159], v[206:209], v[26:29]
	v_mfma_f32_16x16x32_bf16 v[14:17], v[130:133], v[214:217], v[14:17]
	v_mfma_f32_16x16x32_bf16 v[10:13], v[156:159], v[214:217], v[10:13]
	v_mfma_f32_16x16x32_bf16 v[62:65], v[134:137], v[194:197], v[62:65]
	v_mfma_f32_16x16x32_bf16 v[58:61], v[160:163], v[194:197], v[58:61]
	v_mfma_f32_16x16x32_bf16 v[46:49], v[134:137], v[202:205], v[46:49]
	v_mfma_f32_16x16x32_bf16 v[42:45], v[160:163], v[202:205], v[42:45]
	v_mfma_f32_16x16x32_bf16 v[30:33], v[134:137], v[210:213], v[30:33]
	v_mfma_f32_16x16x32_bf16 v[26:29], v[160:163], v[210:213], v[26:29]
	v_mfma_f32_16x16x32_bf16 v[14:17], v[134:137], v[218:221], v[14:17]
	v_mfma_f32_16x16x32_bf16 v[10:13], v[160:163], v[218:221], v[10:13]
	s_setprio 0
	s_setprio 1
	v_mfma_f32_16x16x32_bf16 v[54:57], v[164:167], v[190:193], v[54:57]
	v_mfma_f32_16x16x32_bf16 v[50:53], v[182:185], v[190:193], v[50:53]
	v_mfma_f32_16x16x32_bf16 v[38:41], v[164:167], v[198:201], v[38:41]
	v_mfma_f32_16x16x32_bf16 v[34:37], v[182:185], v[198:201], v[34:37]
	v_mfma_f32_16x16x32_bf16 v[22:25], v[164:167], v[206:209], v[22:25]
	v_mfma_f32_16x16x32_bf16 v[18:21], v[182:185], v[206:209], v[18:21]
	v_mfma_f32_16x16x32_bf16 v[6:9], v[164:167], v[214:217], v[6:9]
	v_mfma_f32_16x16x32_bf16 v[2:5], v[182:185], v[214:217], v[2:5]
	v_mfma_f32_16x16x32_bf16 v[54:57], v[178:181], v[194:197], v[54:57]
	v_mfma_f32_16x16x32_bf16 v[50:53], v[186:189], v[194:197], v[50:53]
	v_mfma_f32_16x16x32_bf16 v[38:41], v[178:181], v[202:205], v[38:41]
	v_mfma_f32_16x16x32_bf16 v[34:37], v[186:189], v[202:205], v[34:37]
	v_mfma_f32_16x16x32_bf16 v[22:25], v[178:181], v[210:213], v[22:25]
	v_mfma_f32_16x16x32_bf16 v[18:21], v[186:189], v[210:213], v[18:21]
	v_mfma_f32_16x16x32_bf16 v[6:9], v[178:181], v[218:221], v[6:9]
	v_mfma_f32_16x16x32_bf16 v[2:5], v[186:189], v[218:221], v[2:5]
	s_setprio 0
	s_barrier
; #define PG8_STAGE(bufoff, gbase, voff) do { _Pragma("unroll") for (int _i = 0; _i < 2; ++_i) \
;         __builtin_amdgcn_global_load_lds((const unsigned*)((const char*)(gbase) + (voff)[_i]), (PG8_LAS unsigned*)(lds + (bufoff) + ldsw + _i * 8192), 16, 0, 0); } while (0)
; #define PG8_LDA(dst, b, h) do { _Pragma("unroll") for (int m = 0; m < 4; ++m) _Pragma("unroll") for (int k = 0; k < 2; ++k) dst[m][k] = *(const PG8_LAS bf16x8*)(lds + PG8_SA(b, h) + aoff + m * 2048 + k * 1024); } while (0)
; #define PG8_LDB(dst, b, h) do { _Pragma("unroll") for (int n = 0; n < 2; ++n) _Pragma("unroll") for (int k = 0; k < 2; ++k) dst[n][k] = *(const PG8_LAS bf16x8*)(lds + PG8_SB(b, h) + boff + n * 2048 + k * 1024); } while (0)
; #define PG8_MMA(ai, bj, At, Bt) do { __builtin_amdgcn_s_setprio(1); _Pragma("unroll") for (int m = 0; m < 4; ++m) _Pragma("unroll") for (int n = 0; n < 2; ++n) _Pragma("unroll") for (int k = 0; k < 2; ++k) \
;         acc[ai][bj][m][n] = __builtin_amdgcn_mfma_f32_16x16x32_bf16(Bt[n][k], At[m][k], acc[ai][bj][m][n], 0, 0, 0); __builtin_amdgcn_s_setprio(0); } while (0)
; #define PG8_WAIT_V(n) asm volatile("s_waitcnt vmcnt(" #n ")" ::: "memory")
; #define PG8_WAIT_L(n) asm volatile("s_waitcnt lgkmcnt(" #n ")" ::: "memory")
; #define PG8_BAR __builtin_amdgcn_s_barrier()
; template <class Epi, class Sched, bool ALIGN_EPI = false, bool SP2 = false>
; __device__ __forceinline__ void gemm_phase(PG8_LAS unsigned char* lds, const Gemm g, const Sched& S, const Epi& E) {
;     ...
;         for (int t = 0; t < nt; t += 2) {
;             const bool last = (t == nt - 2);
;             const char* a1 = cA + (size_t)(t + 1) * kstep;
;             const char* a2 = last ? nA : cA + (size_t)(t + 2) * kstep; const char* b2 = last ? nB : cB + (size_t)(t + 2) * kstep;
;             const char* a3 = a2 + kstep; const char* b3 = b2 + kstep;
;     ...
;             PG8_LDB(B0, 1, 0); PG8_LDB(B1, 1, 1); PG8_SCHED; PG8_LDA(At, 1, 0); PG8_STAGE(PG8_SA(0, 1), a2 + hstep, voffA);
;             PG8_WAIT_V(8); PG8_WAIT_L(0); PG8_BAR; PG8_MMA(0, 0, At, B0); PG8_MMA(0, 1, At, B1); PG8_BAR; PG8_SCHED;
;             PG8_LDA(At, 1, 1); PG8_STAGE(PG8_SB(1, 0), b3, voffB); PG8_STAGE(PG8_SB(1, 1), b3 + hstep, voffB); PG8_STAGE(PG8_SA(1, 0), a3, voffA);
;             PG8_WAIT_V(8); PG8_WAIT_L(0); PG8_BAR; PG8_MMA(1, 0, At, B0); PG8_MMA(1, 1, At, B1); PG8_BAR; PG8_SCHED;
	ds_read_b128 v[130:133], v174
	ds_read_b128 v[134:137], v174 offset:1024
	ds_read_b128 v[156:159], v174 offset:2048
	ds_read_b128 v[160:163], v174 offset:3072
	ds_read_b128 v[164:167], v175
	ds_read_b128 v[178:181], v175 offset:1024
	ds_read_b128 v[182:185], v175 offset:2048
	ds_read_b128 v[186:189], v175 offset:3072
	s_add_u32 s12, s12, 0x40000
	s_addc_u32 s13, s13, 0
	s_mov_b32 m0, s97
	v_lshl_add_u64 v[230:231], s[12:13], 0, v[138:139]
	ds_read_b128 v[190:193], v173 offset:32768
	ds_read_b128 v[194:197], v173 offset:33792
	ds_read_b128 v[198:201], v173 offset:34816
	ds_read_b128 v[202:205], v173 offset:35840
	ds_read_b128 v[206:209], v173 offset:36864
	ds_read_b128 v[210:213], v173 offset:37888
	ds_read_b128 v[214:217], v173 offset:38912
	ds_read_b128 v[218:221], v173 offset:39936
	global_load_lds_dwordx4 v[230:231], off
	v_lshl_add_u64 v[230:231], s[12:13], 0, v[140:141]
	s_mov_b32 m0, s30
	s_nop 0
	global_load_lds_dwordx4 v[230:231], off
	s_waitcnt vmcnt(8)
	s_waitcnt lgkmcnt(0)
	s_barrier
	s_setprio 1
	s_waitcnt lgkmcnt(0)
	v_mfma_f32_16x16x32_bf16 v[126:129], v[130:133], v[190:193], v[126:129]
	v_mfma_f32_16x16x32_bf16 v[122:125], v[156:159], v[190:193], v[122:125]
	v_mfma_f32_16x16x32_bf16 v[110:113], v[130:133], v[198:201], v[110:113]
	v_mfma_f32_16x16x32_bf16 v[106:109], v[156:159], v[198:201], v[106:109]
	v_mfma_f32_16x16x32_bf16 v[94:97], v[130:133], v[206:209], v[94:97]
	v_mfma_f32_16x16x32_bf16 v[90:93], v[156:159], v[206:209], v[90:93]
	v_mfma_f32_16x16x32_bf16 v[78:81], v[130:133], v[214:217], v[78:81]
	v_mfma_f32_16x16x32_bf16 v[74:77], v[156:159], v[214:217], v[74:77]
	v_mfma_f32_16x16x32_bf16 v[126:129], v[134:137], v[194:197], v[126:129]
	v_mfma_f32_16x16x32_bf16 v[122:125], v[160:163], v[194:197], v[122:125]
	v_mfma_f32_16x16x32_bf16 v[110:113], v[134:137], v[202:205], v[110:113]
	v_mfma_f32_16x16x32_bf16 v[106:109], v[160:163], v[202:205], v[106:109]
	v_mfma_f32_16x16x32_bf16 v[94:97], v[134:137], v[210:213], v[94:97]
	v_mfma_f32_16x16x32_bf16 v[90:93], v[160:163], v[210:213], v[90:93]
	v_mfma_f32_16x16x32_bf16 v[78:81], v[134:137], v[218:221], v[78:81]
	v_mfma_f32_16x16x32_bf16 v[74:77], v[160:163], v[218:221], v[74:77]
	s_setprio 0
	s_setprio 1
	v_mfma_f32_16x16x32_bf16 v[118:121], v[164:167], v[190:193], v[118:121]
	v_mfma_f32_16x16x32_bf16 v[114:117], v[182:185], v[190:193], v[114:117]
	v_mfma_f32_16x16x32_bf16 v[102:105], v[164:167], v[198:201], v[102:105]
	v_mfma_f32_16x16x32_bf16 v[98:101], v[182:185], v[198:201], v[98:101]
	v_mfma_f32_16x16x32_bf16 v[86:89], v[164:167], v[206:209], v[86:89]
	v_mfma_f32_16x16x32_bf16 v[82:85], v[182:185], v[206:209], v[82:85]
	v_mfma_f32_16x16x32_bf16 v[70:73], v[164:167], v[214:217], v[70:73]
	v_mfma_f32_16x16x32_bf16 v[66:69], v[182:185], v[214:217], v[66:69]
	v_mfma_f32_16x16x32_bf16 v[118:121], v[178:181], v[194:197], v[118:121]
	v_mfma_f32_16x16x32_bf16 v[114:117], v[186:189], v[194:197], v[114:117]
	v_mfma_f32_16x16x32_bf16 v[102:105], v[178:181], v[202:205], v[102:105]
	v_mfma_f32_16x16x32_bf16 v[98:101], v[186:189], v[202:205], v[98:101]
	v_mfma_f32_16x16x32_bf16 v[86:89], v[178:181], v[210:213], v[86:89]
	v_mfma_f32_16x16x32_bf16 v[82:85], v[186:189], v[210:213], v[82:85]
	v_mfma_f32_16x16x32_bf16 v[70:73], v[178:181], v[218:221], v[70:73]
	v_mfma_f32_16x16x32_bf16 v[66:69], v[186:189], v[218:221], v[66:69]
	s_setprio 0
	s_barrier
	s_mov_b32 m0, s63
	v_lshl_add_u64 v[222:223], v[222:223], 0, s[56:57]
	s_add_u32 s10, s10, 0x40080
	ds_read_b128 v[190:193], v173 offset:49152
	ds_read_b128 v[194:197], v173 offset:50176
	ds_read_b128 v[198:201], v173 offset:51200
	ds_read_b128 v[202:205], v173 offset:52224
	ds_read_b128 v[206:209], v173 offset:53248
	ds_read_b128 v[210:213], v173 offset:54272
	ds_read_b128 v[214:217], v173 offset:55296
	ds_read_b128 v[218:221], v173 offset:56320
	global_load_lds_dwordx4 v[222:223], off
	v_lshl_add_u64 v[222:223], v[224:225], 0, s[56:57]
	s_mov_b32 m0, s64
	s_addc_u32 s11, s11, 0
	global_load_lds_dwordx4 v[222:223], off
	v_lshl_add_u64 v[222:223], s[10:11], 0, v[138:139]
	s_mov_b32 m0, s67
	s_nop 0
	global_load_lds_dwordx4 v[222:223], off
	v_lshl_add_u64 v[222:223], s[10:11], 0, v[140:141]
	s_mov_b32 m0, s26
	s_nop 0
	global_load_lds_dwordx4 v[222:223], off
	v_lshl_add_u64 v[222:223], v[226:227], 0, s[56:57]
	s_mov_b32 m0, s65
	s_nop 0
	global_load_lds_dwordx4 v[222:223], off
	v_lshl_add_u64 v[222:223], v[228:229], 0, s[56:57]
	s_mov_b32 m0, s66
	s_nop 0
	global_load_lds_dwordx4 v[222:223], off
	s_waitcnt vmcnt(8)
	s_waitcnt lgkmcnt(0)
	s_barrier
	s_setprio 1
	s_waitcnt lgkmcnt(0)
	v_mfma_f32_16x16x32_bf16 v[62:65], v[130:133], v[190:193], v[62:65]
	v_mfma_f32_16x16x32_bf16 v[58:61], v[156:159], v[190:193], v[58:61]
	v_mfma_f32_16x16x32_bf16 v[46:49], v[130:133], v[198:201], v[46:49]
	v_mfma_f32_16x16x32_bf16 v[42:45], v[156:159], v[198:201], v[42:45]
	v_mfma_f32_16x16x32_bf16 v[30:33], v[130:133], v[206:209], v[30:33]
	v_mfma_f32_16x16x32_bf16 v[26:29], v[156:159], v[206:209], v[26:29]
	v_mfma_f32_16x16x32_bf16 v[14:17], v[130:133], v[214:217], v[14:17]
	v_mfma_f32_16x16x32_bf16 v[10:13], v[156:159], v[214:217], v[10:13]
	v_mfma_f32_16x16x32_bf16 v[62:65], v[134:137], v[194:197], v[62:65]
	v_mfma_f32_16x16x32_bf16 v[58:61], v[160:163], v[194:197], v[58:61]
	v_mfma_f32_16x16x32_bf16 v[46:49], v[134:137], v[202:205], v[46:49]
	v_mfma_f32_16x16x32_bf16 v[42:45], v[160:163], v[202:205], v[42:45]
	v_mfma_f32_16x16x32_bf16 v[30:33], v[134:137], v[210:213], v[30:33]
	v_mfma_f32_16x16x32_bf16 v[26:29], v[160:163], v[210:213], v[26:29]
	v_mfma_f32_16x16x32_bf16 v[14:17], v[134:137], v[218:221], v[14:17]
	v_mfma_f32_16x16x32_bf16 v[10:13], v[160:163], v[218:221], v[10:13]
	s_setprio 0
	s_setprio 1
	v_mfma_f32_16x16x32_bf16 v[54:57], v[164:167], v[190:193], v[54:57]
	v_mfma_f32_16x16x32_bf16 v[50:53], v[182:185], v[190:193], v[50:53]
	v_mfma_f32_16x16x32_bf16 v[38:41], v[164:167], v[198:201], v[38:41]
	v_mfma_f32_16x16x32_bf16 v[34:37], v[182:185], v[198:201], v[34:37]
	v_mfma_f32_16x16x32_bf16 v[22:25], v[164:167], v[206:209], v[22:25]
	v_mfma_f32_16x16x32_bf16 v[18:21], v[182:185], v[206:209], v[18:21]
	v_mfma_f32_16x16x32_bf16 v[6:9], v[164:167], v[214:217], v[6:9]
	v_mfma_f32_16x16x32_bf16 v[2:5], v[182:185], v[214:217], v[2:5]
	v_mfma_f32_16x16x32_bf16 v[54:57], v[178:181], v[194:197], v[54:57]
	v_mfma_f32_16x16x32_bf16 v[50:53], v[186:189], v[194:197], v[50:53]
	v_mfma_f32_16x16x32_bf16 v[38:41], v[178:181], v[202:205], v[38:41]
	v_mfma_f32_16x16x32_bf16 v[34:37], v[186:189], v[202:205], v[34:37]
	v_mfma_f32_16x16x32_bf16 v[22:25], v[178:181], v[210:213], v[22:25]
	v_mfma_f32_16x16x32_bf16 v[18:21], v[186:189], v[210:213], v[18:21]
	v_mfma_f32_16x16x32_bf16 v[6:9], v[178:181], v[218:221], v[6:9]
	v_mfma_f32_16x16x32_bf16 v[2:5], v[186:189], v[218:221], v[2:5]
	s_setprio 0
	s_add_i32 s19, s19, 2
	s_add_u32 s17, s17, 0x100
	s_addc_u32 s18, s18, 0
	s_add_u32 s8, s8, 0x100
	s_addc_u32 s9, s9, 0
	s_cmp_gt_u32 s19, 13
	s_barrier
	s_cbranch_scc0 .LBB0_1583
	s_and_b64 vcc, exec, s[60:61]
	s_cbranch_vccz .LBB0_1586
	s_barrier

; #define PG8_STAGE(bufoff, gbase, voff) do { _Pragma("unroll") for (int _i = 0; _i < 2; ++_i) \
;         __builtin_amdgcn_global_load_lds((const unsigned*)((const char*)(gbase) + (voff)[_i]), (PG8_LAS unsigned*)(lds + (bufoff) + ldsw + _i * 8192), 16, 0, 0); } while (0)
; #define PG8_LDA(dst, b, h) do { _Pragma("unroll") for (int m = 0; m < 4; ++m) _Pragma("unroll") for (int k = 0; k < 2; ++k) dst[m][k] = *(const PG8_LAS bf16x8*)(lds + PG8_SA(b, h) + aoff + m * 2048 + k * 1024); } while (0)
; #define PG8_LDB(dst, b, h) do { _Pragma("unroll") for (int n = 0; n < 2; ++n) _Pragma("unroll") for (int k = 0; k < 2; ++k) dst[n][k] = *(const PG8_LAS bf16x8*)(lds + PG8_SB(b, h) + boff + n * 2048 + k * 1024); } while (0)
; #define PG8_WAIT_V(n) asm volatile("s_waitcnt vmcnt(" #n ")" ::: "memory")
; #define PG8_WAIT_L(n) asm volatile("s_waitcnt lgkmcnt(" #n ")" ::: "memory")
; #define PG8_BAR __builtin_amdgcn_s_barrier()
; #define PG8_SCHED __builtin_amdgcn_sched_barrier(0)
; template <class Epi, class Sched, bool ALIGN_EPI = false, bool SP2 = false>
; __device__ __forceinline__ void gemm_phase(PG8_LAS unsigned char* lds, const Gemm g, const Sched& S, const Epi& E) {
;     ...
;         const bool has_next = S.next(ui + 1, nxt);
;         const char* nA = has_next ? (const char*)g.A + (size_t)nxt.pm * tstep + (size_t)nxt.ks * K * 2 : cA; const char* nB = has_next ? (const char*)g.Bt + (size_t)nxt.pn * tstep + (size_t)nxt.ks * K * 2 : cB;
;         for (int t = 0; t < nt; t += 2) {
;             const bool last = (t == nt - 2);
;             const char* a1 = cA + (size_t)(t + 1) * kstep;
;             const char* a2 = last ? nA : cA + (size_t)(t + 2) * kstep; const char* b2 = last ? nB : cB + (size_t)(t + 2) * kstep;
;             const char* a3 = a2 + kstep; const char* b3 = b2 + kstep;
;             if (last && has_next) S.a_ready(nxt);
;             if constexpr (SP2) {
;             PG8_LDB(B0, 0, 0); PG8_LDB(B1, 0, 1); PG8_SCHED; PG8_LDA(At, 0, 0); PG8_STAGE(PG8_SA(1, 1), a1 + hstep, voffA);
;             PG8_WAIT_V(8); PG8_WAIT_L(0); PG8_BAR; PG8_MMA(0, 0, At, B0); PG8_MMA(0, 1, At, B1); PG8_BAR; PG8_SCHED;
;             PG8_LDA(At, 0, 1); PG8_STAGE(PG8_SB(0, 0), b2, voffB); PG8_STAGE(PG8_SB(0, 1), b2 + hstep, voffB); PG8_STAGE(PG8_SA(0, 0), a2, voffA);
;             PG8_WAIT_V(8); PG8_WAIT_L(0); PG8_BAR; PG8_MMA(1, 0, At, B0); PG8_MMA(1, 1, At, B1); PG8_BAR; PG8_SCHED;
.LBB0_2133:
	s_ashr_i32 s21, s20, 31
	s_lshl_b64 s[24:25], s[20:21], 19
	s_add_u32 s24, s31, s24
	s_addc_u32 s25, s33, s25
	s_and_b64 s[36:37], s[2:3], exec
	s_cselect_b32 s21, s25, s41
	s_cselect_b32 s64, s24, s40
	s_ashr_i32 s23, s22, 31
	s_lshl_b64 s[36:37], s[22:23], 19
	s_add_u32 s36, s29, s36
	s_addc_u32 s37, s30, s37
	s_and_b64 s[42:43], s[2:3], exec
	s_cselect_b32 s23, s37, s39
	s_cselect_b32 s65, s36, s38
	s_add_u32 s66, s38, 0x100
	s_addc_u32 s67, s39, 0
	s_add_u32 s38, s40, 0x40080
	s_addc_u32 s39, s41, 0
	s_mov_b32 s68, -2
	ds_read_b128 v[154:157], v148
	ds_read_b128 v[158:161], v148 offset:1024
	ds_read_b128 v[162:165], v148 offset:2048
	ds_read_b128 v[166:169], v148 offset:3072
	ds_read_b128 v[170:173], v149
	ds_read_b128 v[174:177], v149 offset:1024
	ds_read_b128 v[178:181], v149 offset:2048
	ds_read_b128 v[182:185], v149 offset:3072
	s_add_u32 s40, s38, 0xfffc0080
	s_addc_u32 s41, s39, -1
	s_cmp_eq_u32 s68, 12
	s_cselect_b32 s43, s21, s41
	s_cselect_b32 s42, s64, s40
	s_cselect_b32 s41, s23, s67
	s_cselect_b32 s40, s65, s66
	v_lshl_add_u64 v[218:219], s[38:39], 0, v[140:141]
	s_add_i32 m0, s47, 0xc000
	ds_read_b128 v[186:189], v150
	ds_read_b128 v[190:193], v150 offset:1024
	ds_read_b128 v[194:197], v150 offset:2048
	ds_read_b128 v[198:201], v150 offset:3072
	ds_read_b128 v[202:205], v150 offset:4096
	ds_read_b128 v[206:209], v150 offset:5120
	ds_read_b128 v[210:213], v150 offset:6144
	ds_read_b128 v[214:217], v150 offset:7168
	global_load_lds_dwordx4 v[218:219], off
	v_lshl_add_u64 v[218:219], s[38:39], 0, v[138:139]
	s_add_i32 m0, s47, 0xe000
	s_nop 0
	global_load_lds_dwordx4 v[218:219], off
	s_waitcnt vmcnt(8)
	s_waitcnt lgkmcnt(0)
	s_barrier
	s_setprio 1
	s_waitcnt lgkmcnt(0)
	v_mfma_f32_16x16x32_bf16 v[126:129], v[154:157], v[186:189], 0
	v_mfma_f32_16x16x32_bf16 v[122:125], v[162:165], v[186:189], 0
	v_mfma_f32_16x16x32_bf16 v[118:121], v[154:157], v[194:197], 0
	v_mfma_f32_16x16x32_bf16 v[114:117], v[162:165], v[194:197], 0
	v_mfma_f32_16x16x32_bf16 v[102:105], v[154:157], v[202:205], 0
	v_mfma_f32_16x16x32_bf16 v[98:101], v[162:165], v[202:205], 0
	v_mfma_f32_16x16x32_bf16 v[86:89], v[154:157], v[210:213], 0
	v_mfma_f32_16x16x32_bf16 v[82:85], v[162:165], v[210:213], 0
	v_mfma_f32_16x16x32_bf16 v[126:129], v[158:161], v[190:193], v[126:129]
	v_mfma_f32_16x16x32_bf16 v[122:125], v[166:169], v[190:193], v[122:125]
	v_mfma_f32_16x16x32_bf16 v[118:121], v[158:161], v[198:201], v[118:121]
	v_mfma_f32_16x16x32_bf16 v[114:117], v[166:169], v[198:201], v[114:117]
	v_mfma_f32_16x16x32_bf16 v[102:105], v[158:161], v[206:209], v[102:105]
	v_mfma_f32_16x16x32_bf16 v[98:101], v[166:169], v[206:209], v[98:101]
	v_mfma_f32_16x16x32_bf16 v[86:89], v[158:161], v[214:217], v[86:89]
	v_mfma_f32_16x16x32_bf16 v[82:85], v[166:169], v[214:217], v[82:85]
	s_setprio 0
	s_setprio 1
	v_mfma_f32_16x16x32_bf16 v[110:113], v[170:173], v[186:189], 0
	v_mfma_f32_16x16x32_bf16 v[106:109], v[178:181], v[186:189], 0
	v_mfma_f32_16x16x32_bf16 v[94:97], v[170:173], v[194:197], 0
	v_mfma_f32_16x16x32_bf16 v[90:93], v[178:181], v[194:197], 0
	v_mfma_f32_16x16x32_bf16 v[78:81], v[170:173], v[202:205], 0
	v_mfma_f32_16x16x32_bf16 v[74:77], v[178:181], v[202:205], 0
	v_mfma_f32_16x16x32_bf16 v[70:73], v[170:173], v[210:213], 0
	v_mfma_f32_16x16x32_bf16 v[66:69], v[178:181], v[210:213], 0
	v_mfma_f32_16x16x32_bf16 v[110:113], v[174:177], v[190:193], v[110:113]
	v_mfma_f32_16x16x32_bf16 v[106:109], v[182:185], v[190:193], v[106:109]
	v_mfma_f32_16x16x32_bf16 v[94:97], v[174:177], v[198:201], v[94:97]
	v_mfma_f32_16x16x32_bf16 v[90:93], v[182:185], v[198:201], v[90:93]
	v_mfma_f32_16x16x32_bf16 v[78:81], v[174:177], v[206:209], v[78:81]
	v_mfma_f32_16x16x32_bf16 v[74:77], v[182:185], v[206:209], v[74:77]
	v_mfma_f32_16x16x32_bf16 v[70:73], v[174:177], v[214:217], v[70:73]
	v_mfma_f32_16x16x32_bf16 v[66:69], v[182:185], v[214:217], v[66:69]
	s_setprio 0
	s_barrier
	s_mov_b32 m0, s19
	v_lshl_add_u64 v[218:219], s[40:41], 0, v[132:133]
	s_add_u32 s70, s40, 0x40000
	ds_read_b128 v[186:189], v150 offset:16384
	ds_read_b128 v[190:193], v150 offset:17408
	ds_read_b128 v[194:197], v150 offset:18432
	ds_read_b128 v[198:201], v150 offset:19456
	ds_read_b128 v[202:205], v150 offset:20480
	ds_read_b128 v[206:209], v150 offset:21504
	ds_read_b128 v[210:213], v150 offset:22528
	ds_read_b128 v[214:217], v150 offset:23552
	global_load_lds_dwordx4 v[218:219], off
	v_lshl_add_u64 v[220:221], s[40:41], 0, v[136:137]
	s_mov_b32 m0, s44
	s_addc_u32 s71, s41, 0
	global_load_lds_dwordx4 v[220:221], off
	v_lshl_add_u64 v[222:223], s[70:71], 0, v[132:133]
	s_mov_b32 m0, s45
	v_lshl_add_u64 v[224:225], s[42:43], 0, v[134:135]
	global_load_lds_dwordx4 v[222:223], off
	v_lshl_add_u64 v[222:223], s[70:71], 0, v[136:137]
	s_mov_b32 m0, s46
	s_nop 0
	global_load_lds_dwordx4 v[222:223], off
	v_lshl_add_u64 v[222:223], s[42:43], 0, v[130:131]
	s_mov_b32 m0, s47
	s_nop 0
	global_load_lds_dwordx4 v[222:223], off
	s_mov_b32 m0, s48
	s_nop 0
	global_load_lds_dwordx4 v[224:225], off
	s_waitcnt vmcnt(8)
	s_waitcnt lgkmcnt(0)
	s_barrier
; #define PG8_STAGE(bufoff, gbase, voff) do { _Pragma("unroll") for (int _i = 0; _i < 2; ++_i) \
;         __builtin_amdgcn_global_load_lds((const unsigned*)((const char*)(gbase) + (voff)[_i]), (PG8_LAS unsigned*)(lds + (bufoff) + ldsw + _i * 8192), 16, 0, 0); } while (0)
; #define PG8_LDA(dst, b, h) do { _Pragma("unroll") for (int m = 0; m < 4; ++m) _Pragma("unroll") for (int k = 0; k < 2; ++k) dst[m][k] = *(const PG8_LAS bf16x8*)(lds + PG8_SA(b, h) + aoff + m * 2048 + k * 1024); } while (0)
; #define PG8_LDB(dst, b, h) do { _Pragma("unroll") for (int n = 0; n < 2; ++n) _Pragma("unroll") for (int k = 0; k < 2; ++k) dst[n][k] = *(const PG8_LAS bf16x8*)(lds + PG8_SB(b, h) + boff + n * 2048 + k * 1024); } while (0)
; #define PG8_MMA(ai, bj, At, Bt) do { __builtin_amdgcn_s_setprio(1); _Pragma("unroll") for (int m = 0; m < 4; ++m) _Pragma("unroll") for (int n = 0; n < 2; ++n) _Pragma("unroll") for (int k = 0; k < 2; ++k) \
;         acc[ai][bj][m][n] = __builtin_amdgcn_mfma_f32_16x16x32_bf16(Bt[n][k], At[m][k], acc[ai][bj][m][n], 0, 0, 0); __builtin_amdgcn_s_setprio(0); } while (0)
; #define PG8_WAIT_V(n) asm volatile("s_waitcnt vmcnt(" #n ")" ::: "memory")
; #define PG8_WAIT_L(n) asm volatile("s_waitcnt lgkmcnt(" #n ")" ::: "memory")
; #define PG8_BAR __builtin_amdgcn_s_barrier()
; #define PG8_SCHED __builtin_amdgcn_sched_barrier(0)
; template <class Epi, class Sched, bool ALIGN_EPI = false, bool SP2 = false>
; __device__ __forceinline__ void gemm_phase(PG8_LAS unsigned char* lds, const Gemm g, const Sched& S, const Epi& E) {
;     ...
;             PG8_WAIT_V(8); PG8_WAIT_L(0); PG8_BAR; PG8_MMA(0, 0, At, B0); PG8_MMA(0, 1, At, B1); PG8_BAR; PG8_SCHED;
;             PG8_LDA(At, 0, 1); PG8_STAGE(PG8_SB(0, 0), b2, voffB); PG8_STAGE(PG8_SB(0, 1), b2 + hstep, voffB); PG8_STAGE(PG8_SA(0, 0), a2, voffA);
;             PG8_WAIT_V(8); PG8_WAIT_L(0); PG8_BAR; PG8_MMA(1, 0, At, B0); PG8_MMA(1, 1, At, B1); PG8_BAR; PG8_SCHED;
;             PG8_LDB(B0, 1, 0); PG8_LDB(B1, 1, 1); PG8_SCHED; PG8_LDA(At, 1, 0); PG8_STAGE(PG8_SA(0, 1), a2 + hstep, voffA);
;             PG8_WAIT_V(8); PG8_WAIT_L(0); PG8_BAR; PG8_MMA(0, 0, At, B0); PG8_MMA(0, 1, At, B1); PG8_BAR; PG8_SCHED;
	s_setprio 1
	s_waitcnt lgkmcnt(0)
	v_mfma_f32_16x16x32_bf16 v[62:65], v[154:157], v[186:189], 0
	v_mfma_f32_16x16x32_bf16 v[58:61], v[162:165], v[186:189], 0
	v_mfma_f32_16x16x32_bf16 v[54:57], v[154:157], v[194:197], 0
	v_mfma_f32_16x16x32_bf16 v[50:53], v[162:165], v[194:197], 0
	v_mfma_f32_16x16x32_bf16 v[38:41], v[154:157], v[202:205], 0
	v_mfma_f32_16x16x32_bf16 v[34:37], v[162:165], v[202:205], 0
	v_mfma_f32_16x16x32_bf16 v[22:25], v[154:157], v[210:213], 0
	v_mfma_f32_16x16x32_bf16 v[18:21], v[162:165], v[210:213], 0
	v_mfma_f32_16x16x32_bf16 v[62:65], v[158:161], v[190:193], v[62:65]
	v_mfma_f32_16x16x32_bf16 v[58:61], v[166:169], v[190:193], v[58:61]
	v_mfma_f32_16x16x32_bf16 v[54:57], v[158:161], v[198:201], v[54:57]
	v_mfma_f32_16x16x32_bf16 v[50:53], v[166:169], v[198:201], v[50:53]
	v_mfma_f32_16x16x32_bf16 v[38:41], v[158:161], v[206:209], v[38:41]
	v_mfma_f32_16x16x32_bf16 v[34:37], v[166:169], v[206:209], v[34:37]
	v_mfma_f32_16x16x32_bf16 v[22:25], v[158:161], v[214:217], v[22:25]
	v_mfma_f32_16x16x32_bf16 v[18:21], v[166:169], v[214:217], v[18:21]
	s_setprio 0
	s_setprio 1
	v_mfma_f32_16x16x32_bf16 v[46:49], v[170:173], v[186:189], 0
	v_mfma_f32_16x16x32_bf16 v[42:45], v[178:181], v[186:189], 0
	v_mfma_f32_16x16x32_bf16 v[30:33], v[170:173], v[194:197], 0
	v_mfma_f32_16x16x32_bf16 v[26:29], v[178:181], v[194:197], 0
	v_mfma_f32_16x16x32_bf16 v[14:17], v[170:173], v[202:205], 0
	v_mfma_f32_16x16x32_bf16 v[10:13], v[178:181], v[202:205], 0
	v_mfma_f32_16x16x32_bf16 v[6:9], v[170:173], v[210:213], 0
	v_mfma_f32_16x16x32_bf16 v[2:5], v[178:181], v[210:213], 0
	v_mfma_f32_16x16x32_bf16 v[46:49], v[174:177], v[190:193], v[46:49]
	v_mfma_f32_16x16x32_bf16 v[42:45], v[182:185], v[190:193], v[42:45]
	v_mfma_f32_16x16x32_bf16 v[30:33], v[174:177], v[198:201], v[30:33]
	v_mfma_f32_16x16x32_bf16 v[26:29], v[182:185], v[198:201], v[26:29]
	v_mfma_f32_16x16x32_bf16 v[14:17], v[174:177], v[206:209], v[14:17]
	v_mfma_f32_16x16x32_bf16 v[10:13], v[182:185], v[206:209], v[10:13]
	v_mfma_f32_16x16x32_bf16 v[6:9], v[174:177], v[214:217], v[6:9]
	v_mfma_f32_16x16x32_bf16 v[2:5], v[182:185], v[214:217], v[2:5]
	s_setprio 0
	s_barrier
	ds_read_b128 v[154:157], v151
	ds_read_b128 v[158:161], v151 offset:1024
	ds_read_b128 v[162:165], v151 offset:2048
	ds_read_b128 v[166:169], v151 offset:3072
	ds_read_b128 v[170:173], v152
	ds_read_b128 v[174:177], v152 offset:1024
	ds_read_b128 v[178:181], v152 offset:2048
	ds_read_b128 v[182:185], v152 offset:3072
	s_add_u32 s42, s42, 0x40000
	s_addc_u32 s43, s43, 0
	s_mov_b32 m0, s49
	v_lshl_add_u64 v[226:227], s[42:43], 0, v[130:131]
	ds_read_b128 v[186:189], v150 offset:32768
	ds_read_b128 v[190:193], v150 offset:33792
	ds_read_b128 v[194:197], v150 offset:34816
	ds_read_b128 v[198:201], v150 offset:35840
	ds_read_b128 v[202:205], v150 offset:36864
	ds_read_b128 v[206:209], v150 offset:37888
	ds_read_b128 v[210:213], v150 offset:38912
	ds_read_b128 v[214:217], v150 offset:39936
	global_load_lds_dwordx4 v[226:227], off
	v_lshl_add_u64 v[226:227], s[42:43], 0, v[134:135]
	s_mov_b32 m0, s50
	s_nop 0
	global_load_lds_dwordx4 v[226:227], off
	s_waitcnt vmcnt(8)
	s_waitcnt lgkmcnt(0)
	s_barrier
	s_setprio 1
	s_waitcnt lgkmcnt(0)
	v_mfma_f32_16x16x32_bf16 v[126:129], v[154:157], v[186:189], v[126:129]
	v_mfma_f32_16x16x32_bf16 v[122:125], v[162:165], v[186:189], v[122:125]
	v_mfma_f32_16x16x32_bf16 v[118:121], v[154:157], v[194:197], v[118:121]
	v_mfma_f32_16x16x32_bf16 v[114:117], v[162:165], v[194:197], v[114:117]
	v_mfma_f32_16x16x32_bf16 v[102:105], v[154:157], v[202:205], v[102:105]
	v_mfma_f32_16x16x32_bf16 v[98:101], v[162:165], v[202:205], v[98:101]
	v_mfma_f32_16x16x32_bf16 v[86:89], v[154:157], v[210:213], v[86:89]
	v_mfma_f32_16x16x32_bf16 v[82:85], v[162:165], v[210:213], v[82:85]
	v_mfma_f32_16x16x32_bf16 v[126:129], v[158:161], v[190:193], v[126:129]
	v_mfma_f32_16x16x32_bf16 v[122:125], v[166:169], v[190:193], v[122:125]
	v_mfma_f32_16x16x32_bf16 v[118:121], v[158:161], v[198:201], v[118:121]
	v_mfma_f32_16x16x32_bf16 v[114:117], v[166:169], v[198:201], v[114:117]
	v_mfma_f32_16x16x32_bf16 v[102:105], v[158:161], v[206:209], v[102:105]
	v_mfma_f32_16x16x32_bf16 v[98:101], v[166:169], v[206:209], v[98:101]
	v_mfma_f32_16x16x32_bf16 v[86:89], v[158:161], v[214:217], v[86:89]
	v_mfma_f32_16x16x32_bf16 v[82:85], v[166:169], v[214:217], v[82:85]
	s_setprio 0
	s_setprio 1
	v_mfma_f32_16x16x32_bf16 v[110:113], v[170:173], v[186:189], v[110:113]
	v_mfma_f32_16x16x32_bf16 v[106:109], v[178:181], v[186:189], v[106:109]
	v_mfma_f32_16x16x32_bf16 v[94:97], v[170:173], v[194:197], v[94:97]
	v_mfma_f32_16x16x32_bf16 v[90:93], v[178:181], v[194:197], v[90:93]
	v_mfma_f32_16x16x32_bf16 v[78:81], v[170:173], v[202:205], v[78:81]
	v_mfma_f32_16x16x32_bf16 v[74:77], v[178:181], v[202:205], v[74:77]
	v_mfma_f32_16x16x32_bf16 v[70:73], v[170:173], v[210:213], v[70:73]
	v_mfma_f32_16x16x32_bf16 v[66:69], v[178:181], v[210:213], v[66:69]
	v_mfma_f32_16x16x32_bf16 v[110:113], v[174:177], v[190:193], v[110:113]
	v_mfma_f32_16x16x32_bf16 v[106:109], v[182:185], v[190:193], v[106:109]
	v_mfma_f32_16x16x32_bf16 v[94:97], v[174:177], v[198:201], v[94:97]
	v_mfma_f32_16x16x32_bf16 v[90:93], v[182:185], v[198:201], v[90:93]
	v_mfma_f32_16x16x32_bf16 v[78:81], v[174:177], v[206:209], v[78:81]
	v_mfma_f32_16x16x32_bf16 v[74:77], v[182:185], v[206:209], v[74:77]
	v_mfma_f32_16x16x32_bf16 v[70:73], v[174:177], v[214:217], v[70:73]
	v_mfma_f32_16x16x32_bf16 v[66:69], v[182:185], v[214:217], v[66:69]
	s_setprio 0
	s_barrier
; #define PG8_STAGE(bufoff, gbase, voff) do { _Pragma("unroll") for (int _i = 0; _i < 2; ++_i) \
;         __builtin_amdgcn_global_load_lds((const unsigned*)((const char*)(gbase) + (voff)[_i]), (PG8_LAS unsigned*)(lds + (bufoff) + ldsw + _i * 8192), 16, 0, 0); } while (0)
; #define PG8_LDA(dst, b, h) do { _Pragma("unroll") for (int m = 0; m < 4; ++m) _Pragma("unroll") for (int k = 0; k < 2; ++k) dst[m][k] = *(const PG8_LAS bf16x8*)(lds + PG8_SA(b, h) + aoff + m * 2048 + k * 1024); } while (0)
; #define PG8_LDB(dst, b, h) do { _Pragma("unroll") for (int n = 0; n < 2; ++n) _Pragma("unroll") for (int k = 0; k < 2; ++k) dst[n][k] = *(const PG8_LAS bf16x8*)(lds + PG8_SB(b, h) + boff + n * 2048 + k * 1024); } while (0)
; template <class Epi, class Sched, bool ALIGN_EPI = false, bool SP2 = false>
; __device__ __forceinline__ void gemm_phase(PG8_LAS unsigned char* lds, const Gemm g, const Sched& S, const Epi& E) {
;     ...
;         for (int t = 0; t < nt; t += 2) {
;             const bool last = (t == nt - 2);
;             const char* a1 = cA + (size_t)(t + 1) * kstep;
;             const char* a2 = last ? nA : cA + (size_t)(t + 2) * kstep; const char* b2 = last ? nB : cB + (size_t)(t + 2) * kstep;
;             const char* a3 = a2 + kstep; const char* b3 = b2 + kstep;
;             if (last && has_next) S.a_ready(nxt);
;             if constexpr (SP2) {
;             PG8_LDB(B0, 0, 0); PG8_LDB(B1, 0, 1); PG8_SCHED; PG8_LDA(At, 0, 0); PG8_STAGE(PG8_SA(1, 1), a1 + hstep, voffA);
;             PG8_WAIT_V(8); PG8_WAIT_L(0); PG8_BAR; PG8_MMA(0, 0, At, B0); PG8_MMA(0, 1, At, B1); PG8_BAR; PG8_SCHED;
;             PG8_LDA(At, 0, 1); PG8_STAGE(PG8_SB(0, 0), b2, voffB); PG8_STAGE(PG8_SB(0, 1), b2 + hstep, voffB); PG8_STAGE(PG8_SA(0, 0), a2, voffA);
;             PG8_WAIT_V(8); PG8_WAIT_L(0); PG8_BAR; PG8_MMA(1, 0, At, B0); PG8_MMA(1, 1, At, B1); PG8_BAR; PG8_SCHED;
;             PG8_LDB(B0, 1, 0); PG8_LDB(B1, 1, 1); PG8_SCHED; PG8_LDA(At, 1, 0); PG8_STAGE(PG8_SA(0, 1), a2 + hstep, voffA);
;             PG8_WAIT_V(8); PG8_WAIT_L(0); PG8_BAR; PG8_MMA(0, 0, At, B0); PG8_MMA(0, 1, At, B1); PG8_BAR; PG8_SCHED;
;             PG8_LDA(At, 1, 1); PG8_STAGE(PG8_SB(1, 0), b3, voffB); PG8_STAGE(PG8_SB(1, 1), b3 + hstep, voffB); PG8_STAGE(PG8_SA(1, 0), a3, voffA);
;             PG8_WAIT_V(8); PG8_WAIT_L(0); PG8_BAR; PG8_MMA(1, 0, At, B0); PG8_MMA(1, 1, At, B1); PG8_BAR; PG8_SCHED;
	s_mov_b32 m0, s52
	v_lshl_add_u64 v[218:219], v[218:219], 0, s[8:9]
	s_add_u32 s40, s40, 0x40080
	ds_read_b128 v[186:189], v150 offset:49152
	ds_read_b128 v[190:193], v150 offset:50176
	ds_read_b128 v[194:197], v150 offset:51200
	ds_read_b128 v[198:201], v150 offset:52224
	ds_read_b128 v[202:205], v150 offset:53248
	ds_read_b128 v[206:209], v150 offset:54272
	ds_read_b128 v[210:213], v150 offset:55296
	ds_read_b128 v[214:217], v150 offset:56320
	global_load_lds_dwordx4 v[218:219], off
	v_lshl_add_u64 v[218:219], v[220:221], 0, s[8:9]
	s_mov_b32 m0, s53
	s_addc_u32 s41, s41, 0
	global_load_lds_dwordx4 v[218:219], off
	v_lshl_add_u64 v[218:219], s[40:41], 0, v[132:133]
	s_mov_b32 m0, s56
	s_nop 0
	global_load_lds_dwordx4 v[218:219], off
	v_lshl_add_u64 v[218:219], s[40:41], 0, v[136:137]
	s_mov_b32 m0, s57
	s_nop 0
	global_load_lds_dwordx4 v[218:219], off
	v_lshl_add_u64 v[218:219], v[222:223], 0, s[8:9]
	s_mov_b32 m0, s54
	s_nop 0
	global_load_lds_dwordx4 v[218:219], off
	v_lshl_add_u64 v[218:219], v[224:225], 0, s[8:9]
	s_mov_b32 m0, s55
	s_nop 0
	global_load_lds_dwordx4 v[218:219], off
	s_waitcnt vmcnt(8)
	s_waitcnt lgkmcnt(0)
	s_barrier
	s_setprio 1
	s_waitcnt lgkmcnt(0)
	v_mfma_f32_16x16x32_bf16 v[62:65], v[154:157], v[186:189], v[62:65]
	v_mfma_f32_16x16x32_bf16 v[58:61], v[162:165], v[186:189], v[58:61]
	v_mfma_f32_16x16x32_bf16 v[54:57], v[154:157], v[194:197], v[54:57]
	v_mfma_f32_16x16x32_bf16 v[50:53], v[162:165], v[194:197], v[50:53]
	v_mfma_f32_16x16x32_bf16 v[38:41], v[154:157], v[202:205], v[38:41]
	v_mfma_f32_16x16x32_bf16 v[34:37], v[162:165], v[202:205], v[34:37]
	v_mfma_f32_16x16x32_bf16 v[22:25], v[154:157], v[210:213], v[22:25]
	v_mfma_f32_16x16x32_bf16 v[18:21], v[162:165], v[210:213], v[18:21]
	v_mfma_f32_16x16x32_bf16 v[62:65], v[158:161], v[190:193], v[62:65]
	v_mfma_f32_16x16x32_bf16 v[58:61], v[166:169], v[190:193], v[58:61]
	v_mfma_f32_16x16x32_bf16 v[54:57], v[158:161], v[198:201], v[54:57]
	v_mfma_f32_16x16x32_bf16 v[50:53], v[166:169], v[198:201], v[50:53]
	v_mfma_f32_16x16x32_bf16 v[38:41], v[158:161], v[206:209], v[38:41]
	v_mfma_f32_16x16x32_bf16 v[34:37], v[166:169], v[206:209], v[34:37]
	v_mfma_f32_16x16x32_bf16 v[22:25], v[158:161], v[214:217], v[22:25]
	v_mfma_f32_16x16x32_bf16 v[18:21], v[166:169], v[214:217], v[18:21]
	s_setprio 0
	s_setprio 1
	v_mfma_f32_16x16x32_bf16 v[46:49], v[170:173], v[186:189], v[46:49]
	v_mfma_f32_16x16x32_bf16 v[42:45], v[178:181], v[186:189], v[42:45]
	v_mfma_f32_16x16x32_bf16 v[30:33], v[170:173], v[194:197], v[30:33]
	v_mfma_f32_16x16x32_bf16 v[26:29], v[178:181], v[194:197], v[26:29]
	v_mfma_f32_16x16x32_bf16 v[14:17], v[170:173], v[202:205], v[14:17]
	v_mfma_f32_16x16x32_bf16 v[10:13], v[178:181], v[202:205], v[10:13]
	v_mfma_f32_16x16x32_bf16 v[6:9], v[170:173], v[210:213], v[6:9]
	v_mfma_f32_16x16x32_bf16 v[2:5], v[178:181], v[210:213], v[2:5]
	v_mfma_f32_16x16x32_bf16 v[46:49], v[174:177], v[190:193], v[46:49]
	v_mfma_f32_16x16x32_bf16 v[42:45], v[182:185], v[190:193], v[42:45]
	v_mfma_f32_16x16x32_bf16 v[30:33], v[174:177], v[198:201], v[30:33]
	v_mfma_f32_16x16x32_bf16 v[26:29], v[182:185], v[198:201], v[26:29]
	v_mfma_f32_16x16x32_bf16 v[14:17], v[174:177], v[206:209], v[14:17]
	v_mfma_f32_16x16x32_bf16 v[10:13], v[182:185], v[206:209], v[10:13]
	v_mfma_f32_16x16x32_bf16 v[6:9], v[174:177], v[214:217], v[6:9]
	v_mfma_f32_16x16x32_bf16 v[2:5], v[182:185], v[214:217], v[2:5]
	s_setprio 0
	s_add_i32 s68, s68, 2
	s_add_u32 s66, s66, 0x100
	s_addc_u32 s67, s67, 0
	s_add_u32 s38, s38, 0x100
	s_addc_u32 s39, s39, 0
	s_cmp_gt_u32 s68, 13
	s_barrier
.LBB0_2134:
	ds_read_b128 v[154:157], v148
	ds_read_b128 v[158:161], v148 offset:1024
	ds_read_b128 v[162:165], v148 offset:2048
	ds_read_b128 v[166:169], v148 offset:3072
	ds_read_b128 v[170:173], v149
	ds_read_b128 v[174:177], v149 offset:1024
	ds_read_b128 v[178:181], v149 offset:2048
	ds_read_b128 v[182:185], v149 offset:3072
	s_add_u32 s40, s38, 0xfffc0080
	s_addc_u32 s41, s39, -1
	s_cmp_eq_u32 s68, 12
	s_cselect_b32 s43, s21, s41
	s_cselect_b32 s42, s64, s40
	s_cselect_b32 s41, s23, s67
	s_cselect_b32 s40, s65, s66
	v_lshl_add_u64 v[218:219], s[38:39], 0, v[140:141]
	s_add_i32 m0, s47, 0xc000
	ds_read_b128 v[186:189], v150
	ds_read_b128 v[190:193], v150 offset:1024
	ds_read_b128 v[194:197], v150 offset:2048
	ds_read_b128 v[198:201], v150 offset:3072
	ds_read_b128 v[202:205], v150 offset:4096
	ds_read_b128 v[206:209], v150 offset:5120
	ds_read_b128 v[210:213], v150 offset:6144
	ds_read_b128 v[214:217], v150 offset:7168
	global_load_lds_dwordx4 v[218:219], off
	v_lshl_add_u64 v[218:219], s[38:39], 0, v[138:139]
	s_add_i32 m0, s47, 0xe000
	s_nop 0
	global_load_lds_dwordx4 v[218:219], off
	s_waitcnt vmcnt(8)
	s_waitcnt lgkmcnt(0)
	s_barrier
; #define PG8_STAGE(bufoff, gbase, voff) do { _Pragma("unroll") for (int _i = 0; _i < 2; ++_i) \
;         __builtin_amdgcn_global_load_lds((const unsigned*)((const char*)(gbase) + (voff)[_i]), (PG8_LAS unsigned*)(lds + (bufoff) + ldsw + _i * 8192), 16, 0, 0); } while (0)
; #define PG8_LDA(dst, b, h) do { _Pragma("unroll") for (int m = 0; m < 4; ++m) _Pragma("unroll") for (int k = 0; k < 2; ++k) dst[m][k] = *(const PG8_LAS bf16x8*)(lds + PG8_SA(b, h) + aoff + m * 2048 + k * 1024); } while (0)
; #define PG8_MMA(ai, bj, At, Bt) do { __builtin_amdgcn_s_setprio(1); _Pragma("unroll") for (int m = 0; m < 4; ++m) _Pragma("unroll") for (int n = 0; n < 2; ++n) _Pragma("unroll") for (int k = 0; k < 2; ++k) \
;         acc[ai][bj][m][n] = __builtin_amdgcn_mfma_f32_16x16x32_bf16(Bt[n][k], At[m][k], acc[ai][bj][m][n], 0, 0, 0); __builtin_amdgcn_s_setprio(0); } while (0)
; #define PG8_WAIT_V(n) asm volatile("s_waitcnt vmcnt(" #n ")" ::: "memory")
; #define PG8_WAIT_L(n) asm volatile("s_waitcnt lgkmcnt(" #n ")" ::: "memory")
; #define PG8_BAR __builtin_amdgcn_s_barrier()
; #define PG8_SCHED __builtin_amdgcn_sched_barrier(0)
; template <class Epi, class Sched, bool ALIGN_EPI = false, bool SP2 = false>
; __device__ __forceinline__ void gemm_phase(PG8_LAS unsigned char* lds, const Gemm g, const Sched& S, const Epi& E) {
;     ...
;             PG8_WAIT_V(8); PG8_WAIT_L(0); PG8_BAR; PG8_MMA(0, 0, At, B0); PG8_MMA(0, 1, At, B1); PG8_BAR; PG8_SCHED;
;             PG8_LDA(At, 0, 1); PG8_STAGE(PG8_SB(0, 0), b2, voffB); PG8_STAGE(PG8_SB(0, 1), b2 + hstep, voffB); PG8_STAGE(PG8_SA(0, 0), a2, voffA);
;             PG8_WAIT_V(8); PG8_WAIT_L(0); PG8_BAR; PG8_MMA(1, 0, At, B0); PG8_MMA(1, 1, At, B1); PG8_BAR; PG8_SCHED;
	s_setprio 1
	s_waitcnt lgkmcnt(0)
	v_mfma_f32_16x16x32_bf16 v[126:129], v[154:157], v[186:189], v[126:129]
	v_mfma_f32_16x16x32_bf16 v[122:125], v[162:165], v[186:189], v[122:125]
	v_mfma_f32_16x16x32_bf16 v[118:121], v[154:157], v[194:197], v[118:121]
	v_mfma_f32_16x16x32_bf16 v[114:117], v[162:165], v[194:197], v[114:117]
	v_mfma_f32_16x16x32_bf16 v[102:105], v[154:157], v[202:205], v[102:105]
	v_mfma_f32_16x16x32_bf16 v[98:101], v[162:165], v[202:205], v[98:101]
	v_mfma_f32_16x16x32_bf16 v[86:89], v[154:157], v[210:213], v[86:89]
	v_mfma_f32_16x16x32_bf16 v[82:85], v[162:165], v[210:213], v[82:85]
	v_mfma_f32_16x16x32_bf16 v[126:129], v[158:161], v[190:193], v[126:129]
	v_mfma_f32_16x16x32_bf16 v[122:125], v[166:169], v[190:193], v[122:125]
	v_mfma_f32_16x16x32_bf16 v[118:121], v[158:161], v[198:201], v[118:121]
	v_mfma_f32_16x16x32_bf16 v[114:117], v[166:169], v[198:201], v[114:117]
	v_mfma_f32_16x16x32_bf16 v[102:105], v[158:161], v[206:209], v[102:105]
	v_mfma_f32_16x16x32_bf16 v[98:101], v[166:169], v[206:209], v[98:101]
	v_mfma_f32_16x16x32_bf16 v[86:89], v[158:161], v[214:217], v[86:89]
	v_mfma_f32_16x16x32_bf16 v[82:85], v[166:169], v[214:217], v[82:85]
	s_setprio 0
	s_setprio 1
	v_mfma_f32_16x16x32_bf16 v[110:113], v[170:173], v[186:189], v[110:113]
	v_mfma_f32_16x16x32_bf16 v[106:109], v[178:181], v[186:189], v[106:109]
	v_mfma_f32_16x16x32_bf16 v[94:97], v[170:173], v[194:197], v[94:97]
	v_mfma_f32_16x16x32_bf16 v[90:93], v[178:181], v[194:197], v[90:93]
	v_mfma_f32_16x16x32_bf16 v[78:81], v[170:173], v[202:205], v[78:81]
	v_mfma_f32_16x16x32_bf16 v[74:77], v[178:181], v[202:205], v[74:77]
	v_mfma_f32_16x16x32_bf16 v[70:73], v[170:173], v[210:213], v[70:73]
	v_mfma_f32_16x16x32_bf16 v[66:69], v[178:181], v[210:213], v[66:69]
	v_mfma_f32_16x16x32_bf16 v[110:113], v[174:177], v[190:193], v[110:113]
	v_mfma_f32_16x16x32_bf16 v[106:109], v[182:185], v[190:193], v[106:109]
	v_mfma_f32_16x16x32_bf16 v[94:97], v[174:177], v[198:201], v[94:97]
	v_mfma_f32_16x16x32_bf16 v[90:93], v[182:185], v[198:201], v[90:93]
	v_mfma_f32_16x16x32_bf16 v[78:81], v[174:177], v[206:209], v[78:81]
	v_mfma_f32_16x16x32_bf16 v[74:77], v[182:185], v[206:209], v[74:77]
	v_mfma_f32_16x16x32_bf16 v[70:73], v[174:177], v[214:217], v[70:73]
	v_mfma_f32_16x16x32_bf16 v[66:69], v[182:185], v[214:217], v[66:69]
	s_setprio 0
	s_barrier
	s_mov_b32 m0, s19
	v_lshl_add_u64 v[218:219], s[40:41], 0, v[132:133]
	s_add_u32 s70, s40, 0x40000
	ds_read_b128 v[186:189], v150 offset:16384
	ds_read_b128 v[190:193], v150 offset:17408
	ds_read_b128 v[194:197], v150 offset:18432
	ds_read_b128 v[198:201], v150 offset:19456
	ds_read_b128 v[202:205], v150 offset:20480
	ds_read_b128 v[206:209], v150 offset:21504
	ds_read_b128 v[210:213], v150 offset:22528
	ds_read_b128 v[214:217], v150 offset:23552
	global_load_lds_dwordx4 v[218:219], off
	v_lshl_add_u64 v[220:221], s[40:41], 0, v[136:137]
	s_mov_b32 m0, s44
	s_addc_u32 s71, s41, 0
	global_load_lds_dwordx4 v[220:221], off
	v_lshl_add_u64 v[222:223], s[70:71], 0, v[132:133]
	s_mov_b32 m0, s45
	v_lshl_add_u64 v[224:225], s[42:43], 0, v[134:135]
	global_load_lds_dwordx4 v[222:223], off
	v_lshl_add_u64 v[222:223], s[70:71], 0, v[136:137]
	s_mov_b32 m0, s46
	s_nop 0
	global_load_lds_dwordx4 v[222:223], off
	v_lshl_add_u64 v[222:223], s[42:43], 0, v[130:131]
	s_mov_b32 m0, s47
	s_nop 0
	global_load_lds_dwordx4 v[222:223], off
	s_mov_b32 m0, s48
	s_nop 0
	global_load_lds_dwordx4 v[224:225], off
	s_waitcnt vmcnt(8)
	s_waitcnt lgkmcnt(0)
	s_barrier
	s_setprio 1
	s_waitcnt lgkmcnt(0)
	v_mfma_f32_16x16x32_bf16 v[62:65], v[154:157], v[186:189], v[62:65]
	v_mfma_f32_16x16x32_bf16 v[58:61], v[162:165], v[186:189], v[58:61]
	v_mfma_f32_16x16x32_bf16 v[54:57], v[154:157], v[194:197], v[54:57]
	v_mfma_f32_16x16x32_bf16 v[50:53], v[162:165], v[194:197], v[50:53]
	v_mfma_f32_16x16x32_bf16 v[38:41], v[154:157], v[202:205], v[38:41]
	v_mfma_f32_16x16x32_bf16 v[34:37], v[162:165], v[202:205], v[34:37]
	v_mfma_f32_16x16x32_bf16 v[22:25], v[154:157], v[210:213], v[22:25]
	v_mfma_f32_16x16x32_bf16 v[18:21], v[162:165], v[210:213], v[18:21]
	v_mfma_f32_16x16x32_bf16 v[62:65], v[158:161], v[190:193], v[62:65]
	v_mfma_f32_16x16x32_bf16 v[58:61], v[166:169], v[190:193], v[58:61]
	v_mfma_f32_16x16x32_bf16 v[54:57], v[158:161], v[198:201], v[54:57]
	v_mfma_f32_16x16x32_bf16 v[50:53], v[166:169], v[198:201], v[50:53]
	v_mfma_f32_16x16x32_bf16 v[38:41], v[158:161], v[206:209], v[38:41]
	v_mfma_f32_16x16x32_bf16 v[34:37], v[166:169], v[206:209], v[34:37]
	v_mfma_f32_16x16x32_bf16 v[22:25], v[158:161], v[214:217], v[22:25]
	v_mfma_f32_16x16x32_bf16 v[18:21], v[166:169], v[214:217], v[18:21]
	s_setprio 0
	s_setprio 1
	v_mfma_f32_16x16x32_bf16 v[46:49], v[170:173], v[186:189], v[46:49]
	v_mfma_f32_16x16x32_bf16 v[42:45], v[178:181], v[186:189], v[42:45]
	v_mfma_f32_16x16x32_bf16 v[30:33], v[170:173], v[194:197], v[30:33]
	v_mfma_f32_16x16x32_bf16 v[26:29], v[178:181], v[194:197], v[26:29]
	v_mfma_f32_16x16x32_bf16 v[14:17], v[170:173], v[202:205], v[14:17]
	v_mfma_f32_16x16x32_bf16 v[10:13], v[178:181], v[202:205], v[10:13]
	v_mfma_f32_16x16x32_bf16 v[6:9], v[170:173], v[210:213], v[6:9]
	v_mfma_f32_16x16x32_bf16 v[2:5], v[178:181], v[210:213], v[2:5]
	v_mfma_f32_16x16x32_bf16 v[46:49], v[174:177], v[190:193], v[46:49]
	v_mfma_f32_16x16x32_bf16 v[42:45], v[182:185], v[190:193], v[42:45]
	v_mfma_f32_16x16x32_bf16 v[30:33], v[174:177], v[198:201], v[30:33]
	v_mfma_f32_16x16x32_bf16 v[26:29], v[182:185], v[198:201], v[26:29]
	v_mfma_f32_16x16x32_bf16 v[14:17], v[174:177], v[206:209], v[14:17]
	v_mfma_f32_16x16x32_bf16 v[10:13], v[182:185], v[206:209], v[10:13]
	v_mfma_f32_16x16x32_bf16 v[6:9], v[174:177], v[214:217], v[6:9]
	v_mfma_f32_16x16x32_bf16 v[2:5], v[182:185], v[214:217], v[2:5]
	s_setprio 0
	s_barrier
; #define PG8_STAGE(bufoff, gbase, voff) do { _Pragma("unroll") for (int _i = 0; _i < 2; ++_i) \
;         __builtin_amdgcn_global_load_lds((const unsigned*)((const char*)(gbase) + (voff)[_i]), (PG8_LAS unsigned*)(lds + (bufoff) + ldsw + _i * 8192), 16, 0, 0); } while (0)
; #define PG8_LDA(dst, b, h) do { _Pragma("unroll") for (int m = 0; m < 4; ++m) _Pragma("unroll") for (int k = 0; k < 2; ++k) dst[m][k] = *(const PG8_LAS bf16x8*)(lds + PG8_SA(b, h) + aoff + m * 2048 + k * 1024); } while (0)
; #define PG8_LDB(dst, b, h) do { _Pragma("unroll") for (int n = 0; n < 2; ++n) _Pragma("unroll") for (int k = 0; k < 2; ++k) dst[n][k] = *(const PG8_LAS bf16x8*)(lds + PG8_SB(b, h) + boff + n * 2048 + k * 1024); } while (0)
; #define PG8_MMA(ai, bj, At, Bt) do { __builtin_amdgcn_s_setprio(1); _Pragma("unroll") for (int m = 0; m < 4; ++m) _Pragma("unroll") for (int n = 0; n < 2; ++n) _Pragma("unroll") for (int k = 0; k < 2; ++k) \
;         acc[ai][bj][m][n] = __builtin_amdgcn_mfma_f32_16x16x32_bf16(Bt[n][k], At[m][k], acc[ai][bj][m][n], 0, 0, 0); __builtin_amdgcn_s_setprio(0); } while (0)
; #define PG8_WAIT_V(n) asm volatile("s_waitcnt vmcnt(" #n ")" ::: "memory")
; #define PG8_WAIT_L(n) asm volatile("s_waitcnt lgkmcnt(" #n ")" ::: "memory")
; #define PG8_BAR __builtin_amdgcn_s_barrier()
; template <class Epi, class Sched, bool ALIGN_EPI = false, bool SP2 = false>
; __device__ __forceinline__ void gemm_phase(PG8_LAS unsigned char* lds, const Gemm g, const Sched& S, const Epi& E) {
;     ...
;         for (int t = 0; t < nt; t += 2) {
;             const bool last = (t == nt - 2);
;             const char* a1 = cA + (size_t)(t + 1) * kstep;
;             const char* a2 = last ? nA : cA + (size_t)(t + 2) * kstep; const char* b2 = last ? nB : cB + (size_t)(t + 2) * kstep;
;             const char* a3 = a2 + kstep; const char* b3 = b2 + kstep;
;     ...
;             PG8_LDB(B0, 1, 0); PG8_LDB(B1, 1, 1); PG8_SCHED; PG8_LDA(At, 1, 0); PG8_STAGE(PG8_SA(0, 1), a2 + hstep, voffA);
;             PG8_WAIT_V(8); PG8_WAIT_L(0); PG8_BAR; PG8_MMA(0, 0, At, B0); PG8_MMA(0, 1, At, B1); PG8_BAR; PG8_SCHED;
;             PG8_LDA(At, 1, 1); PG8_STAGE(PG8_SB(1, 0), b3, voffB); PG8_STAGE(PG8_SB(1, 1), b3 + hstep, voffB); PG8_STAGE(PG8_SA(1, 0), a3, voffA);
;             PG8_WAIT_V(8); PG8_WAIT_L(0); PG8_BAR; PG8_MMA(1, 0, At, B0); PG8_MMA(1, 1, At, B1); PG8_BAR; PG8_SCHED;
	ds_read_b128 v[154:157], v151
	ds_read_b128 v[158:161], v151 offset:1024
	ds_read_b128 v[162:165], v151 offset:2048
	ds_read_b128 v[166:169], v151 offset:3072
	ds_read_b128 v[170:173], v152
	ds_read_b128 v[174:177], v152 offset:1024
	ds_read_b128 v[178:181], v152 offset:2048
	ds_read_b128 v[182:185], v152 offset:3072
	s_add_u32 s42, s42, 0x40000
	s_addc_u32 s43, s43, 0
	s_mov_b32 m0, s49
	v_lshl_add_u64 v[226:227], s[42:43], 0, v[130:131]
	ds_read_b128 v[186:189], v150 offset:32768
	ds_read_b128 v[190:193], v150 offset:33792
	ds_read_b128 v[194:197], v150 offset:34816
	ds_read_b128 v[198:201], v150 offset:35840
	ds_read_b128 v[202:205], v150 offset:36864
	ds_read_b128 v[206:209], v150 offset:37888
	ds_read_b128 v[210:213], v150 offset:38912
	ds_read_b128 v[214:217], v150 offset:39936
	global_load_lds_dwordx4 v[226:227], off
	v_lshl_add_u64 v[226:227], s[42:43], 0, v[134:135]
	s_mov_b32 m0, s50
	s_nop 0
	global_load_lds_dwordx4 v[226:227], off
	s_waitcnt vmcnt(8)
	s_waitcnt lgkmcnt(0)
	s_barrier
	s_setprio 1
	s_waitcnt lgkmcnt(0)
	v_mfma_f32_16x16x32_bf16 v[126:129], v[154:157], v[186:189], v[126:129]
	v_mfma_f32_16x16x32_bf16 v[122:125], v[162:165], v[186:189], v[122:125]
	v_mfma_f32_16x16x32_bf16 v[118:121], v[154:157], v[194:197], v[118:121]
	v_mfma_f32_16x16x32_bf16 v[114:117], v[162:165], v[194:197], v[114:117]
	v_mfma_f32_16x16x32_bf16 v[102:105], v[154:157], v[202:205], v[102:105]
	v_mfma_f32_16x16x32_bf16 v[98:101], v[162:165], v[202:205], v[98:101]
	v_mfma_f32_16x16x32_bf16 v[86:89], v[154:157], v[210:213], v[86:89]
	v_mfma_f32_16x16x32_bf16 v[82:85], v[162:165], v[210:213], v[82:85]
	v_mfma_f32_16x16x32_bf16 v[126:129], v[158:161], v[190:193], v[126:129]
	v_mfma_f32_16x16x32_bf16 v[122:125], v[166:169], v[190:193], v[122:125]
	v_mfma_f32_16x16x32_bf16 v[118:121], v[158:161], v[198:201], v[118:121]
	v_mfma_f32_16x16x32_bf16 v[114:117], v[166:169], v[198:201], v[114:117]
	v_mfma_f32_16x16x32_bf16 v[102:105], v[158:161], v[206:209], v[102:105]
	v_mfma_f32_16x16x32_bf16 v[98:101], v[166:169], v[206:209], v[98:101]
	v_mfma_f32_16x16x32_bf16 v[86:89], v[158:161], v[214:217], v[86:89]
	v_mfma_f32_16x16x32_bf16 v[82:85], v[166:169], v[214:217], v[82:85]
	s_setprio 0
	s_setprio 1
	v_mfma_f32_16x16x32_bf16 v[110:113], v[170:173], v[186:189], v[110:113]
	v_mfma_f32_16x16x32_bf16 v[106:109], v[178:181], v[186:189], v[106:109]
	v_mfma_f32_16x16x32_bf16 v[94:97], v[170:173], v[194:197], v[94:97]
	v_mfma_f32_16x16x32_bf16 v[90:93], v[178:181], v[194:197], v[90:93]
	v_mfma_f32_16x16x32_bf16 v[78:81], v[170:173], v[202:205], v[78:81]
	v_mfma_f32_16x16x32_bf16 v[74:77], v[178:181], v[202:205], v[74:77]
	v_mfma_f32_16x16x32_bf16 v[70:73], v[170:173], v[210:213], v[70:73]
	v_mfma_f32_16x16x32_bf16 v[66:69], v[178:181], v[210:213], v[66:69]
	v_mfma_f32_16x16x32_bf16 v[110:113], v[174:177], v[190:193], v[110:113]
	v_mfma_f32_16x16x32_bf16 v[106:109], v[182:185], v[190:193], v[106:109]
	v_mfma_f32_16x16x32_bf16 v[94:97], v[174:177], v[198:201], v[94:97]
	v_mfma_f32_16x16x32_bf16 v[90:93], v[182:185], v[198:201], v[90:93]
	v_mfma_f32_16x16x32_bf16 v[78:81], v[174:177], v[206:209], v[78:81]
	v_mfma_f32_16x16x32_bf16 v[74:77], v[182:185], v[206:209], v[74:77]
	v_mfma_f32_16x16x32_bf16 v[70:73], v[174:177], v[214:217], v[70:73]
	v_mfma_f32_16x16x32_bf16 v[66:69], v[182:185], v[214:217], v[66:69]
	s_setprio 0
	s_barrier
	s_mov_b32 m0, s52
	v_lshl_add_u64 v[218:219], v[218:219], 0, s[8:9]
	s_add_u32 s40, s40, 0x40080
	ds_read_b128 v[186:189], v150 offset:49152
	ds_read_b128 v[190:193], v150 offset:50176
	ds_read_b128 v[194:197], v150 offset:51200
	ds_read_b128 v[198:201], v150 offset:52224
	ds_read_b128 v[202:205], v150 offset:53248
	ds_read_b128 v[206:209], v150 offset:54272
	ds_read_b128 v[210:213], v150 offset:55296
	ds_read_b128 v[214:217], v150 offset:56320
	global_load_lds_dwordx4 v[218:219], off
	v_lshl_add_u64 v[218:219], v[220:221], 0, s[8:9]
	s_mov_b32 m0, s53
	s_addc_u32 s41, s41, 0
	global_load_lds_dwordx4 v[218:219], off
	v_lshl_add_u64 v[218:219], s[40:41], 0, v[132:133]
	s_mov_b32 m0, s56
	s_nop 0
	global_load_lds_dwordx4 v[218:219], off
	v_lshl_add_u64 v[218:219], s[40:41], 0, v[136:137]
	s_mov_b32 m0, s57
	s_nop 0
	global_load_lds_dwordx4 v[218:219], off
	v_lshl_add_u64 v[218:219], v[222:223], 0, s[8:9]
	s_mov_b32 m0, s54
	s_nop 0
	global_load_lds_dwordx4 v[218:219], off
	v_lshl_add_u64 v[218:219], v[224:225], 0, s[8:9]
	s_mov_b32 m0, s55
	s_nop 0
	global_load_lds_dwordx4 v[218:219], off
	s_waitcnt vmcnt(8)
	s_waitcnt lgkmcnt(0)
	s_barrier
	s_setprio 1
	s_waitcnt lgkmcnt(0)
	v_mfma_f32_16x16x32_bf16 v[62:65], v[154:157], v[186:189], v[62:65]
	v_mfma_f32_16x16x32_bf16 v[58:61], v[162:165], v[186:189], v[58:61]
	v_mfma_f32_16x16x32_bf16 v[54:57], v[154:157], v[194:197], v[54:57]
	v_mfma_f32_16x16x32_bf16 v[50:53], v[162:165], v[194:197], v[50:53]
	v_mfma_f32_16x16x32_bf16 v[38:41], v[154:157], v[202:205], v[38:41]
	v_mfma_f32_16x16x32_bf16 v[34:37], v[162:165], v[202:205], v[34:37]
	v_mfma_f32_16x16x32_bf16 v[22:25], v[154:157], v[210:213], v[22:25]
	v_mfma_f32_16x16x32_bf16 v[18:21], v[162:165], v[210:213], v[18:21]
	v_mfma_f32_16x16x32_bf16 v[62:65], v[158:161], v[190:193], v[62:65]
	v_mfma_f32_16x16x32_bf16 v[58:61], v[166:169], v[190:193], v[58:61]
	v_mfma_f32_16x16x32_bf16 v[54:57], v[158:161], v[198:201], v[54:57]
	v_mfma_f32_16x16x32_bf16 v[50:53], v[166:169], v[198:201], v[50:53]
	v_mfma_f32_16x16x32_bf16 v[38:41], v[158:161], v[206:209], v[38:41]
	v_mfma_f32_16x16x32_bf16 v[34:37], v[166:169], v[206:209], v[34:37]
	v_mfma_f32_16x16x32_bf16 v[22:25], v[158:161], v[214:217], v[22:25]
	v_mfma_f32_16x16x32_bf16 v[18:21], v[166:169], v[214:217], v[18:21]
	s_setprio 0
	s_setprio 1
	v_mfma_f32_16x16x32_bf16 v[46:49], v[170:173], v[186:189], v[46:49]
	v_mfma_f32_16x16x32_bf16 v[42:45], v[178:181], v[186:189], v[42:45]
	v_mfma_f32_16x16x32_bf16 v[30:33], v[170:173], v[194:197], v[30:33]
	v_mfma_f32_16x16x32_bf16 v[26:29], v[178:181], v[194:197], v[26:29]
	v_mfma_f32_16x16x32_bf16 v[14:17], v[170:173], v[202:205], v[14:17]
	v_mfma_f32_16x16x32_bf16 v[10:13], v[178:181], v[202:205], v[10:13]
	v_mfma_f32_16x16x32_bf16 v[6:9], v[170:173], v[210:213], v[6:9]
	v_mfma_f32_16x16x32_bf16 v[2:5], v[178:181], v[210:213], v[2:5]
	v_mfma_f32_16x16x32_bf16 v[46:49], v[174:177], v[190:193], v[46:49]
	v_mfma_f32_16x16x32_bf16 v[42:45], v[182:185], v[190:193], v[42:45]
	v_mfma_f32_16x16x32_bf16 v[30:33], v[174:177], v[198:201], v[30:33]
	v_mfma_f32_16x16x32_bf16 v[26:29], v[182:185], v[198:201], v[26:29]
	v_mfma_f32_16x16x32_bf16 v[14:17], v[174:177], v[206:209], v[14:17]
	v_mfma_f32_16x16x32_bf16 v[10:13], v[182:185], v[206:209], v[10:13]
	v_mfma_f32_16x16x32_bf16 v[6:9], v[174:177], v[214:217], v[6:9]
	v_mfma_f32_16x16x32_bf16 v[2:5], v[182:185], v[214:217], v[2:5]
	s_setprio 0
	s_add_i32 s68, s68, 2
	s_add_u32 s66, s66, 0x100
	s_addc_u32 s67, s67, 0
	s_add_u32 s38, s38, 0x100
	s_addc_u32 s39, s39, 0
	s_cmp_gt_u32 s68, 13
	s_barrier
	s_cbranch_scc0 .LBB0_2134
	s_and_b64 vcc, exec, s[10:11]
	s_cbranch_vccz .LBB0_2137
	s_barrier

; #define PG8_STAGE(bufoff, gbase, voff) do { _Pragma("unroll") for (int _i = 0; _i < 2; ++_i) \
;         __builtin_amdgcn_global_load_lds((const unsigned*)((const char*)(gbase) + (voff)[_i]), (PG8_LAS unsigned*)(lds + (bufoff) + ldsw + _i * 8192), 16, 0, 0); } while (0)
; #define PG8_LDA(dst, b, h) do { _Pragma("unroll") for (int m = 0; m < 4; ++m) _Pragma("unroll") for (int k = 0; k < 2; ++k) dst[m][k] = *(const PG8_LAS bf16x8*)(lds + PG8_SA(b, h) + aoff + m * 2048 + k * 1024); } while (0)
; #define PG8_LDB(dst, b, h) do { _Pragma("unroll") for (int n = 0; n < 2; ++n) _Pragma("unroll") for (int k = 0; k < 2; ++k) dst[n][k] = *(const PG8_LAS bf16x8*)(lds + PG8_SB(b, h) + boff + n * 2048 + k * 1024); } while (0)
; #define PG8_WAIT_V(n) asm volatile("s_waitcnt vmcnt(" #n ")" ::: "memory")
; #define PG8_WAIT_L(n) asm volatile("s_waitcnt lgkmcnt(" #n ")" ::: "memory")
; #define PG8_BAR __builtin_amdgcn_s_barrier()
; #define PG8_SCHED __builtin_amdgcn_sched_barrier(0)
; template <class Epi, class Sched, bool ALIGN_EPI = false, bool SP2 = false>
; __device__ __forceinline__ void gemm_phase(PG8_LAS unsigned char* lds, const Gemm g, const Sched& S, const Epi& E) {
;     ...
;         const bool has_next = S.next(ui + 1, nxt);
;         const char* nA = has_next ? (const char*)g.A + (size_t)nxt.pm * tstep + (size_t)nxt.ks * K * 2 : cA; const char* nB = has_next ? (const char*)g.Bt + (size_t)nxt.pn * tstep + (size_t)nxt.ks * K * 2 : cB;
;         for (int t = 0; t < nt; t += 2) {
;             const bool last = (t == nt - 2);
;             const char* a1 = cA + (size_t)(t + 1) * kstep;
;             const char* a2 = last ? nA : cA + (size_t)(t + 2) * kstep; const char* b2 = last ? nB : cB + (size_t)(t + 2) * kstep;
;             const char* a3 = a2 + kstep; const char* b3 = b2 + kstep;
;             if (last && has_next) S.a_ready(nxt);
;             if constexpr (SP2) {
;             PG8_LDB(B0, 0, 0); PG8_LDB(B1, 0, 1); PG8_SCHED; PG8_LDA(At, 0, 0); PG8_STAGE(PG8_SA(1, 1), a1 + hstep, voffA);
;             PG8_WAIT_V(8); PG8_WAIT_L(0); PG8_BAR; PG8_MMA(0, 0, At, B0); PG8_MMA(0, 1, At, B1); PG8_BAR; PG8_SCHED;
;             PG8_LDA(At, 0, 1); PG8_STAGE(PG8_SB(0, 0), b2, voffB); PG8_STAGE(PG8_SB(0, 1), b2 + hstep, voffB); PG8_STAGE(PG8_SA(0, 0), a2, voffA);
;             PG8_WAIT_V(8); PG8_WAIT_L(0); PG8_BAR; PG8_MMA(1, 0, At, B0); PG8_MMA(1, 1, At, B1); PG8_BAR; PG8_SCHED;
.LBB0_2284:
	s_ashr_i32 s13, s12, 31
	s_lshl_b64 s[14:15], s[12:13], 19
	s_add_u32 s14, s28, s14
	s_addc_u32 s15, s29, s15
	s_and_b64 s[16:17], s[2:3], exec
	s_cselect_b32 s13, s15, s23
	s_cselect_b32 s50, s14, s22
	s_ashr_i32 s11, s10, 31
	s_lshl_b64 s[16:17], s[10:11], 19
	s_add_u32 s16, s30, s16
	s_addc_u32 s17, s31, s17
	s_and_b64 s[24:25], s[2:3], exec
	s_cselect_b32 s11, s17, s21
	s_cselect_b32 s51, s16, s20
	s_add_u32 s54, s20, 0x100
	s_addc_u32 s55, s21, 0
	s_add_u32 s20, s22, 0x40080
	s_addc_u32 s21, s23, 0
	s_mov_b32 s58, -2
	ds_read_b128 v[146:149], v152
	ds_read_b128 v[158:161], v152 offset:1024
	ds_read_b128 v[162:165], v152 offset:2048
	ds_read_b128 v[166:169], v152 offset:3072
	ds_read_b128 v[170:173], v153
	ds_read_b128 v[174:177], v153 offset:1024
	ds_read_b128 v[178:181], v153 offset:2048
	ds_read_b128 v[182:185], v153 offset:3072
	s_add_u32 s22, s20, 0xfffc0080
	s_addc_u32 s23, s21, -1
	s_cmp_eq_u32 s58, 12
	s_cselect_b32 s25, s13, s23
	s_cselect_b32 s24, s50, s22
	s_cselect_b32 s23, s11, s55
	s_cselect_b32 s22, s51, s54
	v_lshl_add_u64 v[218:219], s[20:21], 0, v[140:141]
	s_add_i32 m0, s41, 0xc000
	ds_read_b128 v[186:189], v154
	ds_read_b128 v[190:193], v154 offset:1024
	ds_read_b128 v[194:197], v154 offset:2048
	ds_read_b128 v[198:201], v154 offset:3072
	ds_read_b128 v[202:205], v154 offset:4096
	ds_read_b128 v[206:209], v154 offset:5120
	ds_read_b128 v[210:213], v154 offset:6144
	ds_read_b128 v[214:217], v154 offset:7168
	global_load_lds_dwordx4 v[218:219], off
	v_lshl_add_u64 v[218:219], s[20:21], 0, v[138:139]
	s_add_i32 m0, s41, 0xe000
	s_nop 0
	global_load_lds_dwordx4 v[218:219], off
	s_waitcnt vmcnt(8)
	s_waitcnt lgkmcnt(0)
	s_barrier
	s_setprio 1
	s_waitcnt lgkmcnt(0)
	v_mfma_f32_16x16x32_bf16 v[126:129], v[146:149], v[186:189], 0
	v_mfma_f32_16x16x32_bf16 v[118:121], v[162:165], v[186:189], 0
	v_mfma_f32_16x16x32_bf16 v[110:113], v[146:149], v[194:197], 0
	v_mfma_f32_16x16x32_bf16 v[102:105], v[162:165], v[194:197], 0
	v_mfma_f32_16x16x32_bf16 v[94:97], v[146:149], v[202:205], 0
	v_mfma_f32_16x16x32_bf16 v[86:89], v[162:165], v[202:205], 0
	v_mfma_f32_16x16x32_bf16 v[78:81], v[146:149], v[210:213], 0
	v_mfma_f32_16x16x32_bf16 v[70:73], v[162:165], v[210:213], 0
	v_mfma_f32_16x16x32_bf16 v[126:129], v[158:161], v[190:193], v[126:129]
	v_mfma_f32_16x16x32_bf16 v[118:121], v[166:169], v[190:193], v[118:121]
	v_mfma_f32_16x16x32_bf16 v[110:113], v[158:161], v[198:201], v[110:113]
	v_mfma_f32_16x16x32_bf16 v[102:105], v[166:169], v[198:201], v[102:105]
	v_mfma_f32_16x16x32_bf16 v[94:97], v[158:161], v[206:209], v[94:97]
	v_mfma_f32_16x16x32_bf16 v[86:89], v[166:169], v[206:209], v[86:89]
	v_mfma_f32_16x16x32_bf16 v[78:81], v[158:161], v[214:217], v[78:81]
	v_mfma_f32_16x16x32_bf16 v[70:73], v[166:169], v[214:217], v[70:73]
	s_setprio 0
	s_setprio 1
	v_mfma_f32_16x16x32_bf16 v[122:125], v[170:173], v[186:189], 0
	v_mfma_f32_16x16x32_bf16 v[114:117], v[178:181], v[186:189], 0
	v_mfma_f32_16x16x32_bf16 v[106:109], v[170:173], v[194:197], 0
	v_mfma_f32_16x16x32_bf16 v[98:101], v[178:181], v[194:197], 0
	v_mfma_f32_16x16x32_bf16 v[90:93], v[170:173], v[202:205], 0
	v_mfma_f32_16x16x32_bf16 v[82:85], v[178:181], v[202:205], 0
	v_mfma_f32_16x16x32_bf16 v[74:77], v[170:173], v[210:213], 0
	v_mfma_f32_16x16x32_bf16 v[66:69], v[178:181], v[210:213], 0
	v_mfma_f32_16x16x32_bf16 v[122:125], v[174:177], v[190:193], v[122:125]
	v_mfma_f32_16x16x32_bf16 v[114:117], v[182:185], v[190:193], v[114:117]
	v_mfma_f32_16x16x32_bf16 v[106:109], v[174:177], v[198:201], v[106:109]
	v_mfma_f32_16x16x32_bf16 v[98:101], v[182:185], v[198:201], v[98:101]
	v_mfma_f32_16x16x32_bf16 v[90:93], v[174:177], v[206:209], v[90:93]
	v_mfma_f32_16x16x32_bf16 v[82:85], v[182:185], v[206:209], v[82:85]
	v_mfma_f32_16x16x32_bf16 v[74:77], v[174:177], v[214:217], v[74:77]
	v_mfma_f32_16x16x32_bf16 v[66:69], v[182:185], v[214:217], v[66:69]
	s_setprio 0
	s_barrier
	s_mov_b32 m0, s19
	v_lshl_add_u64 v[218:219], s[22:23], 0, v[134:135]
	s_add_u32 s60, s22, 0x40000
	ds_read_b128 v[186:189], v154 offset:16384
	ds_read_b128 v[190:193], v154 offset:17408
	ds_read_b128 v[194:197], v154 offset:18432
	ds_read_b128 v[198:201], v154 offset:19456
	ds_read_b128 v[202:205], v154 offset:20480
	ds_read_b128 v[206:209], v154 offset:21504
	ds_read_b128 v[210:213], v154 offset:22528
	ds_read_b128 v[214:217], v154 offset:23552
	global_load_lds_dwordx4 v[218:219], off
	v_lshl_add_u64 v[220:221], s[22:23], 0, v[130:131]
	s_mov_b32 m0, s38
	s_addc_u32 s61, s23, 0
	global_load_lds_dwordx4 v[220:221], off
	v_lshl_add_u64 v[222:223], s[60:61], 0, v[134:135]
	s_mov_b32 m0, s39
	v_lshl_add_u64 v[224:225], s[24:25], 0, v[132:133]
	global_load_lds_dwordx4 v[222:223], off
	v_lshl_add_u64 v[222:223], s[60:61], 0, v[130:131]
	s_mov_b32 m0, s40
	s_nop 0
	global_load_lds_dwordx4 v[222:223], off
	v_lshl_add_u64 v[222:223], s[24:25], 0, v[136:137]
	s_mov_b32 m0, s41
	s_nop 0
	global_load_lds_dwordx4 v[222:223], off
	s_mov_b32 m0, s42
	s_nop 0
	global_load_lds_dwordx4 v[224:225], off
	s_waitcnt vmcnt(8)
	s_waitcnt lgkmcnt(0)
	s_barrier
; #define PG8_STAGE(bufoff, gbase, voff) do { _Pragma("unroll") for (int _i = 0; _i < 2; ++_i) \
;         __builtin_amdgcn_global_load_lds((const unsigned*)((const char*)(gbase) + (voff)[_i]), (PG8_LAS unsigned*)(lds + (bufoff) + ldsw + _i * 8192), 16, 0, 0); } while (0)
; #define PG8_LDA(dst, b, h) do { _Pragma("unroll") for (int m = 0; m < 4; ++m) _Pragma("unroll") for (int k = 0; k < 2; ++k) dst[m][k] = *(const PG8_LAS bf16x8*)(lds + PG8_SA(b, h) + aoff + m * 2048 + k * 1024); } while (0)
; #define PG8_LDB(dst, b, h) do { _Pragma("unroll") for (int n = 0; n < 2; ++n) _Pragma("unroll") for (int k = 0; k < 2; ++k) dst[n][k] = *(const PG8_LAS bf16x8*)(lds + PG8_SB(b, h) + boff + n * 2048 + k * 1024); } while (0)
; #define PG8_MMA(ai, bj, At, Bt) do { __builtin_amdgcn_s_setprio(1); _Pragma("unroll") for (int m = 0; m < 4; ++m) _Pragma("unroll") for (int n = 0; n < 2; ++n) _Pragma("unroll") for (int k = 0; k < 2; ++k) \
;         acc[ai][bj][m][n] = __builtin_amdgcn_mfma_f32_16x16x32_bf16(Bt[n][k], At[m][k], acc[ai][bj][m][n], 0, 0, 0); __builtin_amdgcn_s_setprio(0); } while (0)
; #define PG8_WAIT_V(n) asm volatile("s_waitcnt vmcnt(" #n ")" ::: "memory")
; #define PG8_WAIT_L(n) asm volatile("s_waitcnt lgkmcnt(" #n ")" ::: "memory")
; #define PG8_BAR __builtin_amdgcn_s_barrier()
; #define PG8_SCHED __builtin_amdgcn_sched_barrier(0)
; template <class Epi, class Sched, bool ALIGN_EPI = false, bool SP2 = false>
; __device__ __forceinline__ void gemm_phase(PG8_LAS unsigned char* lds, const Gemm g, const Sched& S, const Epi& E) {
;     ...
;             PG8_WAIT_V(8); PG8_WAIT_L(0); PG8_BAR; PG8_MMA(0, 0, At, B0); PG8_MMA(0, 1, At, B1); PG8_BAR; PG8_SCHED;
;             PG8_LDA(At, 0, 1); PG8_STAGE(PG8_SB(0, 0), b2, voffB); PG8_STAGE(PG8_SB(0, 1), b2 + hstep, voffB); PG8_STAGE(PG8_SA(0, 0), a2, voffA);
;             PG8_WAIT_V(8); PG8_WAIT_L(0); PG8_BAR; PG8_MMA(1, 0, At, B0); PG8_MMA(1, 1, At, B1); PG8_BAR; PG8_SCHED;
;             PG8_LDB(B0, 1, 0); PG8_LDB(B1, 1, 1); PG8_SCHED; PG8_LDA(At, 1, 0); PG8_STAGE(PG8_SA(0, 1), a2 + hstep, voffA);
;             PG8_WAIT_V(8); PG8_WAIT_L(0); PG8_BAR; PG8_MMA(0, 0, At, B0); PG8_MMA(0, 1, At, B1); PG8_BAR; PG8_SCHED;
	s_setprio 1
	s_waitcnt lgkmcnt(0)
	v_mfma_f32_16x16x32_bf16 v[62:65], v[146:149], v[186:189], 0
	v_mfma_f32_16x16x32_bf16 v[54:57], v[162:165], v[186:189], 0
	v_mfma_f32_16x16x32_bf16 v[46:49], v[146:149], v[194:197], 0
	v_mfma_f32_16x16x32_bf16 v[38:41], v[162:165], v[194:197], 0
	v_mfma_f32_16x16x32_bf16 v[30:33], v[146:149], v[202:205], 0
	v_mfma_f32_16x16x32_bf16 v[22:25], v[162:165], v[202:205], 0
	v_mfma_f32_16x16x32_bf16 v[14:17], v[146:149], v[210:213], 0
	v_mfma_f32_16x16x32_bf16 v[6:9], v[162:165], v[210:213], 0
	v_mfma_f32_16x16x32_bf16 v[62:65], v[158:161], v[190:193], v[62:65]
	v_mfma_f32_16x16x32_bf16 v[54:57], v[166:169], v[190:193], v[54:57]
	v_mfma_f32_16x16x32_bf16 v[46:49], v[158:161], v[198:201], v[46:49]
	v_mfma_f32_16x16x32_bf16 v[38:41], v[166:169], v[198:201], v[38:41]
	v_mfma_f32_16x16x32_bf16 v[30:33], v[158:161], v[206:209], v[30:33]
	v_mfma_f32_16x16x32_bf16 v[22:25], v[166:169], v[206:209], v[22:25]
	v_mfma_f32_16x16x32_bf16 v[14:17], v[158:161], v[214:217], v[14:17]
	v_mfma_f32_16x16x32_bf16 v[6:9], v[166:169], v[214:217], v[6:9]
	s_setprio 0
	s_setprio 1
	v_mfma_f32_16x16x32_bf16 v[58:61], v[170:173], v[186:189], 0
	v_mfma_f32_16x16x32_bf16 v[50:53], v[178:181], v[186:189], 0
	v_mfma_f32_16x16x32_bf16 v[42:45], v[170:173], v[194:197], 0
	v_mfma_f32_16x16x32_bf16 v[34:37], v[178:181], v[194:197], 0
	v_mfma_f32_16x16x32_bf16 v[26:29], v[170:173], v[202:205], 0
	v_mfma_f32_16x16x32_bf16 v[18:21], v[178:181], v[202:205], 0
	v_mfma_f32_16x16x32_bf16 v[10:13], v[170:173], v[210:213], 0
	v_mfma_f32_16x16x32_bf16 v[2:5], v[178:181], v[210:213], 0
	v_mfma_f32_16x16x32_bf16 v[58:61], v[174:177], v[190:193], v[58:61]
	v_mfma_f32_16x16x32_bf16 v[50:53], v[182:185], v[190:193], v[50:53]
	v_mfma_f32_16x16x32_bf16 v[42:45], v[174:177], v[198:201], v[42:45]
	v_mfma_f32_16x16x32_bf16 v[34:37], v[182:185], v[198:201], v[34:37]
	v_mfma_f32_16x16x32_bf16 v[26:29], v[174:177], v[206:209], v[26:29]
	v_mfma_f32_16x16x32_bf16 v[18:21], v[182:185], v[206:209], v[18:21]
	v_mfma_f32_16x16x32_bf16 v[10:13], v[174:177], v[214:217], v[10:13]
	v_mfma_f32_16x16x32_bf16 v[2:5], v[182:185], v[214:217], v[2:5]
	s_setprio 0
	s_barrier
	ds_read_b128 v[146:149], v155
	ds_read_b128 v[158:161], v155 offset:1024
	ds_read_b128 v[162:165], v155 offset:2048
	ds_read_b128 v[166:169], v155 offset:3072
	ds_read_b128 v[170:173], v156
	ds_read_b128 v[174:177], v156 offset:1024
	ds_read_b128 v[178:181], v156 offset:2048
	ds_read_b128 v[182:185], v156 offset:3072
	s_add_u32 s24, s24, 0x40000
	s_addc_u32 s25, s25, 0
	s_mov_b32 m0, s43
	v_lshl_add_u64 v[226:227], s[24:25], 0, v[136:137]
	ds_read_b128 v[186:189], v154 offset:32768
	ds_read_b128 v[190:193], v154 offset:33792
	ds_read_b128 v[194:197], v154 offset:34816
	ds_read_b128 v[198:201], v154 offset:35840
	ds_read_b128 v[202:205], v154 offset:36864
	ds_read_b128 v[206:209], v154 offset:37888
	ds_read_b128 v[210:213], v154 offset:38912
	ds_read_b128 v[214:217], v154 offset:39936
	global_load_lds_dwordx4 v[226:227], off
	v_lshl_add_u64 v[226:227], s[24:25], 0, v[132:133]
	s_mov_b32 m0, s44
	s_nop 0
	global_load_lds_dwordx4 v[226:227], off
	s_waitcnt vmcnt(8)
	s_waitcnt lgkmcnt(0)
	s_barrier
	s_setprio 1
	s_waitcnt lgkmcnt(0)
	v_mfma_f32_16x16x32_bf16 v[126:129], v[146:149], v[186:189], v[126:129]
	v_mfma_f32_16x16x32_bf16 v[118:121], v[162:165], v[186:189], v[118:121]
	v_mfma_f32_16x16x32_bf16 v[110:113], v[146:149], v[194:197], v[110:113]
	v_mfma_f32_16x16x32_bf16 v[102:105], v[162:165], v[194:197], v[102:105]
	v_mfma_f32_16x16x32_bf16 v[94:97], v[146:149], v[202:205], v[94:97]
	v_mfma_f32_16x16x32_bf16 v[86:89], v[162:165], v[202:205], v[86:89]
	v_mfma_f32_16x16x32_bf16 v[78:81], v[146:149], v[210:213], v[78:81]
	v_mfma_f32_16x16x32_bf16 v[70:73], v[162:165], v[210:213], v[70:73]
	v_mfma_f32_16x16x32_bf16 v[126:129], v[158:161], v[190:193], v[126:129]
	v_mfma_f32_16x16x32_bf16 v[118:121], v[166:169], v[190:193], v[118:121]
	v_mfma_f32_16x16x32_bf16 v[110:113], v[158:161], v[198:201], v[110:113]
	v_mfma_f32_16x16x32_bf16 v[102:105], v[166:169], v[198:201], v[102:105]
	v_mfma_f32_16x16x32_bf16 v[94:97], v[158:161], v[206:209], v[94:97]
	v_mfma_f32_16x16x32_bf16 v[86:89], v[166:169], v[206:209], v[86:89]
	v_mfma_f32_16x16x32_bf16 v[78:81], v[158:161], v[214:217], v[78:81]
	v_mfma_f32_16x16x32_bf16 v[70:73], v[166:169], v[214:217], v[70:73]
	s_setprio 0
	s_setprio 1
	v_mfma_f32_16x16x32_bf16 v[122:125], v[170:173], v[186:189], v[122:125]
	v_mfma_f32_16x16x32_bf16 v[114:117], v[178:181], v[186:189], v[114:117]
	v_mfma_f32_16x16x32_bf16 v[106:109], v[170:173], v[194:197], v[106:109]
	v_mfma_f32_16x16x32_bf16 v[98:101], v[178:181], v[194:197], v[98:101]
	v_mfma_f32_16x16x32_bf16 v[90:93], v[170:173], v[202:205], v[90:93]
	v_mfma_f32_16x16x32_bf16 v[82:85], v[178:181], v[202:205], v[82:85]
	v_mfma_f32_16x16x32_bf16 v[74:77], v[170:173], v[210:213], v[74:77]
	v_mfma_f32_16x16x32_bf16 v[66:69], v[178:181], v[210:213], v[66:69]
	v_mfma_f32_16x16x32_bf16 v[122:125], v[174:177], v[190:193], v[122:125]
	v_mfma_f32_16x16x32_bf16 v[114:117], v[182:185], v[190:193], v[114:117]
	v_mfma_f32_16x16x32_bf16 v[106:109], v[174:177], v[198:201], v[106:109]
	v_mfma_f32_16x16x32_bf16 v[98:101], v[182:185], v[198:201], v[98:101]
	v_mfma_f32_16x16x32_bf16 v[90:93], v[174:177], v[206:209], v[90:93]
	v_mfma_f32_16x16x32_bf16 v[82:85], v[182:185], v[206:209], v[82:85]
	v_mfma_f32_16x16x32_bf16 v[74:77], v[174:177], v[214:217], v[74:77]
	v_mfma_f32_16x16x32_bf16 v[66:69], v[182:185], v[214:217], v[66:69]
	s_setprio 0
	s_barrier
; #define PG8_STAGE(bufoff, gbase, voff) do { _Pragma("unroll") for (int _i = 0; _i < 2; ++_i) \
;         __builtin_amdgcn_global_load_lds((const unsigned*)((const char*)(gbase) + (voff)[_i]), (PG8_LAS unsigned*)(lds + (bufoff) + ldsw + _i * 8192), 16, 0, 0); } while (0)
; #define PG8_LDA(dst, b, h) do { _Pragma("unroll") for (int m = 0; m < 4; ++m) _Pragma("unroll") for (int k = 0; k < 2; ++k) dst[m][k] = *(const PG8_LAS bf16x8*)(lds + PG8_SA(b, h) + aoff + m * 2048 + k * 1024); } while (0)
; #define PG8_LDB(dst, b, h) do { _Pragma("unroll") for (int n = 0; n < 2; ++n) _Pragma("unroll") for (int k = 0; k < 2; ++k) dst[n][k] = *(const PG8_LAS bf16x8*)(lds + PG8_SB(b, h) + boff + n * 2048 + k * 1024); } while (0)
; template <class Epi, class Sched, bool ALIGN_EPI = false, bool SP2 = false>
; __device__ __forceinline__ void gemm_phase(PG8_LAS unsigned char* lds, const Gemm g, const Sched& S, const Epi& E) {
;     ...
;         for (int t = 0; t < nt; t += 2) {
;             const bool last = (t == nt - 2);
;             const char* a1 = cA + (size_t)(t + 1) * kstep;
;             const char* a2 = last ? nA : cA + (size_t)(t + 2) * kstep; const char* b2 = last ? nB : cB + (size_t)(t + 2) * kstep;
;             const char* a3 = a2 + kstep; const char* b3 = b2 + kstep;
;             if (last && has_next) S.a_ready(nxt);
;             if constexpr (SP2) {
;             PG8_LDB(B0, 0, 0); PG8_LDB(B1, 0, 1); PG8_SCHED; PG8_LDA(At, 0, 0); PG8_STAGE(PG8_SA(1, 1), a1 + hstep, voffA);
;             PG8_WAIT_V(8); PG8_WAIT_L(0); PG8_BAR; PG8_MMA(0, 0, At, B0); PG8_MMA(0, 1, At, B1); PG8_BAR; PG8_SCHED;
;             PG8_LDA(At, 0, 1); PG8_STAGE(PG8_SB(0, 0), b2, voffB); PG8_STAGE(PG8_SB(0, 1), b2 + hstep, voffB); PG8_STAGE(PG8_SA(0, 0), a2, voffA);
;             PG8_WAIT_V(8); PG8_WAIT_L(0); PG8_BAR; PG8_MMA(1, 0, At, B0); PG8_MMA(1, 1, At, B1); PG8_BAR; PG8_SCHED;
;             PG8_LDB(B0, 1, 0); PG8_LDB(B1, 1, 1); PG8_SCHED; PG8_LDA(At, 1, 0); PG8_STAGE(PG8_SA(0, 1), a2 + hstep, voffA);
;             PG8_WAIT_V(8); PG8_WAIT_L(0); PG8_BAR; PG8_MMA(0, 0, At, B0); PG8_MMA(0, 1, At, B1); PG8_BAR; PG8_SCHED;
;             PG8_LDA(At, 1, 1); PG8_STAGE(PG8_SB(1, 0), b3, voffB); PG8_STAGE(PG8_SB(1, 1), b3 + hstep, voffB); PG8_STAGE(PG8_SA(1, 0), a3, voffA);
;             PG8_WAIT_V(8); PG8_WAIT_L(0); PG8_BAR; PG8_MMA(1, 0, At, B0); PG8_MMA(1, 1, At, B1); PG8_BAR; PG8_SCHED;
	s_mov_b32 m0, s45
	v_lshl_add_u64 v[218:219], v[218:219], 0, s[6:7]
	s_add_u32 s22, s22, 0x40080
	ds_read_b128 v[186:189], v154 offset:49152
	ds_read_b128 v[190:193], v154 offset:50176
	ds_read_b128 v[194:197], v154 offset:51200
	ds_read_b128 v[198:201], v154 offset:52224
	ds_read_b128 v[202:205], v154 offset:53248
	ds_read_b128 v[206:209], v154 offset:54272
	ds_read_b128 v[210:213], v154 offset:55296
	ds_read_b128 v[214:217], v154 offset:56320
	global_load_lds_dwordx4 v[218:219], off
	v_lshl_add_u64 v[218:219], v[220:221], 0, s[6:7]
	s_mov_b32 m0, s46
	s_addc_u32 s23, s23, 0
	global_load_lds_dwordx4 v[218:219], off
	v_lshl_add_u64 v[218:219], s[22:23], 0, v[134:135]
	s_mov_b32 m0, s49
	s_nop 0
	global_load_lds_dwordx4 v[218:219], off
	v_lshl_add_u64 v[218:219], s[22:23], 0, v[130:131]
	s_mov_b32 m0, s52
	s_nop 0
	global_load_lds_dwordx4 v[218:219], off
	v_lshl_add_u64 v[218:219], v[222:223], 0, s[6:7]
	s_mov_b32 m0, s47
	s_nop 0
	global_load_lds_dwordx4 v[218:219], off
	v_lshl_add_u64 v[218:219], v[224:225], 0, s[6:7]
	s_mov_b32 m0, s48
	s_nop 0
	global_load_lds_dwordx4 v[218:219], off
	s_waitcnt vmcnt(8)
	s_waitcnt lgkmcnt(0)
	s_barrier
	s_setprio 1
	s_waitcnt lgkmcnt(0)
	v_mfma_f32_16x16x32_bf16 v[62:65], v[146:149], v[186:189], v[62:65]
	v_mfma_f32_16x16x32_bf16 v[54:57], v[162:165], v[186:189], v[54:57]
	v_mfma_f32_16x16x32_bf16 v[46:49], v[146:149], v[194:197], v[46:49]
	v_mfma_f32_16x16x32_bf16 v[38:41], v[162:165], v[194:197], v[38:41]
	v_mfma_f32_16x16x32_bf16 v[30:33], v[146:149], v[202:205], v[30:33]
	v_mfma_f32_16x16x32_bf16 v[22:25], v[162:165], v[202:205], v[22:25]
	v_mfma_f32_16x16x32_bf16 v[14:17], v[146:149], v[210:213], v[14:17]
	v_mfma_f32_16x16x32_bf16 v[6:9], v[162:165], v[210:213], v[6:9]
	v_mfma_f32_16x16x32_bf16 v[62:65], v[158:161], v[190:193], v[62:65]
	v_mfma_f32_16x16x32_bf16 v[54:57], v[166:169], v[190:193], v[54:57]
	v_mfma_f32_16x16x32_bf16 v[46:49], v[158:161], v[198:201], v[46:49]
	v_mfma_f32_16x16x32_bf16 v[38:41], v[166:169], v[198:201], v[38:41]
	v_mfma_f32_16x16x32_bf16 v[30:33], v[158:161], v[206:209], v[30:33]
	v_mfma_f32_16x16x32_bf16 v[22:25], v[166:169], v[206:209], v[22:25]
	v_mfma_f32_16x16x32_bf16 v[14:17], v[158:161], v[214:217], v[14:17]
	v_mfma_f32_16x16x32_bf16 v[6:9], v[166:169], v[214:217], v[6:9]
	s_setprio 0
	s_setprio 1
	v_mfma_f32_16x16x32_bf16 v[58:61], v[170:173], v[186:189], v[58:61]
	v_mfma_f32_16x16x32_bf16 v[50:53], v[178:181], v[186:189], v[50:53]
	v_mfma_f32_16x16x32_bf16 v[42:45], v[170:173], v[194:197], v[42:45]
	v_mfma_f32_16x16x32_bf16 v[34:37], v[178:181], v[194:197], v[34:37]
	v_mfma_f32_16x16x32_bf16 v[26:29], v[170:173], v[202:205], v[26:29]
	v_mfma_f32_16x16x32_bf16 v[18:21], v[178:181], v[202:205], v[18:21]
	v_mfma_f32_16x16x32_bf16 v[10:13], v[170:173], v[210:213], v[10:13]
	v_mfma_f32_16x16x32_bf16 v[2:5], v[178:181], v[210:213], v[2:5]
	v_mfma_f32_16x16x32_bf16 v[58:61], v[174:177], v[190:193], v[58:61]
	v_mfma_f32_16x16x32_bf16 v[50:53], v[182:185], v[190:193], v[50:53]
	v_mfma_f32_16x16x32_bf16 v[42:45], v[174:177], v[198:201], v[42:45]
	v_mfma_f32_16x16x32_bf16 v[34:37], v[182:185], v[198:201], v[34:37]
	v_mfma_f32_16x16x32_bf16 v[26:29], v[174:177], v[206:209], v[26:29]
	v_mfma_f32_16x16x32_bf16 v[18:21], v[182:185], v[206:209], v[18:21]
	v_mfma_f32_16x16x32_bf16 v[10:13], v[174:177], v[214:217], v[10:13]
	v_mfma_f32_16x16x32_bf16 v[2:5], v[182:185], v[214:217], v[2:5]
	s_setprio 0
	s_add_i32 s58, s58, 2
	s_add_u32 s54, s54, 0x100
	s_addc_u32 s55, s55, 0
	s_add_u32 s20, s20, 0x100
	s_addc_u32 s21, s21, 0
	s_cmp_gt_u32 s58, 13
	s_barrier
.LBB0_2285:
	ds_read_b128 v[146:149], v152
	ds_read_b128 v[158:161], v152 offset:1024
	ds_read_b128 v[162:165], v152 offset:2048
	ds_read_b128 v[166:169], v152 offset:3072
	ds_read_b128 v[170:173], v153
	ds_read_b128 v[174:177], v153 offset:1024
	ds_read_b128 v[178:181], v153 offset:2048
	ds_read_b128 v[182:185], v153 offset:3072
	s_add_u32 s22, s20, 0xfffc0080
	s_addc_u32 s23, s21, -1
	s_cmp_eq_u32 s58, 12
	s_cselect_b32 s25, s13, s23
	s_cselect_b32 s24, s50, s22
	s_cselect_b32 s23, s11, s55
	s_cselect_b32 s22, s51, s54
	v_lshl_add_u64 v[218:219], s[20:21], 0, v[140:141]
	s_add_i32 m0, s41, 0xc000
	ds_read_b128 v[186:189], v154
	ds_read_b128 v[190:193], v154 offset:1024
	ds_read_b128 v[194:197], v154 offset:2048
	ds_read_b128 v[198:201], v154 offset:3072
	ds_read_b128 v[202:205], v154 offset:4096
	ds_read_b128 v[206:209], v154 offset:5120
	ds_read_b128 v[210:213], v154 offset:6144
	ds_read_b128 v[214:217], v154 offset:7168
	global_load_lds_dwordx4 v[218:219], off
	v_lshl_add_u64 v[218:219], s[20:21], 0, v[138:139]
	s_add_i32 m0, s41, 0xe000
	s_nop 0
	global_load_lds_dwordx4 v[218:219], off
	s_waitcnt vmcnt(8)
	s_waitcnt lgkmcnt(0)
	s_barrier
; #define PG8_STAGE(bufoff, gbase, voff) do { _Pragma("unroll") for (int _i = 0; _i < 2; ++_i) \
;         __builtin_amdgcn_global_load_lds((const unsigned*)((const char*)(gbase) + (voff)[_i]), (PG8_LAS unsigned*)(lds + (bufoff) + ldsw + _i * 8192), 16, 0, 0); } while (0)
; #define PG8_LDA(dst, b, h) do { _Pragma("unroll") for (int m = 0; m < 4; ++m) _Pragma("unroll") for (int k = 0; k < 2; ++k) dst[m][k] = *(const PG8_LAS bf16x8*)(lds + PG8_SA(b, h) + aoff + m * 2048 + k * 1024); } while (0)
; #define PG8_MMA(ai, bj, At, Bt) do { __builtin_amdgcn_s_setprio(1); _Pragma("unroll") for (int m = 0; m < 4; ++m) _Pragma("unroll") for (int n = 0; n < 2; ++n) _Pragma("unroll") for (int k = 0; k < 2; ++k) \
;         acc[ai][bj][m][n] = __builtin_amdgcn_mfma_f32_16x16x32_bf16(Bt[n][k], At[m][k], acc[ai][bj][m][n], 0, 0, 0); __builtin_amdgcn_s_setprio(0); } while (0)
; #define PG8_WAIT_V(n) asm volatile("s_waitcnt vmcnt(" #n ")" ::: "memory")
; #define PG8_WAIT_L(n) asm volatile("s_waitcnt lgkmcnt(" #n ")" ::: "memory")
; #define PG8_BAR __builtin_amdgcn_s_barrier()
; #define PG8_SCHED __builtin_amdgcn_sched_barrier(0)
; template <class Epi, class Sched, bool ALIGN_EPI = false, bool SP2 = false>
; __device__ __forceinline__ void gemm_phase(PG8_LAS unsigned char* lds, const Gemm g, const Sched& S, const Epi& E) {
;     ...
;             PG8_WAIT_V(8); PG8_WAIT_L(0); PG8_BAR; PG8_MMA(0, 0, At, B0); PG8_MMA(0, 1, At, B1); PG8_BAR; PG8_SCHED;
;             PG8_LDA(At, 0, 1); PG8_STAGE(PG8_SB(0, 0), b2, voffB); PG8_STAGE(PG8_SB(0, 1), b2 + hstep, voffB); PG8_STAGE(PG8_SA(0, 0), a2, voffA);
;             PG8_WAIT_V(8); PG8_WAIT_L(0); PG8_BAR; PG8_MMA(1, 0, At, B0); PG8_MMA(1, 1, At, B1); PG8_BAR; PG8_SCHED;
	s_setprio 1
	s_waitcnt lgkmcnt(0)
	v_mfma_f32_16x16x32_bf16 v[126:129], v[146:149], v[186:189], v[126:129]
	v_mfma_f32_16x16x32_bf16 v[118:121], v[162:165], v[186:189], v[118:121]
	v_mfma_f32_16x16x32_bf16 v[110:113], v[146:149], v[194:197], v[110:113]
	v_mfma_f32_16x16x32_bf16 v[102:105], v[162:165], v[194:197], v[102:105]
	v_mfma_f32_16x16x32_bf16 v[94:97], v[146:149], v[202:205], v[94:97]
	v_mfma_f32_16x16x32_bf16 v[86:89], v[162:165], v[202:205], v[86:89]
	v_mfma_f32_16x16x32_bf16 v[78:81], v[146:149], v[210:213], v[78:81]
	v_mfma_f32_16x16x32_bf16 v[70:73], v[162:165], v[210:213], v[70:73]
	v_mfma_f32_16x16x32_bf16 v[126:129], v[158:161], v[190:193], v[126:129]
	v_mfma_f32_16x16x32_bf16 v[118:121], v[166:169], v[190:193], v[118:121]
	v_mfma_f32_16x16x32_bf16 v[110:113], v[158:161], v[198:201], v[110:113]
	v_mfma_f32_16x16x32_bf16 v[102:105], v[166:169], v[198:201], v[102:105]
	v_mfma_f32_16x16x32_bf16 v[94:97], v[158:161], v[206:209], v[94:97]
	v_mfma_f32_16x16x32_bf16 v[86:89], v[166:169], v[206:209], v[86:89]
	v_mfma_f32_16x16x32_bf16 v[78:81], v[158:161], v[214:217], v[78:81]
	v_mfma_f32_16x16x32_bf16 v[70:73], v[166:169], v[214:217], v[70:73]
	s_setprio 0
	s_setprio 1
	v_mfma_f32_16x16x32_bf16 v[122:125], v[170:173], v[186:189], v[122:125]
	v_mfma_f32_16x16x32_bf16 v[114:117], v[178:181], v[186:189], v[114:117]
	v_mfma_f32_16x16x32_bf16 v[106:109], v[170:173], v[194:197], v[106:109]
	v_mfma_f32_16x16x32_bf16 v[98:101], v[178:181], v[194:197], v[98:101]
	v_mfma_f32_16x16x32_bf16 v[90:93], v[170:173], v[202:205], v[90:93]
	v_mfma_f32_16x16x32_bf16 v[82:85], v[178:181], v[202:205], v[82:85]
	v_mfma_f32_16x16x32_bf16 v[74:77], v[170:173], v[210:213], v[74:77]
	v_mfma_f32_16x16x32_bf16 v[66:69], v[178:181], v[210:213], v[66:69]
	v_mfma_f32_16x16x32_bf16 v[122:125], v[174:177], v[190:193], v[122:125]
	v_mfma_f32_16x16x32_bf16 v[114:117], v[182:185], v[190:193], v[114:117]
	v_mfma_f32_16x16x32_bf16 v[106:109], v[174:177], v[198:201], v[106:109]
	v_mfma_f32_16x16x32_bf16 v[98:101], v[182:185], v[198:201], v[98:101]
	v_mfma_f32_16x16x32_bf16 v[90:93], v[174:177], v[206:209], v[90:93]
	v_mfma_f32_16x16x32_bf16 v[82:85], v[182:185], v[206:209], v[82:85]
	v_mfma_f32_16x16x32_bf16 v[74:77], v[174:177], v[214:217], v[74:77]
	v_mfma_f32_16x16x32_bf16 v[66:69], v[182:185], v[214:217], v[66:69]
	s_setprio 0
	s_barrier
	s_mov_b32 m0, s19
	v_lshl_add_u64 v[218:219], s[22:23], 0, v[134:135]
	s_add_u32 s60, s22, 0x40000
	ds_read_b128 v[186:189], v154 offset:16384
	ds_read_b128 v[190:193], v154 offset:17408
	ds_read_b128 v[194:197], v154 offset:18432
	ds_read_b128 v[198:201], v154 offset:19456
	ds_read_b128 v[202:205], v154 offset:20480
	ds_read_b128 v[206:209], v154 offset:21504
	ds_read_b128 v[210:213], v154 offset:22528
	ds_read_b128 v[214:217], v154 offset:23552
	global_load_lds_dwordx4 v[218:219], off
	v_lshl_add_u64 v[220:221], s[22:23], 0, v[130:131]
	s_mov_b32 m0, s38
	s_addc_u32 s61, s23, 0
	global_load_lds_dwordx4 v[220:221], off
	v_lshl_add_u64 v[222:223], s[60:61], 0, v[134:135]
	s_mov_b32 m0, s39
	v_lshl_add_u64 v[224:225], s[24:25], 0, v[132:133]
	global_load_lds_dwordx4 v[222:223], off
	v_lshl_add_u64 v[222:223], s[60:61], 0, v[130:131]
	s_mov_b32 m0, s40
	s_nop 0
	global_load_lds_dwordx4 v[222:223], off
	v_lshl_add_u64 v[222:223], s[24:25], 0, v[136:137]
	s_mov_b32 m0, s41
	s_nop 0
	global_load_lds_dwordx4 v[222:223], off
	s_mov_b32 m0, s42
	s_nop 0
	global_load_lds_dwordx4 v[224:225], off
	s_waitcnt vmcnt(8)
	s_waitcnt lgkmcnt(0)
	s_barrier
	s_setprio 1
	s_waitcnt lgkmcnt(0)
	v_mfma_f32_16x16x32_bf16 v[62:65], v[146:149], v[186:189], v[62:65]
	v_mfma_f32_16x16x32_bf16 v[54:57], v[162:165], v[186:189], v[54:57]
	v_mfma_f32_16x16x32_bf16 v[46:49], v[146:149], v[194:197], v[46:49]
	v_mfma_f32_16x16x32_bf16 v[38:41], v[162:165], v[194:197], v[38:41]
	v_mfma_f32_16x16x32_bf16 v[30:33], v[146:149], v[202:205], v[30:33]
	v_mfma_f32_16x16x32_bf16 v[22:25], v[162:165], v[202:205], v[22:25]
	v_mfma_f32_16x16x32_bf16 v[14:17], v[146:149], v[210:213], v[14:17]
	v_mfma_f32_16x16x32_bf16 v[6:9], v[162:165], v[210:213], v[6:9]
	v_mfma_f32_16x16x32_bf16 v[62:65], v[158:161], v[190:193], v[62:65]
	v_mfma_f32_16x16x32_bf16 v[54:57], v[166:169], v[190:193], v[54:57]
	v_mfma_f32_16x16x32_bf16 v[46:49], v[158:161], v[198:201], v[46:49]
	v_mfma_f32_16x16x32_bf16 v[38:41], v[166:169], v[198:201], v[38:41]
	v_mfma_f32_16x16x32_bf16 v[30:33], v[158:161], v[206:209], v[30:33]
	v_mfma_f32_16x16x32_bf16 v[22:25], v[166:169], v[206:209], v[22:25]
	v_mfma_f32_16x16x32_bf16 v[14:17], v[158:161], v[214:217], v[14:17]
	v_mfma_f32_16x16x32_bf16 v[6:9], v[166:169], v[214:217], v[6:9]
	s_setprio 0
	s_setprio 1
	v_mfma_f32_16x16x32_bf16 v[58:61], v[170:173], v[186:189], v[58:61]
	v_mfma_f32_16x16x32_bf16 v[50:53], v[178:181], v[186:189], v[50:53]
	v_mfma_f32_16x16x32_bf16 v[42:45], v[170:173], v[194:197], v[42:45]
	v_mfma_f32_16x16x32_bf16 v[34:37], v[178:181], v[194:197], v[34:37]
	v_mfma_f32_16x16x32_bf16 v[26:29], v[170:173], v[202:205], v[26:29]
	v_mfma_f32_16x16x32_bf16 v[18:21], v[178:181], v[202:205], v[18:21]
	v_mfma_f32_16x16x32_bf16 v[10:13], v[170:173], v[210:213], v[10:13]
	v_mfma_f32_16x16x32_bf16 v[2:5], v[178:181], v[210:213], v[2:5]
	v_mfma_f32_16x16x32_bf16 v[58:61], v[174:177], v[190:193], v[58:61]
	v_mfma_f32_16x16x32_bf16 v[50:53], v[182:185], v[190:193], v[50:53]
	v_mfma_f32_16x16x32_bf16 v[42:45], v[174:177], v[198:201], v[42:45]
	v_mfma_f32_16x16x32_bf16 v[34:37], v[182:185], v[198:201], v[34:37]
	v_mfma_f32_16x16x32_bf16 v[26:29], v[174:177], v[206:209], v[26:29]
	v_mfma_f32_16x16x32_bf16 v[18:21], v[182:185], v[206:209], v[18:21]
	v_mfma_f32_16x16x32_bf16 v[10:13], v[174:177], v[214:217], v[10:13]
	v_mfma_f32_16x16x32_bf16 v[2:5], v[182:185], v[214:217], v[2:5]
	s_setprio 0
	s_barrier
; #define PG8_STAGE(bufoff, gbase, voff) do { _Pragma("unroll") for (int _i = 0; _i < 2; ++_i) \
;         __builtin_amdgcn_global_load_lds((const unsigned*)((const char*)(gbase) + (voff)[_i]), (PG8_LAS unsigned*)(lds + (bufoff) + ldsw + _i * 8192), 16, 0, 0); } while (0)
; #define PG8_LDA(dst, b, h) do { _Pragma("unroll") for (int m = 0; m < 4; ++m) _Pragma("unroll") for (int k = 0; k < 2; ++k) dst[m][k] = *(const PG8_LAS bf16x8*)(lds + PG8_SA(b, h) + aoff + m * 2048 + k * 1024); } while (0)
; #define PG8_LDB(dst, b, h) do { _Pragma("unroll") for (int n = 0; n < 2; ++n) _Pragma("unroll") for (int k = 0; k < 2; ++k) dst[n][k] = *(const PG8_LAS bf16x8*)(lds + PG8_SB(b, h) + boff + n * 2048 + k * 1024); } while (0)
; #define PG8_MMA(ai, bj, At, Bt) do { __builtin_amdgcn_s_setprio(1); _Pragma("unroll") for (int m = 0; m < 4; ++m) _Pragma("unroll") for (int n = 0; n < 2; ++n) _Pragma("unroll") for (int k = 0; k < 2; ++k) \
;         acc[ai][bj][m][n] = __builtin_amdgcn_mfma_f32_16x16x32_bf16(Bt[n][k], At[m][k], acc[ai][bj][m][n], 0, 0, 0); __builtin_amdgcn_s_setprio(0); } while (0)
; #define PG8_WAIT_V(n) asm volatile("s_waitcnt vmcnt(" #n ")" ::: "memory")
; #define PG8_WAIT_L(n) asm volatile("s_waitcnt lgkmcnt(" #n ")" ::: "memory")
; #define PG8_BAR __builtin_amdgcn_s_barrier()
; template <class Epi, class Sched, bool ALIGN_EPI = false, bool SP2 = false>
; __device__ __forceinline__ void gemm_phase(PG8_LAS unsigned char* lds, const Gemm g, const Sched& S, const Epi& E) {
;     ...
;         for (int t = 0; t < nt; t += 2) {
;             const bool last = (t == nt - 2);
;             const char* a1 = cA + (size_t)(t + 1) * kstep;
;             const char* a2 = last ? nA : cA + (size_t)(t + 2) * kstep; const char* b2 = last ? nB : cB + (size_t)(t + 2) * kstep;
;             const char* a3 = a2 + kstep; const char* b3 = b2 + kstep;
;     ...
;             PG8_LDB(B0, 1, 0); PG8_LDB(B1, 1, 1); PG8_SCHED; PG8_LDA(At, 1, 0); PG8_STAGE(PG8_SA(0, 1), a2 + hstep, voffA);
;             PG8_WAIT_V(8); PG8_WAIT_L(0); PG8_BAR; PG8_MMA(0, 0, At, B0); PG8_MMA(0, 1, At, B1); PG8_BAR; PG8_SCHED;
;             PG8_LDA(At, 1, 1); PG8_STAGE(PG8_SB(1, 0), b3, voffB); PG8_STAGE(PG8_SB(1, 1), b3 + hstep, voffB); PG8_STAGE(PG8_SA(1, 0), a3, voffA);
;             PG8_WAIT_V(8); PG8_WAIT_L(0); PG8_BAR; PG8_MMA(1, 0, At, B0); PG8_MMA(1, 1, At, B1); PG8_BAR; PG8_SCHED;
	ds_read_b128 v[146:149], v155
	ds_read_b128 v[158:161], v155 offset:1024
	ds_read_b128 v[162:165], v155 offset:2048
	ds_read_b128 v[166:169], v155 offset:3072
	ds_read_b128 v[170:173], v156
	ds_read_b128 v[174:177], v156 offset:1024
	ds_read_b128 v[178:181], v156 offset:2048
	ds_read_b128 v[182:185], v156 offset:3072
	s_add_u32 s24, s24, 0x40000
	s_addc_u32 s25, s25, 0
	s_mov_b32 m0, s43
	v_lshl_add_u64 v[226:227], s[24:25], 0, v[136:137]
	ds_read_b128 v[186:189], v154 offset:32768
	ds_read_b128 v[190:193], v154 offset:33792
	ds_read_b128 v[194:197], v154 offset:34816
	ds_read_b128 v[198:201], v154 offset:35840
	ds_read_b128 v[202:205], v154 offset:36864
	ds_read_b128 v[206:209], v154 offset:37888
	ds_read_b128 v[210:213], v154 offset:38912
	ds_read_b128 v[214:217], v154 offset:39936
	global_load_lds_dwordx4 v[226:227], off
	v_lshl_add_u64 v[226:227], s[24:25], 0, v[132:133]
	s_mov_b32 m0, s44
	s_nop 0
	global_load_lds_dwordx4 v[226:227], off
	s_waitcnt vmcnt(8)
	s_waitcnt lgkmcnt(0)
	s_barrier
	s_setprio 1
	s_waitcnt lgkmcnt(0)
	v_mfma_f32_16x16x32_bf16 v[126:129], v[146:149], v[186:189], v[126:129]
	v_mfma_f32_16x16x32_bf16 v[118:121], v[162:165], v[186:189], v[118:121]
	v_mfma_f32_16x16x32_bf16 v[110:113], v[146:149], v[194:197], v[110:113]
	v_mfma_f32_16x16x32_bf16 v[102:105], v[162:165], v[194:197], v[102:105]
	v_mfma_f32_16x16x32_bf16 v[94:97], v[146:149], v[202:205], v[94:97]
	v_mfma_f32_16x16x32_bf16 v[86:89], v[162:165], v[202:205], v[86:89]
	v_mfma_f32_16x16x32_bf16 v[78:81], v[146:149], v[210:213], v[78:81]
	v_mfma_f32_16x16x32_bf16 v[70:73], v[162:165], v[210:213], v[70:73]
	v_mfma_f32_16x16x32_bf16 v[126:129], v[158:161], v[190:193], v[126:129]
	v_mfma_f32_16x16x32_bf16 v[118:121], v[166:169], v[190:193], v[118:121]
	v_mfma_f32_16x16x32_bf16 v[110:113], v[158:161], v[198:201], v[110:113]
	v_mfma_f32_16x16x32_bf16 v[102:105], v[166:169], v[198:201], v[102:105]
	v_mfma_f32_16x16x32_bf16 v[94:97], v[158:161], v[206:209], v[94:97]
	v_mfma_f32_16x16x32_bf16 v[86:89], v[166:169], v[206:209], v[86:89]
	v_mfma_f32_16x16x32_bf16 v[78:81], v[158:161], v[214:217], v[78:81]
	v_mfma_f32_16x16x32_bf16 v[70:73], v[166:169], v[214:217], v[70:73]
	s_setprio 0
	s_setprio 1
	v_mfma_f32_16x16x32_bf16 v[122:125], v[170:173], v[186:189], v[122:125]
	v_mfma_f32_16x16x32_bf16 v[114:117], v[178:181], v[186:189], v[114:117]
	v_mfma_f32_16x16x32_bf16 v[106:109], v[170:173], v[194:197], v[106:109]
	v_mfma_f32_16x16x32_bf16 v[98:101], v[178:181], v[194:197], v[98:101]
	v_mfma_f32_16x16x32_bf16 v[90:93], v[170:173], v[202:205], v[90:93]
	v_mfma_f32_16x16x32_bf16 v[82:85], v[178:181], v[202:205], v[82:85]
	v_mfma_f32_16x16x32_bf16 v[74:77], v[170:173], v[210:213], v[74:77]
	v_mfma_f32_16x16x32_bf16 v[66:69], v[178:181], v[210:213], v[66:69]
	v_mfma_f32_16x16x32_bf16 v[122:125], v[174:177], v[190:193], v[122:125]
	v_mfma_f32_16x16x32_bf16 v[114:117], v[182:185], v[190:193], v[114:117]
	v_mfma_f32_16x16x32_bf16 v[106:109], v[174:177], v[198:201], v[106:109]
	v_mfma_f32_16x16x32_bf16 v[98:101], v[182:185], v[198:201], v[98:101]
	v_mfma_f32_16x16x32_bf16 v[90:93], v[174:177], v[206:209], v[90:93]
	v_mfma_f32_16x16x32_bf16 v[82:85], v[182:185], v[206:209], v[82:85]
	v_mfma_f32_16x16x32_bf16 v[74:77], v[174:177], v[214:217], v[74:77]
	v_mfma_f32_16x16x32_bf16 v[66:69], v[182:185], v[214:217], v[66:69]
	s_setprio 0
	s_barrier
	s_mov_b32 m0, s45
	v_lshl_add_u64 v[218:219], v[218:219], 0, s[6:7]
	s_add_u32 s22, s22, 0x40080
	ds_read_b128 v[186:189], v154 offset:49152
	ds_read_b128 v[190:193], v154 offset:50176
	ds_read_b128 v[194:197], v154 offset:51200
	ds_read_b128 v[198:201], v154 offset:52224
	ds_read_b128 v[202:205], v154 offset:53248
	ds_read_b128 v[206:209], v154 offset:54272
	ds_read_b128 v[210:213], v154 offset:55296
	ds_read_b128 v[214:217], v154 offset:56320
	global_load_lds_dwordx4 v[218:219], off
	v_lshl_add_u64 v[218:219], v[220:221], 0, s[6:7]
	s_mov_b32 m0, s46
	s_addc_u32 s23, s23, 0
	global_load_lds_dwordx4 v[218:219], off
	v_lshl_add_u64 v[218:219], s[22:23], 0, v[134:135]
	s_mov_b32 m0, s49
	s_nop 0
	global_load_lds_dwordx4 v[218:219], off
	v_lshl_add_u64 v[218:219], s[22:23], 0, v[130:131]
	s_mov_b32 m0, s52
	s_nop 0
	global_load_lds_dwordx4 v[218:219], off
	v_lshl_add_u64 v[218:219], v[222:223], 0, s[6:7]
	s_mov_b32 m0, s47
	s_nop 0
	global_load_lds_dwordx4 v[218:219], off
	v_lshl_add_u64 v[218:219], v[224:225], 0, s[6:7]
	s_mov_b32 m0, s48
	s_nop 0
	global_load_lds_dwordx4 v[218:219], off
	s_waitcnt vmcnt(8)
	s_waitcnt lgkmcnt(0)
	s_barrier
	s_setprio 1
	s_waitcnt lgkmcnt(0)
	v_mfma_f32_16x16x32_bf16 v[62:65], v[146:149], v[186:189], v[62:65]
	v_mfma_f32_16x16x32_bf16 v[54:57], v[162:165], v[186:189], v[54:57]
	v_mfma_f32_16x16x32_bf16 v[46:49], v[146:149], v[194:197], v[46:49]
	v_mfma_f32_16x16x32_bf16 v[38:41], v[162:165], v[194:197], v[38:41]
	v_mfma_f32_16x16x32_bf16 v[30:33], v[146:149], v[202:205], v[30:33]
	v_mfma_f32_16x16x32_bf16 v[22:25], v[162:165], v[202:205], v[22:25]
	v_mfma_f32_16x16x32_bf16 v[14:17], v[146:149], v[210:213], v[14:17]
	v_mfma_f32_16x16x32_bf16 v[6:9], v[162:165], v[210:213], v[6:9]
	v_mfma_f32_16x16x32_bf16 v[62:65], v[158:161], v[190:193], v[62:65]
	v_mfma_f32_16x16x32_bf16 v[54:57], v[166:169], v[190:193], v[54:57]
	v_mfma_f32_16x16x32_bf16 v[46:49], v[158:161], v[198:201], v[46:49]
	v_mfma_f32_16x16x32_bf16 v[38:41], v[166:169], v[198:201], v[38:41]
	v_mfma_f32_16x16x32_bf16 v[30:33], v[158:161], v[206:209], v[30:33]
	v_mfma_f32_16x16x32_bf16 v[22:25], v[166:169], v[206:209], v[22:25]
	v_mfma_f32_16x16x32_bf16 v[14:17], v[158:161], v[214:217], v[14:17]
	v_mfma_f32_16x16x32_bf16 v[6:9], v[166:169], v[214:217], v[6:9]
	s_setprio 0
	s_setprio 1
	v_mfma_f32_16x16x32_bf16 v[58:61], v[170:173], v[186:189], v[58:61]
	v_mfma_f32_16x16x32_bf16 v[50:53], v[178:181], v[186:189], v[50:53]
	v_mfma_f32_16x16x32_bf16 v[42:45], v[170:173], v[194:197], v[42:45]
	v_mfma_f32_16x16x32_bf16 v[34:37], v[178:181], v[194:197], v[34:37]
	v_mfma_f32_16x16x32_bf16 v[26:29], v[170:173], v[202:205], v[26:29]
	v_mfma_f32_16x16x32_bf16 v[18:21], v[178:181], v[202:205], v[18:21]
	v_mfma_f32_16x16x32_bf16 v[10:13], v[170:173], v[210:213], v[10:13]
	v_mfma_f32_16x16x32_bf16 v[2:5], v[178:181], v[210:213], v[2:5]
	v_mfma_f32_16x16x32_bf16 v[58:61], v[174:177], v[190:193], v[58:61]
	v_mfma_f32_16x16x32_bf16 v[50:53], v[182:185], v[190:193], v[50:53]
	v_mfma_f32_16x16x32_bf16 v[42:45], v[174:177], v[198:201], v[42:45]
	v_mfma_f32_16x16x32_bf16 v[34:37], v[182:185], v[198:201], v[34:37]
	v_mfma_f32_16x16x32_bf16 v[26:29], v[174:177], v[206:209], v[26:29]
	v_mfma_f32_16x16x32_bf16 v[18:21], v[182:185], v[206:209], v[18:21]
	v_mfma_f32_16x16x32_bf16 v[10:13], v[174:177], v[214:217], v[10:13]
	v_mfma_f32_16x16x32_bf16 v[2:5], v[182:185], v[214:217], v[2:5]
	s_setprio 0
	s_add_i32 s58, s58, 2
	s_add_u32 s54, s54, 0x100
	s_addc_u32 s55, s55, 0
	s_add_u32 s20, s20, 0x100
	s_addc_u32 s21, s21, 0
	s_cmp_gt_u32 s58, 13
	s_barrier
	s_cbranch_scc0 .LBB0_2285
	s_and_b64 vcc, exec, s[8:9]
	s_cbranch_vccz .LBB0_2288
	s_barrier

; #define PG8_STAGE(bufoff, gbase, voff) do { _Pragma("unroll") for (int _i = 0; _i < 2; ++_i) \
;         __builtin_amdgcn_global_load_lds((const unsigned*)((const char*)(gbase) + (voff)[_i]), (PG8_LAS unsigned*)(lds + (bufoff) + ldsw + _i * 8192), 16, 0, 0); } while (0)
; #define PG8_LDA(dst, b, h) do { _Pragma("unroll") for (int m = 0; m < 4; ++m) _Pragma("unroll") for (int k = 0; k < 2; ++k) dst[m][k] = *(const PG8_LAS bf16x8*)(lds + PG8_SA(b, h) + aoff + m * 2048 + k * 1024); } while (0)
; #define PG8_LDB(dst, b, h) do { _Pragma("unroll") for (int n = 0; n < 2; ++n) _Pragma("unroll") for (int k = 0; k < 2; ++k) dst[n][k] = *(const PG8_LAS bf16x8*)(lds + PG8_SB(b, h) + boff + n * 2048 + k * 1024); } while (0)
; #define PG8_WAIT_V(n) asm volatile("s_waitcnt vmcnt(" #n ")" ::: "memory")
; #define PG8_WAIT_L(n) asm volatile("s_waitcnt lgkmcnt(" #n ")" ::: "memory")
; #define PG8_BAR __builtin_amdgcn_s_barrier()
; #define PG8_SCHED __builtin_amdgcn_sched_barrier(0)
; template <class Epi, class Sched, bool ALIGN_EPI = false, bool SP2 = false>
; __device__ __forceinline__ void gemm_phase(PG8_LAS unsigned char* lds, const Gemm g, const Sched& S, const Epi& E) {
;     ...
;         const bool has_next = S.next(ui + 1, nxt);
;         const char* nA = has_next ? (const char*)g.A + (size_t)nxt.pm * tstep + (size_t)nxt.ks * K * 2 : cA; const char* nB = has_next ? (const char*)g.Bt + (size_t)nxt.pn * tstep + (size_t)nxt.ks * K * 2 : cB;
;         for (int t = 0; t < nt; t += 2) {
;             const bool last = (t == nt - 2);
;             const char* a1 = cA + (size_t)(t + 1) * kstep;
;             const char* a2 = last ? nA : cA + (size_t)(t + 2) * kstep; const char* b2 = last ? nB : cB + (size_t)(t + 2) * kstep;
;             const char* a3 = a2 + kstep; const char* b3 = b2 + kstep;
;             if (last && has_next) S.a_ready(nxt);
;             if constexpr (SP2) {
;             PG8_LDB(B0, 0, 0); PG8_LDB(B1, 0, 1); PG8_SCHED; PG8_LDA(At, 0, 0); PG8_STAGE(PG8_SA(1, 1), a1 + hstep, voffA);
;             PG8_WAIT_V(8); PG8_WAIT_L(0); PG8_BAR; PG8_MMA(0, 0, At, B0); PG8_MMA(0, 1, At, B1); PG8_BAR; PG8_SCHED;
;             PG8_LDA(At, 0, 1); PG8_STAGE(PG8_SB(0, 0), b2, voffB); PG8_STAGE(PG8_SB(0, 1), b2 + hstep, voffB); PG8_STAGE(PG8_SA(0, 0), a2, voffA);
;             PG8_WAIT_V(8); PG8_WAIT_L(0); PG8_BAR; PG8_MMA(1, 0, At, B0); PG8_MMA(1, 1, At, B1); PG8_BAR; PG8_SCHED;
.LBB0_2366:
	s_add_u32 s64, s24, 0x100
	s_addc_u32 s65, s25, 0
	s_mov_b32 s66, -2
	ds_read_b128 v[154:157], v148
	ds_read_b128 v[158:161], v148 offset:1024
	ds_read_b128 v[162:165], v148 offset:2048
	ds_read_b128 v[166:169], v148 offset:3072
	ds_read_b128 v[170:173], v149
	ds_read_b128 v[174:177], v149 offset:1024
	ds_read_b128 v[178:181], v149 offset:2048
	ds_read_b128 v[182:185], v149 offset:3072
	s_add_u32 s24, s22, 0x100
	s_addc_u32 s25, s23, 0
	s_cmp_eq_u32 s66, 40
	s_cselect_b32 s39, s5, s25
	s_cselect_b32 s38, s4, s24
	s_cselect_b32 s37, s21, s65
	s_cselect_b32 s36, s20, s64
	v_lshl_add_u64 v[218:219], s[22:23], 0, v[140:141]
	s_add_i32 m0, s44, 0xc000
	ds_read_b128 v[186:189], v150
	ds_read_b128 v[190:193], v150 offset:1024
	ds_read_b128 v[194:197], v150 offset:2048
	ds_read_b128 v[198:201], v150 offset:3072
	ds_read_b128 v[202:205], v150 offset:4096
	ds_read_b128 v[206:209], v150 offset:5120
	ds_read_b128 v[210:213], v150 offset:6144
	ds_read_b128 v[214:217], v150 offset:7168
	global_load_lds_dwordx4 v[218:219], off
	v_lshl_add_u64 v[218:219], s[22:23], 0, v[138:139]
	s_add_i32 m0, s44, 0xe000
	s_nop 0
	global_load_lds_dwordx4 v[218:219], off
	s_waitcnt vmcnt(8)
	s_waitcnt lgkmcnt(0)
	s_barrier
	s_setprio 1
	s_waitcnt lgkmcnt(0)
	v_mfma_f32_16x16x32_bf16 v[126:129], v[154:157], v[186:189], 0
	v_mfma_f32_16x16x32_bf16 v[122:125], v[162:165], v[186:189], 0
	v_mfma_f32_16x16x32_bf16 v[118:121], v[154:157], v[194:197], 0
	v_mfma_f32_16x16x32_bf16 v[114:117], v[162:165], v[194:197], 0
	v_mfma_f32_16x16x32_bf16 v[102:105], v[154:157], v[202:205], 0
	v_mfma_f32_16x16x32_bf16 v[98:101], v[162:165], v[202:205], 0
	v_mfma_f32_16x16x32_bf16 v[86:89], v[154:157], v[210:213], 0
	v_mfma_f32_16x16x32_bf16 v[82:85], v[162:165], v[210:213], 0
	v_mfma_f32_16x16x32_bf16 v[126:129], v[158:161], v[190:193], v[126:129]
	v_mfma_f32_16x16x32_bf16 v[122:125], v[166:169], v[190:193], v[122:125]
	v_mfma_f32_16x16x32_bf16 v[118:121], v[158:161], v[198:201], v[118:121]
	v_mfma_f32_16x16x32_bf16 v[114:117], v[166:169], v[198:201], v[114:117]
	v_mfma_f32_16x16x32_bf16 v[102:105], v[158:161], v[206:209], v[102:105]
	v_mfma_f32_16x16x32_bf16 v[98:101], v[166:169], v[206:209], v[98:101]
	v_mfma_f32_16x16x32_bf16 v[86:89], v[158:161], v[214:217], v[86:89]
	v_mfma_f32_16x16x32_bf16 v[82:85], v[166:169], v[214:217], v[82:85]
	s_setprio 0
	s_setprio 1
	v_mfma_f32_16x16x32_bf16 v[110:113], v[170:173], v[186:189], 0
	v_mfma_f32_16x16x32_bf16 v[106:109], v[178:181], v[186:189], 0
	v_mfma_f32_16x16x32_bf16 v[94:97], v[170:173], v[194:197], 0
	v_mfma_f32_16x16x32_bf16 v[90:93], v[178:181], v[194:197], 0
	v_mfma_f32_16x16x32_bf16 v[78:81], v[170:173], v[202:205], 0
	v_mfma_f32_16x16x32_bf16 v[74:77], v[178:181], v[202:205], 0
	v_mfma_f32_16x16x32_bf16 v[70:73], v[170:173], v[210:213], 0
	v_mfma_f32_16x16x32_bf16 v[66:69], v[178:181], v[210:213], 0
	v_mfma_f32_16x16x32_bf16 v[110:113], v[174:177], v[190:193], v[110:113]
	v_mfma_f32_16x16x32_bf16 v[106:109], v[182:185], v[190:193], v[106:109]
	v_mfma_f32_16x16x32_bf16 v[94:97], v[174:177], v[198:201], v[94:97]
	v_mfma_f32_16x16x32_bf16 v[90:93], v[182:185], v[198:201], v[90:93]
	v_mfma_f32_16x16x32_bf16 v[78:81], v[174:177], v[206:209], v[78:81]
	v_mfma_f32_16x16x32_bf16 v[74:77], v[182:185], v[206:209], v[74:77]
	v_mfma_f32_16x16x32_bf16 v[70:73], v[174:177], v[214:217], v[70:73]
	v_mfma_f32_16x16x32_bf16 v[66:69], v[182:185], v[214:217], v[66:69]
	s_setprio 0
	s_barrier
	s_mov_b32 m0, s40
	v_lshl_add_u64 v[218:219], s[36:37], 0, v[132:133]
	s_add_u32 s22, s36, 0xb0000
	ds_read_b128 v[186:189], v150 offset:16384
	ds_read_b128 v[190:193], v150 offset:17408
	ds_read_b128 v[194:197], v150 offset:18432
	ds_read_b128 v[198:201], v150 offset:19456
	ds_read_b128 v[202:205], v150 offset:20480
	ds_read_b128 v[206:209], v150 offset:21504
	ds_read_b128 v[210:213], v150 offset:22528
	ds_read_b128 v[214:217], v150 offset:23552
	global_load_lds_dwordx4 v[218:219], off
	v_lshl_add_u64 v[220:221], s[36:37], 0, v[136:137]
	s_mov_b32 m0, s41
	s_addc_u32 s23, s37, 0
	global_load_lds_dwordx4 v[220:221], off
	v_lshl_add_u64 v[222:223], s[22:23], 0, v[132:133]
	s_mov_b32 m0, s42
	v_lshl_add_u64 v[224:225], s[38:39], 0, v[134:135]
	global_load_lds_dwordx4 v[222:223], off
	v_lshl_add_u64 v[222:223], s[22:23], 0, v[136:137]
	s_mov_b32 m0, s43
	s_nop 0
	global_load_lds_dwordx4 v[222:223], off
	v_lshl_add_u64 v[222:223], s[38:39], 0, v[130:131]
	s_mov_b32 m0, s44
	s_nop 0
	global_load_lds_dwordx4 v[222:223], off
	s_mov_b32 m0, s45
	s_nop 0
	global_load_lds_dwordx4 v[224:225], off
	s_waitcnt vmcnt(8)
	s_waitcnt lgkmcnt(0)
	s_barrier
; #define PG8_STAGE(bufoff, gbase, voff) do { _Pragma("unroll") for (int _i = 0; _i < 2; ++_i) \
;         __builtin_amdgcn_global_load_lds((const unsigned*)((const char*)(gbase) + (voff)[_i]), (PG8_LAS unsigned*)(lds + (bufoff) + ldsw + _i * 8192), 16, 0, 0); } while (0)
; #define PG8_LDA(dst, b, h) do { _Pragma("unroll") for (int m = 0; m < 4; ++m) _Pragma("unroll") for (int k = 0; k < 2; ++k) dst[m][k] = *(const PG8_LAS bf16x8*)(lds + PG8_SA(b, h) + aoff + m * 2048 + k * 1024); } while (0)
; #define PG8_LDB(dst, b, h) do { _Pragma("unroll") for (int n = 0; n < 2; ++n) _Pragma("unroll") for (int k = 0; k < 2; ++k) dst[n][k] = *(const PG8_LAS bf16x8*)(lds + PG8_SB(b, h) + boff + n * 2048 + k * 1024); } while (0)
; #define PG8_MMA(ai, bj, At, Bt) do { __builtin_amdgcn_s_setprio(1); _Pragma("unroll") for (int m = 0; m < 4; ++m) _Pragma("unroll") for (int n = 0; n < 2; ++n) _Pragma("unroll") for (int k = 0; k < 2; ++k) \
;         acc[ai][bj][m][n] = __builtin_amdgcn_mfma_f32_16x16x32_bf16(Bt[n][k], At[m][k], acc[ai][bj][m][n], 0, 0, 0); __builtin_amdgcn_s_setprio(0); } while (0)
; #define PG8_WAIT_V(n) asm volatile("s_waitcnt vmcnt(" #n ")" ::: "memory")
; #define PG8_WAIT_L(n) asm volatile("s_waitcnt lgkmcnt(" #n ")" ::: "memory")
; #define PG8_BAR __builtin_amdgcn_s_barrier()
; #define PG8_SCHED __builtin_amdgcn_sched_barrier(0)
; template <class Epi, class Sched, bool ALIGN_EPI = false, bool SP2 = false>
; __device__ __forceinline__ void gemm_phase(PG8_LAS unsigned char* lds, const Gemm g, const Sched& S, const Epi& E) {
;     ...
;             PG8_WAIT_V(8); PG8_WAIT_L(0); PG8_BAR; PG8_MMA(0, 0, At, B0); PG8_MMA(0, 1, At, B1); PG8_BAR; PG8_SCHED;
;             PG8_LDA(At, 0, 1); PG8_STAGE(PG8_SB(0, 0), b2, voffB); PG8_STAGE(PG8_SB(0, 1), b2 + hstep, voffB); PG8_STAGE(PG8_SA(0, 0), a2, voffA);
;             PG8_WAIT_V(8); PG8_WAIT_L(0); PG8_BAR; PG8_MMA(1, 0, At, B0); PG8_MMA(1, 1, At, B1); PG8_BAR; PG8_SCHED;
;             PG8_LDB(B0, 1, 0); PG8_LDB(B1, 1, 1); PG8_SCHED; PG8_LDA(At, 1, 0); PG8_STAGE(PG8_SA(0, 1), a2 + hstep, voffA);
;             PG8_WAIT_V(8); PG8_WAIT_L(0); PG8_BAR; PG8_MMA(0, 0, At, B0); PG8_MMA(0, 1, At, B1); PG8_BAR; PG8_SCHED;
	s_setprio 1
	s_waitcnt lgkmcnt(0)
	v_mfma_f32_16x16x32_bf16 v[62:65], v[154:157], v[186:189], 0
	v_mfma_f32_16x16x32_bf16 v[58:61], v[162:165], v[186:189], 0
	v_mfma_f32_16x16x32_bf16 v[54:57], v[154:157], v[194:197], 0
	v_mfma_f32_16x16x32_bf16 v[50:53], v[162:165], v[194:197], 0
	v_mfma_f32_16x16x32_bf16 v[38:41], v[154:157], v[202:205], 0
	v_mfma_f32_16x16x32_bf16 v[34:37], v[162:165], v[202:205], 0
	v_mfma_f32_16x16x32_bf16 v[22:25], v[154:157], v[210:213], 0
	v_mfma_f32_16x16x32_bf16 v[18:21], v[162:165], v[210:213], 0
	v_mfma_f32_16x16x32_bf16 v[62:65], v[158:161], v[190:193], v[62:65]
	v_mfma_f32_16x16x32_bf16 v[58:61], v[166:169], v[190:193], v[58:61]
	v_mfma_f32_16x16x32_bf16 v[54:57], v[158:161], v[198:201], v[54:57]
	v_mfma_f32_16x16x32_bf16 v[50:53], v[166:169], v[198:201], v[50:53]
	v_mfma_f32_16x16x32_bf16 v[38:41], v[158:161], v[206:209], v[38:41]
	v_mfma_f32_16x16x32_bf16 v[34:37], v[166:169], v[206:209], v[34:37]
	v_mfma_f32_16x16x32_bf16 v[22:25], v[158:161], v[214:217], v[22:25]
	v_mfma_f32_16x16x32_bf16 v[18:21], v[166:169], v[214:217], v[18:21]
	s_setprio 0
	s_setprio 1
	v_mfma_f32_16x16x32_bf16 v[46:49], v[170:173], v[186:189], 0
	v_mfma_f32_16x16x32_bf16 v[42:45], v[178:181], v[186:189], 0
	v_mfma_f32_16x16x32_bf16 v[30:33], v[170:173], v[194:197], 0
	v_mfma_f32_16x16x32_bf16 v[26:29], v[178:181], v[194:197], 0
	v_mfma_f32_16x16x32_bf16 v[14:17], v[170:173], v[202:205], 0
	v_mfma_f32_16x16x32_bf16 v[10:13], v[178:181], v[202:205], 0
	v_mfma_f32_16x16x32_bf16 v[6:9], v[170:173], v[210:213], 0
	v_mfma_f32_16x16x32_bf16 v[2:5], v[178:181], v[210:213], 0
	v_mfma_f32_16x16x32_bf16 v[46:49], v[174:177], v[190:193], v[46:49]
	v_mfma_f32_16x16x32_bf16 v[42:45], v[182:185], v[190:193], v[42:45]
	v_mfma_f32_16x16x32_bf16 v[30:33], v[174:177], v[198:201], v[30:33]
	v_mfma_f32_16x16x32_bf16 v[26:29], v[182:185], v[198:201], v[26:29]
	v_mfma_f32_16x16x32_bf16 v[14:17], v[174:177], v[206:209], v[14:17]
	v_mfma_f32_16x16x32_bf16 v[10:13], v[182:185], v[206:209], v[10:13]
	v_mfma_f32_16x16x32_bf16 v[6:9], v[174:177], v[214:217], v[6:9]
	v_mfma_f32_16x16x32_bf16 v[2:5], v[182:185], v[214:217], v[2:5]
	s_setprio 0
	s_barrier
	ds_read_b128 v[154:157], v151
	ds_read_b128 v[158:161], v151 offset:1024
	ds_read_b128 v[162:165], v151 offset:2048
	ds_read_b128 v[166:169], v151 offset:3072
	ds_read_b128 v[170:173], v152
	ds_read_b128 v[174:177], v152 offset:1024
	ds_read_b128 v[178:181], v152 offset:2048
	ds_read_b128 v[182:185], v152 offset:3072
	s_add_u32 s22, s38, 0xb0000
	s_addc_u32 s23, s39, 0
	s_mov_b32 m0, s46
	v_lshl_add_u64 v[226:227], s[22:23], 0, v[130:131]
	ds_read_b128 v[186:189], v150 offset:32768
	ds_read_b128 v[190:193], v150 offset:33792
	ds_read_b128 v[194:197], v150 offset:34816
	ds_read_b128 v[198:201], v150 offset:35840
	ds_read_b128 v[202:205], v150 offset:36864
	ds_read_b128 v[206:209], v150 offset:37888
	ds_read_b128 v[210:213], v150 offset:38912
	ds_read_b128 v[214:217], v150 offset:39936
	global_load_lds_dwordx4 v[226:227], off
	v_lshl_add_u64 v[226:227], s[22:23], 0, v[134:135]
	s_mov_b32 m0, s47
	s_nop 0
	global_load_lds_dwordx4 v[226:227], off
	s_waitcnt vmcnt(8)
	s_waitcnt lgkmcnt(0)
	s_barrier
	s_setprio 1
	s_waitcnt lgkmcnt(0)
	v_mfma_f32_16x16x32_bf16 v[126:129], v[154:157], v[186:189], v[126:129]
	v_mfma_f32_16x16x32_bf16 v[122:125], v[162:165], v[186:189], v[122:125]
	v_mfma_f32_16x16x32_bf16 v[118:121], v[154:157], v[194:197], v[118:121]
	v_mfma_f32_16x16x32_bf16 v[114:117], v[162:165], v[194:197], v[114:117]
	v_mfma_f32_16x16x32_bf16 v[102:105], v[154:157], v[202:205], v[102:105]
	v_mfma_f32_16x16x32_bf16 v[98:101], v[162:165], v[202:205], v[98:101]
	v_mfma_f32_16x16x32_bf16 v[86:89], v[154:157], v[210:213], v[86:89]
	v_mfma_f32_16x16x32_bf16 v[82:85], v[162:165], v[210:213], v[82:85]
	v_mfma_f32_16x16x32_bf16 v[126:129], v[158:161], v[190:193], v[126:129]
	v_mfma_f32_16x16x32_bf16 v[122:125], v[166:169], v[190:193], v[122:125]
	v_mfma_f32_16x16x32_bf16 v[118:121], v[158:161], v[198:201], v[118:121]
	v_mfma_f32_16x16x32_bf16 v[114:117], v[166:169], v[198:201], v[114:117]
	v_mfma_f32_16x16x32_bf16 v[102:105], v[158:161], v[206:209], v[102:105]
	v_mfma_f32_16x16x32_bf16 v[98:101], v[166:169], v[206:209], v[98:101]
	v_mfma_f32_16x16x32_bf16 v[86:89], v[158:161], v[214:217], v[86:89]
	v_mfma_f32_16x16x32_bf16 v[82:85], v[166:169], v[214:217], v[82:85]
	s_setprio 0
	s_setprio 1
	v_mfma_f32_16x16x32_bf16 v[110:113], v[170:173], v[186:189], v[110:113]
	v_mfma_f32_16x16x32_bf16 v[106:109], v[178:181], v[186:189], v[106:109]
	v_mfma_f32_16x16x32_bf16 v[94:97], v[170:173], v[194:197], v[94:97]
	v_mfma_f32_16x16x32_bf16 v[90:93], v[178:181], v[194:197], v[90:93]
	v_mfma_f32_16x16x32_bf16 v[78:81], v[170:173], v[202:205], v[78:81]
	v_mfma_f32_16x16x32_bf16 v[74:77], v[178:181], v[202:205], v[74:77]
	v_mfma_f32_16x16x32_bf16 v[70:73], v[170:173], v[210:213], v[70:73]
	v_mfma_f32_16x16x32_bf16 v[66:69], v[178:181], v[210:213], v[66:69]
	v_mfma_f32_16x16x32_bf16 v[110:113], v[174:177], v[190:193], v[110:113]
	v_mfma_f32_16x16x32_bf16 v[106:109], v[182:185], v[190:193], v[106:109]
	v_mfma_f32_16x16x32_bf16 v[94:97], v[174:177], v[198:201], v[94:97]
	v_mfma_f32_16x16x32_bf16 v[90:93], v[182:185], v[198:201], v[90:93]
	v_mfma_f32_16x16x32_bf16 v[78:81], v[174:177], v[206:209], v[78:81]
	v_mfma_f32_16x16x32_bf16 v[74:77], v[182:185], v[206:209], v[74:77]
	v_mfma_f32_16x16x32_bf16 v[70:73], v[174:177], v[214:217], v[70:73]
	v_mfma_f32_16x16x32_bf16 v[66:69], v[182:185], v[214:217], v[66:69]
	s_setprio 0
	s_barrier
; #define PG8_STAGE(bufoff, gbase, voff) do { _Pragma("unroll") for (int _i = 0; _i < 2; ++_i) \
;         __builtin_amdgcn_global_load_lds((const unsigned*)((const char*)(gbase) + (voff)[_i]), (PG8_LAS unsigned*)(lds + (bufoff) + ldsw + _i * 8192), 16, 0, 0); } while (0)
; #define PG8_LDA(dst, b, h) do { _Pragma("unroll") for (int m = 0; m < 4; ++m) _Pragma("unroll") for (int k = 0; k < 2; ++k) dst[m][k] = *(const PG8_LAS bf16x8*)(lds + PG8_SA(b, h) + aoff + m * 2048 + k * 1024); } while (0)
; #define PG8_LDB(dst, b, h) do { _Pragma("unroll") for (int n = 0; n < 2; ++n) _Pragma("unroll") for (int k = 0; k < 2; ++k) dst[n][k] = *(const PG8_LAS bf16x8*)(lds + PG8_SB(b, h) + boff + n * 2048 + k * 1024); } while (0)
; template <class Epi, class Sched, bool ALIGN_EPI = false, bool SP2 = false>
; __device__ __forceinline__ void gemm_phase(PG8_LAS unsigned char* lds, const Gemm g, const Sched& S, const Epi& E) {
;     ...
;         for (int t = 0; t < nt; t += 2) {
;             const bool last = (t == nt - 2);
;             const char* a1 = cA + (size_t)(t + 1) * kstep;
;             const char* a2 = last ? nA : cA + (size_t)(t + 2) * kstep; const char* b2 = last ? nB : cB + (size_t)(t + 2) * kstep;
;             const char* a3 = a2 + kstep; const char* b3 = b2 + kstep;
;             if (last && has_next) S.a_ready(nxt);
;             if constexpr (SP2) {
;             PG8_LDB(B0, 0, 0); PG8_LDB(B1, 0, 1); PG8_SCHED; PG8_LDA(At, 0, 0); PG8_STAGE(PG8_SA(1, 1), a1 + hstep, voffA);
;             PG8_WAIT_V(8); PG8_WAIT_L(0); PG8_BAR; PG8_MMA(0, 0, At, B0); PG8_MMA(0, 1, At, B1); PG8_BAR; PG8_SCHED;
;             PG8_LDA(At, 0, 1); PG8_STAGE(PG8_SB(0, 0), b2, voffB); PG8_STAGE(PG8_SB(0, 1), b2 + hstep, voffB); PG8_STAGE(PG8_SA(0, 0), a2, voffA);
;             PG8_WAIT_V(8); PG8_WAIT_L(0); PG8_BAR; PG8_MMA(1, 0, At, B0); PG8_MMA(1, 1, At, B1); PG8_BAR; PG8_SCHED;
;             PG8_LDB(B0, 1, 0); PG8_LDB(B1, 1, 1); PG8_SCHED; PG8_LDA(At, 1, 0); PG8_STAGE(PG8_SA(0, 1), a2 + hstep, voffA);
;             PG8_WAIT_V(8); PG8_WAIT_L(0); PG8_BAR; PG8_MMA(0, 0, At, B0); PG8_MMA(0, 1, At, B1); PG8_BAR; PG8_SCHED;
;             PG8_LDA(At, 1, 1); PG8_STAGE(PG8_SB(1, 0), b3, voffB); PG8_STAGE(PG8_SB(1, 1), b3 + hstep, voffB); PG8_STAGE(PG8_SA(1, 0), a3, voffA);
;             PG8_WAIT_V(8); PG8_WAIT_L(0); PG8_BAR; PG8_MMA(1, 0, At, B0); PG8_MMA(1, 1, At, B1); PG8_BAR; PG8_SCHED;
	s_mov_b32 m0, s49
	v_lshl_add_u64 v[218:219], v[218:219], 0, s[8:9]
	s_add_u32 s22, s36, 0xb0080
	ds_read_b128 v[186:189], v150 offset:49152
	ds_read_b128 v[190:193], v150 offset:50176
	ds_read_b128 v[194:197], v150 offset:51200
	ds_read_b128 v[198:201], v150 offset:52224
	ds_read_b128 v[202:205], v150 offset:53248
	ds_read_b128 v[206:209], v150 offset:54272
	ds_read_b128 v[210:213], v150 offset:55296
	ds_read_b128 v[214:217], v150 offset:56320
	global_load_lds_dwordx4 v[218:219], off
	v_lshl_add_u64 v[218:219], v[220:221], 0, s[8:9]
	s_mov_b32 m0, s50
	s_addc_u32 s23, s37, 0
	global_load_lds_dwordx4 v[218:219], off
	v_lshl_add_u64 v[218:219], s[22:23], 0, v[132:133]
	s_mov_b32 m0, s53
	s_nop 0
	global_load_lds_dwordx4 v[218:219], off
	v_lshl_add_u64 v[218:219], s[22:23], 0, v[136:137]
	s_mov_b32 m0, s54
	s_nop 0
	global_load_lds_dwordx4 v[218:219], off
	v_lshl_add_u64 v[218:219], v[222:223], 0, s[8:9]
	s_mov_b32 m0, s51
	s_nop 0
	global_load_lds_dwordx4 v[218:219], off
	v_lshl_add_u64 v[218:219], v[224:225], 0, s[8:9]
	s_mov_b32 m0, s52
	s_nop 0
	global_load_lds_dwordx4 v[218:219], off
	s_waitcnt vmcnt(8)
	s_waitcnt lgkmcnt(0)
	s_barrier
	s_setprio 1
	s_waitcnt lgkmcnt(0)
	v_mfma_f32_16x16x32_bf16 v[62:65], v[154:157], v[186:189], v[62:65]
	v_mfma_f32_16x16x32_bf16 v[58:61], v[162:165], v[186:189], v[58:61]
	v_mfma_f32_16x16x32_bf16 v[54:57], v[154:157], v[194:197], v[54:57]
	v_mfma_f32_16x16x32_bf16 v[50:53], v[162:165], v[194:197], v[50:53]
	v_mfma_f32_16x16x32_bf16 v[38:41], v[154:157], v[202:205], v[38:41]
	v_mfma_f32_16x16x32_bf16 v[34:37], v[162:165], v[202:205], v[34:37]
	v_mfma_f32_16x16x32_bf16 v[22:25], v[154:157], v[210:213], v[22:25]
	v_mfma_f32_16x16x32_bf16 v[18:21], v[162:165], v[210:213], v[18:21]
	v_mfma_f32_16x16x32_bf16 v[62:65], v[158:161], v[190:193], v[62:65]
	v_mfma_f32_16x16x32_bf16 v[58:61], v[166:169], v[190:193], v[58:61]
	v_mfma_f32_16x16x32_bf16 v[54:57], v[158:161], v[198:201], v[54:57]
	v_mfma_f32_16x16x32_bf16 v[50:53], v[166:169], v[198:201], v[50:53]
	v_mfma_f32_16x16x32_bf16 v[38:41], v[158:161], v[206:209], v[38:41]
	v_mfma_f32_16x16x32_bf16 v[34:37], v[166:169], v[206:209], v[34:37]
	v_mfma_f32_16x16x32_bf16 v[22:25], v[158:161], v[214:217], v[22:25]
	v_mfma_f32_16x16x32_bf16 v[18:21], v[166:169], v[214:217], v[18:21]
	s_setprio 0
	s_setprio 1
	v_mfma_f32_16x16x32_bf16 v[46:49], v[170:173], v[186:189], v[46:49]
	v_mfma_f32_16x16x32_bf16 v[42:45], v[178:181], v[186:189], v[42:45]
	v_mfma_f32_16x16x32_bf16 v[30:33], v[170:173], v[194:197], v[30:33]
	v_mfma_f32_16x16x32_bf16 v[26:29], v[178:181], v[194:197], v[26:29]
	v_mfma_f32_16x16x32_bf16 v[14:17], v[170:173], v[202:205], v[14:17]
	v_mfma_f32_16x16x32_bf16 v[10:13], v[178:181], v[202:205], v[10:13]
	v_mfma_f32_16x16x32_bf16 v[6:9], v[170:173], v[210:213], v[6:9]
	v_mfma_f32_16x16x32_bf16 v[2:5], v[178:181], v[210:213], v[2:5]
	v_mfma_f32_16x16x32_bf16 v[46:49], v[174:177], v[190:193], v[46:49]
	v_mfma_f32_16x16x32_bf16 v[42:45], v[182:185], v[190:193], v[42:45]
	v_mfma_f32_16x16x32_bf16 v[30:33], v[174:177], v[198:201], v[30:33]
	v_mfma_f32_16x16x32_bf16 v[26:29], v[182:185], v[198:201], v[26:29]
	v_mfma_f32_16x16x32_bf16 v[14:17], v[174:177], v[206:209], v[14:17]
	v_mfma_f32_16x16x32_bf16 v[10:13], v[182:185], v[206:209], v[10:13]
	v_mfma_f32_16x16x32_bf16 v[6:9], v[174:177], v[214:217], v[6:9]
	v_mfma_f32_16x16x32_bf16 v[2:5], v[182:185], v[214:217], v[2:5]
	s_setprio 0
	s_add_i32 s66, s66, 2
	s_add_u32 s64, s64, 0x100
	s_addc_u32 s65, s65, 0
	s_cmp_gt_u32 s66, 41
	s_mov_b64 s[22:23], s[24:25]
	s_barrier
.LBB0_2367:
	ds_read_b128 v[154:157], v148
	ds_read_b128 v[158:161], v148 offset:1024
	ds_read_b128 v[162:165], v148 offset:2048
	ds_read_b128 v[166:169], v148 offset:3072
	ds_read_b128 v[170:173], v149
	ds_read_b128 v[174:177], v149 offset:1024
	ds_read_b128 v[178:181], v149 offset:2048
	ds_read_b128 v[182:185], v149 offset:3072
	s_add_u32 s24, s22, 0x100
	s_addc_u32 s25, s23, 0
	s_cmp_eq_u32 s66, 40
	s_cselect_b32 s39, s5, s25
	s_cselect_b32 s38, s4, s24
	s_cselect_b32 s37, s21, s65
	s_cselect_b32 s36, s20, s64
	v_lshl_add_u64 v[218:219], s[22:23], 0, v[140:141]
	s_add_i32 m0, s44, 0xc000
	ds_read_b128 v[186:189], v150
	ds_read_b128 v[190:193], v150 offset:1024
	ds_read_b128 v[194:197], v150 offset:2048
	ds_read_b128 v[198:201], v150 offset:3072
	ds_read_b128 v[202:205], v150 offset:4096
	ds_read_b128 v[206:209], v150 offset:5120
	ds_read_b128 v[210:213], v150 offset:6144
	ds_read_b128 v[214:217], v150 offset:7168
	global_load_lds_dwordx4 v[218:219], off
	v_lshl_add_u64 v[218:219], s[22:23], 0, v[138:139]
	s_add_i32 m0, s44, 0xe000
	s_nop 0
	global_load_lds_dwordx4 v[218:219], off
	s_waitcnt vmcnt(8)
	s_waitcnt lgkmcnt(0)
	s_barrier
; #define PG8_STAGE(bufoff, gbase, voff) do { _Pragma("unroll") for (int _i = 0; _i < 2; ++_i) \
;         __builtin_amdgcn_global_load_lds((const unsigned*)((const char*)(gbase) + (voff)[_i]), (PG8_LAS unsigned*)(lds + (bufoff) + ldsw + _i * 8192), 16, 0, 0); } while (0)
; #define PG8_LDA(dst, b, h) do { _Pragma("unroll") for (int m = 0; m < 4; ++m) _Pragma("unroll") for (int k = 0; k < 2; ++k) dst[m][k] = *(const PG8_LAS bf16x8*)(lds + PG8_SA(b, h) + aoff + m * 2048 + k * 1024); } while (0)
; #define PG8_MMA(ai, bj, At, Bt) do { __builtin_amdgcn_s_setprio(1); _Pragma("unroll") for (int m = 0; m < 4; ++m) _Pragma("unroll") for (int n = 0; n < 2; ++n) _Pragma("unroll") for (int k = 0; k < 2; ++k) \
;         acc[ai][bj][m][n] = __builtin_amdgcn_mfma_f32_16x16x32_bf16(Bt[n][k], At[m][k], acc[ai][bj][m][n], 0, 0, 0); __builtin_amdgcn_s_setprio(0); } while (0)
; #define PG8_WAIT_V(n) asm volatile("s_waitcnt vmcnt(" #n ")" ::: "memory")
; #define PG8_WAIT_L(n) asm volatile("s_waitcnt lgkmcnt(" #n ")" ::: "memory")
; #define PG8_BAR __builtin_amdgcn_s_barrier()
; #define PG8_SCHED __builtin_amdgcn_sched_barrier(0)
; template <class Epi, class Sched, bool ALIGN_EPI = false, bool SP2 = false>
; __device__ __forceinline__ void gemm_phase(PG8_LAS unsigned char* lds, const Gemm g, const Sched& S, const Epi& E) {
;     ...
;             PG8_WAIT_V(8); PG8_WAIT_L(0); PG8_BAR; PG8_MMA(0, 0, At, B0); PG8_MMA(0, 1, At, B1); PG8_BAR; PG8_SCHED;
;             PG8_LDA(At, 0, 1); PG8_STAGE(PG8_SB(0, 0), b2, voffB); PG8_STAGE(PG8_SB(0, 1), b2 + hstep, voffB); PG8_STAGE(PG8_SA(0, 0), a2, voffA);
;             PG8_WAIT_V(8); PG8_WAIT_L(0); PG8_BAR; PG8_MMA(1, 0, At, B0); PG8_MMA(1, 1, At, B1); PG8_BAR; PG8_SCHED;
	s_setprio 1
	s_waitcnt lgkmcnt(0)
	v_mfma_f32_16x16x32_bf16 v[126:129], v[154:157], v[186:189], v[126:129]
	v_mfma_f32_16x16x32_bf16 v[122:125], v[162:165], v[186:189], v[122:125]
	v_mfma_f32_16x16x32_bf16 v[118:121], v[154:157], v[194:197], v[118:121]
	v_mfma_f32_16x16x32_bf16 v[114:117], v[162:165], v[194:197], v[114:117]
	v_mfma_f32_16x16x32_bf16 v[102:105], v[154:157], v[202:205], v[102:105]
	v_mfma_f32_16x16x32_bf16 v[98:101], v[162:165], v[202:205], v[98:101]
	v_mfma_f32_16x16x32_bf16 v[86:89], v[154:157], v[210:213], v[86:89]
	v_mfma_f32_16x16x32_bf16 v[82:85], v[162:165], v[210:213], v[82:85]
	v_mfma_f32_16x16x32_bf16 v[126:129], v[158:161], v[190:193], v[126:129]
	v_mfma_f32_16x16x32_bf16 v[122:125], v[166:169], v[190:193], v[122:125]
	v_mfma_f32_16x16x32_bf16 v[118:121], v[158:161], v[198:201], v[118:121]
	v_mfma_f32_16x16x32_bf16 v[114:117], v[166:169], v[198:201], v[114:117]
	v_mfma_f32_16x16x32_bf16 v[102:105], v[158:161], v[206:209], v[102:105]
	v_mfma_f32_16x16x32_bf16 v[98:101], v[166:169], v[206:209], v[98:101]
	v_mfma_f32_16x16x32_bf16 v[86:89], v[158:161], v[214:217], v[86:89]
	v_mfma_f32_16x16x32_bf16 v[82:85], v[166:169], v[214:217], v[82:85]
	s_setprio 0
	s_setprio 1
	v_mfma_f32_16x16x32_bf16 v[110:113], v[170:173], v[186:189], v[110:113]
	v_mfma_f32_16x16x32_bf16 v[106:109], v[178:181], v[186:189], v[106:109]
	v_mfma_f32_16x16x32_bf16 v[94:97], v[170:173], v[194:197], v[94:97]
	v_mfma_f32_16x16x32_bf16 v[90:93], v[178:181], v[194:197], v[90:93]
	v_mfma_f32_16x16x32_bf16 v[78:81], v[170:173], v[202:205], v[78:81]
	v_mfma_f32_16x16x32_bf16 v[74:77], v[178:181], v[202:205], v[74:77]
	v_mfma_f32_16x16x32_bf16 v[70:73], v[170:173], v[210:213], v[70:73]
	v_mfma_f32_16x16x32_bf16 v[66:69], v[178:181], v[210:213], v[66:69]
	v_mfma_f32_16x16x32_bf16 v[110:113], v[174:177], v[190:193], v[110:113]
	v_mfma_f32_16x16x32_bf16 v[106:109], v[182:185], v[190:193], v[106:109]
	v_mfma_f32_16x16x32_bf16 v[94:97], v[174:177], v[198:201], v[94:97]
	v_mfma_f32_16x16x32_bf16 v[90:93], v[182:185], v[198:201], v[90:93]
	v_mfma_f32_16x16x32_bf16 v[78:81], v[174:177], v[206:209], v[78:81]
	v_mfma_f32_16x16x32_bf16 v[74:77], v[182:185], v[206:209], v[74:77]
	v_mfma_f32_16x16x32_bf16 v[70:73], v[174:177], v[214:217], v[70:73]
	v_mfma_f32_16x16x32_bf16 v[66:69], v[182:185], v[214:217], v[66:69]
	s_setprio 0
	s_barrier
	s_mov_b32 m0, s40
	v_lshl_add_u64 v[218:219], s[36:37], 0, v[132:133]
	s_add_u32 s22, s36, 0xb0000
	ds_read_b128 v[186:189], v150 offset:16384
	ds_read_b128 v[190:193], v150 offset:17408
	ds_read_b128 v[194:197], v150 offset:18432
	ds_read_b128 v[198:201], v150 offset:19456
	ds_read_b128 v[202:205], v150 offset:20480
	ds_read_b128 v[206:209], v150 offset:21504
	ds_read_b128 v[210:213], v150 offset:22528
	ds_read_b128 v[214:217], v150 offset:23552
	global_load_lds_dwordx4 v[218:219], off
	v_lshl_add_u64 v[220:221], s[36:37], 0, v[136:137]
	s_mov_b32 m0, s41
	s_addc_u32 s23, s37, 0
	global_load_lds_dwordx4 v[220:221], off
	v_lshl_add_u64 v[222:223], s[22:23], 0, v[132:133]
	s_mov_b32 m0, s42
	v_lshl_add_u64 v[224:225], s[38:39], 0, v[134:135]
	global_load_lds_dwordx4 v[222:223], off
	v_lshl_add_u64 v[222:223], s[22:23], 0, v[136:137]
	s_mov_b32 m0, s43
	s_nop 0
	global_load_lds_dwordx4 v[222:223], off
	v_lshl_add_u64 v[222:223], s[38:39], 0, v[130:131]
	s_mov_b32 m0, s44
	s_nop 0
	global_load_lds_dwordx4 v[222:223], off
	s_mov_b32 m0, s45
	s_nop 0
	global_load_lds_dwordx4 v[224:225], off
	s_waitcnt vmcnt(8)
	s_waitcnt lgkmcnt(0)
	s_barrier
	s_setprio 1
	s_waitcnt lgkmcnt(0)
	v_mfma_f32_16x16x32_bf16 v[62:65], v[154:157], v[186:189], v[62:65]
	v_mfma_f32_16x16x32_bf16 v[58:61], v[162:165], v[186:189], v[58:61]
	v_mfma_f32_16x16x32_bf16 v[54:57], v[154:157], v[194:197], v[54:57]
	v_mfma_f32_16x16x32_bf16 v[50:53], v[162:165], v[194:197], v[50:53]
	v_mfma_f32_16x16x32_bf16 v[38:41], v[154:157], v[202:205], v[38:41]
	v_mfma_f32_16x16x32_bf16 v[34:37], v[162:165], v[202:205], v[34:37]
	v_mfma_f32_16x16x32_bf16 v[22:25], v[154:157], v[210:213], v[22:25]
	v_mfma_f32_16x16x32_bf16 v[18:21], v[162:165], v[210:213], v[18:21]
	v_mfma_f32_16x16x32_bf16 v[62:65], v[158:161], v[190:193], v[62:65]
	v_mfma_f32_16x16x32_bf16 v[58:61], v[166:169], v[190:193], v[58:61]
	v_mfma_f32_16x16x32_bf16 v[54:57], v[158:161], v[198:201], v[54:57]
	v_mfma_f32_16x16x32_bf16 v[50:53], v[166:169], v[198:201], v[50:53]
	v_mfma_f32_16x16x32_bf16 v[38:41], v[158:161], v[206:209], v[38:41]
	v_mfma_f32_16x16x32_bf16 v[34:37], v[166:169], v[206:209], v[34:37]
	v_mfma_f32_16x16x32_bf16 v[22:25], v[158:161], v[214:217], v[22:25]
	v_mfma_f32_16x16x32_bf16 v[18:21], v[166:169], v[214:217], v[18:21]
	s_setprio 0
	s_setprio 1
	v_mfma_f32_16x16x32_bf16 v[46:49], v[170:173], v[186:189], v[46:49]
	v_mfma_f32_16x16x32_bf16 v[42:45], v[178:181], v[186:189], v[42:45]
	v_mfma_f32_16x16x32_bf16 v[30:33], v[170:173], v[194:197], v[30:33]
	v_mfma_f32_16x16x32_bf16 v[26:29], v[178:181], v[194:197], v[26:29]
	v_mfma_f32_16x16x32_bf16 v[14:17], v[170:173], v[202:205], v[14:17]
	v_mfma_f32_16x16x32_bf16 v[10:13], v[178:181], v[202:205], v[10:13]
	v_mfma_f32_16x16x32_bf16 v[6:9], v[170:173], v[210:213], v[6:9]
	v_mfma_f32_16x16x32_bf16 v[2:5], v[178:181], v[210:213], v[2:5]
	v_mfma_f32_16x16x32_bf16 v[46:49], v[174:177], v[190:193], v[46:49]
	v_mfma_f32_16x16x32_bf16 v[42:45], v[182:185], v[190:193], v[42:45]
	v_mfma_f32_16x16x32_bf16 v[30:33], v[174:177], v[198:201], v[30:33]
	v_mfma_f32_16x16x32_bf16 v[26:29], v[182:185], v[198:201], v[26:29]
	v_mfma_f32_16x16x32_bf16 v[14:17], v[174:177], v[206:209], v[14:17]
	v_mfma_f32_16x16x32_bf16 v[10:13], v[182:185], v[206:209], v[10:13]
	v_mfma_f32_16x16x32_bf16 v[6:9], v[174:177], v[214:217], v[6:9]
	v_mfma_f32_16x16x32_bf16 v[2:5], v[182:185], v[214:217], v[2:5]
	s_setprio 0
	s_barrier
; #define PG8_STAGE(bufoff, gbase, voff) do { _Pragma("unroll") for (int _i = 0; _i < 2; ++_i) \
;         __builtin_amdgcn_global_load_lds((const unsigned*)((const char*)(gbase) + (voff)[_i]), (PG8_LAS unsigned*)(lds + (bufoff) + ldsw + _i * 8192), 16, 0, 0); } while (0)
; #define PG8_LDA(dst, b, h) do { _Pragma("unroll") for (int m = 0; m < 4; ++m) _Pragma("unroll") for (int k = 0; k < 2; ++k) dst[m][k] = *(const PG8_LAS bf16x8*)(lds + PG8_SA(b, h) + aoff + m * 2048 + k * 1024); } while (0)
; #define PG8_LDB(dst, b, h) do { _Pragma("unroll") for (int n = 0; n < 2; ++n) _Pragma("unroll") for (int k = 0; k < 2; ++k) dst[n][k] = *(const PG8_LAS bf16x8*)(lds + PG8_SB(b, h) + boff + n * 2048 + k * 1024); } while (0)
; #define PG8_MMA(ai, bj, At, Bt) do { __builtin_amdgcn_s_setprio(1); _Pragma("unroll") for (int m = 0; m < 4; ++m) _Pragma("unroll") for (int n = 0; n < 2; ++n) _Pragma("unroll") for (int k = 0; k < 2; ++k) \
;         acc[ai][bj][m][n] = __builtin_amdgcn_mfma_f32_16x16x32_bf16(Bt[n][k], At[m][k], acc[ai][bj][m][n], 0, 0, 0); __builtin_amdgcn_s_setprio(0); } while (0)
; #define PG8_WAIT_V(n) asm volatile("s_waitcnt vmcnt(" #n ")" ::: "memory")
; #define PG8_WAIT_L(n) asm volatile("s_waitcnt lgkmcnt(" #n ")" ::: "memory")
; #define PG8_BAR __builtin_amdgcn_s_barrier()
; template <class Epi, class Sched, bool ALIGN_EPI = false, bool SP2 = false>
; __device__ __forceinline__ void gemm_phase(PG8_LAS unsigned char* lds, const Gemm g, const Sched& S, const Epi& E) {
;     ...
;         for (int t = 0; t < nt; t += 2) {
;             const bool last = (t == nt - 2);
;             const char* a1 = cA + (size_t)(t + 1) * kstep;
;             const char* a2 = last ? nA : cA + (size_t)(t + 2) * kstep; const char* b2 = last ? nB : cB + (size_t)(t + 2) * kstep;
;             const char* a3 = a2 + kstep; const char* b3 = b2 + kstep;
;     ...
;             PG8_LDB(B0, 1, 0); PG8_LDB(B1, 1, 1); PG8_SCHED; PG8_LDA(At, 1, 0); PG8_STAGE(PG8_SA(0, 1), a2 + hstep, voffA);
;             PG8_WAIT_V(8); PG8_WAIT_L(0); PG8_BAR; PG8_MMA(0, 0, At, B0); PG8_MMA(0, 1, At, B1); PG8_BAR; PG8_SCHED;
;             PG8_LDA(At, 1, 1); PG8_STAGE(PG8_SB(1, 0), b3, voffB); PG8_STAGE(PG8_SB(1, 1), b3 + hstep, voffB); PG8_STAGE(PG8_SA(1, 0), a3, voffA);
;             PG8_WAIT_V(8); PG8_WAIT_L(0); PG8_BAR; PG8_MMA(1, 0, At, B0); PG8_MMA(1, 1, At, B1); PG8_BAR; PG8_SCHED;
	ds_read_b128 v[154:157], v151
	ds_read_b128 v[158:161], v151 offset:1024
	ds_read_b128 v[162:165], v151 offset:2048
	ds_read_b128 v[166:169], v151 offset:3072
	ds_read_b128 v[170:173], v152
	ds_read_b128 v[174:177], v152 offset:1024
	ds_read_b128 v[178:181], v152 offset:2048
	ds_read_b128 v[182:185], v152 offset:3072
	s_add_u32 s22, s38, 0xb0000
	s_addc_u32 s23, s39, 0
	s_mov_b32 m0, s46
	v_lshl_add_u64 v[226:227], s[22:23], 0, v[130:131]
	ds_read_b128 v[186:189], v150 offset:32768
	ds_read_b128 v[190:193], v150 offset:33792
	ds_read_b128 v[194:197], v150 offset:34816
	ds_read_b128 v[198:201], v150 offset:35840
	ds_read_b128 v[202:205], v150 offset:36864
	ds_read_b128 v[206:209], v150 offset:37888
	ds_read_b128 v[210:213], v150 offset:38912
	ds_read_b128 v[214:217], v150 offset:39936
	global_load_lds_dwordx4 v[226:227], off
	v_lshl_add_u64 v[226:227], s[22:23], 0, v[134:135]
	s_mov_b32 m0, s47
	s_nop 0
	global_load_lds_dwordx4 v[226:227], off
	s_waitcnt vmcnt(8)
	s_waitcnt lgkmcnt(0)
	s_barrier
	s_setprio 1
	s_waitcnt lgkmcnt(0)
	v_mfma_f32_16x16x32_bf16 v[126:129], v[154:157], v[186:189], v[126:129]
	v_mfma_f32_16x16x32_bf16 v[122:125], v[162:165], v[186:189], v[122:125]
	v_mfma_f32_16x16x32_bf16 v[118:121], v[154:157], v[194:197], v[118:121]
	v_mfma_f32_16x16x32_bf16 v[114:117], v[162:165], v[194:197], v[114:117]
	v_mfma_f32_16x16x32_bf16 v[102:105], v[154:157], v[202:205], v[102:105]
	v_mfma_f32_16x16x32_bf16 v[98:101], v[162:165], v[202:205], v[98:101]
	v_mfma_f32_16x16x32_bf16 v[86:89], v[154:157], v[210:213], v[86:89]
	v_mfma_f32_16x16x32_bf16 v[82:85], v[162:165], v[210:213], v[82:85]
	v_mfma_f32_16x16x32_bf16 v[126:129], v[158:161], v[190:193], v[126:129]
	v_mfma_f32_16x16x32_bf16 v[122:125], v[166:169], v[190:193], v[122:125]
	v_mfma_f32_16x16x32_bf16 v[118:121], v[158:161], v[198:201], v[118:121]
	v_mfma_f32_16x16x32_bf16 v[114:117], v[166:169], v[198:201], v[114:117]
	v_mfma_f32_16x16x32_bf16 v[102:105], v[158:161], v[206:209], v[102:105]
	v_mfma_f32_16x16x32_bf16 v[98:101], v[166:169], v[206:209], v[98:101]
	v_mfma_f32_16x16x32_bf16 v[86:89], v[158:161], v[214:217], v[86:89]
	v_mfma_f32_16x16x32_bf16 v[82:85], v[166:169], v[214:217], v[82:85]
	s_setprio 0
	s_setprio 1
	v_mfma_f32_16x16x32_bf16 v[110:113], v[170:173], v[186:189], v[110:113]
	v_mfma_f32_16x16x32_bf16 v[106:109], v[178:181], v[186:189], v[106:109]
	v_mfma_f32_16x16x32_bf16 v[94:97], v[170:173], v[194:197], v[94:97]
	v_mfma_f32_16x16x32_bf16 v[90:93], v[178:181], v[194:197], v[90:93]
	v_mfma_f32_16x16x32_bf16 v[78:81], v[170:173], v[202:205], v[78:81]
	v_mfma_f32_16x16x32_bf16 v[74:77], v[178:181], v[202:205], v[74:77]
	v_mfma_f32_16x16x32_bf16 v[70:73], v[170:173], v[210:213], v[70:73]
	v_mfma_f32_16x16x32_bf16 v[66:69], v[178:181], v[210:213], v[66:69]
	v_mfma_f32_16x16x32_bf16 v[110:113], v[174:177], v[190:193], v[110:113]
	v_mfma_f32_16x16x32_bf16 v[106:109], v[182:185], v[190:193], v[106:109]
	v_mfma_f32_16x16x32_bf16 v[94:97], v[174:177], v[198:201], v[94:97]
	v_mfma_f32_16x16x32_bf16 v[90:93], v[182:185], v[198:201], v[90:93]
	v_mfma_f32_16x16x32_bf16 v[78:81], v[174:177], v[206:209], v[78:81]
	v_mfma_f32_16x16x32_bf16 v[74:77], v[182:185], v[206:209], v[74:77]
	v_mfma_f32_16x16x32_bf16 v[70:73], v[174:177], v[214:217], v[70:73]
	v_mfma_f32_16x16x32_bf16 v[66:69], v[182:185], v[214:217], v[66:69]
	s_setprio 0
	s_barrier
	s_mov_b32 m0, s49
	v_lshl_add_u64 v[218:219], v[218:219], 0, s[8:9]
	s_add_u32 s22, s36, 0xb0080
	ds_read_b128 v[186:189], v150 offset:49152
	ds_read_b128 v[190:193], v150 offset:50176
	ds_read_b128 v[194:197], v150 offset:51200
	ds_read_b128 v[198:201], v150 offset:52224
	ds_read_b128 v[202:205], v150 offset:53248
	ds_read_b128 v[206:209], v150 offset:54272
	ds_read_b128 v[210:213], v150 offset:55296
	ds_read_b128 v[214:217], v150 offset:56320
	global_load_lds_dwordx4 v[218:219], off
	v_lshl_add_u64 v[218:219], v[220:221], 0, s[8:9]
	s_mov_b32 m0, s50
	s_addc_u32 s23, s37, 0
	global_load_lds_dwordx4 v[218:219], off
	v_lshl_add_u64 v[218:219], s[22:23], 0, v[132:133]
	s_mov_b32 m0, s53
	s_nop 0
	global_load_lds_dwordx4 v[218:219], off
	v_lshl_add_u64 v[218:219], s[22:23], 0, v[136:137]
	s_mov_b32 m0, s54
	s_nop 0
	global_load_lds_dwordx4 v[218:219], off
	v_lshl_add_u64 v[218:219], v[222:223], 0, s[8:9]
	s_mov_b32 m0, s51
	s_nop 0
	global_load_lds_dwordx4 v[218:219], off
	v_lshl_add_u64 v[218:219], v[224:225], 0, s[8:9]
	s_mov_b32 m0, s52
	s_nop 0
	global_load_lds_dwordx4 v[218:219], off
	s_waitcnt vmcnt(8)
	s_waitcnt lgkmcnt(0)
	s_barrier
	s_setprio 1
	s_waitcnt lgkmcnt(0)
	v_mfma_f32_16x16x32_bf16 v[62:65], v[154:157], v[186:189], v[62:65]
	v_mfma_f32_16x16x32_bf16 v[58:61], v[162:165], v[186:189], v[58:61]
	v_mfma_f32_16x16x32_bf16 v[54:57], v[154:157], v[194:197], v[54:57]
	v_mfma_f32_16x16x32_bf16 v[50:53], v[162:165], v[194:197], v[50:53]
	v_mfma_f32_16x16x32_bf16 v[38:41], v[154:157], v[202:205], v[38:41]
	v_mfma_f32_16x16x32_bf16 v[34:37], v[162:165], v[202:205], v[34:37]
	v_mfma_f32_16x16x32_bf16 v[22:25], v[154:157], v[210:213], v[22:25]
	v_mfma_f32_16x16x32_bf16 v[18:21], v[162:165], v[210:213], v[18:21]
	v_mfma_f32_16x16x32_bf16 v[62:65], v[158:161], v[190:193], v[62:65]
	v_mfma_f32_16x16x32_bf16 v[58:61], v[166:169], v[190:193], v[58:61]
	v_mfma_f32_16x16x32_bf16 v[54:57], v[158:161], v[198:201], v[54:57]
	v_mfma_f32_16x16x32_bf16 v[50:53], v[166:169], v[198:201], v[50:53]
	v_mfma_f32_16x16x32_bf16 v[38:41], v[158:161], v[206:209], v[38:41]
	v_mfma_f32_16x16x32_bf16 v[34:37], v[166:169], v[206:209], v[34:37]
	v_mfma_f32_16x16x32_bf16 v[22:25], v[158:161], v[214:217], v[22:25]
	v_mfma_f32_16x16x32_bf16 v[18:21], v[166:169], v[214:217], v[18:21]
	s_setprio 0
	s_setprio 1
	v_mfma_f32_16x16x32_bf16 v[46:49], v[170:173], v[186:189], v[46:49]
	v_mfma_f32_16x16x32_bf16 v[42:45], v[178:181], v[186:189], v[42:45]
	v_mfma_f32_16x16x32_bf16 v[30:33], v[170:173], v[194:197], v[30:33]
	v_mfma_f32_16x16x32_bf16 v[26:29], v[178:181], v[194:197], v[26:29]
	v_mfma_f32_16x16x32_bf16 v[14:17], v[170:173], v[202:205], v[14:17]
	v_mfma_f32_16x16x32_bf16 v[10:13], v[178:181], v[202:205], v[10:13]
	v_mfma_f32_16x16x32_bf16 v[6:9], v[170:173], v[210:213], v[6:9]
	v_mfma_f32_16x16x32_bf16 v[2:5], v[178:181], v[210:213], v[2:5]
	v_mfma_f32_16x16x32_bf16 v[46:49], v[174:177], v[190:193], v[46:49]
	v_mfma_f32_16x16x32_bf16 v[42:45], v[182:185], v[190:193], v[42:45]
	v_mfma_f32_16x16x32_bf16 v[30:33], v[174:177], v[198:201], v[30:33]
	v_mfma_f32_16x16x32_bf16 v[26:29], v[182:185], v[198:201], v[26:29]
	v_mfma_f32_16x16x32_bf16 v[14:17], v[174:177], v[206:209], v[14:17]
	v_mfma_f32_16x16x32_bf16 v[10:13], v[182:185], v[206:209], v[10:13]
	v_mfma_f32_16x16x32_bf16 v[6:9], v[174:177], v[214:217], v[6:9]
	v_mfma_f32_16x16x32_bf16 v[2:5], v[182:185], v[214:217], v[2:5]
	s_setprio 0
	s_add_i32 s66, s66, 2
	s_add_u32 s64, s64, 0x100
	s_addc_u32 s65, s65, 0
	s_cmp_gt_u32 s66, 41
	s_mov_b64 s[22:23], s[24:25]
	s_barrier
	s_cbranch_scc0 .LBB0_2367
	s_and_b64 vcc, exec, s[10:11]
	s_cbranch_vccz .LBB0_2370
	s_barrier
